# minimal-edit variant: barrier sink k=2 with prio-2 tail + setprio-1 hoist + final-norm prefetch, no shadow LDS reads
# speedup vs baseline: 1.0158x; 1.0015x over previous
; #define PG8_STAGE(bufoff, gbase, voff) do { _Pragma("unroll") for (int _i = 0; _i < 2; ++_i) \
;         __builtin_amdgcn_global_load_lds((const unsigned*)((const char*)(gbase) + (voff)[_i]), (LAS unsigned*)(lds + (bufoff) + ldsw + _i * 8192), 16, 0, 0); } while (0)
; #define PG8_LDA(dst, b, h) do { _Pragma("unroll") for (int m = 0; m < 4; ++m) _Pragma("unroll") for (int k = 0; k < 2; ++k) dst[m][k] = *(const LAS bf16x8*)(lds + PG8_SA(b, h) + aoff + m * 2048 + k * 1024); } while (0)
; #define PG8_LDB(dst, b, h) do { _Pragma("unroll") for (int n = 0; n < 2; ++n) _Pragma("unroll") for (int k = 0; k < 2; ++k) dst[n][k] = *(const LAS bf16x8*)(lds + PG8_SB(b, h) + boff + n * 2048 + k * 1024); } while (0)
; #define PG8_MMA(ai, bj, At, Bt) do { __builtin_amdgcn_s_setprio(1); _Pragma("unroll") for (int m = 0; m < 4; ++m) _Pragma("unroll") for (int n = 0; n < 2; ++n) _Pragma("unroll") for (int k = 0; k < 2; ++k) \
;         acc[ai][bj][m][n] = __builtin_amdgcn_mfma_f32_16x16x32_bf16(Bt[n][k], At[m][k], acc[ai][bj][m][n], 0, 0, 0); __builtin_amdgcn_s_setprio(0); } while (0)
; #define PG8_WAIT_V(n) asm volatile("s_waitcnt vmcnt(" #n ")" ::: "memory")
; #define PG8_WAIT_L(n) asm volatile("s_waitcnt lgkmcnt(" #n ")" ::: "memory")
; #define PG8_BAR __builtin_amdgcn_s_barrier()
; #define PG8_SCHED __builtin_amdgcn_sched_barrier(0)
; template <class Epi>
; DI void gemm_phase(LAS unsigned char* lds, const Gemm g, const StaticOrder S, const Epi E) {
;     ...
;             const bool last = (t == nt - 2);
;             const char* a1 = cA + (size_t)(t + 1) * kstep;
;             const char* a2 = last ? nA : cA + (size_t)(t + 2) * kstep; const char* b2 = last ? nB : cB + (size_t)(t + 2) * kstep;
;             const char* a3 = a2 + kstep; const char* b3 = b2 + kstep;
;             PG8_LDB(B0, 0, 0); PG8_SCHED; PG8_LDA(At, 0, 0); PG8_STAGE(PG8_SA(1, 1), a1 + hstep, voffA);
;             PG8_WAIT_L(8); PG8_BAR; PG8_WAIT_L(0); PG8_MMA(0, 0, At, B0); PG8_BAR; PG8_SCHED;
;             PG8_LDB(B1, 0, 1); PG8_STAGE(PG8_SB(0, 0), b2, voffB);
;             PG8_BAR; PG8_WAIT_L(0); PG8_MMA(0, 1, At, B1); PG8_BAR;
;             PG8_LDA(At, 0, 1); PG8_STAGE(PG8_SA(0, 0), a2, voffA);
;             PG8_BAR; PG8_WAIT_L(0); PG8_MMA(1, 0, At, B0); PG8_BAR; PG8_SCHED;
;             PG8_STAGE(PG8_SB(0, 1), b2 + hstep, voffB);
;             PG8_WAIT_V(6); PG8_BAR; PG8_MMA(1, 1, At, B1); PG8_BAR;
.LBB0_107:
	ds_read_b128 v[152:155], v149
	ds_read_b128 v[156:159], v149 offset:1024
	ds_read_b128 v[160:163], v149 offset:2048
	ds_read_b128 v[164:167], v149 offset:3072
	s_add_u32 s14, s76, 0xfffc0080
	s_addc_u32 s15, s77, -1
	s_cmp_eq_u32 s97, 12
	s_cselect_b32 s81, s11, s15
	s_cselect_b32 s80, s93, s14
	s_cselect_b32 s79, s9, s96
	s_cselect_b32 s78, s94, s95
	v_lshl_add_u64 v[144:145], s[76:77], 0, v[136:137]
	s_add_i32 m0, s29, 0xc000
	ds_read_b128 v[168:171], v150
	ds_read_b128 v[172:175], v150 offset:1024
	ds_read_b128 v[176:179], v150 offset:2048
	ds_read_b128 v[180:183], v150 offset:3072
	ds_read_b128 v[184:187], v150 offset:4096
	ds_read_b128 v[188:191], v150 offset:5120
	ds_read_b128 v[192:195], v150 offset:6144
	ds_read_b128 v[196:199], v150 offset:7168
	global_load_lds_dwordx4 v[144:145], off
	v_lshl_add_u64 v[144:145], s[76:77], 0, v[138:139]
	s_add_i32 m0, s29, 0xe000
	s_nop 0
	global_load_lds_dwordx4 v[144:145], off
	s_waitcnt lgkmcnt(8)
	s_setprio 1
	s_barrier
	s_waitcnt lgkmcnt(0)
	v_mfma_f32_16x16x32_bf16 v[124:127], v[152:155], v[168:171], v[124:127]
	v_mfma_f32_16x16x32_bf16 v[116:119], v[160:163], v[168:171], v[116:119]
	v_mfma_f32_16x16x32_bf16 v[108:111], v[152:155], v[176:179], v[108:111]
	v_mfma_f32_16x16x32_bf16 v[100:103], v[160:163], v[176:179], v[100:103]
	v_mfma_f32_16x16x32_bf16 v[92:95], v[152:155], v[184:187], v[92:95]
	v_mfma_f32_16x16x32_bf16 v[84:87], v[160:163], v[184:187], v[84:87]
	v_mfma_f32_16x16x32_bf16 v[76:79], v[152:155], v[192:195], v[76:79]
	v_mfma_f32_16x16x32_bf16 v[68:71], v[160:163], v[192:195], v[68:71]
	v_mfma_f32_16x16x32_bf16 v[124:127], v[156:159], v[172:175], v[124:127]
	v_mfma_f32_16x16x32_bf16 v[116:119], v[164:167], v[172:175], v[116:119]
	v_mfma_f32_16x16x32_bf16 v[108:111], v[156:159], v[180:183], v[108:111]
	v_mfma_f32_16x16x32_bf16 v[100:103], v[164:167], v[180:183], v[100:103]
	v_mfma_f32_16x16x32_bf16 v[92:95], v[156:159], v[188:191], v[92:95]
	v_mfma_f32_16x16x32_bf16 v[84:87], v[164:167], v[188:191], v[84:87]
	s_setprio 2
	s_barrier
	v_mfma_f32_16x16x32_bf16 v[76:79], v[156:159], v[196:199], v[76:79]
	v_mfma_f32_16x16x32_bf16 v[68:71], v[164:167], v[196:199], v[68:71]
	s_setprio 0
	s_add_i32 s14, s89, s7
	v_lshl_add_u64 v[144:145], s[78:79], 0, v[132:133]
	s_mov_b32 m0, s14
	ds_read_b128 v[200:203], v151
	ds_read_b128 v[204:207], v151 offset:1024
	ds_read_b128 v[208:211], v151 offset:2048
	ds_read_b128 v[212:215], v151 offset:3072
	global_load_lds_dwordx4 v[144:145], off
	v_lshl_add_u64 v[216:217], s[78:79], 0, v[128:129]
	s_add_i32 m0, s14, 0x2000
	s_nop 0
	global_load_lds_dwordx4 v[216:217], off
	s_setprio 1
	s_barrier
	s_waitcnt lgkmcnt(0)
	v_mfma_f32_16x16x32_bf16 v[120:123], v[200:203], v[168:171], v[120:123]
	v_mfma_f32_16x16x32_bf16 v[112:115], v[208:211], v[168:171], v[112:115]
	v_mfma_f32_16x16x32_bf16 v[104:107], v[200:203], v[176:179], v[104:107]
	v_mfma_f32_16x16x32_bf16 v[96:99], v[208:211], v[176:179], v[96:99]
	v_mfma_f32_16x16x32_bf16 v[88:91], v[200:203], v[184:187], v[88:91]
	v_mfma_f32_16x16x32_bf16 v[80:83], v[208:211], v[184:187], v[80:83]
	v_mfma_f32_16x16x32_bf16 v[72:75], v[200:203], v[192:195], v[72:75]
	v_mfma_f32_16x16x32_bf16 v[64:67], v[208:211], v[192:195], v[64:67]
	v_mfma_f32_16x16x32_bf16 v[120:123], v[204:207], v[172:175], v[120:123]
	v_mfma_f32_16x16x32_bf16 v[112:115], v[212:215], v[172:175], v[112:115]
	v_mfma_f32_16x16x32_bf16 v[104:107], v[204:207], v[180:183], v[104:107]
	v_mfma_f32_16x16x32_bf16 v[96:99], v[212:215], v[180:183], v[96:99]
	v_mfma_f32_16x16x32_bf16 v[88:91], v[204:207], v[188:191], v[88:91]
	v_mfma_f32_16x16x32_bf16 v[80:83], v[212:215], v[188:191], v[80:83]
	s_setprio 2
	s_barrier
	v_mfma_f32_16x16x32_bf16 v[72:75], v[204:207], v[196:199], v[72:75]
	v_mfma_f32_16x16x32_bf16 v[64:67], v[212:215], v[196:199], v[64:67]
	s_setprio 0
	s_mov_b32 m0, s29
	v_lshl_add_u64 v[218:219], s[80:81], 0, v[134:135]
	ds_read_b128 v[168:171], v150 offset:16384
	ds_read_b128 v[172:175], v150 offset:17408
	ds_read_b128 v[176:179], v150 offset:18432
	ds_read_b128 v[180:183], v150 offset:19456
	ds_read_b128 v[184:187], v150 offset:20480
	ds_read_b128 v[188:191], v150 offset:21504
	ds_read_b128 v[192:195], v150 offset:22528
	ds_read_b128 v[196:199], v150 offset:23552
	global_load_lds_dwordx4 v[218:219], off
	v_lshl_add_u64 v[220:221], s[80:81], 0, v[130:131]
	s_mov_b32 m0, s59
	s_nop 0
	global_load_lds_dwordx4 v[220:221], off
	s_setprio 1
	s_barrier
	s_waitcnt lgkmcnt(0)
	v_mfma_f32_16x16x32_bf16 v[60:63], v[152:155], v[168:171], v[60:63]
	v_mfma_f32_16x16x32_bf16 v[52:55], v[160:163], v[168:171], v[52:55]
	v_mfma_f32_16x16x32_bf16 v[44:47], v[152:155], v[176:179], v[44:47]
	v_mfma_f32_16x16x32_bf16 v[36:39], v[160:163], v[176:179], v[36:39]
	v_mfma_f32_16x16x32_bf16 v[28:31], v[152:155], v[184:187], v[28:31]
	v_mfma_f32_16x16x32_bf16 v[20:23], v[160:163], v[184:187], v[20:23]
	v_mfma_f32_16x16x32_bf16 v[12:15], v[152:155], v[192:195], v[12:15]
	v_mfma_f32_16x16x32_bf16 v[4:7], v[160:163], v[192:195], v[4:7]
	v_mfma_f32_16x16x32_bf16 v[60:63], v[156:159], v[172:175], v[60:63]
	v_mfma_f32_16x16x32_bf16 v[52:55], v[164:167], v[172:175], v[52:55]
	v_mfma_f32_16x16x32_bf16 v[44:47], v[156:159], v[180:183], v[44:47]
	v_mfma_f32_16x16x32_bf16 v[36:39], v[164:167], v[180:183], v[36:39]
	v_mfma_f32_16x16x32_bf16 v[28:31], v[156:159], v[188:191], v[28:31]
	v_mfma_f32_16x16x32_bf16 v[20:23], v[164:167], v[188:191], v[20:23]
	s_setprio 2
	s_barrier
; #define PG8_STAGE(bufoff, gbase, voff) do { _Pragma("unroll") for (int _i = 0; _i < 2; ++_i) \
;         __builtin_amdgcn_global_load_lds((const unsigned*)((const char*)(gbase) + (voff)[_i]), (LAS unsigned*)(lds + (bufoff) + ldsw + _i * 8192), 16, 0, 0); } while (0)
; #define PG8_LDA(dst, b, h) do { _Pragma("unroll") for (int m = 0; m < 4; ++m) _Pragma("unroll") for (int k = 0; k < 2; ++k) dst[m][k] = *(const LAS bf16x8*)(lds + PG8_SA(b, h) + aoff + m * 2048 + k * 1024); } while (0)
; #define PG8_LDB(dst, b, h) do { _Pragma("unroll") for (int n = 0; n < 2; ++n) _Pragma("unroll") for (int k = 0; k < 2; ++k) dst[n][k] = *(const LAS bf16x8*)(lds + PG8_SB(b, h) + boff + n * 2048 + k * 1024); } while (0)
; #define PG8_MMA(ai, bj, At, Bt) do { __builtin_amdgcn_s_setprio(1); _Pragma("unroll") for (int m = 0; m < 4; ++m) _Pragma("unroll") for (int n = 0; n < 2; ++n) _Pragma("unroll") for (int k = 0; k < 2; ++k) \
;         acc[ai][bj][m][n] = __builtin_amdgcn_mfma_f32_16x16x32_bf16(Bt[n][k], At[m][k], acc[ai][bj][m][n], 0, 0, 0); __builtin_amdgcn_s_setprio(0); } while (0)
; #define PG8_WAIT_V(n) asm volatile("s_waitcnt vmcnt(" #n ")" ::: "memory")
; #define PG8_WAIT_L(n) asm volatile("s_waitcnt lgkmcnt(" #n ")" ::: "memory")
; #define PG8_BAR __builtin_amdgcn_s_barrier()
; #define PG8_SCHED __builtin_amdgcn_sched_barrier(0)
; #define PG8_STAGE(bufoff, gbase, voff) do { _Pragma("unroll") for (int _i = 0; _i < 2; ++_i) \
;         __builtin_amdgcn_global_load_lds((const unsigned*)((const char*)(gbase) + (voff)[_i]), (LAS unsigned*)(lds + (bufoff) + ldsw + _i * 8192), 16, 0, 0); } while (0)
; #define PG8_WAIT_V(n) asm volatile("s_waitcnt vmcnt(" #n ")" ::: "memory")
; template <class Epi>
; DI void gemm_phase(LAS unsigned char* lds, const Gemm g, const StaticOrder S, const Epi E) {
;     ...
;             PG8_BAR; PG8_WAIT_L(0); PG8_MMA(1, 0, At, B0); PG8_BAR; PG8_SCHED;
;             PG8_STAGE(PG8_SB(0, 1), b2 + hstep, voffB);
;             PG8_WAIT_V(6); PG8_BAR; PG8_MMA(1, 1, At, B1); PG8_BAR;
;             PG8_LDB(B0, 1, 0); PG8_SCHED; PG8_LDA(At, 1, 0); PG8_STAGE(PG8_SA(0, 1), a2 + hstep, voffA);
;             PG8_WAIT_L(8); PG8_BAR; PG8_WAIT_L(0); PG8_MMA(0, 0, At, B0); PG8_BAR; PG8_SCHED;
;             PG8_LDB(B1, 1, 1); PG8_STAGE(PG8_SB(1, 0), b3, voffB);
;             PG8_BAR; PG8_WAIT_L(0); PG8_MMA(0, 1, At, B1); PG8_BAR;
	v_mfma_f32_16x16x32_bf16 v[12:15], v[156:159], v[196:199], v[12:15]
	v_mfma_f32_16x16x32_bf16 v[4:7], v[164:167], v[196:199], v[4:7]
	s_setprio 0
	s_add_u32 s14, s78, 0x40000
	s_addc_u32 s15, s79, 0
	s_add_i32 s35, s90, s7
	v_lshl_add_u64 v[152:153], s[14:15], 0, v[132:133]
	s_mov_b32 m0, s35
	s_nop 0
	global_load_lds_dwordx4 v[152:153], off
	v_lshl_add_u64 v[152:153], s[14:15], 0, v[128:129]
	s_add_i32 m0, s35, 0x2000
	s_nop 0
	global_load_lds_dwordx4 v[152:153], off
	s_waitcnt vmcnt(6)
	s_setprio 1
	s_barrier
	v_mfma_f32_16x16x32_bf16 v[56:59], v[200:203], v[168:171], v[56:59]
	v_mfma_f32_16x16x32_bf16 v[48:51], v[208:211], v[168:171], v[48:51]
	v_mfma_f32_16x16x32_bf16 v[40:43], v[200:203], v[176:179], v[40:43]
	v_mfma_f32_16x16x32_bf16 v[32:35], v[208:211], v[176:179], v[32:35]
	v_mfma_f32_16x16x32_bf16 v[24:27], v[200:203], v[184:187], v[24:27]
	v_mfma_f32_16x16x32_bf16 v[16:19], v[208:211], v[184:187], v[16:19]
	v_mfma_f32_16x16x32_bf16 v[8:11], v[200:203], v[192:195], v[8:11]
	v_mfma_f32_16x16x32_bf16 v[0:3], v[208:211], v[192:195], v[0:3]
	v_mfma_f32_16x16x32_bf16 v[56:59], v[204:207], v[172:175], v[56:59]
	v_mfma_f32_16x16x32_bf16 v[48:51], v[212:215], v[172:175], v[48:51]
	v_mfma_f32_16x16x32_bf16 v[40:43], v[204:207], v[180:183], v[40:43]
	v_mfma_f32_16x16x32_bf16 v[32:35], v[212:215], v[180:183], v[32:35]
	v_mfma_f32_16x16x32_bf16 v[24:27], v[204:207], v[188:191], v[24:27]
	v_mfma_f32_16x16x32_bf16 v[16:19], v[212:215], v[188:191], v[16:19]
	s_setprio 2
	s_barrier
	v_mfma_f32_16x16x32_bf16 v[8:11], v[204:207], v[196:199], v[8:11]
	v_mfma_f32_16x16x32_bf16 v[0:3], v[212:215], v[196:199], v[0:3]
	s_setprio 0
	s_add_i32 s35, 0, 0x18000
	v_add_u32_e32 v164, s35, v147
	ds_read_b128 v[152:155], v164
	ds_read_b128 v[156:159], v164 offset:1024
	ds_read_b128 v[160:163], v164 offset:2048
	ds_read_b128 v[164:167], v164 offset:3072
	s_add_u32 s14, s80, 0x40000
	s_addc_u32 s15, s81, 0
	s_mov_b32 m0, s82
	v_lshl_add_u64 v[200:201], s[14:15], 0, v[134:135]
	ds_read_b128 v[168:171], v150 offset:32768
	ds_read_b128 v[172:175], v150 offset:33792
	ds_read_b128 v[176:179], v150 offset:34816
	ds_read_b128 v[180:183], v150 offset:35840
	ds_read_b128 v[184:187], v150 offset:36864
	ds_read_b128 v[188:191], v150 offset:37888
	ds_read_b128 v[192:195], v150 offset:38912
	ds_read_b128 v[196:199], v150 offset:39936
	global_load_lds_dwordx4 v[200:201], off
	v_lshl_add_u64 v[200:201], s[14:15], 0, v[130:131]
	s_mov_b32 m0, s83
	s_nop 0
	global_load_lds_dwordx4 v[200:201], off
	s_waitcnt lgkmcnt(8)
	s_setprio 1
	s_barrier
	s_waitcnt lgkmcnt(0)
	v_mfma_f32_16x16x32_bf16 v[124:127], v[152:155], v[168:171], v[124:127]
	v_mfma_f32_16x16x32_bf16 v[116:119], v[160:163], v[168:171], v[116:119]
	v_mfma_f32_16x16x32_bf16 v[108:111], v[152:155], v[176:179], v[108:111]
	v_mfma_f32_16x16x32_bf16 v[100:103], v[160:163], v[176:179], v[100:103]
	v_mfma_f32_16x16x32_bf16 v[92:95], v[152:155], v[184:187], v[92:95]
	v_mfma_f32_16x16x32_bf16 v[84:87], v[160:163], v[184:187], v[84:87]
	v_mfma_f32_16x16x32_bf16 v[76:79], v[152:155], v[192:195], v[76:79]
	v_mfma_f32_16x16x32_bf16 v[68:71], v[160:163], v[192:195], v[68:71]
	v_mfma_f32_16x16x32_bf16 v[124:127], v[156:159], v[172:175], v[124:127]
	v_mfma_f32_16x16x32_bf16 v[116:119], v[164:167], v[172:175], v[116:119]
	v_mfma_f32_16x16x32_bf16 v[108:111], v[156:159], v[180:183], v[108:111]
	v_mfma_f32_16x16x32_bf16 v[100:103], v[164:167], v[180:183], v[100:103]
	v_mfma_f32_16x16x32_bf16 v[92:95], v[156:159], v[188:191], v[92:95]
	v_mfma_f32_16x16x32_bf16 v[84:87], v[164:167], v[188:191], v[84:87]
	s_setprio 2
	s_barrier
	v_mfma_f32_16x16x32_bf16 v[76:79], v[156:159], v[196:199], v[76:79]
	v_mfma_f32_16x16x32_bf16 v[68:71], v[164:167], v[196:199], v[68:71]
	s_setprio 0
	s_add_i32 s80, 0, 0x1c000
	s_add_i32 s14, s35, s7
	v_add_u32_e32 v212, s80, v147
	v_lshl_add_u64 v[144:145], v[144:145], 0, s[4:5]
	s_mov_b32 m0, s14
	ds_read_b128 v[200:203], v212
	ds_read_b128 v[204:207], v212 offset:1024
	ds_read_b128 v[208:211], v212 offset:2048
	ds_read_b128 v[212:215], v212 offset:3072
	global_load_lds_dwordx4 v[144:145], off
	v_lshl_add_u64 v[144:145], v[216:217], 0, s[4:5]
	s_add_i32 m0, s14, 0x2000
	s_nop 0
	global_load_lds_dwordx4 v[144:145], off
	s_setprio 1
	s_barrier
	s_waitcnt lgkmcnt(0)
	v_mfma_f32_16x16x32_bf16 v[120:123], v[200:203], v[168:171], v[120:123]
	v_mfma_f32_16x16x32_bf16 v[112:115], v[208:211], v[168:171], v[112:115]
	v_mfma_f32_16x16x32_bf16 v[104:107], v[200:203], v[176:179], v[104:107]
	v_mfma_f32_16x16x32_bf16 v[96:99], v[208:211], v[176:179], v[96:99]
	v_mfma_f32_16x16x32_bf16 v[88:91], v[200:203], v[184:187], v[88:91]
	v_mfma_f32_16x16x32_bf16 v[80:83], v[208:211], v[184:187], v[80:83]
	v_mfma_f32_16x16x32_bf16 v[72:75], v[200:203], v[192:195], v[72:75]
	v_mfma_f32_16x16x32_bf16 v[64:67], v[208:211], v[192:195], v[64:67]
	v_mfma_f32_16x16x32_bf16 v[120:123], v[204:207], v[172:175], v[120:123]
	v_mfma_f32_16x16x32_bf16 v[112:115], v[212:215], v[172:175], v[112:115]
	v_mfma_f32_16x16x32_bf16 v[104:107], v[204:207], v[180:183], v[104:107]
	v_mfma_f32_16x16x32_bf16 v[96:99], v[212:215], v[180:183], v[96:99]
	v_mfma_f32_16x16x32_bf16 v[88:91], v[204:207], v[188:191], v[88:91]
	v_mfma_f32_16x16x32_bf16 v[80:83], v[212:215], v[188:191], v[80:83]
	s_setprio 2
	s_barrier
; DI unsigned pk_bf16(float lo, float hi) { f32x2 v = {lo, hi}; return __builtin_bit_cast(unsigned, __builtin_convertvector(v, bf16v2)); }
; DI float fast_silu(float x) { return x * fast_sigmoid(x); }
; #define PG8_STAGE(bufoff, gbase, voff) do { _Pragma("unroll") for (int _i = 0; _i < 2; ++_i) \
;         __builtin_amdgcn_global_load_lds((const unsigned*)((const char*)(gbase) + (voff)[_i]), (LAS unsigned*)(lds + (bufoff) + ldsw + _i * 8192), 16, 0, 0); } while (0)
; #define PG8_LDA(dst, b, h) do { _Pragma("unroll") for (int m = 0; m < 4; ++m) _Pragma("unroll") for (int k = 0; k < 2; ++k) dst[m][k] = *(const LAS bf16x8*)(lds + PG8_SA(b, h) + aoff + m * 2048 + k * 1024); } while (0)
; #define PG8_WAIT_V(n) asm volatile("s_waitcnt vmcnt(" #n ")" ::: "memory")
; #define PG8_WAIT_L(n) asm volatile("s_waitcnt lgkmcnt(" #n ")" ::: "memory")
; #define PG8_BAR __builtin_amdgcn_s_barrier()
; #define PG8_SCHED __builtin_amdgcn_sched_barrier(0)
; template <class Epi>
; DI void gemm_phase(LAS unsigned char* lds, const Gemm g, const StaticOrder S, const Epi E) {
;     ...
;             PG8_BAR; PG8_WAIT_L(0); PG8_MMA(0, 1, At, B1); PG8_BAR;
;             PG8_LDA(At, 1, 1); PG8_STAGE(PG8_SA(1, 0), a3, voffA);
;             PG8_BAR; PG8_WAIT_L(0); PG8_MMA(1, 0, At, B0); PG8_BAR; PG8_SCHED;
;             PG8_STAGE(PG8_SB(1, 1), b3 + hstep, voffB);
;             PG8_WAIT_V(6); PG8_BAR; PG8_MMA(1, 1, At, B1); PG8_BAR;
;     DI void operator()(AccRef acc, const Unit& u, int wr, int wc, int fr, int fq) const {
;         const int row0 = u.pm * 256 + wr * 64 + fr, col = u.pn * 128 + wc * 32 + 8 * fq;
;         RowScales rsc; if (RS) rsc = load_rowscales(ss, row0);
; #pragma unroll
;         for (int ai = 0; ai < 2; ++ai)
; #pragma unroll
;             for (int m = 0; m < 4; ++m) {
;                 const int row = row0 + ai * 128 + m * 16;
;                 const float r = RS ? rsc.r[ai][m] : 1.0f;
;                 const f32x4 a0 = acc[ai][0][m][0] * r, a1 = acc[ai][0][m][1] * r, b0 = acc[ai][1][m][0] * r, b1 = acc[ai][1][m][1] * r;
;                 u32x4 w;
;                 w.x = pk_bf16(fast_silu(a0[0]) * b0[0], fast_silu(a0[1]) * b0[1]); w.y = pk_bf16(fast_silu(a0[2]) * b0[2], fast_silu(a0[3]) * b0[3]);
;                 w.z = pk_bf16(fast_silu(a1[0]) * b1[0], fast_silu(a1[1]) * b1[1]); w.w = pk_bf16(fast_silu(a1[2]) * b1[2], fast_silu(a1[3]) * b1[3]);
	v_mfma_f32_16x16x32_bf16 v[72:75], v[204:207], v[196:199], v[72:75]
	v_mfma_f32_16x16x32_bf16 v[64:67], v[212:215], v[196:199], v[64:67]
	s_setprio 0
	s_mov_b32 m0, s85
	v_lshl_add_u64 v[144:145], v[218:219], 0, s[4:5]
	ds_read_b128 v[168:171], v150 offset:49152
	ds_read_b128 v[172:175], v150 offset:50176
	ds_read_b128 v[176:179], v150 offset:51200
	ds_read_b128 v[180:183], v150 offset:52224
	ds_read_b128 v[184:187], v150 offset:53248
	ds_read_b128 v[188:191], v150 offset:54272
	ds_read_b128 v[192:195], v150 offset:55296
	ds_read_b128 v[196:199], v150 offset:56320
	global_load_lds_dwordx4 v[144:145], off
	v_lshl_add_u64 v[144:145], v[220:221], 0, s[4:5]
	s_mov_b32 m0, s86
	s_nop 0
	global_load_lds_dwordx4 v[144:145], off
	s_setprio 1
	s_barrier
	s_waitcnt lgkmcnt(0)
	v_mfma_f32_16x16x32_bf16 v[60:63], v[152:155], v[168:171], v[60:63]
	v_mfma_f32_16x16x32_bf16 v[52:55], v[160:163], v[168:171], v[52:55]
	v_mfma_f32_16x16x32_bf16 v[44:47], v[152:155], v[176:179], v[44:47]
	v_mfma_f32_16x16x32_bf16 v[36:39], v[160:163], v[176:179], v[36:39]
	v_mfma_f32_16x16x32_bf16 v[28:31], v[152:155], v[184:187], v[28:31]
	v_mfma_f32_16x16x32_bf16 v[20:23], v[160:163], v[184:187], v[20:23]
	v_mfma_f32_16x16x32_bf16 v[12:15], v[152:155], v[192:195], v[12:15]
	v_mfma_f32_16x16x32_bf16 v[4:7], v[160:163], v[192:195], v[4:7]
	v_mfma_f32_16x16x32_bf16 v[60:63], v[156:159], v[172:175], v[60:63]
	v_mfma_f32_16x16x32_bf16 v[52:55], v[164:167], v[172:175], v[52:55]
	v_mfma_f32_16x16x32_bf16 v[44:47], v[156:159], v[180:183], v[44:47]
	v_mfma_f32_16x16x32_bf16 v[36:39], v[164:167], v[180:183], v[36:39]
	v_mfma_f32_16x16x32_bf16 v[28:31], v[156:159], v[188:191], v[28:31]
	v_mfma_f32_16x16x32_bf16 v[20:23], v[164:167], v[188:191], v[20:23]
	s_setprio 2
	s_barrier
	v_mfma_f32_16x16x32_bf16 v[12:15], v[156:159], v[196:199], v[12:15]
	v_mfma_f32_16x16x32_bf16 v[4:7], v[164:167], v[196:199], v[4:7]
	s_setprio 0
	s_add_u32 s14, s78, 0x40080
	s_addc_u32 s15, s79, 0
	s_add_i32 s35, s80, s7
	v_lshl_add_u64 v[144:145], s[14:15], 0, v[132:133]
	s_mov_b32 m0, s35
	s_nop 0
	global_load_lds_dwordx4 v[144:145], off
	v_lshl_add_u64 v[144:145], s[14:15], 0, v[128:129]
	s_add_i32 m0, s35, 0x2000
	s_nop 0
	global_load_lds_dwordx4 v[144:145], off
	s_waitcnt vmcnt(6)
	s_setprio 1
	s_barrier
	v_mfma_f32_16x16x32_bf16 v[56:59], v[200:203], v[168:171], v[56:59]
	v_mfma_f32_16x16x32_bf16 v[48:51], v[208:211], v[168:171], v[48:51]
	v_mfma_f32_16x16x32_bf16 v[40:43], v[200:203], v[176:179], v[40:43]
	v_mfma_f32_16x16x32_bf16 v[32:35], v[208:211], v[176:179], v[32:35]
	v_mfma_f32_16x16x32_bf16 v[24:27], v[200:203], v[184:187], v[24:27]
	v_mfma_f32_16x16x32_bf16 v[16:19], v[208:211], v[184:187], v[16:19]
	v_mfma_f32_16x16x32_bf16 v[8:11], v[200:203], v[192:195], v[8:11]
	v_mfma_f32_16x16x32_bf16 v[0:3], v[208:211], v[192:195], v[0:3]
	v_mfma_f32_16x16x32_bf16 v[56:59], v[204:207], v[172:175], v[56:59]
	v_mfma_f32_16x16x32_bf16 v[48:51], v[212:215], v[172:175], v[48:51]
	v_mfma_f32_16x16x32_bf16 v[40:43], v[204:207], v[180:183], v[40:43]
	v_mfma_f32_16x16x32_bf16 v[32:35], v[212:215], v[180:183], v[32:35]
	v_mfma_f32_16x16x32_bf16 v[24:27], v[204:207], v[188:191], v[24:27]
	v_mfma_f32_16x16x32_bf16 v[16:19], v[212:215], v[188:191], v[16:19]
	s_setprio 2
	s_barrier
	v_mfma_f32_16x16x32_bf16 v[8:11], v[204:207], v[196:199], v[8:11]
	v_mfma_f32_16x16x32_bf16 v[0:3], v[212:215], v[196:199], v[0:3]
	s_setprio 0
	s_add_i32 s97, s97, 2
	s_add_u32 s76, s76, 0x100
	s_addc_u32 s77, s77, 0
	s_add_u32 s95, s95, 0x100
	s_addc_u32 s96, s96, 0
	s_cmp_gt_u32 s97, 13
	s_cbranch_scc0 .LBB0_107
	v_mul_f32_e32 v153, 0xbfb8aa3b, v124
	v_exp_f32_e32 v153, v153
	v_mul_f32_e32 v154, 0xbfb8aa3b, v125
	v_exp_f32_e32 v155, v154
	v_lshl_or_b32 v144, s92, 7, v148
	v_add_f32_e32 v153, 1.0, v153
	v_rcp_f32_e32 v154, v153
	v_add_f32_e32 v153, 1.0, v155
	v_mul_f32_e32 v155, 0xbfb8aa3b, v126
	v_exp_f32_e32 v156, v155
	v_mul_f32_e32 v155, 0xbfb8aa3b, v127
	v_exp_f32_e32 v157, v155
	v_rcp_f32_e32 v155, v153
	v_add_f32_e32 v153, 1.0, v156
	v_rcp_f32_e32 v156, v153
	v_add_f32_e32 v153, 1.0, v157
	v_rcp_f32_e32 v157, v153
	v_pk_mul_f32 v[124:125], v[124:125], v[154:155]
	v_ashrrev_i32_e32 v145, 31, v144
	v_pk_mul_f32 v[120:121], v[124:125], v[120:121]
	v_pk_mul_f32 v[124:125], v[126:127], v[156:157]
	v_cvt_pk_bf16_f32 v120, v120, v121
	v_mul_f32_e32 v121, 0xbfb8aa3b, v116
	v_pk_mul_f32 v[122:123], v[124:125], v[122:123]
	v_exp_f32_e32 v124, v121
	v_mul_f32_e32 v121, 0xbfb8aa3b, v117
	v_exp_f32_e32 v125, v121
	v_cvt_pk_bf16_f32 v121, v122, v123
	v_add_f32_e32 v122, 1.0, v124
	v_mul_f32_e32 v124, 0xbfb8aa3b, v118
	v_add_f32_e32 v123, 1.0, v125
	v_mul_f32_e32 v125, 0xbfb8aa3b, v119
	v_exp_f32_e32 v124, v124
	v_exp_f32_e32 v125, v125
	v_rcp_f32_e32 v122, v122
	v_rcp_f32_e32 v123, v123
	v_add_f32_e32 v124, 1.0, v124
	v_add_f32_e32 v125, 1.0, v125
	v_rcp_f32_e32 v124, v124
	v_rcp_f32_e32 v125, v125
	v_pk_mul_f32 v[116:117], v[116:117], v[122:123]
	v_lshl_add_u32 v152, s28, 8, v146
	v_pk_mul_f32 v[112:113], v[116:117], v[112:113]
	v_lshl_add_u64 v[144:145], v[144:145], 1, s[54:55]
	v_cvt_pk_bf16_f32 v122, v112, v113
	v_pk_mul_f32 v[112:113], v[118:119], v[124:125]
	v_or_b32_e32 v116, 16, v152
	v_pk_mul_f32 v[112:113], v[112:113], v[114:115]
	v_mul_f32_e32 v114, 0xbfb8aa3b, v110
	v_cvt_pk_bf16_f32 v123, v112, v113
	v_mad_i64_i32 v[112:113], s[14:15], v152, s91, v[144:145]
	global_store_dwordx4 v[112:113], v[120:123], off
	v_mul_f32_e32 v112, 0xbfb8aa3b, v108
	v_mul_f32_e32 v113, 0xbfb8aa3b, v109
	v_exp_f32_e32 v112, v112
	v_exp_f32_e32 v113, v113
	v_mul_f32_e32 v115, 0xbfb8aa3b, v111
	v_exp_f32_e32 v114, v114
	v_exp_f32_e32 v115, v115
; DI unsigned pk_bf16(float lo, float hi) { f32x2 v = {lo, hi}; return __builtin_bit_cast(unsigned, __builtin_convertvector(v, bf16v2)); }
; DI float fast_silu(float x) { return x * fast_sigmoid(x); }
;     DI void operator()(AccRef acc, const Unit& u, int wr, int wc, int fr, int fq) const {
;     ...
;             for (int m = 0; m < 4; ++m) {
;                 const int row = row0 + ai * 128 + m * 16;
;                 const float r = RS ? rsc.r[ai][m] : 1.0f;
;                 const f32x4 a0 = acc[ai][0][m][0] * r, a1 = acc[ai][0][m][1] * r, b0 = acc[ai][1][m][0] * r, b1 = acc[ai][1][m][1] * r;
;                 u32x4 w;
;                 w.x = pk_bf16(fast_silu(a0[0]) * b0[0], fast_silu(a0[1]) * b0[1]); w.y = pk_bf16(fast_silu(a0[2]) * b0[2], fast_silu(a0[3]) * b0[3]);
;                 w.z = pk_bf16(fast_silu(a1[0]) * b1[0], fast_silu(a1[1]) * b1[1]); w.w = pk_bf16(fast_silu(a1[2]) * b1[2], fast_silu(a1[3]) * b1[3]);
;                 *(u32x4*)(G + (size_t)row * DFF + col) = w;
	v_add_f32_e32 v112, 1.0, v112
	v_add_f32_e32 v113, 1.0, v113
	v_rcp_f32_e32 v112, v112
	v_rcp_f32_e32 v113, v113
	v_add_f32_e32 v114, 1.0, v114
	v_add_f32_e32 v115, 1.0, v115
	v_rcp_f32_e32 v114, v114
	v_rcp_f32_e32 v115, v115
	v_pk_mul_f32 v[108:109], v[108:109], v[112:113]
	s_and_b64 vcc, exec, s[0:1]
	v_pk_mul_f32 v[104:105], v[108:109], v[104:105]
	v_pk_mul_f32 v[108:109], v[110:111], v[114:115]
	v_cvt_pk_bf16_f32 v104, v104, v105
	v_mul_f32_e32 v105, 0xbfb8aa3b, v100
	v_pk_mul_f32 v[106:107], v[108:109], v[106:107]
	v_exp_f32_e32 v108, v105
	v_mul_f32_e32 v105, 0xbfb8aa3b, v101
	v_exp_f32_e32 v109, v105
	v_cvt_pk_bf16_f32 v105, v106, v107
	v_add_f32_e32 v106, 1.0, v108
	v_mul_f32_e32 v108, 0xbfb8aa3b, v102
	v_add_f32_e32 v107, 1.0, v109
	v_mul_f32_e32 v109, 0xbfb8aa3b, v103
	v_exp_f32_e32 v108, v108
	v_exp_f32_e32 v109, v109
	v_rcp_f32_e32 v106, v106
	v_rcp_f32_e32 v107, v107
	v_add_f32_e32 v108, 1.0, v108
	v_add_f32_e32 v109, 1.0, v109
	v_rcp_f32_e32 v108, v108
	v_rcp_f32_e32 v109, v109
	v_pk_mul_f32 v[100:101], v[100:101], v[106:107]
	s_mov_b32 s92, s8
	v_pk_mul_f32 v[96:97], v[100:101], v[96:97]
	v_or_b32_e32 v100, 32, v152
	v_cvt_pk_bf16_f32 v106, v96, v97
	v_pk_mul_f32 v[96:97], v[102:103], v[108:109]
	s_mov_b32 s28, s10
	v_pk_mul_f32 v[96:97], v[96:97], v[98:99]
	v_mul_f32_e32 v98, 0xbfb8aa3b, v94
	v_cvt_pk_bf16_f32 v107, v96, v97
	v_mad_i64_i32 v[96:97], s[14:15], v116, s91, v[144:145]
	global_store_dwordx4 v[96:97], v[104:107], off
	v_mul_f32_e32 v96, 0xbfb8aa3b, v92
	v_mul_f32_e32 v97, 0xbfb8aa3b, v93
	v_exp_f32_e32 v96, v96
	v_exp_f32_e32 v97, v97
	v_mul_f32_e32 v99, 0xbfb8aa3b, v95
	v_exp_f32_e32 v98, v98
	v_exp_f32_e32 v99, v99
	v_add_f32_e32 v96, 1.0, v96
	v_add_f32_e32 v97, 1.0, v97
	v_rcp_f32_e32 v96, v96
	v_rcp_f32_e32 v97, v97
	v_add_f32_e32 v98, 1.0, v98
	v_add_f32_e32 v99, 1.0, v99
	v_rcp_f32_e32 v98, v98
	v_rcp_f32_e32 v99, v99
	v_pk_mul_f32 v[92:93], v[92:93], v[96:97]
	s_mov_b64 s[78:79], s[26:27]
	v_pk_mul_f32 v[88:89], v[92:93], v[88:89]
	v_pk_mul_f32 v[92:93], v[94:95], v[98:99]
	v_cvt_pk_bf16_f32 v88, v88, v89
	v_mul_f32_e32 v89, 0xbfb8aa3b, v84
	v_pk_mul_f32 v[90:91], v[92:93], v[90:91]
	v_exp_f32_e32 v92, v89
	v_mul_f32_e32 v89, 0xbfb8aa3b, v85
	v_exp_f32_e32 v93, v89
	v_cvt_pk_bf16_f32 v89, v90, v91
	v_add_f32_e32 v90, 1.0, v92
	v_mul_f32_e32 v92, 0xbfb8aa3b, v86
	v_add_f32_e32 v91, 1.0, v93
	v_mul_f32_e32 v93, 0xbfb8aa3b, v87
	v_exp_f32_e32 v92, v92
	v_exp_f32_e32 v93, v93
	v_rcp_f32_e32 v90, v90
	v_rcp_f32_e32 v91, v91
	v_add_f32_e32 v92, 1.0, v92
	v_add_f32_e32 v93, 1.0, v93
	v_rcp_f32_e32 v92, v92
	v_rcp_f32_e32 v93, v93
	v_pk_mul_f32 v[84:85], v[84:85], v[90:91]
	s_mov_b64 s[76:77], s[24:25]
	v_pk_mul_f32 v[80:81], v[84:85], v[80:81]
	v_or_b32_e32 v84, 48, v152
	v_cvt_pk_bf16_f32 v90, v80, v81
	v_pk_mul_f32 v[80:81], v[86:87], v[92:93]
	s_nop 0
	v_pk_mul_f32 v[80:81], v[80:81], v[82:83]
	v_mul_f32_e32 v82, 0xbfb8aa3b, v78
	v_cvt_pk_bf16_f32 v91, v80, v81
	v_mad_i64_i32 v[80:81], s[14:15], v100, s91, v[144:145]
	global_store_dwordx4 v[80:81], v[88:91], off
	v_mul_f32_e32 v80, 0xbfb8aa3b, v76
	v_mul_f32_e32 v81, 0xbfb8aa3b, v77
	v_exp_f32_e32 v80, v80
	v_exp_f32_e32 v81, v81
	v_mul_f32_e32 v83, 0xbfb8aa3b, v79
	v_exp_f32_e32 v82, v82
	v_exp_f32_e32 v83, v83
	v_add_f32_e32 v80, 1.0, v80
	v_add_f32_e32 v81, 1.0, v81
	v_rcp_f32_e32 v80, v80
	v_rcp_f32_e32 v81, v81
	v_add_f32_e32 v82, 1.0, v82
	v_add_f32_e32 v83, 1.0, v83
	v_rcp_f32_e32 v82, v82
	v_rcp_f32_e32 v83, v83
	v_pk_mul_f32 v[76:77], v[76:77], v[80:81]
	s_nop 0
	v_pk_mul_f32 v[72:73], v[76:77], v[72:73]
	v_pk_mul_f32 v[76:77], v[78:79], v[82:83]
	v_cvt_pk_bf16_f32 v72, v72, v73
	v_mul_f32_e32 v73, 0xbfb8aa3b, v68
	v_pk_mul_f32 v[74:75], v[76:77], v[74:75]
	v_exp_f32_e32 v76, v73
	v_mul_f32_e32 v73, 0xbfb8aa3b, v69
	v_exp_f32_e32 v77, v73
	v_cvt_pk_bf16_f32 v73, v74, v75
	v_add_f32_e32 v74, 1.0, v76
	v_mul_f32_e32 v76, 0xbfb8aa3b, v70
	v_add_f32_e32 v75, 1.0, v77
	v_mul_f32_e32 v77, 0xbfb8aa3b, v71
	v_exp_f32_e32 v76, v76
	v_exp_f32_e32 v77, v77
	v_rcp_f32_e32 v74, v74
	v_rcp_f32_e32 v75, v75
	v_add_f32_e32 v76, 1.0, v76
	v_add_f32_e32 v77, 1.0, v77
	v_rcp_f32_e32 v76, v76
	v_rcp_f32_e32 v77, v77
	v_pk_mul_f32 v[68:69], v[68:69], v[74:75]
	s_nop 0
	v_pk_mul_f32 v[64:65], v[68:69], v[64:65]
	v_add_u32_e32 v68, 0x80, v152
	v_cvt_pk_bf16_f32 v74, v64, v65
	v_pk_mul_f32 v[64:65], v[70:71], v[76:77]
	s_nop 0
	v_pk_mul_f32 v[64:65], v[64:65], v[66:67]
	v_mul_f32_e32 v66, 0xbfb8aa3b, v62
	v_cvt_pk_bf16_f32 v75, v64, v65
	v_mad_i64_i32 v[64:65], s[14:15], v84, s91, v[144:145]
	global_store_dwordx4 v[64:65], v[72:75], off
	v_mul_f32_e32 v64, 0xbfb8aa3b, v60
	v_mul_f32_e32 v65, 0xbfb8aa3b, v61
	v_exp_f32_e32 v64, v64
	v_exp_f32_e32 v65, v65
	v_mul_f32_e32 v67, 0xbfb8aa3b, v63
	v_exp_f32_e32 v66, v66
	v_exp_f32_e32 v67, v67
	v_add_f32_e32 v64, 1.0, v64
	v_add_f32_e32 v65, 1.0, v65
	v_rcp_f32_e32 v64, v64
	v_rcp_f32_e32 v65, v65
	v_add_f32_e32 v66, 1.0, v66
	v_add_f32_e32 v67, 1.0, v67
	v_rcp_f32_e32 v66, v66
	v_rcp_f32_e32 v67, v67
	v_pk_mul_f32 v[60:61], v[60:61], v[64:65]
	s_nop 0
	v_pk_mul_f32 v[56:57], v[60:61], v[56:57]
	v_pk_mul_f32 v[60:61], v[62:63], v[66:67]
	v_cvt_pk_bf16_f32 v56, v56, v57
	v_mul_f32_e32 v57, 0xbfb8aa3b, v52
	v_pk_mul_f32 v[58:59], v[60:61], v[58:59]
	v_exp_f32_e32 v60, v57
	v_mul_f32_e32 v57, 0xbfb8aa3b, v53
	v_exp_f32_e32 v61, v57
	v_cvt_pk_bf16_f32 v57, v58, v59
	v_add_f32_e32 v58, 1.0, v60
; DI unsigned pk_bf16(float lo, float hi) { f32x2 v = {lo, hi}; return __builtin_bit_cast(unsigned, __builtin_convertvector(v, bf16v2)); }
; DI float fast_silu(float x) { return x * fast_sigmoid(x); }
; #define PG8_WAIT_V(n) asm volatile("s_waitcnt vmcnt(" #n ")" ::: "memory")
; #define PG8_BAR __builtin_amdgcn_s_barrier()
; #define PG8_WAIT_V(n) asm volatile("s_waitcnt vmcnt(" #n ")" ::: "memory")
; #define PG8_BAR __builtin_amdgcn_s_barrier()
; template <class Epi>
; DI void gemm_phase(LAS unsigned char* lds, const Gemm g, const StaticOrder S, const Epi E) {
;     ...
;     PG8_WAIT_V(0);
;     if (wr == 0) PG8_BAR;
;     PG8_BAR;
;     DI void operator()(AccRef acc, const Unit& u, int wr, int wc, int fr, int fq) const {
;     ...
;             for (int m = 0; m < 4; ++m) {
;                 const int row = row0 + ai * 128 + m * 16;
;                 const float r = RS ? rsc.r[ai][m] : 1.0f;
;                 const f32x4 a0 = acc[ai][0][m][0] * r, a1 = acc[ai][0][m][1] * r, b0 = acc[ai][1][m][0] * r, b1 = acc[ai][1][m][1] * r;
;                 u32x4 w;
;                 w.x = pk_bf16(fast_silu(a0[0]) * b0[0], fast_silu(a0[1]) * b0[1]); w.y = pk_bf16(fast_silu(a0[2]) * b0[2], fast_silu(a0[3]) * b0[3]);
;                 w.z = pk_bf16(fast_silu(a1[0]) * b1[0], fast_silu(a1[1]) * b1[1]); w.w = pk_bf16(fast_silu(a1[2]) * b1[2], fast_silu(a1[3]) * b1[3]);
;                 *(u32x4*)(G + (size_t)row * DFF + col) = w;
;             }
	v_mul_f32_e32 v60, 0xbfb8aa3b, v54
	v_add_f32_e32 v59, 1.0, v61
	v_mul_f32_e32 v61, 0xbfb8aa3b, v55
	v_exp_f32_e32 v60, v60
	v_exp_f32_e32 v61, v61
	v_rcp_f32_e32 v58, v58
	v_rcp_f32_e32 v59, v59
	v_add_f32_e32 v60, 1.0, v60
	v_add_f32_e32 v61, 1.0, v61
	v_rcp_f32_e32 v60, v60
	v_rcp_f32_e32 v61, v61
	v_pk_mul_f32 v[52:53], v[52:53], v[58:59]
	s_nop 0
	v_pk_mul_f32 v[48:49], v[52:53], v[48:49]
	v_add_u32_e32 v52, 0x90, v152
	v_cvt_pk_bf16_f32 v58, v48, v49
	v_pk_mul_f32 v[48:49], v[54:55], v[60:61]
	s_nop 0
	v_pk_mul_f32 v[48:49], v[48:49], v[50:51]
	v_mul_f32_e32 v50, 0xbfb8aa3b, v46
	v_cvt_pk_bf16_f32 v59, v48, v49
	v_mad_i64_i32 v[48:49], s[14:15], v68, s91, v[144:145]
	global_store_dwordx4 v[48:49], v[56:59], off
	v_mul_f32_e32 v48, 0xbfb8aa3b, v44
	v_mul_f32_e32 v49, 0xbfb8aa3b, v45
	v_exp_f32_e32 v48, v48
	v_exp_f32_e32 v49, v49
	v_mul_f32_e32 v51, 0xbfb8aa3b, v47
	v_exp_f32_e32 v50, v50
	v_exp_f32_e32 v51, v51
	v_add_f32_e32 v48, 1.0, v48
	v_add_f32_e32 v49, 1.0, v49
	v_rcp_f32_e32 v48, v48
	v_rcp_f32_e32 v49, v49
	v_add_f32_e32 v50, 1.0, v50
	v_add_f32_e32 v51, 1.0, v51
	v_rcp_f32_e32 v50, v50
	v_rcp_f32_e32 v51, v51
	v_pk_mul_f32 v[44:45], v[44:45], v[48:49]
	s_nop 0
	v_pk_mul_f32 v[40:41], v[44:45], v[40:41]
	v_pk_mul_f32 v[44:45], v[46:47], v[50:51]
	v_cvt_pk_bf16_f32 v40, v40, v41
	v_mul_f32_e32 v41, 0xbfb8aa3b, v36
	v_pk_mul_f32 v[42:43], v[44:45], v[42:43]
	v_exp_f32_e32 v44, v41
	v_mul_f32_e32 v41, 0xbfb8aa3b, v37
	v_exp_f32_e32 v45, v41
	v_cvt_pk_bf16_f32 v41, v42, v43
	v_add_f32_e32 v42, 1.0, v44
	v_mul_f32_e32 v44, 0xbfb8aa3b, v38
	v_add_f32_e32 v43, 1.0, v45
	v_mul_f32_e32 v45, 0xbfb8aa3b, v39
	v_exp_f32_e32 v44, v44
	v_exp_f32_e32 v45, v45
	v_rcp_f32_e32 v42, v42
	v_rcp_f32_e32 v43, v43
	v_add_f32_e32 v44, 1.0, v44
	v_add_f32_e32 v45, 1.0, v45
	v_rcp_f32_e32 v44, v44
	v_rcp_f32_e32 v45, v45
	v_pk_mul_f32 v[36:37], v[36:37], v[42:43]
	s_nop 0
	v_pk_mul_f32 v[32:33], v[36:37], v[32:33]
	v_add_u32_e32 v36, 0xa0, v152
	v_cvt_pk_bf16_f32 v42, v32, v33
	v_pk_mul_f32 v[32:33], v[38:39], v[44:45]
	s_nop 0
	v_pk_mul_f32 v[32:33], v[32:33], v[34:35]
	v_mul_f32_e32 v34, 0xbfb8aa3b, v30
	v_cvt_pk_bf16_f32 v43, v32, v33
	v_mad_i64_i32 v[32:33], s[14:15], v52, s91, v[144:145]
	global_store_dwordx4 v[32:33], v[40:43], off
	v_mul_f32_e32 v32, 0xbfb8aa3b, v28
	v_mul_f32_e32 v33, 0xbfb8aa3b, v29
	v_exp_f32_e32 v32, v32
	v_exp_f32_e32 v33, v33
	v_mul_f32_e32 v35, 0xbfb8aa3b, v31
	v_exp_f32_e32 v34, v34
	v_exp_f32_e32 v35, v35
	v_add_f32_e32 v32, 1.0, v32
	v_add_f32_e32 v33, 1.0, v33
	v_rcp_f32_e32 v32, v32
	v_rcp_f32_e32 v33, v33
	v_add_f32_e32 v34, 1.0, v34
	v_add_f32_e32 v35, 1.0, v35
	v_rcp_f32_e32 v34, v34
	v_rcp_f32_e32 v35, v35
	v_pk_mul_f32 v[28:29], v[28:29], v[32:33]
	s_nop 0
	v_pk_mul_f32 v[24:25], v[28:29], v[24:25]
	v_pk_mul_f32 v[28:29], v[30:31], v[34:35]
	v_cvt_pk_bf16_f32 v24, v24, v25
	v_mul_f32_e32 v25, 0xbfb8aa3b, v20
	v_pk_mul_f32 v[26:27], v[28:29], v[26:27]
	v_exp_f32_e32 v28, v25
	v_mul_f32_e32 v25, 0xbfb8aa3b, v21
	v_exp_f32_e32 v29, v25
	v_cvt_pk_bf16_f32 v25, v26, v27
	v_add_f32_e32 v26, 1.0, v28
	v_mul_f32_e32 v28, 0xbfb8aa3b, v22
	v_add_f32_e32 v27, 1.0, v29
	v_mul_f32_e32 v29, 0xbfb8aa3b, v23
	v_exp_f32_e32 v28, v28
	v_exp_f32_e32 v29, v29
	v_rcp_f32_e32 v26, v26
	v_rcp_f32_e32 v27, v27
	v_add_f32_e32 v28, 1.0, v28
	v_add_f32_e32 v29, 1.0, v29
	v_rcp_f32_e32 v28, v28
	v_rcp_f32_e32 v29, v29
	v_pk_mul_f32 v[20:21], v[20:21], v[26:27]
	s_nop 0
	v_pk_mul_f32 v[16:17], v[20:21], v[16:17]
	v_add_u32_e32 v20, 0xb0, v152
	v_cvt_pk_bf16_f32 v26, v16, v17
	v_pk_mul_f32 v[16:17], v[22:23], v[28:29]
	s_nop 0
	v_pk_mul_f32 v[16:17], v[16:17], v[18:19]
	v_mul_f32_e32 v18, 0xbfb8aa3b, v14
	v_cvt_pk_bf16_f32 v27, v16, v17
	v_mad_i64_i32 v[16:17], s[14:15], v36, s91, v[144:145]
	global_store_dwordx4 v[16:17], v[24:27], off
	v_mul_f32_e32 v16, 0xbfb8aa3b, v12
	v_mul_f32_e32 v17, 0xbfb8aa3b, v13
	v_exp_f32_e32 v16, v16
	v_exp_f32_e32 v17, v17
	v_mul_f32_e32 v19, 0xbfb8aa3b, v15
	v_exp_f32_e32 v18, v18
	v_exp_f32_e32 v19, v19
	v_add_f32_e32 v16, 1.0, v16
	v_add_f32_e32 v17, 1.0, v17
	v_rcp_f32_e32 v16, v16
	v_rcp_f32_e32 v17, v17
	v_add_f32_e32 v18, 1.0, v18
	v_add_f32_e32 v19, 1.0, v19
	v_rcp_f32_e32 v18, v18
	v_rcp_f32_e32 v19, v19
	v_pk_mul_f32 v[12:13], v[12:13], v[16:17]
	s_nop 0
	v_pk_mul_f32 v[8:9], v[12:13], v[8:9]
	v_pk_mul_f32 v[12:13], v[14:15], v[18:19]
	v_cvt_pk_bf16_f32 v8, v8, v9
	v_mul_f32_e32 v9, 0xbfb8aa3b, v4
	v_pk_mul_f32 v[10:11], v[12:13], v[10:11]
	v_exp_f32_e32 v12, v9
	v_mul_f32_e32 v9, 0xbfb8aa3b, v5
	v_exp_f32_e32 v13, v9
	v_cvt_pk_bf16_f32 v9, v10, v11
	v_add_f32_e32 v10, 1.0, v12
	v_mul_f32_e32 v12, 0xbfb8aa3b, v6
	v_add_f32_e32 v11, 1.0, v13
	v_mul_f32_e32 v13, 0xbfb8aa3b, v7
	v_exp_f32_e32 v12, v12
	v_exp_f32_e32 v13, v13
	v_rcp_f32_e32 v10, v10
	v_rcp_f32_e32 v11, v11
	v_add_f32_e32 v12, 1.0, v12
	v_add_f32_e32 v13, 1.0, v13
	v_rcp_f32_e32 v12, v12
	v_rcp_f32_e32 v13, v13
	v_pk_mul_f32 v[4:5], v[4:5], v[10:11]
	s_nop 0
	v_pk_mul_f32 v[0:1], v[4:5], v[0:1]
	s_nop 0
	v_cvt_pk_bf16_f32 v10, v0, v1
	v_pk_mul_f32 v[0:1], v[6:7], v[12:13]
	s_nop 0
	v_pk_mul_f32 v[0:1], v[0:1], v[2:3]
	s_nop 0
	v_cvt_pk_bf16_f32 v11, v0, v1
	v_mad_i64_i32 v[0:1], s[14:15], v20, s91, v[144:145]
	global_store_dwordx4 v[0:1], v[8:11], off
	s_cbranch_vccz .LBB0_104
	s_waitcnt vmcnt(0)
	v_readlane_b32 s92, v243, 8
	s_cmpk_gt_u32 s6, 0xff
	v_readlane_b32 s93, v243, 9
	s_cbranch_scc1 .LBB0_111
	s_barrier

; #define PG8_STAGE(bufoff, gbase, voff) do { _Pragma("unroll") for (int _i = 0; _i < 2; ++_i) \
;         __builtin_amdgcn_global_load_lds((const unsigned*)((const char*)(gbase) + (voff)[_i]), (LAS unsigned*)(lds + (bufoff) + ldsw + _i * 8192), 16, 0, 0); } while (0)
; #define PG8_LDA(dst, b, h) do { _Pragma("unroll") for (int m = 0; m < 4; ++m) _Pragma("unroll") for (int k = 0; k < 2; ++k) dst[m][k] = *(const LAS bf16x8*)(lds + PG8_SA(b, h) + aoff + m * 2048 + k * 1024); } while (0)
; #define PG8_LDB(dst, b, h) do { _Pragma("unroll") for (int n = 0; n < 2; ++n) _Pragma("unroll") for (int k = 0; k < 2; ++k) dst[n][k] = *(const LAS bf16x8*)(lds + PG8_SB(b, h) + boff + n * 2048 + k * 1024); } while (0)
; #define PG8_MMA(ai, bj, At, Bt) do { __builtin_amdgcn_s_setprio(1); _Pragma("unroll") for (int m = 0; m < 4; ++m) _Pragma("unroll") for (int n = 0; n < 2; ++n) _Pragma("unroll") for (int k = 0; k < 2; ++k) \
;         acc[ai][bj][m][n] = __builtin_amdgcn_mfma_f32_16x16x32_bf16(Bt[n][k], At[m][k], acc[ai][bj][m][n], 0, 0, 0); __builtin_amdgcn_s_setprio(0); } while (0)
; #define PG8_WAIT_V(n) asm volatile("s_waitcnt vmcnt(" #n ")" ::: "memory")
; #define PG8_WAIT_L(n) asm volatile("s_waitcnt lgkmcnt(" #n ")" ::: "memory")
; #define PG8_BAR __builtin_amdgcn_s_barrier()
; #define PG8_SCHED __builtin_amdgcn_sched_barrier(0)
; template <class Epi>
; DI void gemm_phase(LAS unsigned char* lds, const Gemm g, const StaticOrder S, const Epi E) {
;     ...
;             const bool last = (t == nt - 2);
;             const char* a1 = cA + (size_t)(t + 1) * kstep;
;             const char* a2 = last ? nA : cA + (size_t)(t + 2) * kstep; const char* b2 = last ? nB : cB + (size_t)(t + 2) * kstep;
;             const char* a3 = a2 + kstep; const char* b3 = b2 + kstep;
;             PG8_LDB(B0, 0, 0); PG8_SCHED; PG8_LDA(At, 0, 0); PG8_STAGE(PG8_SA(1, 1), a1 + hstep, voffA);
;             PG8_WAIT_L(8); PG8_BAR; PG8_WAIT_L(0); PG8_MMA(0, 0, At, B0); PG8_BAR; PG8_SCHED;
;             PG8_LDB(B1, 0, 1); PG8_STAGE(PG8_SB(0, 0), b2, voffB);
;             PG8_BAR; PG8_WAIT_L(0); PG8_MMA(0, 1, At, B1); PG8_BAR;
;             PG8_LDA(At, 0, 1); PG8_STAGE(PG8_SA(0, 0), a2, voffA);
;             PG8_BAR; PG8_WAIT_L(0); PG8_MMA(1, 0, At, B0); PG8_BAR; PG8_SCHED;
;             PG8_STAGE(PG8_SB(0, 1), b2 + hstep, voffB);
;             PG8_WAIT_V(6); PG8_BAR; PG8_MMA(1, 1, At, B1); PG8_BAR;
.LBB0_186:
	ds_read_b128 v[128:131], v207
	ds_read_b128 v[132:135], v207 offset:1024
	ds_read_b128 v[136:139], v207 offset:2048
	ds_read_b128 v[140:143], v207 offset:3072
	s_add_u32 s76, s28, 0x100
	s_addc_u32 s77, s29, 0
	s_cmp_eq_u32 s97, 40
	s_cselect_b32 s81, s9, s77
	s_cselect_b32 s80, s8, s76
	s_cselect_b32 s79, s11, s7
	s_cselect_b32 s78, s10, s6
	v_lshl_add_u64 v[192:193], s[28:29], 0, v[184:185]
	s_add_i32 m0, s82, 0xc000
	ds_read_b128 v[144:147], v208
	ds_read_b128 v[148:151], v208 offset:1024
	ds_read_b128 v[152:155], v208 offset:2048
	ds_read_b128 v[156:159], v208 offset:3072
	ds_read_b128 v[160:163], v208 offset:4096
	ds_read_b128 v[164:167], v208 offset:5120
	ds_read_b128 v[168:171], v208 offset:6144
	ds_read_b128 v[172:175], v208 offset:7168
	global_load_lds_dwordx4 v[192:193], off
	v_lshl_add_u64 v[192:193], s[28:29], 0, v[186:187]
	s_add_i32 m0, s82, 0xe000
	s_nop 0
	global_load_lds_dwordx4 v[192:193], off
	s_waitcnt lgkmcnt(8)
	s_setprio 1
	s_barrier
	s_waitcnt lgkmcnt(0)
	v_mfma_f32_16x16x32_bf16 v[124:127], v[128:131], v[144:147], v[124:127]
	v_mfma_f32_16x16x32_bf16 v[120:123], v[136:139], v[144:147], v[120:123]
	v_mfma_f32_16x16x32_bf16 v[108:111], v[128:131], v[152:155], v[108:111]
	v_mfma_f32_16x16x32_bf16 v[104:107], v[136:139], v[152:155], v[104:107]
	v_mfma_f32_16x16x32_bf16 v[92:95], v[128:131], v[160:163], v[92:95]
	v_mfma_f32_16x16x32_bf16 v[88:91], v[136:139], v[160:163], v[88:91]
	v_mfma_f32_16x16x32_bf16 v[76:79], v[128:131], v[168:171], v[76:79]
	v_mfma_f32_16x16x32_bf16 v[72:75], v[136:139], v[168:171], v[72:75]
	v_mfma_f32_16x16x32_bf16 v[124:127], v[132:135], v[148:151], v[124:127]
	v_mfma_f32_16x16x32_bf16 v[120:123], v[140:143], v[148:151], v[120:123]
	v_mfma_f32_16x16x32_bf16 v[108:111], v[132:135], v[156:159], v[108:111]
	v_mfma_f32_16x16x32_bf16 v[104:107], v[140:143], v[156:159], v[104:107]
	v_mfma_f32_16x16x32_bf16 v[92:95], v[132:135], v[164:167], v[92:95]
	v_mfma_f32_16x16x32_bf16 v[88:91], v[140:143], v[164:167], v[88:91]
	s_setprio 2
	s_barrier
	v_mfma_f32_16x16x32_bf16 v[76:79], v[132:135], v[172:175], v[76:79]
	v_mfma_f32_16x16x32_bf16 v[72:75], v[140:143], v[172:175], v[72:75]
	s_setprio 0
	s_add_i32 s14, s91, s59
	v_lshl_add_u64 v[216:217], s[78:79], 0, v[178:179]
	s_mov_b32 m0, s14
	ds_read_b128 v[192:195], v209
	ds_read_b128 v[196:199], v209 offset:1024
	ds_read_b128 v[200:203], v209 offset:2048
	ds_read_b128 v[212:215], v209 offset:3072
	global_load_lds_dwordx4 v[216:217], off
	v_lshl_add_u64 v[218:219], s[78:79], 0, v[182:183]
	s_add_i32 m0, s14, 0x2000
	s_nop 0
	global_load_lds_dwordx4 v[218:219], off
	s_setprio 1
	s_barrier
	s_waitcnt lgkmcnt(0)
	v_mfma_f32_16x16x32_bf16 v[116:119], v[192:195], v[144:147], v[116:119]
	v_mfma_f32_16x16x32_bf16 v[112:115], v[200:203], v[144:147], v[112:115]
	v_mfma_f32_16x16x32_bf16 v[100:103], v[192:195], v[152:155], v[100:103]
	v_mfma_f32_16x16x32_bf16 v[96:99], v[200:203], v[152:155], v[96:99]
	v_mfma_f32_16x16x32_bf16 v[84:87], v[192:195], v[160:163], v[84:87]
	v_mfma_f32_16x16x32_bf16 v[80:83], v[200:203], v[160:163], v[80:83]
	v_mfma_f32_16x16x32_bf16 v[68:71], v[192:195], v[168:171], v[68:71]
	v_mfma_f32_16x16x32_bf16 v[64:67], v[200:203], v[168:171], v[64:67]
	v_mfma_f32_16x16x32_bf16 v[116:119], v[196:199], v[148:151], v[116:119]
	v_mfma_f32_16x16x32_bf16 v[112:115], v[212:215], v[148:151], v[112:115]
	v_mfma_f32_16x16x32_bf16 v[100:103], v[196:199], v[156:159], v[100:103]
	v_mfma_f32_16x16x32_bf16 v[96:99], v[212:215], v[156:159], v[96:99]
	v_mfma_f32_16x16x32_bf16 v[84:87], v[196:199], v[164:167], v[84:87]
	v_mfma_f32_16x16x32_bf16 v[80:83], v[212:215], v[164:167], v[80:83]
	s_setprio 2
	s_barrier
	v_mfma_f32_16x16x32_bf16 v[68:71], v[196:199], v[172:175], v[68:71]
	v_mfma_f32_16x16x32_bf16 v[64:67], v[212:215], v[172:175], v[64:67]
	s_setprio 0
	s_mov_b32 m0, s82
	v_lshl_add_u64 v[220:221], s[80:81], 0, v[176:177]
	ds_read_b128 v[144:147], v208 offset:16384
	ds_read_b128 v[148:151], v208 offset:17408
	ds_read_b128 v[152:155], v208 offset:18432
	ds_read_b128 v[156:159], v208 offset:19456
	ds_read_b128 v[160:163], v208 offset:20480
	ds_read_b128 v[164:167], v208 offset:21504
	ds_read_b128 v[168:171], v208 offset:22528
	ds_read_b128 v[172:175], v208 offset:23552
	global_load_lds_dwordx4 v[220:221], off
	v_lshl_add_u64 v[224:225], s[80:81], 0, v[180:181]
	s_mov_b32 m0, s83
	s_nop 0
	global_load_lds_dwordx4 v[224:225], off
	s_setprio 1
	s_barrier
	s_waitcnt lgkmcnt(0)
	v_mfma_f32_16x16x32_bf16 v[60:63], v[128:131], v[144:147], v[60:63]
	v_mfma_f32_16x16x32_bf16 v[56:59], v[136:139], v[144:147], v[56:59]
	v_mfma_f32_16x16x32_bf16 v[44:47], v[128:131], v[152:155], v[44:47]
	v_mfma_f32_16x16x32_bf16 v[40:43], v[136:139], v[152:155], v[40:43]
	v_mfma_f32_16x16x32_bf16 v[28:31], v[128:131], v[160:163], v[28:31]
	v_mfma_f32_16x16x32_bf16 v[24:27], v[136:139], v[160:163], v[24:27]
	v_mfma_f32_16x16x32_bf16 v[12:15], v[128:131], v[168:171], v[12:15]
	v_mfma_f32_16x16x32_bf16 v[8:11], v[136:139], v[168:171], v[8:11]
	v_mfma_f32_16x16x32_bf16 v[60:63], v[132:135], v[148:151], v[60:63]
	v_mfma_f32_16x16x32_bf16 v[56:59], v[140:143], v[148:151], v[56:59]
	v_mfma_f32_16x16x32_bf16 v[44:47], v[132:135], v[156:159], v[44:47]
	v_mfma_f32_16x16x32_bf16 v[40:43], v[140:143], v[156:159], v[40:43]
	v_mfma_f32_16x16x32_bf16 v[28:31], v[132:135], v[164:167], v[28:31]
	v_mfma_f32_16x16x32_bf16 v[24:27], v[140:143], v[164:167], v[24:27]
	s_setprio 2
	s_barrier
; #define PG8_STAGE(bufoff, gbase, voff) do { _Pragma("unroll") for (int _i = 0; _i < 2; ++_i) \
;         __builtin_amdgcn_global_load_lds((const unsigned*)((const char*)(gbase) + (voff)[_i]), (LAS unsigned*)(lds + (bufoff) + ldsw + _i * 8192), 16, 0, 0); } while (0)
; #define PG8_LDA(dst, b, h) do { _Pragma("unroll") for (int m = 0; m < 4; ++m) _Pragma("unroll") for (int k = 0; k < 2; ++k) dst[m][k] = *(const LAS bf16x8*)(lds + PG8_SA(b, h) + aoff + m * 2048 + k * 1024); } while (0)
; #define PG8_LDB(dst, b, h) do { _Pragma("unroll") for (int n = 0; n < 2; ++n) _Pragma("unroll") for (int k = 0; k < 2; ++k) dst[n][k] = *(const LAS bf16x8*)(lds + PG8_SB(b, h) + boff + n * 2048 + k * 1024); } while (0)
; #define PG8_MMA(ai, bj, At, Bt) do { __builtin_amdgcn_s_setprio(1); _Pragma("unroll") for (int m = 0; m < 4; ++m) _Pragma("unroll") for (int n = 0; n < 2; ++n) _Pragma("unroll") for (int k = 0; k < 2; ++k) \
;         acc[ai][bj][m][n] = __builtin_amdgcn_mfma_f32_16x16x32_bf16(Bt[n][k], At[m][k], acc[ai][bj][m][n], 0, 0, 0); __builtin_amdgcn_s_setprio(0); } while (0)
; #define PG8_WAIT_V(n) asm volatile("s_waitcnt vmcnt(" #n ")" ::: "memory")
; #define PG8_WAIT_L(n) asm volatile("s_waitcnt lgkmcnt(" #n ")" ::: "memory")
; #define PG8_BAR __builtin_amdgcn_s_barrier()
; #define PG8_SCHED __builtin_amdgcn_sched_barrier(0)
; #define PG8_STAGE(bufoff, gbase, voff) do { _Pragma("unroll") for (int _i = 0; _i < 2; ++_i) \
;         __builtin_amdgcn_global_load_lds((const unsigned*)((const char*)(gbase) + (voff)[_i]), (LAS unsigned*)(lds + (bufoff) + ldsw + _i * 8192), 16, 0, 0); } while (0)
; #define PG8_WAIT_V(n) asm volatile("s_waitcnt vmcnt(" #n ")" ::: "memory")
; template <class Epi>
; DI void gemm_phase(LAS unsigned char* lds, const Gemm g, const StaticOrder S, const Epi E) {
;     ...
;             PG8_BAR; PG8_WAIT_L(0); PG8_MMA(1, 0, At, B0); PG8_BAR; PG8_SCHED;
;             PG8_STAGE(PG8_SB(0, 1), b2 + hstep, voffB);
;             PG8_WAIT_V(6); PG8_BAR; PG8_MMA(1, 1, At, B1); PG8_BAR;
;             PG8_LDB(B0, 1, 0); PG8_SCHED; PG8_LDA(At, 1, 0); PG8_STAGE(PG8_SA(0, 1), a2 + hstep, voffA);
;             PG8_WAIT_L(8); PG8_BAR; PG8_WAIT_L(0); PG8_MMA(0, 0, At, B0); PG8_BAR; PG8_SCHED;
;             PG8_LDB(B1, 1, 1); PG8_STAGE(PG8_SB(1, 0), b3, voffB);
;             PG8_BAR; PG8_WAIT_L(0); PG8_MMA(0, 1, At, B1); PG8_BAR;
	v_mfma_f32_16x16x32_bf16 v[12:15], v[132:135], v[172:175], v[12:15]
	v_mfma_f32_16x16x32_bf16 v[8:11], v[140:143], v[172:175], v[8:11]
	s_setprio 0
	s_add_u32 s14, s78, 0xb0000
	s_addc_u32 s15, s79, 0
	s_add_i32 s28, s92, s59
	v_lshl_add_u64 v[128:129], s[14:15], 0, v[178:179]
	s_mov_b32 m0, s28
	s_nop 0
	global_load_lds_dwordx4 v[128:129], off
	v_lshl_add_u64 v[128:129], s[14:15], 0, v[182:183]
	s_add_i32 m0, s28, 0x2000
	s_nop 0
	global_load_lds_dwordx4 v[128:129], off
	s_waitcnt vmcnt(6)
	s_setprio 1
	s_barrier
	v_mfma_f32_16x16x32_bf16 v[52:55], v[192:195], v[144:147], v[52:55]
	v_mfma_f32_16x16x32_bf16 v[48:51], v[200:203], v[144:147], v[48:51]
	v_mfma_f32_16x16x32_bf16 v[36:39], v[192:195], v[152:155], v[36:39]
	v_mfma_f32_16x16x32_bf16 v[32:35], v[200:203], v[152:155], v[32:35]
	v_mfma_f32_16x16x32_bf16 v[20:23], v[192:195], v[160:163], v[20:23]
	v_mfma_f32_16x16x32_bf16 v[16:19], v[200:203], v[160:163], v[16:19]
	v_mfma_f32_16x16x32_bf16 v[4:7], v[192:195], v[168:171], v[4:7]
	v_mfma_f32_16x16x32_bf16 v[0:3], v[200:203], v[168:171], v[0:3]
	v_mfma_f32_16x16x32_bf16 v[52:55], v[196:199], v[148:151], v[52:55]
	v_mfma_f32_16x16x32_bf16 v[48:51], v[212:215], v[148:151], v[48:51]
	v_mfma_f32_16x16x32_bf16 v[36:39], v[196:199], v[156:159], v[36:39]
	v_mfma_f32_16x16x32_bf16 v[32:35], v[212:215], v[156:159], v[32:35]
	v_mfma_f32_16x16x32_bf16 v[20:23], v[196:199], v[164:167], v[20:23]
	v_mfma_f32_16x16x32_bf16 v[16:19], v[212:215], v[164:167], v[16:19]
	s_setprio 2
	s_barrier
	v_mfma_f32_16x16x32_bf16 v[4:7], v[196:199], v[172:175], v[4:7]
	v_mfma_f32_16x16x32_bf16 v[0:3], v[212:215], v[172:175], v[0:3]
	s_setprio 0
	s_add_i32 s28, 0, 0x18000
	v_add_u32_e32 v140, s28, v205
	ds_read_b128 v[128:131], v140
	ds_read_b128 v[132:135], v140 offset:1024
	ds_read_b128 v[136:139], v140 offset:2048
	ds_read_b128 v[140:143], v140 offset:3072
	s_add_u32 s14, s80, 0xb0000
	s_addc_u32 s15, s81, 0
	s_mov_b32 m0, s84
	v_lshl_add_u64 v[192:193], s[14:15], 0, v[176:177]
	ds_read_b128 v[144:147], v208 offset:32768
	ds_read_b128 v[148:151], v208 offset:33792
	ds_read_b128 v[152:155], v208 offset:34816
	ds_read_b128 v[156:159], v208 offset:35840
	ds_read_b128 v[160:163], v208 offset:36864
	ds_read_b128 v[164:167], v208 offset:37888
	ds_read_b128 v[168:171], v208 offset:38912
	ds_read_b128 v[172:175], v208 offset:39936
	global_load_lds_dwordx4 v[192:193], off
	v_lshl_add_u64 v[192:193], s[14:15], 0, v[180:181]
	s_mov_b32 m0, s85
	s_nop 0
	global_load_lds_dwordx4 v[192:193], off
	s_waitcnt lgkmcnt(8)
	s_setprio 1
	s_barrier
	s_waitcnt lgkmcnt(0)
	v_mfma_f32_16x16x32_bf16 v[124:127], v[128:131], v[144:147], v[124:127]
	v_mfma_f32_16x16x32_bf16 v[120:123], v[136:139], v[144:147], v[120:123]
	v_mfma_f32_16x16x32_bf16 v[108:111], v[128:131], v[152:155], v[108:111]
	v_mfma_f32_16x16x32_bf16 v[104:107], v[136:139], v[152:155], v[104:107]
	v_mfma_f32_16x16x32_bf16 v[92:95], v[128:131], v[160:163], v[92:95]
	v_mfma_f32_16x16x32_bf16 v[88:91], v[136:139], v[160:163], v[88:91]
	v_mfma_f32_16x16x32_bf16 v[76:79], v[128:131], v[168:171], v[76:79]
	v_mfma_f32_16x16x32_bf16 v[72:75], v[136:139], v[168:171], v[72:75]
	v_mfma_f32_16x16x32_bf16 v[124:127], v[132:135], v[148:151], v[124:127]
	v_mfma_f32_16x16x32_bf16 v[120:123], v[140:143], v[148:151], v[120:123]
	v_mfma_f32_16x16x32_bf16 v[108:111], v[132:135], v[156:159], v[108:111]
	v_mfma_f32_16x16x32_bf16 v[104:107], v[140:143], v[156:159], v[104:107]
	v_mfma_f32_16x16x32_bf16 v[92:95], v[132:135], v[164:167], v[92:95]
	v_mfma_f32_16x16x32_bf16 v[88:91], v[140:143], v[164:167], v[88:91]
	s_setprio 2
	s_barrier
	v_mfma_f32_16x16x32_bf16 v[76:79], v[132:135], v[172:175], v[76:79]
	v_mfma_f32_16x16x32_bf16 v[72:75], v[140:143], v[172:175], v[72:75]
	s_setprio 0
	s_add_i32 s29, 0, 0x1c000
	s_add_i32 s14, s28, s59
	v_add_u32_e32 v211, s29, v205
	v_lshl_add_u64 v[216:217], v[216:217], 0, s[24:25]
	s_mov_b32 m0, s14
	ds_read_b128 v[192:195], v211
	ds_read_b128 v[196:199], v211 offset:1024
	ds_read_b128 v[200:203], v211 offset:2048
	ds_read_b128 v[212:215], v211 offset:3072
	global_load_lds_dwordx4 v[216:217], off
	v_lshl_add_u64 v[216:217], v[218:219], 0, s[24:25]
	s_add_i32 m0, s14, 0x2000
	s_nop 0
	global_load_lds_dwordx4 v[216:217], off
	s_setprio 1
	s_barrier
	s_waitcnt lgkmcnt(0)
	v_mfma_f32_16x16x32_bf16 v[116:119], v[192:195], v[144:147], v[116:119]
	v_mfma_f32_16x16x32_bf16 v[112:115], v[200:203], v[144:147], v[112:115]
	v_mfma_f32_16x16x32_bf16 v[100:103], v[192:195], v[152:155], v[100:103]
	v_mfma_f32_16x16x32_bf16 v[96:99], v[200:203], v[152:155], v[96:99]
	v_mfma_f32_16x16x32_bf16 v[84:87], v[192:195], v[160:163], v[84:87]
	v_mfma_f32_16x16x32_bf16 v[80:83], v[200:203], v[160:163], v[80:83]
	v_mfma_f32_16x16x32_bf16 v[68:71], v[192:195], v[168:171], v[68:71]
	v_mfma_f32_16x16x32_bf16 v[64:67], v[200:203], v[168:171], v[64:67]
	v_mfma_f32_16x16x32_bf16 v[116:119], v[196:199], v[148:151], v[116:119]
	v_mfma_f32_16x16x32_bf16 v[112:115], v[212:215], v[148:151], v[112:115]
	v_mfma_f32_16x16x32_bf16 v[100:103], v[196:199], v[156:159], v[100:103]
	v_mfma_f32_16x16x32_bf16 v[96:99], v[212:215], v[156:159], v[96:99]
	v_mfma_f32_16x16x32_bf16 v[84:87], v[196:199], v[164:167], v[84:87]
	v_mfma_f32_16x16x32_bf16 v[80:83], v[212:215], v[164:167], v[80:83]
	s_setprio 2
	s_barrier
; #define PG8_STAGE(bufoff, gbase, voff) do { _Pragma("unroll") for (int _i = 0; _i < 2; ++_i) \
;         __builtin_amdgcn_global_load_lds((const unsigned*)((const char*)(gbase) + (voff)[_i]), (LAS unsigned*)(lds + (bufoff) + ldsw + _i * 8192), 16, 0, 0); } while (0)
; #define PG8_LDA(dst, b, h) do { _Pragma("unroll") for (int m = 0; m < 4; ++m) _Pragma("unroll") for (int k = 0; k < 2; ++k) dst[m][k] = *(const LAS bf16x8*)(lds + PG8_SA(b, h) + aoff + m * 2048 + k * 1024); } while (0)
; #define PG8_MMA(ai, bj, At, Bt) do { __builtin_amdgcn_s_setprio(1); _Pragma("unroll") for (int m = 0; m < 4; ++m) _Pragma("unroll") for (int n = 0; n < 2; ++n) _Pragma("unroll") for (int k = 0; k < 2; ++k) \
;         acc[ai][bj][m][n] = __builtin_amdgcn_mfma_f32_16x16x32_bf16(Bt[n][k], At[m][k], acc[ai][bj][m][n], 0, 0, 0); __builtin_amdgcn_s_setprio(0); } while (0)
; #define PG8_WAIT_V(n) asm volatile("s_waitcnt vmcnt(" #n ")" ::: "memory")
; #define PG8_WAIT_L(n) asm volatile("s_waitcnt lgkmcnt(" #n ")" ::: "memory")
; #define PG8_BAR __builtin_amdgcn_s_barrier()
; #define PG8_SCHED __builtin_amdgcn_sched_barrier(0)
; #define PG8_STAGE(bufoff, gbase, voff) do { _Pragma("unroll") for (int _i = 0; _i < 2; ++_i) \
;         __builtin_amdgcn_global_load_lds((const unsigned*)((const char*)(gbase) + (voff)[_i]), (LAS unsigned*)(lds + (bufoff) + ldsw + _i * 8192), 16, 0, 0); } while (0)
; #define PG8_LDA(dst, b, h) do { _Pragma("unroll") for (int m = 0; m < 4; ++m) _Pragma("unroll") for (int k = 0; k < 2; ++k) dst[m][k] = *(const LAS bf16x8*)(lds + PG8_SA(b, h) + aoff + m * 2048 + k * 1024); } while (0)
; #define PG8_WAIT_V(n) asm volatile("s_waitcnt vmcnt(" #n ")" ::: "memory")
; #define PG8_WAIT_L(n) asm volatile("s_waitcnt lgkmcnt(" #n ")" ::: "memory")
; #define PG8_BAR __builtin_amdgcn_s_barrier()
; #define PG8_SCHED __builtin_amdgcn_sched_barrier(0)
; template <class Epi>
; DI void gemm_phase(LAS unsigned char* lds, const Gemm g, const StaticOrder S, const Epi E) {
;     ...
;             PG8_BAR; PG8_WAIT_L(0); PG8_MMA(0, 1, At, B1); PG8_BAR;
;             PG8_LDA(At, 1, 1); PG8_STAGE(PG8_SA(1, 0), a3, voffA);
;             PG8_BAR; PG8_WAIT_L(0); PG8_MMA(1, 0, At, B0); PG8_BAR; PG8_SCHED;
;             PG8_STAGE(PG8_SB(1, 1), b3 + hstep, voffB);
;             PG8_WAIT_V(6); PG8_BAR; PG8_MMA(1, 1, At, B1); PG8_BAR;
	v_mfma_f32_16x16x32_bf16 v[68:71], v[196:199], v[172:175], v[68:71]
	v_mfma_f32_16x16x32_bf16 v[64:67], v[212:215], v[172:175], v[64:67]
	s_setprio 0
	s_mov_b32 m0, s87
	v_lshl_add_u64 v[216:217], v[220:221], 0, s[24:25]
	ds_read_b128 v[144:147], v208 offset:49152
	ds_read_b128 v[148:151], v208 offset:50176
	ds_read_b128 v[152:155], v208 offset:51200
	ds_read_b128 v[156:159], v208 offset:52224
	ds_read_b128 v[160:163], v208 offset:53248
	ds_read_b128 v[164:167], v208 offset:54272
	ds_read_b128 v[168:171], v208 offset:55296
	ds_read_b128 v[172:175], v208 offset:56320
	global_load_lds_dwordx4 v[216:217], off
	v_lshl_add_u64 v[216:217], v[224:225], 0, s[24:25]
	s_mov_b32 m0, s88
	s_nop 0
	global_load_lds_dwordx4 v[216:217], off
	s_setprio 1
	s_barrier
	s_waitcnt lgkmcnt(0)
	v_mfma_f32_16x16x32_bf16 v[60:63], v[128:131], v[144:147], v[60:63]
	v_mfma_f32_16x16x32_bf16 v[56:59], v[136:139], v[144:147], v[56:59]
	v_mfma_f32_16x16x32_bf16 v[44:47], v[128:131], v[152:155], v[44:47]
	v_mfma_f32_16x16x32_bf16 v[40:43], v[136:139], v[152:155], v[40:43]
	v_mfma_f32_16x16x32_bf16 v[28:31], v[128:131], v[160:163], v[28:31]
	v_mfma_f32_16x16x32_bf16 v[24:27], v[136:139], v[160:163], v[24:27]
	v_mfma_f32_16x16x32_bf16 v[12:15], v[128:131], v[168:171], v[12:15]
	v_mfma_f32_16x16x32_bf16 v[8:11], v[136:139], v[168:171], v[8:11]
	v_mfma_f32_16x16x32_bf16 v[60:63], v[132:135], v[148:151], v[60:63]
	v_mfma_f32_16x16x32_bf16 v[56:59], v[140:143], v[148:151], v[56:59]
	v_mfma_f32_16x16x32_bf16 v[44:47], v[132:135], v[156:159], v[44:47]
	v_mfma_f32_16x16x32_bf16 v[40:43], v[140:143], v[156:159], v[40:43]
	v_mfma_f32_16x16x32_bf16 v[28:31], v[132:135], v[164:167], v[28:31]
	v_mfma_f32_16x16x32_bf16 v[24:27], v[140:143], v[164:167], v[24:27]
	s_setprio 2
	s_barrier
	v_mfma_f32_16x16x32_bf16 v[12:15], v[132:135], v[172:175], v[12:15]
	v_mfma_f32_16x16x32_bf16 v[8:11], v[140:143], v[172:175], v[8:11]
	s_setprio 0
	s_add_u32 s14, s78, 0xb0080
	s_addc_u32 s15, s79, 0
	s_add_i32 s28, s29, s59
	v_lshl_add_u64 v[128:129], s[14:15], 0, v[178:179]
	s_mov_b32 m0, s28
	s_nop 0
	global_load_lds_dwordx4 v[128:129], off
	v_lshl_add_u64 v[128:129], s[14:15], 0, v[182:183]
	s_add_i32 m0, s28, 0x2000
	s_nop 0
	global_load_lds_dwordx4 v[128:129], off
	s_waitcnt vmcnt(6)
	s_setprio 1
	s_barrier
	v_mfma_f32_16x16x32_bf16 v[52:55], v[192:195], v[144:147], v[52:55]
	v_mfma_f32_16x16x32_bf16 v[48:51], v[200:203], v[144:147], v[48:51]
	v_mfma_f32_16x16x32_bf16 v[36:39], v[192:195], v[152:155], v[36:39]
	v_mfma_f32_16x16x32_bf16 v[32:35], v[200:203], v[152:155], v[32:35]
	v_mfma_f32_16x16x32_bf16 v[20:23], v[192:195], v[160:163], v[20:23]
	v_mfma_f32_16x16x32_bf16 v[16:19], v[200:203], v[160:163], v[16:19]
	v_mfma_f32_16x16x32_bf16 v[4:7], v[192:195], v[168:171], v[4:7]
	v_mfma_f32_16x16x32_bf16 v[0:3], v[200:203], v[168:171], v[0:3]
	v_mfma_f32_16x16x32_bf16 v[52:55], v[196:199], v[148:151], v[52:55]
	v_mfma_f32_16x16x32_bf16 v[48:51], v[212:215], v[148:151], v[48:51]
	v_mfma_f32_16x16x32_bf16 v[36:39], v[196:199], v[156:159], v[36:39]
	v_mfma_f32_16x16x32_bf16 v[32:35], v[212:215], v[156:159], v[32:35]
	v_mfma_f32_16x16x32_bf16 v[20:23], v[196:199], v[164:167], v[20:23]
	v_mfma_f32_16x16x32_bf16 v[16:19], v[212:215], v[164:167], v[16:19]
	s_setprio 2
	s_barrier
	v_mfma_f32_16x16x32_bf16 v[4:7], v[196:199], v[172:175], v[4:7]
	v_mfma_f32_16x16x32_bf16 v[0:3], v[212:215], v[172:175], v[0:3]
	s_setprio 0
	s_add_i32 s97, s97, 2
	s_add_u32 s6, s6, 0x100
	s_addc_u32 s7, s7, 0
	s_cmp_gt_u32 s97, 41
	s_mov_b64 s[28:29], s[76:77]
	s_cbranch_scc0 .LBB0_186
; DI unsigned pk_bf16(float lo, float hi) { f32x2 v = {lo, hi}; return __builtin_bit_cast(unsigned, __builtin_convertvector(v, bf16v2)); }
; DI f32x4 bf_lo4(u32x4 w) { f32x4 r; r[0] = bf_lo(w.x); r[1] = bf_hi(w.x); r[2] = bf_lo(w.y); r[3] = bf_hi(w.y); return r; }
; DI f32x4 bf_hi4(u32x4 w) { f32x4 r; r[0] = bf_lo(w.z); r[1] = bf_hi(w.z); r[2] = bf_lo(w.w); r[3] = bf_hi(w.w); return r; }
;     DI void operator()(AccRef acc, const Unit& u, int wr, int wc, int fr, int fq) const {
;     ...
;         const int row0 = u.pm * 256 + wr * 64 + fr, col0 = u.pn * 256 + wc * 32 + 8 * fq;
; #pragma unroll
;         for (int ai = 0; ai < 2; ++ai) {
;             f32x4 bv[4][2][2];
; #pragma unroll
;             for (int m = 0; m < 4; ++m)
; #pragma unroll
;                 for (int bj = 0; bj < 2; ++bj) {
;                     const size_t o = (size_t)(row0 + ai * 128 + m * 16) * DM + col0 + bj * 128;
;                     if (BASEF32) { bv[m][bj][0] = *(const f32x4*)(basef + o); bv[m][bj][1] = *(const f32x4*)(basef + o + 4); }
;                     else { const u32x4 h = *(const u32x4*)(xnb + o); bv[m][bj][0] = bf_lo4(h); bv[m][bj][1] = bf_hi4(h); }
;                 }
; #pragma unroll
;             for (int m = 0; m < 4; ++m) {
;                 const int row = row0 + ai * 128 + m * 16;
;                 float q = 0.f;
; #pragma unroll
;                 for (int bj = 0; bj < 2; ++bj) {
;                     const size_t o = (size_t)row * DM + col0 + bj * 128;
;                     const f32x4 r0 = bv[m][bj][0] + scale * acc[ai][bj][m][0], r1 = bv[m][bj][1] + scale * acc[ai][bj][m][1];
;                     u32x4 w; w.x = pk_bf16(r0[0], r0[1]); w.y = pk_bf16(r0[2], r0[3]); w.z = pk_bf16(r1[0], r1[1]); w.w = pk_bf16(r1[2], r1[3]);
;                     *(u32x4*)(xnb + o) = w;
;                     if (STATS) q += r0[0] * r0[0] + r0[1] * r0[1] + r0[2] * r0[2] + r0[3] * r0[3] + r1[0] * r1[0] + r1[1] * r1[1] + r1[2] * r1[2] + r1[3] * r1[3];
;                 }
;                 if (STATS) { q += __shfl_xor(q, 16); q += __shfl_xor(q, 32); if (fq == 0) atomicAdd(ss + row, q); }
	v_lshl_add_u32 v194, s96, 8, v204
	v_lshl_or_b32 v192, s95, 8, v206
	v_ashrrev_i32_e32 v193, 31, v192
	v_ashrrev_i32_e32 v195, 31, v194
	v_lshl_add_u64 v[196:197], v[192:193], 2, s[52:53]
	v_lshlrev_b64 v[128:129], 12, v[194:195]
	v_lshl_add_u64 v[128:129], v[196:197], 0, v[128:129]
	global_load_dwordx4 v[214:217], v[128:129], off
	global_load_dwordx4 v[218:221], v[128:129], off offset:16
	global_load_dwordx4 v[224:227], v[128:129], off offset:512
	global_load_dwordx4 v[228:231], v[128:129], off offset:528
	v_or_b32_e32 v202, 16, v194
	v_or_b32_e32 v200, 32, v194
	v_or_b32_e32 v198, 48, v194
	v_ashrrev_i32_e32 v203, 31, v202
	v_ashrrev_i32_e32 v201, 31, v200
	v_ashrrev_i32_e32 v199, 31, v198
	v_lshlrev_b64 v[128:129], 12, v[202:203]
	v_lshlrev_b64 v[130:131], 12, v[200:201]
	v_lshlrev_b64 v[132:133], 12, v[198:199]
	v_lshl_add_u64 v[128:129], v[196:197], 0, v[128:129]
	v_lshl_add_u64 v[130:131], v[196:197], 0, v[130:131]
	v_lshl_add_u64 v[132:133], v[196:197], 0, v[132:133]
	global_load_dwordx4 v[168:171], v[128:129], off offset:16
	global_load_dwordx4 v[172:175], v[128:129], off
	global_load_dwordx4 v[160:163], v[128:129], off offset:528
	global_load_dwordx4 v[164:167], v[128:129], off offset:512
	global_load_dwordx4 v[152:155], v[130:131], off offset:16
	global_load_dwordx4 v[156:159], v[130:131], off
	global_load_dwordx4 v[144:147], v[130:131], off offset:528
	global_load_dwordx4 v[148:151], v[130:131], off offset:512
	global_load_dwordx4 v[136:139], v[132:133], off offset:16
	global_load_dwordx4 v[140:143], v[132:133], off
	s_nop 0
	global_load_dwordx4 v[128:131], v[132:133], off offset:528
	s_nop 0
	global_load_dwordx4 v[132:135], v[132:133], off offset:512
	v_and_b32_e32 v212, 64, v210
	v_xor_b32_e32 v211, 16, v210
	v_add_u32_e32 v212, 64, v212
	v_xor_b32_e32 v213, 32, v210
	v_cmp_lt_i32_e32 vcc, v211, v212
	v_lshlrev_b64 v[232:233], 11, v[194:195]
	s_waitcnt vmcnt(0)
	v_pk_fma_f32 v[124:125], v[124:125], 0.5, v[214:215] op_sel_hi:[1,0,1]
	v_cndmask_b32_e32 v211, v210, v211, vcc
	v_cmp_lt_i32_e32 vcc, v213, v212
	v_pk_fma_f32 v[116:117], v[116:117], 0.5, v[224:225] op_sel_hi:[1,0,1]
	v_lshlrev_b32_e32 v212, 2, v211
	v_cndmask_b32_e32 v213, v210, v213, vcc
	v_lshlrev_b32_e32 v211, 2, v213
	v_pk_fma_f32 v[126:127], v[126:127], 0.5, v[216:217] op_sel_hi:[1,0,1]
	v_pk_fma_f32 v[216:217], v[112:113], 0.5, v[228:229] op_sel_hi:[1,0,1]
	v_cvt_pk_bf16_f32 v112, v124, v125
	v_mul_f32_e32 v125, v125, v125
	v_mul_f32_e32 v213, v117, v117
	v_pk_fma_f32 v[118:119], v[118:119], 0.5, v[226:227] op_sel_hi:[1,0,1]
	v_fmac_f32_e32 v125, v124, v124
	v_fmac_f32_e32 v213, v116, v116
	v_fmac_f32_e32 v125, v126, v126
	v_fmac_f32_e32 v213, v118, v118
	v_pk_fma_f32 v[120:121], v[120:121], 0.5, v[218:219] op_sel_hi:[1,0,1]
	v_fmac_f32_e32 v125, v127, v127
	v_fmac_f32_e32 v213, v119, v119
	v_fmac_f32_e32 v125, v120, v120
	v_fmac_f32_e32 v213, v216, v216
	v_pk_fma_f32 v[122:123], v[122:123], 0.5, v[220:221] op_sel_hi:[1,0,1]
	v_pk_fma_f32 v[214:215], v[114:115], 0.5, v[230:231] op_sel_hi:[1,0,1]
	v_fmac_f32_e32 v125, v121, v121
	v_fmac_f32_e32 v213, v217, v217
	v_fmac_f32_e32 v125, v122, v122
	v_fmac_f32_e32 v213, v214, v214
	v_fmac_f32_e32 v125, v123, v123
	v_fmac_f32_e32 v213, v215, v215
	v_cvt_pk_bf16_f32 v115, v122, v123
	v_add_f32_e32 v122, v125, v213
	ds_bpermute_b32 v123, v212, v122
	v_cvt_pk_bf16_f32 v114, v120, v121
	v_lshl_add_u64 v[120:121], s[56:57], 0, v[232:233]
	v_cvt_pk_bf16_f32 v113, v126, v127
	v_lshl_add_u64 v[120:121], v[192:193], 1, v[120:121]
	global_store_dwordx4 v[120:121], v[112:115], off
	s_waitcnt lgkmcnt(0)
	s_nop 0
	v_add_f32_e32 v112, v122, v123
	ds_bpermute_b32 v113, v211, v112
	v_cvt_pk_bf16_f32 v114, v116, v117
	v_cvt_pk_bf16_f32 v115, v118, v119
	v_cvt_pk_bf16_f32 v116, v216, v217
	v_cvt_pk_bf16_f32 v117, v214, v215
	global_store_dwordx4 v[120:121], v[114:117], off offset:256
	s_and_saveexec_b64 s[6:7], s[0:1]
	s_cbranch_execz .LBB0_189
	v_lshl_add_u64 v[114:115], v[194:195], 2, s[60:61]
	s_waitcnt lgkmcnt(0)
	v_add_f32_e32 v112, v112, v113
	global_atomic_add_f32 v[114:115], v112, off

; #define PG8_STAGE(bufoff, gbase, voff) do { _Pragma("unroll") for (int _i = 0; _i < 2; ++_i) \
;         __builtin_amdgcn_global_load_lds((const unsigned*)((const char*)(gbase) + (voff)[_i]), (LAS unsigned*)(lds + (bufoff) + ldsw + _i * 8192), 16, 0, 0); } while (0)
; #define PG8_LDA(dst, b, h) do { _Pragma("unroll") for (int m = 0; m < 4; ++m) _Pragma("unroll") for (int k = 0; k < 2; ++k) dst[m][k] = *(const LAS bf16x8*)(lds + PG8_SA(b, h) + aoff + m * 2048 + k * 1024); } while (0)
; #define PG8_LDB(dst, b, h) do { _Pragma("unroll") for (int n = 0; n < 2; ++n) _Pragma("unroll") for (int k = 0; k < 2; ++k) dst[n][k] = *(const LAS bf16x8*)(lds + PG8_SB(b, h) + boff + n * 2048 + k * 1024); } while (0)
; #define PG8_MMA(ai, bj, At, Bt) do { __builtin_amdgcn_s_setprio(1); _Pragma("unroll") for (int m = 0; m < 4; ++m) _Pragma("unroll") for (int n = 0; n < 2; ++n) _Pragma("unroll") for (int k = 0; k < 2; ++k) \
;         acc[ai][bj][m][n] = __builtin_amdgcn_mfma_f32_16x16x32_bf16(Bt[n][k], At[m][k], acc[ai][bj][m][n], 0, 0, 0); __builtin_amdgcn_s_setprio(0); } while (0)
; #define PG8_WAIT_V(n) asm volatile("s_waitcnt vmcnt(" #n ")" ::: "memory")
; #define PG8_WAIT_L(n) asm volatile("s_waitcnt lgkmcnt(" #n ")" ::: "memory")
; #define PG8_BAR __builtin_amdgcn_s_barrier()
; #define PG8_SCHED __builtin_amdgcn_sched_barrier(0)
; template <class Epi>
; DI void gemm_phase(LAS unsigned char* lds, const Gemm g, const StaticOrder S, const Epi E) {
;     ...
;             const bool last = (t == nt - 2);
;             const char* a1 = cA + (size_t)(t + 1) * kstep;
;             const char* a2 = last ? nA : cA + (size_t)(t + 2) * kstep; const char* b2 = last ? nB : cB + (size_t)(t + 2) * kstep;
;             const char* a3 = a2 + kstep; const char* b3 = b2 + kstep;
;             PG8_LDB(B0, 0, 0); PG8_SCHED; PG8_LDA(At, 0, 0); PG8_STAGE(PG8_SA(1, 1), a1 + hstep, voffA);
;             PG8_WAIT_L(8); PG8_BAR; PG8_WAIT_L(0); PG8_MMA(0, 0, At, B0); PG8_BAR; PG8_SCHED;
;             PG8_LDB(B1, 0, 1); PG8_STAGE(PG8_SB(0, 0), b2, voffB);
;             PG8_BAR; PG8_WAIT_L(0); PG8_MMA(0, 1, At, B1); PG8_BAR;
;             PG8_LDA(At, 0, 1); PG8_STAGE(PG8_SA(0, 0), a2, voffA);
;             PG8_BAR; PG8_WAIT_L(0); PG8_MMA(1, 0, At, B0); PG8_BAR; PG8_SCHED;
;             PG8_STAGE(PG8_SB(0, 1), b2 + hstep, voffB);
;             PG8_WAIT_V(6); PG8_BAR; PG8_MMA(1, 1, At, B1); PG8_BAR;
.LBB0_274:
	ds_read_b128 v[100:103], v227
	ds_read_b128 v[134:137], v227 offset:1024
	ds_read_b128 v[138:141], v227 offset:2048
	ds_read_b128 v[142:145], v227 offset:3072
	s_add_u32 s14, s8, 0xfffc0080
	s_addc_u32 s15, s9, -1
	s_cmp_eq_u32 s95, 12
	s_cselect_b32 s77, s1, s15
	s_cselect_b32 s76, s6, s14
	s_cselect_b32 s53, s7, s94
	s_cselect_b32 s52, s21, s23
	v_lshl_add_u64 v[104:105], s[8:9], 0, v[212:213]
	s_add_i32 m0, s78, 0xc000
	ds_read_b128 v[146:149], v228
	ds_read_b128 v[150:153], v228 offset:1024
	ds_read_b128 v[154:157], v228 offset:2048
	ds_read_b128 v[158:161], v228 offset:3072
	ds_read_b128 v[162:165], v228 offset:4096
	ds_read_b128 v[166:169], v228 offset:5120
	ds_read_b128 v[170:173], v228 offset:6144
	ds_read_b128 v[174:177], v228 offset:7168
	global_load_lds_dwordx4 v[104:105], off
	v_lshl_add_u64 v[104:105], s[8:9], 0, v[214:215]
	s_add_i32 m0, s78, 0xe000
	s_nop 0
	global_load_lds_dwordx4 v[104:105], off
	s_waitcnt lgkmcnt(8)
	s_setprio 1
	s_barrier
	s_waitcnt lgkmcnt(0)
	v_mfma_f32_16x16x32_bf16 v[130:133], v[100:103], v[146:149], v[130:133]
	v_mfma_f32_16x16x32_bf16 v[126:129], v[138:141], v[146:149], v[126:129]
	v_mfma_f32_16x16x32_bf16 v[114:117], v[100:103], v[154:157], v[114:117]
	v_mfma_f32_16x16x32_bf16 v[110:113], v[138:141], v[154:157], v[110:113]
	v_mfma_f32_16x16x32_bf16 v[92:95], v[100:103], v[162:165], v[92:95]
	v_mfma_f32_16x16x32_bf16 v[88:91], v[138:141], v[162:165], v[88:91]
	v_mfma_f32_16x16x32_bf16 v[76:79], v[100:103], v[170:173], v[76:79]
	v_mfma_f32_16x16x32_bf16 v[72:75], v[138:141], v[170:173], v[72:75]
	v_mfma_f32_16x16x32_bf16 v[130:133], v[134:137], v[150:153], v[130:133]
	v_mfma_f32_16x16x32_bf16 v[126:129], v[142:145], v[150:153], v[126:129]
	v_mfma_f32_16x16x32_bf16 v[114:117], v[134:137], v[158:161], v[114:117]
	v_mfma_f32_16x16x32_bf16 v[110:113], v[142:145], v[158:161], v[110:113]
	v_mfma_f32_16x16x32_bf16 v[92:95], v[134:137], v[166:169], v[92:95]
	v_mfma_f32_16x16x32_bf16 v[88:91], v[142:145], v[166:169], v[88:91]
	s_setprio 2
	s_barrier
	v_mfma_f32_16x16x32_bf16 v[76:79], v[134:137], v[174:177], v[76:79]
	v_mfma_f32_16x16x32_bf16 v[72:75], v[142:145], v[174:177], v[72:75]
	s_setprio 0
	s_add_i32 s14, s87, s59
	v_lshl_add_u64 v[194:195], s[52:53], 0, v[200:201]
	s_mov_b32 m0, s14
	ds_read_b128 v[178:181], v229
	ds_read_b128 v[182:185], v229 offset:1024
	ds_read_b128 v[186:189], v229 offset:2048
	ds_read_b128 v[190:193], v229 offset:3072
	global_load_lds_dwordx4 v[194:195], off
	v_lshl_add_u64 v[196:197], s[52:53], 0, v[204:205]
	s_add_i32 m0, s14, 0x2000
	s_nop 0
	global_load_lds_dwordx4 v[196:197], off
	s_setprio 1
	s_barrier
	s_waitcnt lgkmcnt(0)
	v_mfma_f32_16x16x32_bf16 v[122:125], v[178:181], v[146:149], v[122:125]
	v_mfma_f32_16x16x32_bf16 v[118:121], v[186:189], v[146:149], v[118:121]
	v_mfma_f32_16x16x32_bf16 v[104:107], v[178:181], v[154:157], v[106:109]
	v_mfma_f32_16x16x32_bf16 v[96:99], v[186:189], v[154:157], v[96:99]
	v_mfma_f32_16x16x32_bf16 v[84:87], v[178:181], v[162:165], v[84:87]
	v_mfma_f32_16x16x32_bf16 v[80:83], v[186:189], v[162:165], v[80:83]
	v_mfma_f32_16x16x32_bf16 v[68:71], v[178:181], v[170:173], v[68:71]
	v_mfma_f32_16x16x32_bf16 v[64:67], v[186:189], v[170:173], v[64:67]
	v_mfma_f32_16x16x32_bf16 v[122:125], v[182:185], v[150:153], v[122:125]
	v_mfma_f32_16x16x32_bf16 v[118:121], v[190:193], v[150:153], v[118:121]
	v_mfma_f32_16x16x32_bf16 v[104:107], v[182:185], v[158:161], v[104:107]
	v_mfma_f32_16x16x32_bf16 v[96:99], v[190:193], v[158:161], v[96:99]
	v_mfma_f32_16x16x32_bf16 v[84:87], v[182:185], v[166:169], v[84:87]
	v_mfma_f32_16x16x32_bf16 v[80:83], v[190:193], v[166:169], v[80:83]
	s_setprio 2
	s_barrier
	v_mfma_f32_16x16x32_bf16 v[68:71], v[182:185], v[174:177], v[68:71]
	v_mfma_f32_16x16x32_bf16 v[64:67], v[190:193], v[174:177], v[64:67]
	s_setprio 0
	s_mov_b32 m0, s78
	v_lshl_add_u64 v[220:221], s[76:77], 0, v[198:199]
	ds_read_b128 v[146:149], v228 offset:16384
	ds_read_b128 v[150:153], v228 offset:17408
	ds_read_b128 v[154:157], v228 offset:18432
	ds_read_b128 v[158:161], v228 offset:19456
	ds_read_b128 v[162:165], v228 offset:20480
	ds_read_b128 v[166:169], v228 offset:21504
	ds_read_b128 v[170:173], v228 offset:22528
	ds_read_b128 v[174:177], v228 offset:23552
	global_load_lds_dwordx4 v[220:221], off
	v_lshl_add_u64 v[232:233], s[76:77], 0, v[202:203]
	s_mov_b32 m0, s79
	s_nop 0
	global_load_lds_dwordx4 v[232:233], off
	s_setprio 1
	s_barrier
	s_waitcnt lgkmcnt(0)
	v_mfma_f32_16x16x32_bf16 v[60:63], v[100:103], v[146:149], v[60:63]
	v_mfma_f32_16x16x32_bf16 v[56:59], v[138:141], v[146:149], v[56:59]
	v_mfma_f32_16x16x32_bf16 v[44:47], v[100:103], v[154:157], v[44:47]
	v_mfma_f32_16x16x32_bf16 v[40:43], v[138:141], v[154:157], v[40:43]
	v_mfma_f32_16x16x32_bf16 v[28:31], v[100:103], v[162:165], v[28:31]
	v_mfma_f32_16x16x32_bf16 v[24:27], v[138:141], v[162:165], v[24:27]
	v_mfma_f32_16x16x32_bf16 v[12:15], v[100:103], v[170:173], v[12:15]
	v_mfma_f32_16x16x32_bf16 v[8:11], v[138:141], v[170:173], v[8:11]
	v_mfma_f32_16x16x32_bf16 v[60:63], v[134:137], v[150:153], v[60:63]
	v_mfma_f32_16x16x32_bf16 v[56:59], v[142:145], v[150:153], v[56:59]
	v_mfma_f32_16x16x32_bf16 v[44:47], v[134:137], v[158:161], v[44:47]
	v_mfma_f32_16x16x32_bf16 v[40:43], v[142:145], v[158:161], v[40:43]
	v_mfma_f32_16x16x32_bf16 v[28:31], v[134:137], v[166:169], v[28:31]
	v_mfma_f32_16x16x32_bf16 v[24:27], v[142:145], v[166:169], v[24:27]
	s_setprio 2
	s_barrier
; #define PG8_STAGE(bufoff, gbase, voff) do { _Pragma("unroll") for (int _i = 0; _i < 2; ++_i) \
;         __builtin_amdgcn_global_load_lds((const unsigned*)((const char*)(gbase) + (voff)[_i]), (LAS unsigned*)(lds + (bufoff) + ldsw + _i * 8192), 16, 0, 0); } while (0)
; #define PG8_LDA(dst, b, h) do { _Pragma("unroll") for (int m = 0; m < 4; ++m) _Pragma("unroll") for (int k = 0; k < 2; ++k) dst[m][k] = *(const LAS bf16x8*)(lds + PG8_SA(b, h) + aoff + m * 2048 + k * 1024); } while (0)
; #define PG8_LDB(dst, b, h) do { _Pragma("unroll") for (int n = 0; n < 2; ++n) _Pragma("unroll") for (int k = 0; k < 2; ++k) dst[n][k] = *(const LAS bf16x8*)(lds + PG8_SB(b, h) + boff + n * 2048 + k * 1024); } while (0)
; #define PG8_MMA(ai, bj, At, Bt) do { __builtin_amdgcn_s_setprio(1); _Pragma("unroll") for (int m = 0; m < 4; ++m) _Pragma("unroll") for (int n = 0; n < 2; ++n) _Pragma("unroll") for (int k = 0; k < 2; ++k) \
;         acc[ai][bj][m][n] = __builtin_amdgcn_mfma_f32_16x16x32_bf16(Bt[n][k], At[m][k], acc[ai][bj][m][n], 0, 0, 0); __builtin_amdgcn_s_setprio(0); } while (0)
; #define PG8_WAIT_V(n) asm volatile("s_waitcnt vmcnt(" #n ")" ::: "memory")
; #define PG8_WAIT_L(n) asm volatile("s_waitcnt lgkmcnt(" #n ")" ::: "memory")
; #define PG8_BAR __builtin_amdgcn_s_barrier()
; #define PG8_SCHED __builtin_amdgcn_sched_barrier(0)
; #define PG8_STAGE(bufoff, gbase, voff) do { _Pragma("unroll") for (int _i = 0; _i < 2; ++_i) \
;         __builtin_amdgcn_global_load_lds((const unsigned*)((const char*)(gbase) + (voff)[_i]), (LAS unsigned*)(lds + (bufoff) + ldsw + _i * 8192), 16, 0, 0); } while (0)
; #define PG8_WAIT_V(n) asm volatile("s_waitcnt vmcnt(" #n ")" ::: "memory")
; template <class Epi>
; DI void gemm_phase(LAS unsigned char* lds, const Gemm g, const StaticOrder S, const Epi E) {
;     ...
;             PG8_BAR; PG8_WAIT_L(0); PG8_MMA(1, 0, At, B0); PG8_BAR; PG8_SCHED;
;             PG8_STAGE(PG8_SB(0, 1), b2 + hstep, voffB);
;             PG8_WAIT_V(6); PG8_BAR; PG8_MMA(1, 1, At, B1); PG8_BAR;
;             PG8_LDB(B0, 1, 0); PG8_SCHED; PG8_LDA(At, 1, 0); PG8_STAGE(PG8_SA(0, 1), a2 + hstep, voffA);
;             PG8_WAIT_L(8); PG8_BAR; PG8_WAIT_L(0); PG8_MMA(0, 0, At, B0); PG8_BAR; PG8_SCHED;
;             PG8_LDB(B1, 1, 1); PG8_STAGE(PG8_SB(1, 0), b3, voffB);
;             PG8_BAR; PG8_WAIT_L(0); PG8_MMA(0, 1, At, B1); PG8_BAR;
	v_mfma_f32_16x16x32_bf16 v[12:15], v[134:137], v[174:177], v[12:15]
	v_mfma_f32_16x16x32_bf16 v[8:11], v[142:145], v[174:177], v[8:11]
	s_setprio 0
	s_add_u32 s14, s52, 0x40000
	s_addc_u32 s15, s53, 0
	s_add_i32 s35, s90, s59
	v_lshl_add_u64 v[100:101], s[14:15], 0, v[200:201]
	s_mov_b32 m0, s35
	s_nop 0
	global_load_lds_dwordx4 v[100:101], off
	v_lshl_add_u64 v[100:101], s[14:15], 0, v[204:205]
	s_add_i32 m0, s35, 0x2000
	s_nop 0
	global_load_lds_dwordx4 v[100:101], off
	s_waitcnt vmcnt(6)
	s_setprio 1
	s_barrier
	v_mfma_f32_16x16x32_bf16 v[52:55], v[178:181], v[146:149], v[52:55]
	v_mfma_f32_16x16x32_bf16 v[48:51], v[186:189], v[146:149], v[48:51]
	v_mfma_f32_16x16x32_bf16 v[36:39], v[178:181], v[154:157], v[36:39]
	v_mfma_f32_16x16x32_bf16 v[32:35], v[186:189], v[154:157], v[32:35]
	v_mfma_f32_16x16x32_bf16 v[20:23], v[178:181], v[162:165], v[20:23]
	v_mfma_f32_16x16x32_bf16 v[16:19], v[186:189], v[162:165], v[16:19]
	v_mfma_f32_16x16x32_bf16 v[4:7], v[178:181], v[170:173], v[4:7]
	v_mfma_f32_16x16x32_bf16 v[0:3], v[186:189], v[170:173], v[0:3]
	v_mfma_f32_16x16x32_bf16 v[52:55], v[182:185], v[150:153], v[52:55]
	v_mfma_f32_16x16x32_bf16 v[48:51], v[190:193], v[150:153], v[48:51]
	v_mfma_f32_16x16x32_bf16 v[36:39], v[182:185], v[158:161], v[36:39]
	v_mfma_f32_16x16x32_bf16 v[32:35], v[190:193], v[158:161], v[32:35]
	v_mfma_f32_16x16x32_bf16 v[20:23], v[182:185], v[166:169], v[20:23]
	v_mfma_f32_16x16x32_bf16 v[16:19], v[190:193], v[166:169], v[16:19]
	s_setprio 2
	s_barrier
	v_mfma_f32_16x16x32_bf16 v[4:7], v[182:185], v[174:177], v[4:7]
	v_mfma_f32_16x16x32_bf16 v[0:3], v[190:193], v[174:177], v[0:3]
	s_setprio 0
	s_add_i32 s35, 0, 0x18000
	v_add_u32_e32 v108, s35, v225
	ds_read_b128 v[100:103], v108
	ds_read_b128 v[134:137], v108 offset:1024
	ds_read_b128 v[138:141], v108 offset:2048
	ds_read_b128 v[142:145], v108 offset:3072
	s_add_u32 s14, s76, 0x40000
	s_addc_u32 s15, s77, 0
	s_mov_b32 m0, s80
	v_lshl_add_u64 v[108:109], s[14:15], 0, v[198:199]
	ds_read_b128 v[146:149], v228 offset:32768
	ds_read_b128 v[150:153], v228 offset:33792
	ds_read_b128 v[154:157], v228 offset:34816
	ds_read_b128 v[158:161], v228 offset:35840
	ds_read_b128 v[162:165], v228 offset:36864
	ds_read_b128 v[166:169], v228 offset:37888
	ds_read_b128 v[170:173], v228 offset:38912
	ds_read_b128 v[174:177], v228 offset:39936
	global_load_lds_dwordx4 v[108:109], off
	v_lshl_add_u64 v[108:109], s[14:15], 0, v[202:203]
	s_mov_b32 m0, s81
	s_nop 0
	global_load_lds_dwordx4 v[108:109], off
	s_waitcnt lgkmcnt(8)
	s_setprio 1
	s_barrier
	s_waitcnt lgkmcnt(0)
	v_mfma_f32_16x16x32_bf16 v[130:133], v[100:103], v[146:149], v[130:133]
	v_mfma_f32_16x16x32_bf16 v[126:129], v[138:141], v[146:149], v[126:129]
	v_mfma_f32_16x16x32_bf16 v[114:117], v[100:103], v[154:157], v[114:117]
	v_mfma_f32_16x16x32_bf16 v[108:111], v[138:141], v[154:157], v[110:113]
	v_mfma_f32_16x16x32_bf16 v[92:95], v[100:103], v[162:165], v[92:95]
	v_mfma_f32_16x16x32_bf16 v[88:91], v[138:141], v[162:165], v[88:91]
	v_mfma_f32_16x16x32_bf16 v[76:79], v[100:103], v[170:173], v[76:79]
	v_mfma_f32_16x16x32_bf16 v[72:75], v[138:141], v[170:173], v[72:75]
	v_mfma_f32_16x16x32_bf16 v[130:133], v[134:137], v[150:153], v[130:133]
	v_mfma_f32_16x16x32_bf16 v[126:129], v[142:145], v[150:153], v[126:129]
	v_mfma_f32_16x16x32_bf16 v[114:117], v[134:137], v[158:161], v[114:117]
	v_mfma_f32_16x16x32_bf16 v[110:113], v[142:145], v[158:161], v[108:111]
	v_mfma_f32_16x16x32_bf16 v[92:95], v[134:137], v[166:169], v[92:95]
	v_mfma_f32_16x16x32_bf16 v[88:91], v[142:145], v[166:169], v[88:91]
	s_setprio 2
	s_barrier
	v_mfma_f32_16x16x32_bf16 v[76:79], v[134:137], v[174:177], v[76:79]
	v_mfma_f32_16x16x32_bf16 v[72:75], v[142:145], v[174:177], v[72:75]
	s_setprio 0
	s_add_i32 s76, 0, 0x1c000
	v_add_u32_e32 v108, s76, v225
	s_add_i32 s14, s35, s59
	ds_read_b128 v[178:181], v108
	ds_read_b128 v[182:185], v108 offset:1024
	ds_read_b128 v[186:189], v108 offset:2048
	ds_read_b128 v[190:193], v108 offset:3072
	v_lshl_add_u64 v[108:109], v[194:195], 0, s[18:19]
	s_mov_b32 m0, s14
	s_nop 0
	global_load_lds_dwordx4 v[108:109], off
	v_lshl_add_u64 v[108:109], v[196:197], 0, s[18:19]
	s_add_i32 m0, s14, 0x2000
	s_nop 0
	global_load_lds_dwordx4 v[108:109], off
	s_setprio 1
	s_barrier
	s_waitcnt lgkmcnt(0)
	v_mfma_f32_16x16x32_bf16 v[122:125], v[178:181], v[146:149], v[122:125]
	v_mfma_f32_16x16x32_bf16 v[118:121], v[186:189], v[146:149], v[118:121]
	v_mfma_f32_16x16x32_bf16 v[104:107], v[178:181], v[154:157], v[104:107]
	v_mfma_f32_16x16x32_bf16 v[96:99], v[186:189], v[154:157], v[96:99]
	v_mfma_f32_16x16x32_bf16 v[84:87], v[178:181], v[162:165], v[84:87]
	v_mfma_f32_16x16x32_bf16 v[80:83], v[186:189], v[162:165], v[80:83]
	v_mfma_f32_16x16x32_bf16 v[68:71], v[178:181], v[170:173], v[68:71]
	v_mfma_f32_16x16x32_bf16 v[64:67], v[186:189], v[170:173], v[64:67]
	v_mfma_f32_16x16x32_bf16 v[122:125], v[182:185], v[150:153], v[122:125]
	v_mfma_f32_16x16x32_bf16 v[118:121], v[190:193], v[150:153], v[118:121]
	v_mfma_f32_16x16x32_bf16 v[106:109], v[182:185], v[158:161], v[104:107]
	v_mfma_f32_16x16x32_bf16 v[96:99], v[190:193], v[158:161], v[96:99]
	v_mfma_f32_16x16x32_bf16 v[84:87], v[182:185], v[166:169], v[84:87]
	v_mfma_f32_16x16x32_bf16 v[80:83], v[190:193], v[166:169], v[80:83]
	s_setprio 2
	s_barrier
; #define PG8_STAGE(bufoff, gbase, voff) do { _Pragma("unroll") for (int _i = 0; _i < 2; ++_i) \
;         __builtin_amdgcn_global_load_lds((const unsigned*)((const char*)(gbase) + (voff)[_i]), (LAS unsigned*)(lds + (bufoff) + ldsw + _i * 8192), 16, 0, 0); } while (0)
; #define PG8_LDA(dst, b, h) do { _Pragma("unroll") for (int m = 0; m < 4; ++m) _Pragma("unroll") for (int k = 0; k < 2; ++k) dst[m][k] = *(const LAS bf16x8*)(lds + PG8_SA(b, h) + aoff + m * 2048 + k * 1024); } while (0)
; #define PG8_MMA(ai, bj, At, Bt) do { __builtin_amdgcn_s_setprio(1); _Pragma("unroll") for (int m = 0; m < 4; ++m) _Pragma("unroll") for (int n = 0; n < 2; ++n) _Pragma("unroll") for (int k = 0; k < 2; ++k) \
;         acc[ai][bj][m][n] = __builtin_amdgcn_mfma_f32_16x16x32_bf16(Bt[n][k], At[m][k], acc[ai][bj][m][n], 0, 0, 0); __builtin_amdgcn_s_setprio(0); } while (0)
; #define PG8_WAIT_V(n) asm volatile("s_waitcnt vmcnt(" #n ")" ::: "memory")
; #define PG8_WAIT_L(n) asm volatile("s_waitcnt lgkmcnt(" #n ")" ::: "memory")
; #define PG8_BAR __builtin_amdgcn_s_barrier()
; #define PG8_SCHED __builtin_amdgcn_sched_barrier(0)
; #define PG8_STAGE(bufoff, gbase, voff) do { _Pragma("unroll") for (int _i = 0; _i < 2; ++_i) \
;         __builtin_amdgcn_global_load_lds((const unsigned*)((const char*)(gbase) + (voff)[_i]), (LAS unsigned*)(lds + (bufoff) + ldsw + _i * 8192), 16, 0, 0); } while (0)
; #define PG8_LDA(dst, b, h) do { _Pragma("unroll") for (int m = 0; m < 4; ++m) _Pragma("unroll") for (int k = 0; k < 2; ++k) dst[m][k] = *(const LAS bf16x8*)(lds + PG8_SA(b, h) + aoff + m * 2048 + k * 1024); } while (0)
; #define PG8_WAIT_V(n) asm volatile("s_waitcnt vmcnt(" #n ")" ::: "memory")
; #define PG8_WAIT_L(n) asm volatile("s_waitcnt lgkmcnt(" #n ")" ::: "memory")
; #define PG8_BAR __builtin_amdgcn_s_barrier()
; #define PG8_SCHED __builtin_amdgcn_sched_barrier(0)
; template <class Epi>
; DI void gemm_phase(LAS unsigned char* lds, const Gemm g, const StaticOrder S, const Epi E) {
;     ...
;             PG8_BAR; PG8_WAIT_L(0); PG8_MMA(0, 1, At, B1); PG8_BAR;
;             PG8_LDA(At, 1, 1); PG8_STAGE(PG8_SA(1, 0), a3, voffA);
;             PG8_BAR; PG8_WAIT_L(0); PG8_MMA(1, 0, At, B0); PG8_BAR; PG8_SCHED;
;             PG8_STAGE(PG8_SB(1, 1), b3 + hstep, voffB);
;             PG8_WAIT_V(6); PG8_BAR; PG8_MMA(1, 1, At, B1); PG8_BAR;
	v_mfma_f32_16x16x32_bf16 v[68:71], v[182:185], v[174:177], v[68:71]
	v_mfma_f32_16x16x32_bf16 v[64:67], v[190:193], v[174:177], v[64:67]
	s_setprio 0
	s_mov_b32 m0, s83
	v_lshl_add_u64 v[104:105], v[220:221], 0, s[18:19]
	ds_read_b128 v[146:149], v228 offset:49152
	ds_read_b128 v[150:153], v228 offset:50176
	ds_read_b128 v[154:157], v228 offset:51200
	ds_read_b128 v[158:161], v228 offset:52224
	ds_read_b128 v[162:165], v228 offset:53248
	ds_read_b128 v[166:169], v228 offset:54272
	ds_read_b128 v[170:173], v228 offset:55296
	ds_read_b128 v[174:177], v228 offset:56320
	global_load_lds_dwordx4 v[104:105], off
	v_lshl_add_u64 v[104:105], v[232:233], 0, s[18:19]
	s_mov_b32 m0, s84
	s_nop 0
	global_load_lds_dwordx4 v[104:105], off
	s_setprio 1
	s_barrier
	s_waitcnt lgkmcnt(0)
	v_mfma_f32_16x16x32_bf16 v[60:63], v[100:103], v[146:149], v[60:63]
	v_mfma_f32_16x16x32_bf16 v[56:59], v[138:141], v[146:149], v[56:59]
	v_mfma_f32_16x16x32_bf16 v[44:47], v[100:103], v[154:157], v[44:47]
	v_mfma_f32_16x16x32_bf16 v[40:43], v[138:141], v[154:157], v[40:43]
	v_mfma_f32_16x16x32_bf16 v[28:31], v[100:103], v[162:165], v[28:31]
	v_mfma_f32_16x16x32_bf16 v[24:27], v[138:141], v[162:165], v[24:27]
	v_mfma_f32_16x16x32_bf16 v[12:15], v[100:103], v[170:173], v[12:15]
	v_mfma_f32_16x16x32_bf16 v[8:11], v[138:141], v[170:173], v[8:11]
	v_mfma_f32_16x16x32_bf16 v[60:63], v[134:137], v[150:153], v[60:63]
	v_mfma_f32_16x16x32_bf16 v[56:59], v[142:145], v[150:153], v[56:59]
	v_mfma_f32_16x16x32_bf16 v[44:47], v[134:137], v[158:161], v[44:47]
	v_mfma_f32_16x16x32_bf16 v[40:43], v[142:145], v[158:161], v[40:43]
	v_mfma_f32_16x16x32_bf16 v[28:31], v[134:137], v[166:169], v[28:31]
	v_mfma_f32_16x16x32_bf16 v[24:27], v[142:145], v[166:169], v[24:27]
	s_setprio 2
	s_barrier
	v_mfma_f32_16x16x32_bf16 v[12:15], v[134:137], v[174:177], v[12:15]
	v_mfma_f32_16x16x32_bf16 v[8:11], v[142:145], v[174:177], v[8:11]
	s_setprio 0
	s_add_u32 s14, s52, 0x40080
	s_addc_u32 s15, s53, 0
	s_add_i32 s35, s76, s59
	v_lshl_add_u64 v[100:101], s[14:15], 0, v[200:201]
	s_mov_b32 m0, s35
	s_nop 0
	global_load_lds_dwordx4 v[100:101], off
	v_lshl_add_u64 v[100:101], s[14:15], 0, v[204:205]
	s_add_i32 m0, s35, 0x2000
	s_nop 0
	global_load_lds_dwordx4 v[100:101], off
	s_waitcnt vmcnt(6)
	s_setprio 1
	s_barrier
	v_mfma_f32_16x16x32_bf16 v[52:55], v[178:181], v[146:149], v[52:55]
	v_mfma_f32_16x16x32_bf16 v[48:51], v[186:189], v[146:149], v[48:51]
	v_mfma_f32_16x16x32_bf16 v[36:39], v[178:181], v[154:157], v[36:39]
	v_mfma_f32_16x16x32_bf16 v[32:35], v[186:189], v[154:157], v[32:35]
	v_mfma_f32_16x16x32_bf16 v[20:23], v[178:181], v[162:165], v[20:23]
	v_mfma_f32_16x16x32_bf16 v[16:19], v[186:189], v[162:165], v[16:19]
	v_mfma_f32_16x16x32_bf16 v[4:7], v[178:181], v[170:173], v[4:7]
	v_mfma_f32_16x16x32_bf16 v[0:3], v[186:189], v[170:173], v[0:3]
	v_mfma_f32_16x16x32_bf16 v[52:55], v[182:185], v[150:153], v[52:55]
	v_mfma_f32_16x16x32_bf16 v[48:51], v[190:193], v[150:153], v[48:51]
	v_mfma_f32_16x16x32_bf16 v[36:39], v[182:185], v[158:161], v[36:39]
	v_mfma_f32_16x16x32_bf16 v[32:35], v[190:193], v[158:161], v[32:35]
	v_mfma_f32_16x16x32_bf16 v[20:23], v[182:185], v[166:169], v[20:23]
	v_mfma_f32_16x16x32_bf16 v[16:19], v[190:193], v[166:169], v[16:19]
	s_setprio 2
	s_barrier
	v_mfma_f32_16x16x32_bf16 v[4:7], v[182:185], v[174:177], v[4:7]
	v_mfma_f32_16x16x32_bf16 v[0:3], v[190:193], v[174:177], v[0:3]
	s_setprio 0
	s_add_i32 s95, s95, 2
	s_add_u32 s8, s8, 0x100
	s_addc_u32 s9, s9, 0
	s_add_u32 s23, s23, 0x100
	s_addc_u32 s94, s94, 0
	s_cmp_gt_u32 s95, 13
	s_cbranch_scc0 .LBB0_274
; DI RowScales load_rowscales(const float* ss, int row0) {
;     RowScales t;
; #pragma unroll
;     for (int ai = 0; ai < 2; ++ai)
; #pragma unroll
;         for (int m = 0; m < 4; ++m) t.r[ai][m] = ss[row0 + ai * 128 + m * 16];
;     DI void operator()(AccRef acc, const Unit& u, int wr, int wc, int fr, int fq) const {
;         const int X = u.pn >> 2, h = u.pn & 3, isk = wc >> 1, i0 = (wc & 1) * 32 + 8 * fq;
;         bf16_t* dst = (X ? qkoB : qkoA) + h * 256 + isk * 128 + i0;
;         const float qs0 = isk ? 1.0f : 0.08838834764831845f;
;         const int row0 = u.pm * 256 + wr * 64 + fr;
;         const RowScales rsc = load_rowscales(ss, row0);
; #pragma unroll
;         for (int ai = 0; ai < 2; ++ai) {
;             f32x4 cs[4][2], sn[4][2];
;             if (X == 0) {
; #pragma unroll
;                 for (int m = 0; m < 4; ++m) {
;                     const int pos = (row0 + ai * 128 + m * 16) & (SEQ - 1);
;                     cs[m][0] = *(const f32x4*)(cosT + pos * 64 + i0); cs[m][1] = *(const f32x4*)(cosT + pos * 64 + i0 + 4);
;                     sn[m][0] = *(const f32x4*)(sinT + pos * 64 + i0); sn[m][1] = *(const f32x4*)(sinT + pos * 64 + i0 + 4);
;                 }
;             } else {
; #pragma unroll
;                 for (int m = 0; m < 4; ++m) { cs[m][0] = cs[m][1] = (f32x4){1.f, 1.f, 1.f, 1.f}; sn[m][0] = sn[m][1] = (f32x4){0.f, 0.f, 0.f, 0.f}; }
;             }
	v_lshl_add_u32 v102, s0, 8, v224
	v_ashrrev_i32_e32 v103, 31, v102
	v_lshl_add_u64 v[134:135], v[102:103], 2, s[60:61]
	global_load_dword v237, v[134:135], off
	global_load_dword v236, v[134:135], off offset:64
	global_load_dword v105, v[134:135], off offset:128
	global_load_dword v101, v[134:135], off offset:192
	global_load_dword v231, v[134:135], off offset:512
	global_load_dword v232, v[134:135], off offset:576
	global_load_dword v233, v[134:135], off offset:640
	global_load_dword v234, v[134:135], off offset:704
	s_cmp_lt_u32 s93, 4
	s_cselect_b64 s[0:1], -1, 0
	s_cmp_gt_u32 s93, 3
	v_lshlrev_b32_e32 v235, 6, v102
	v_mov_b32_e32 v100, 1.0
	v_mov_b32_e32 v104, 0
	v_mov_b32_e32 v134, 0
	v_mov_b32_e32 v135, 0
	v_mov_b32_e32 v136, 0
	v_mov_b32_e32 v137, 0
	v_mov_b32_e32 v142, 0
	v_mov_b32_e32 v143, 0
	v_mov_b32_e32 v144, 0
	v_mov_b32_e32 v145, 0
	v_mov_b32_e32 v146, 0
	v_mov_b32_e32 v147, 0
	v_mov_b32_e32 v148, 0
	v_mov_b32_e32 v149, 0
	v_mov_b32_e32 v154, 0
	v_mov_b32_e32 v155, 0
	v_mov_b32_e32 v156, 0
	v_mov_b32_e32 v157, 0
	v_mov_b32_e32 v162, 0
	v_mov_b32_e32 v163, 0
	v_mov_b32_e32 v164, 0
	v_mov_b32_e32 v165, 0
	v_mov_b32_e32 v174, 0
	v_mov_b32_e32 v175, 0
	v_mov_b32_e32 v176, 0
	v_mov_b32_e32 v177, 0
	v_mov_b32_e32 v182, 0
	v_mov_b32_e32 v183, 0
	v_mov_b32_e32 v184, 0
	v_mov_b32_e32 v185, 0
	v_mov_b32_e32 v194, 0
	v_mov_b32_e32 v195, 0
	v_mov_b32_e32 v196, 0
	v_mov_b32_e32 v197, 0
	v_mov_b32_e32 v138, 1.0
	v_mov_b32_e32 v139, 1.0
	v_mov_b32_e32 v140, 1.0
	v_mov_b32_e32 v141, 1.0
	v_mov_b32_e32 v190, 1.0
	v_mov_b32_e32 v191, 1.0
	v_mov_b32_e32 v192, 1.0
	v_mov_b32_e32 v193, 1.0
	v_mov_b32_e32 v186, 1.0
	v_mov_b32_e32 v187, 1.0
	v_mov_b32_e32 v188, 1.0
	v_mov_b32_e32 v189, 1.0
	v_mov_b32_e32 v178, 1.0
	v_mov_b32_e32 v179, 1.0
	v_mov_b32_e32 v180, 1.0
	v_mov_b32_e32 v181, 1.0
	v_mov_b32_e32 v170, 1.0
	v_mov_b32_e32 v171, 1.0
	v_mov_b32_e32 v172, 1.0
	v_mov_b32_e32 v173, 1.0
	v_mov_b32_e32 v166, 1.0
	v_mov_b32_e32 v167, 1.0
	v_mov_b32_e32 v168, 1.0
	v_mov_b32_e32 v169, 1.0
	v_mov_b32_e32 v158, 1.0
	v_mov_b32_e32 v159, 1.0
	v_mov_b32_e32 v160, 1.0
	v_mov_b32_e32 v161, 1.0
	v_mov_b32_e32 v150, 1.0
	v_mov_b32_e32 v151, 1.0
	v_mov_b32_e32 v152, 1.0
	v_mov_b32_e32 v153, 1.0
	s_cbranch_scc1 .LBB0_277
	v_lshlrev_b32_e32 v134, 2, v235
	v_and_b32_e32 v134, 0x1fcf00, v134
	v_mov_b32_e32 v135, v207
	v_lshl_add_u64 v[136:137], v[208:209], 0, v[134:135]
	global_load_dwordx4 v[190:193], v[136:137], off
	global_load_dwordx4 v[186:189], v[136:137], off offset:16
	v_lshl_add_u64 v[136:137], v[210:211], 0, v[134:135]
	global_load_dwordx4 v[182:185], v[136:137], off offset:16
	global_load_dwordx4 v[194:197], v[136:137], off
	v_or_b32_e32 v136, 0x1000, v134
	v_mov_b32_e32 v137, v207
	v_lshl_add_u64 v[138:139], v[208:209], 0, v[136:137]
	v_lshl_add_u64 v[136:137], v[210:211], 0, v[136:137]
	global_load_dwordx4 v[178:181], v[138:139], off
	global_load_dwordx4 v[170:173], v[138:139], off offset:16
	global_load_dwordx4 v[162:165], v[136:137], off offset:16
	global_load_dwordx4 v[174:177], v[136:137], off
	v_or_b32_e32 v136, 0x2000, v134
	v_mov_b32_e32 v137, v207
	v_lshl_add_u64 v[138:139], v[208:209], 0, v[136:137]
	v_lshl_add_u64 v[136:137], v[210:211], 0, v[136:137]
	v_or_b32_e32 v134, 0x3000, v134
	global_load_dwordx4 v[166:169], v[138:139], off
	global_load_dwordx4 v[158:161], v[138:139], off offset:16
	global_load_dwordx4 v[146:149], v[136:137], off offset:16
	global_load_dwordx4 v[154:157], v[136:137], off
	v_lshl_add_u64 v[136:137], v[208:209], 0, v[134:135]
	v_lshl_add_u64 v[142:143], v[210:211], 0, v[134:135]
	global_load_dwordx4 v[138:141], v[136:137], off offset:16
	global_load_dwordx4 v[150:153], v[136:137], off
	s_nop 0
	global_load_dwordx4 v[134:137], v[142:143], off offset:16
	s_nop 0
	global_load_dwordx4 v[142:145], v[142:143], off

; #define PG8_STAGE(bufoff, gbase, voff) do { _Pragma("unroll") for (int _i = 0; _i < 2; ++_i) \
;         __builtin_amdgcn_global_load_lds((const unsigned*)((const char*)(gbase) + (voff)[_i]), (LAS unsigned*)(lds + (bufoff) + ldsw + _i * 8192), 16, 0, 0); } while (0)
; #define PG8_LDA(dst, b, h) do { _Pragma("unroll") for (int m = 0; m < 4; ++m) _Pragma("unroll") for (int k = 0; k < 2; ++k) dst[m][k] = *(const LAS bf16x8*)(lds + PG8_SA(b, h) + aoff + m * 2048 + k * 1024); } while (0)
; #define PG8_LDB(dst, b, h) do { _Pragma("unroll") for (int n = 0; n < 2; ++n) _Pragma("unroll") for (int k = 0; k < 2; ++k) dst[n][k] = *(const LAS bf16x8*)(lds + PG8_SB(b, h) + boff + n * 2048 + k * 1024); } while (0)
; #define PG8_MMA(ai, bj, At, Bt) do { __builtin_amdgcn_s_setprio(1); _Pragma("unroll") for (int m = 0; m < 4; ++m) _Pragma("unroll") for (int n = 0; n < 2; ++n) _Pragma("unroll") for (int k = 0; k < 2; ++k) \
;         acc[ai][bj][m][n] = __builtin_amdgcn_mfma_f32_16x16x32_bf16(Bt[n][k], At[m][k], acc[ai][bj][m][n], 0, 0, 0); __builtin_amdgcn_s_setprio(0); } while (0)
; #define PG8_WAIT_V(n) asm volatile("s_waitcnt vmcnt(" #n ")" ::: "memory")
; #define PG8_WAIT_L(n) asm volatile("s_waitcnt lgkmcnt(" #n ")" ::: "memory")
; #define PG8_BAR __builtin_amdgcn_s_barrier()
; #define PG8_SCHED __builtin_amdgcn_sched_barrier(0)
; template <class Epi>
; DI void gemm_phase(LAS unsigned char* lds, const Gemm g, const StaticOrder S, const Epi E) {
;     ...
;             const bool last = (t == nt - 2);
;             const char* a1 = cA + (size_t)(t + 1) * kstep;
;             const char* a2 = last ? nA : cA + (size_t)(t + 2) * kstep; const char* b2 = last ? nB : cB + (size_t)(t + 2) * kstep;
;             const char* a3 = a2 + kstep; const char* b3 = b2 + kstep;
;             PG8_LDB(B0, 0, 0); PG8_SCHED; PG8_LDA(At, 0, 0); PG8_STAGE(PG8_SA(1, 1), a1 + hstep, voffA);
;             PG8_WAIT_L(8); PG8_BAR; PG8_WAIT_L(0); PG8_MMA(0, 0, At, B0); PG8_BAR; PG8_SCHED;
;             PG8_LDB(B1, 0, 1); PG8_STAGE(PG8_SB(0, 0), b2, voffB);
;             PG8_BAR; PG8_WAIT_L(0); PG8_MMA(0, 1, At, B1); PG8_BAR;
;             PG8_LDA(At, 0, 1); PG8_STAGE(PG8_SA(0, 0), a2, voffA);
;             PG8_BAR; PG8_WAIT_L(0); PG8_MMA(1, 0, At, B0); PG8_BAR; PG8_SCHED;
;             PG8_STAGE(PG8_SB(0, 1), b2 + hstep, voffB);
;             PG8_WAIT_V(6); PG8_BAR; PG8_MMA(1, 1, At, B1); PG8_BAR;
.LBB0_298:
	ds_read_b128 v[128:131], v168
	ds_read_b128 v[132:135], v168 offset:1024
	ds_read_b128 v[154:157], v168 offset:2048
	ds_read_b128 v[158:161], v168 offset:3072
	s_add_u32 s5, s8, 0xfffc0080
	s_addc_u32 s14, s9, -1
	s_cmp_eq_u32 s4, 12
	s_cselect_b32 s81, s6, s14
	s_cselect_b32 s80, s7, s5
	s_cselect_b32 s79, s21, vcc_hi
	s_cselect_b32 s78, s23, vcc_lo
	v_lshl_add_u64 v[162:163], s[8:9], 0, v[146:147]
	s_add_i32 m0, s58, 0xc000
	ds_read_b128 v[172:175], v169
	ds_read_b128 v[176:179], v169 offset:1024
	ds_read_b128 v[180:183], v169 offset:2048
	ds_read_b128 v[184:187], v169 offset:3072
	ds_read_b128 v[188:191], v169 offset:4096
	ds_read_b128 v[192:195], v169 offset:5120
	ds_read_b128 v[196:199], v169 offset:6144
	ds_read_b128 v[200:203], v169 offset:7168
	global_load_lds_dwordx4 v[162:163], off
	v_lshl_add_u64 v[162:163], s[8:9], 0, v[148:149]
	s_add_i32 m0, s58, 0xe000
	s_nop 0
	global_load_lds_dwordx4 v[162:163], off
	s_waitcnt lgkmcnt(8)
	s_setprio 1
	s_barrier
	s_waitcnt lgkmcnt(0)
	v_mfma_f32_16x16x32_bf16 v[124:127], v[128:131], v[172:175], v[124:127]
	v_mfma_f32_16x16x32_bf16 v[120:123], v[154:157], v[172:175], v[120:123]
	v_mfma_f32_16x16x32_bf16 v[112:115], v[128:131], v[180:183], v[112:115]
	v_mfma_f32_16x16x32_bf16 v[104:107], v[154:157], v[180:183], v[104:107]
	v_mfma_f32_16x16x32_bf16 v[96:99], v[128:131], v[188:191], v[96:99]
	v_mfma_f32_16x16x32_bf16 v[88:91], v[154:157], v[188:191], v[88:91]
	v_mfma_f32_16x16x32_bf16 v[80:83], v[128:131], v[196:199], v[80:83]
	v_mfma_f32_16x16x32_bf16 v[72:75], v[154:157], v[196:199], v[72:75]
	v_mfma_f32_16x16x32_bf16 v[124:127], v[132:135], v[176:179], v[124:127]
	v_mfma_f32_16x16x32_bf16 v[120:123], v[158:161], v[176:179], v[120:123]
	v_mfma_f32_16x16x32_bf16 v[112:115], v[132:135], v[184:187], v[112:115]
	v_mfma_f32_16x16x32_bf16 v[104:107], v[158:161], v[184:187], v[104:107]
	v_mfma_f32_16x16x32_bf16 v[96:99], v[132:135], v[192:195], v[96:99]
	v_mfma_f32_16x16x32_bf16 v[88:91], v[158:161], v[192:195], v[88:91]
	s_setprio 2
	s_barrier
	v_mfma_f32_16x16x32_bf16 v[80:83], v[132:135], v[200:203], v[80:83]
	v_mfma_f32_16x16x32_bf16 v[72:75], v[158:161], v[200:203], v[72:75]
	s_setprio 0
	s_add_i32 s5, s94, s19
	v_lshl_add_u64 v[162:163], s[78:79], 0, v[138:139]
	s_mov_b32 m0, s5
	ds_read_b128 v[204:207], v170
	ds_read_b128 v[208:211], v170 offset:1024
	ds_read_b128 v[212:215], v170 offset:2048
	ds_read_b128 v[216:219], v170 offset:3072
	global_load_lds_dwordx4 v[162:163], off
	v_lshl_add_u64 v[220:221], s[78:79], 0, v[142:143]
	s_add_i32 m0, s5, 0x2000
	s_nop 0
	global_load_lds_dwordx4 v[220:221], off
	s_setprio 1
	s_barrier
	s_waitcnt lgkmcnt(0)
	v_mfma_f32_16x16x32_bf16 v[116:119], v[204:207], v[172:175], v[116:119]
	v_mfma_f32_16x16x32_bf16 v[108:111], v[212:215], v[172:175], v[108:111]
	v_mfma_f32_16x16x32_bf16 v[100:103], v[204:207], v[180:183], v[100:103]
	v_mfma_f32_16x16x32_bf16 v[92:95], v[212:215], v[180:183], v[92:95]
	v_mfma_f32_16x16x32_bf16 v[84:87], v[204:207], v[188:191], v[84:87]
	v_mfma_f32_16x16x32_bf16 v[76:79], v[212:215], v[188:191], v[76:79]
	v_mfma_f32_16x16x32_bf16 v[68:71], v[204:207], v[196:199], v[68:71]
	v_mfma_f32_16x16x32_bf16 v[64:67], v[212:215], v[196:199], v[64:67]
	v_mfma_f32_16x16x32_bf16 v[116:119], v[208:211], v[176:179], v[116:119]
	v_mfma_f32_16x16x32_bf16 v[108:111], v[216:219], v[176:179], v[108:111]
	v_mfma_f32_16x16x32_bf16 v[100:103], v[208:211], v[184:187], v[100:103]
	v_mfma_f32_16x16x32_bf16 v[92:95], v[216:219], v[184:187], v[92:95]
	v_mfma_f32_16x16x32_bf16 v[84:87], v[208:211], v[192:195], v[84:87]
	v_mfma_f32_16x16x32_bf16 v[76:79], v[216:219], v[192:195], v[76:79]
	s_setprio 2
	s_barrier
	v_mfma_f32_16x16x32_bf16 v[68:71], v[208:211], v[200:203], v[68:71]
	v_mfma_f32_16x16x32_bf16 v[64:67], v[216:219], v[200:203], v[64:67]
	s_setprio 0
	s_mov_b32 m0, s58
	v_lshl_add_u64 v[224:225], s[80:81], 0, v[136:137]
	ds_read_b128 v[172:175], v169 offset:16384
	ds_read_b128 v[176:179], v169 offset:17408
	ds_read_b128 v[180:183], v169 offset:18432
	ds_read_b128 v[184:187], v169 offset:19456
	ds_read_b128 v[188:191], v169 offset:20480
	ds_read_b128 v[192:195], v169 offset:21504
	ds_read_b128 v[196:199], v169 offset:22528
	ds_read_b128 v[200:203], v169 offset:23552
	global_load_lds_dwordx4 v[224:225], off
	v_lshl_add_u64 v[226:227], s[80:81], 0, v[140:141]
	s_mov_b32 m0, s59
	s_nop 0
	global_load_lds_dwordx4 v[226:227], off
	s_setprio 1
	s_barrier
	s_waitcnt lgkmcnt(0)
	v_mfma_f32_16x16x32_bf16 v[60:63], v[128:131], v[172:175], v[60:63]
	v_mfma_f32_16x16x32_bf16 v[56:59], v[154:157], v[172:175], v[56:59]
	v_mfma_f32_16x16x32_bf16 v[48:51], v[128:131], v[180:183], v[48:51]
	v_mfma_f32_16x16x32_bf16 v[40:43], v[154:157], v[180:183], v[40:43]
	v_mfma_f32_16x16x32_bf16 v[32:35], v[128:131], v[188:191], v[32:35]
	v_mfma_f32_16x16x32_bf16 v[24:27], v[154:157], v[188:191], v[24:27]
	v_mfma_f32_16x16x32_bf16 v[16:19], v[128:131], v[196:199], v[16:19]
	v_mfma_f32_16x16x32_bf16 v[8:11], v[154:157], v[196:199], v[8:11]
	v_mfma_f32_16x16x32_bf16 v[60:63], v[132:135], v[176:179], v[60:63]
	v_mfma_f32_16x16x32_bf16 v[56:59], v[158:161], v[176:179], v[56:59]
	v_mfma_f32_16x16x32_bf16 v[48:51], v[132:135], v[184:187], v[48:51]
	v_mfma_f32_16x16x32_bf16 v[40:43], v[158:161], v[184:187], v[40:43]
	v_mfma_f32_16x16x32_bf16 v[32:35], v[132:135], v[192:195], v[32:35]
	v_mfma_f32_16x16x32_bf16 v[24:27], v[158:161], v[192:195], v[24:27]
	s_setprio 2
	s_barrier
; #define PG8_STAGE(bufoff, gbase, voff) do { _Pragma("unroll") for (int _i = 0; _i < 2; ++_i) \
;         __builtin_amdgcn_global_load_lds((const unsigned*)((const char*)(gbase) + (voff)[_i]), (LAS unsigned*)(lds + (bufoff) + ldsw + _i * 8192), 16, 0, 0); } while (0)
; #define PG8_LDA(dst, b, h) do { _Pragma("unroll") for (int m = 0; m < 4; ++m) _Pragma("unroll") for (int k = 0; k < 2; ++k) dst[m][k] = *(const LAS bf16x8*)(lds + PG8_SA(b, h) + aoff + m * 2048 + k * 1024); } while (0)
; #define PG8_LDB(dst, b, h) do { _Pragma("unroll") for (int n = 0; n < 2; ++n) _Pragma("unroll") for (int k = 0; k < 2; ++k) dst[n][k] = *(const LAS bf16x8*)(lds + PG8_SB(b, h) + boff + n * 2048 + k * 1024); } while (0)
; #define PG8_MMA(ai, bj, At, Bt) do { __builtin_amdgcn_s_setprio(1); _Pragma("unroll") for (int m = 0; m < 4; ++m) _Pragma("unroll") for (int n = 0; n < 2; ++n) _Pragma("unroll") for (int k = 0; k < 2; ++k) \
;         acc[ai][bj][m][n] = __builtin_amdgcn_mfma_f32_16x16x32_bf16(Bt[n][k], At[m][k], acc[ai][bj][m][n], 0, 0, 0); __builtin_amdgcn_s_setprio(0); } while (0)
; #define PG8_WAIT_V(n) asm volatile("s_waitcnt vmcnt(" #n ")" ::: "memory")
; #define PG8_WAIT_L(n) asm volatile("s_waitcnt lgkmcnt(" #n ")" ::: "memory")
; #define PG8_BAR __builtin_amdgcn_s_barrier()
; #define PG8_SCHED __builtin_amdgcn_sched_barrier(0)
; #define PG8_STAGE(bufoff, gbase, voff) do { _Pragma("unroll") for (int _i = 0; _i < 2; ++_i) \
;         __builtin_amdgcn_global_load_lds((const unsigned*)((const char*)(gbase) + (voff)[_i]), (LAS unsigned*)(lds + (bufoff) + ldsw + _i * 8192), 16, 0, 0); } while (0)
; #define PG8_WAIT_V(n) asm volatile("s_waitcnt vmcnt(" #n ")" ::: "memory")
; template <class Epi>
; DI void gemm_phase(LAS unsigned char* lds, const Gemm g, const StaticOrder S, const Epi E) {
;     ...
;             PG8_BAR; PG8_WAIT_L(0); PG8_MMA(1, 0, At, B0); PG8_BAR; PG8_SCHED;
;             PG8_STAGE(PG8_SB(0, 1), b2 + hstep, voffB);
;             PG8_WAIT_V(6); PG8_BAR; PG8_MMA(1, 1, At, B1); PG8_BAR;
;             PG8_LDB(B0, 1, 0); PG8_SCHED; PG8_LDA(At, 1, 0); PG8_STAGE(PG8_SA(0, 1), a2 + hstep, voffA);
;             PG8_WAIT_L(8); PG8_BAR; PG8_WAIT_L(0); PG8_MMA(0, 0, At, B0); PG8_BAR; PG8_SCHED;
;             PG8_LDB(B1, 1, 1); PG8_STAGE(PG8_SB(1, 0), b3, voffB);
;             PG8_BAR; PG8_WAIT_L(0); PG8_MMA(0, 1, At, B1); PG8_BAR;
	v_mfma_f32_16x16x32_bf16 v[16:19], v[132:135], v[200:203], v[16:19]
	v_mfma_f32_16x16x32_bf16 v[8:11], v[158:161], v[200:203], v[8:11]
	s_setprio 0
	s_add_u32 s14, s78, 0x40000
	s_addc_u32 s15, s79, 0
	s_add_i32 s5, s95, s19
	v_lshl_add_u64 v[128:129], s[14:15], 0, v[138:139]
	s_mov_b32 m0, s5
	s_nop 0
	global_load_lds_dwordx4 v[128:129], off
	v_lshl_add_u64 v[128:129], s[14:15], 0, v[142:143]
	s_add_i32 m0, s5, 0x2000
	s_nop 0
	global_load_lds_dwordx4 v[128:129], off
	s_waitcnt vmcnt(6)
	s_setprio 1
	s_barrier
	v_mfma_f32_16x16x32_bf16 v[52:55], v[204:207], v[172:175], v[52:55]
	v_mfma_f32_16x16x32_bf16 v[44:47], v[212:215], v[172:175], v[44:47]
	v_mfma_f32_16x16x32_bf16 v[36:39], v[204:207], v[180:183], v[36:39]
	v_mfma_f32_16x16x32_bf16 v[28:31], v[212:215], v[180:183], v[28:31]
	v_mfma_f32_16x16x32_bf16 v[20:23], v[204:207], v[188:191], v[20:23]
	v_mfma_f32_16x16x32_bf16 v[12:15], v[212:215], v[188:191], v[12:15]
	v_mfma_f32_16x16x32_bf16 v[4:7], v[204:207], v[196:199], v[4:7]
	v_mfma_f32_16x16x32_bf16 v[0:3], v[212:215], v[196:199], v[0:3]
	v_mfma_f32_16x16x32_bf16 v[52:55], v[208:211], v[176:179], v[52:55]
	v_mfma_f32_16x16x32_bf16 v[44:47], v[216:219], v[176:179], v[44:47]
	v_mfma_f32_16x16x32_bf16 v[36:39], v[208:211], v[184:187], v[36:39]
	v_mfma_f32_16x16x32_bf16 v[28:31], v[216:219], v[184:187], v[28:31]
	v_mfma_f32_16x16x32_bf16 v[20:23], v[208:211], v[192:195], v[20:23]
	v_mfma_f32_16x16x32_bf16 v[12:15], v[216:219], v[192:195], v[12:15]
	s_setprio 2
	s_barrier
	v_mfma_f32_16x16x32_bf16 v[4:7], v[208:211], v[200:203], v[4:7]
	v_mfma_f32_16x16x32_bf16 v[0:3], v[216:219], v[200:203], v[0:3]
	s_setprio 0
	s_add_i32 s5, 0, 0x18000
	v_add_u32_e32 v158, s5, v165
	ds_read_b128 v[128:131], v158
	ds_read_b128 v[132:135], v158 offset:1024
	ds_read_b128 v[154:157], v158 offset:2048
	ds_read_b128 v[158:161], v158 offset:3072
	s_add_u32 s14, s80, 0x40000
	s_addc_u32 s15, s81, 0
	s_mov_b32 m0, s77
	v_lshl_add_u64 v[204:205], s[14:15], 0, v[136:137]
	ds_read_b128 v[172:175], v169 offset:32768
	ds_read_b128 v[176:179], v169 offset:33792
	ds_read_b128 v[180:183], v169 offset:34816
	ds_read_b128 v[184:187], v169 offset:35840
	ds_read_b128 v[188:191], v169 offset:36864
	ds_read_b128 v[192:195], v169 offset:37888
	ds_read_b128 v[196:199], v169 offset:38912
	ds_read_b128 v[200:203], v169 offset:39936
	global_load_lds_dwordx4 v[204:205], off
	v_lshl_add_u64 v[204:205], s[14:15], 0, v[140:141]
	s_mov_b32 m0, s82
	s_nop 0
	global_load_lds_dwordx4 v[204:205], off
	s_waitcnt lgkmcnt(8)
	s_setprio 1
	s_barrier
	s_waitcnt lgkmcnt(0)
	v_mfma_f32_16x16x32_bf16 v[124:127], v[128:131], v[172:175], v[124:127]
	v_mfma_f32_16x16x32_bf16 v[120:123], v[154:157], v[172:175], v[120:123]
	v_mfma_f32_16x16x32_bf16 v[112:115], v[128:131], v[180:183], v[112:115]
	v_mfma_f32_16x16x32_bf16 v[104:107], v[154:157], v[180:183], v[104:107]
	v_mfma_f32_16x16x32_bf16 v[96:99], v[128:131], v[188:191], v[96:99]
	v_mfma_f32_16x16x32_bf16 v[88:91], v[154:157], v[188:191], v[88:91]
	v_mfma_f32_16x16x32_bf16 v[80:83], v[128:131], v[196:199], v[80:83]
	v_mfma_f32_16x16x32_bf16 v[72:75], v[154:157], v[196:199], v[72:75]
	v_mfma_f32_16x16x32_bf16 v[124:127], v[132:135], v[176:179], v[124:127]
	v_mfma_f32_16x16x32_bf16 v[120:123], v[158:161], v[176:179], v[120:123]
	v_mfma_f32_16x16x32_bf16 v[112:115], v[132:135], v[184:187], v[112:115]
	v_mfma_f32_16x16x32_bf16 v[104:107], v[158:161], v[184:187], v[104:107]
	v_mfma_f32_16x16x32_bf16 v[96:99], v[132:135], v[192:195], v[96:99]
	v_mfma_f32_16x16x32_bf16 v[88:91], v[158:161], v[192:195], v[88:91]
	s_setprio 2
	s_barrier
	v_mfma_f32_16x16x32_bf16 v[80:83], v[132:135], v[200:203], v[80:83]
	v_mfma_f32_16x16x32_bf16 v[72:75], v[158:161], v[200:203], v[72:75]
	s_setprio 0
	s_add_i32 s35, 0, 0x1c000
	s_add_i32 s5, s5, s19
	v_add_u32_e32 v171, s35, v165
	v_lshl_add_u64 v[162:163], v[162:163], 0, s[10:11]
	s_mov_b32 m0, s5
	ds_read_b128 v[204:207], v171
	ds_read_b128 v[208:211], v171 offset:1024
	ds_read_b128 v[212:215], v171 offset:2048
	ds_read_b128 v[216:219], v171 offset:3072
	global_load_lds_dwordx4 v[162:163], off
	v_lshl_add_u64 v[162:163], v[220:221], 0, s[10:11]
	s_add_i32 m0, s5, 0x2000
	s_nop 0
	global_load_lds_dwordx4 v[162:163], off
	s_setprio 1
	s_barrier
	s_waitcnt lgkmcnt(0)
	v_mfma_f32_16x16x32_bf16 v[116:119], v[204:207], v[172:175], v[116:119]
	v_mfma_f32_16x16x32_bf16 v[108:111], v[212:215], v[172:175], v[108:111]
	v_mfma_f32_16x16x32_bf16 v[100:103], v[204:207], v[180:183], v[100:103]
	v_mfma_f32_16x16x32_bf16 v[92:95], v[212:215], v[180:183], v[92:95]
	v_mfma_f32_16x16x32_bf16 v[84:87], v[204:207], v[188:191], v[84:87]
	v_mfma_f32_16x16x32_bf16 v[76:79], v[212:215], v[188:191], v[76:79]
	v_mfma_f32_16x16x32_bf16 v[68:71], v[204:207], v[196:199], v[68:71]
	v_mfma_f32_16x16x32_bf16 v[64:67], v[212:215], v[196:199], v[64:67]
	v_mfma_f32_16x16x32_bf16 v[116:119], v[208:211], v[176:179], v[116:119]
	v_mfma_f32_16x16x32_bf16 v[108:111], v[216:219], v[176:179], v[108:111]
	v_mfma_f32_16x16x32_bf16 v[100:103], v[208:211], v[184:187], v[100:103]
	v_mfma_f32_16x16x32_bf16 v[92:95], v[216:219], v[184:187], v[92:95]
	v_mfma_f32_16x16x32_bf16 v[84:87], v[208:211], v[192:195], v[84:87]
	v_mfma_f32_16x16x32_bf16 v[76:79], v[216:219], v[192:195], v[76:79]
	s_setprio 2
	s_barrier
; #define PG8_STAGE(bufoff, gbase, voff) do { _Pragma("unroll") for (int _i = 0; _i < 2; ++_i) \
;         __builtin_amdgcn_global_load_lds((const unsigned*)((const char*)(gbase) + (voff)[_i]), (LAS unsigned*)(lds + (bufoff) + ldsw + _i * 8192), 16, 0, 0); } while (0)
; #define PG8_LDA(dst, b, h) do { _Pragma("unroll") for (int m = 0; m < 4; ++m) _Pragma("unroll") for (int k = 0; k < 2; ++k) dst[m][k] = *(const LAS bf16x8*)(lds + PG8_SA(b, h) + aoff + m * 2048 + k * 1024); } while (0)
; #define PG8_MMA(ai, bj, At, Bt) do { __builtin_amdgcn_s_setprio(1); _Pragma("unroll") for (int m = 0; m < 4; ++m) _Pragma("unroll") for (int n = 0; n < 2; ++n) _Pragma("unroll") for (int k = 0; k < 2; ++k) \
;         acc[ai][bj][m][n] = __builtin_amdgcn_mfma_f32_16x16x32_bf16(Bt[n][k], At[m][k], acc[ai][bj][m][n], 0, 0, 0); __builtin_amdgcn_s_setprio(0); } while (0)
; #define PG8_WAIT_V(n) asm volatile("s_waitcnt vmcnt(" #n ")" ::: "memory")
; #define PG8_WAIT_L(n) asm volatile("s_waitcnt lgkmcnt(" #n ")" ::: "memory")
; #define PG8_BAR __builtin_amdgcn_s_barrier()
; #define PG8_SCHED __builtin_amdgcn_sched_barrier(0)
; #define PG8_LDA(dst, b, h) do { _Pragma("unroll") for (int m = 0; m < 4; ++m) _Pragma("unroll") for (int k = 0; k < 2; ++k) dst[m][k] = *(const LAS bf16x8*)(lds + PG8_SA(b, h) + aoff + m * 2048 + k * 1024); } while (0)
; template <class Epi>
; DI void gemm_phase(LAS unsigned char* lds, const Gemm g, const StaticOrder S, const Epi E) {
;     ...
;             PG8_BAR; PG8_WAIT_L(0); PG8_MMA(0, 1, At, B1); PG8_BAR;
;             PG8_LDA(At, 1, 1); PG8_STAGE(PG8_SA(1, 0), a3, voffA);
;             PG8_BAR; PG8_WAIT_L(0); PG8_MMA(1, 0, At, B0); PG8_BAR; PG8_SCHED;
;             PG8_STAGE(PG8_SB(1, 1), b3 + hstep, voffB);
;             PG8_WAIT_V(6); PG8_BAR; PG8_MMA(1, 1, At, B1); PG8_BAR;
;     DI void operator()(AccRef acc, const Unit& u, int wr, int wc, int fr, int fq) const {
;         f32x4 ts[2][2];
; #pragma unroll
;         for (int bj = 0; bj < 2; ++bj) { const int tok = u.pn * 256 + bj * 128 + wc * 32 + 8 * fq; ts[bj][0] = *(const f32x4*)(ss + tok); ts[bj][1] = *(const f32x4*)(ss + tok + 4); }
; #pragma unroll
;         for (int bj = 0; bj < 2; ++bj)
; #pragma unroll
;             for (int n = 0; n < 2; ++n)
; #pragma unroll
;                 for (int e = 0; e < 4; ++e) ts[bj][n][e] = rsqrtf(ts[bj][n][e] * (1.0f / 1024.0f) + 1e-6f);
	v_mfma_f32_16x16x32_bf16 v[68:71], v[208:211], v[200:203], v[68:71]
	v_mfma_f32_16x16x32_bf16 v[64:67], v[216:219], v[200:203], v[64:67]
	s_setprio 0
	s_mov_b32 m0, s86
	v_lshl_add_u64 v[162:163], v[224:225], 0, s[10:11]
	ds_read_b128 v[172:175], v169 offset:49152
	ds_read_b128 v[176:179], v169 offset:50176
	ds_read_b128 v[180:183], v169 offset:51200
	ds_read_b128 v[184:187], v169 offset:52224
	ds_read_b128 v[188:191], v169 offset:53248
	ds_read_b128 v[192:195], v169 offset:54272
	ds_read_b128 v[196:199], v169 offset:55296
	ds_read_b128 v[200:203], v169 offset:56320
	global_load_lds_dwordx4 v[162:163], off
	v_lshl_add_u64 v[162:163], v[226:227], 0, s[10:11]
	s_mov_b32 m0, s87
	s_nop 0
	global_load_lds_dwordx4 v[162:163], off
	s_setprio 1
	s_barrier
	s_waitcnt lgkmcnt(0)
	v_mfma_f32_16x16x32_bf16 v[60:63], v[128:131], v[172:175], v[60:63]
	v_mfma_f32_16x16x32_bf16 v[56:59], v[154:157], v[172:175], v[56:59]
	v_mfma_f32_16x16x32_bf16 v[48:51], v[128:131], v[180:183], v[48:51]
	v_mfma_f32_16x16x32_bf16 v[40:43], v[154:157], v[180:183], v[40:43]
	v_mfma_f32_16x16x32_bf16 v[32:35], v[128:131], v[188:191], v[32:35]
	v_mfma_f32_16x16x32_bf16 v[24:27], v[154:157], v[188:191], v[24:27]
	v_mfma_f32_16x16x32_bf16 v[16:19], v[128:131], v[196:199], v[16:19]
	v_mfma_f32_16x16x32_bf16 v[8:11], v[154:157], v[196:199], v[8:11]
	v_mfma_f32_16x16x32_bf16 v[60:63], v[132:135], v[176:179], v[60:63]
	v_mfma_f32_16x16x32_bf16 v[56:59], v[158:161], v[176:179], v[56:59]
	v_mfma_f32_16x16x32_bf16 v[48:51], v[132:135], v[184:187], v[48:51]
	v_mfma_f32_16x16x32_bf16 v[40:43], v[158:161], v[184:187], v[40:43]
	v_mfma_f32_16x16x32_bf16 v[32:35], v[132:135], v[192:195], v[32:35]
	v_mfma_f32_16x16x32_bf16 v[24:27], v[158:161], v[192:195], v[24:27]
	s_setprio 2
	s_barrier
	v_mfma_f32_16x16x32_bf16 v[16:19], v[132:135], v[200:203], v[16:19]
	v_mfma_f32_16x16x32_bf16 v[8:11], v[158:161], v[200:203], v[8:11]
	s_setprio 0
	s_add_u32 s14, s78, 0x40080
	s_addc_u32 s15, s79, 0
	s_add_i32 s5, s35, s19
	v_lshl_add_u64 v[128:129], s[14:15], 0, v[138:139]
	s_mov_b32 m0, s5
	s_nop 0
	global_load_lds_dwordx4 v[128:129], off
	v_lshl_add_u64 v[128:129], s[14:15], 0, v[142:143]
	s_add_i32 m0, s5, 0x2000
	s_nop 0
	global_load_lds_dwordx4 v[128:129], off
	s_waitcnt vmcnt(6)
	s_setprio 1
	s_barrier
	v_mfma_f32_16x16x32_bf16 v[52:55], v[204:207], v[172:175], v[52:55]
	v_mfma_f32_16x16x32_bf16 v[44:47], v[212:215], v[172:175], v[44:47]
	v_mfma_f32_16x16x32_bf16 v[36:39], v[204:207], v[180:183], v[36:39]
	v_mfma_f32_16x16x32_bf16 v[28:31], v[212:215], v[180:183], v[28:31]
	v_mfma_f32_16x16x32_bf16 v[20:23], v[204:207], v[188:191], v[20:23]
	v_mfma_f32_16x16x32_bf16 v[12:15], v[212:215], v[188:191], v[12:15]
	v_mfma_f32_16x16x32_bf16 v[4:7], v[204:207], v[196:199], v[4:7]
	v_mfma_f32_16x16x32_bf16 v[0:3], v[212:215], v[196:199], v[0:3]
	v_mfma_f32_16x16x32_bf16 v[52:55], v[208:211], v[176:179], v[52:55]
	v_mfma_f32_16x16x32_bf16 v[44:47], v[216:219], v[176:179], v[44:47]
	v_mfma_f32_16x16x32_bf16 v[36:39], v[208:211], v[184:187], v[36:39]
	v_mfma_f32_16x16x32_bf16 v[28:31], v[216:219], v[184:187], v[28:31]
	v_mfma_f32_16x16x32_bf16 v[20:23], v[208:211], v[192:195], v[20:23]
	v_mfma_f32_16x16x32_bf16 v[12:15], v[216:219], v[192:195], v[12:15]
	s_setprio 2
	s_barrier
	v_mfma_f32_16x16x32_bf16 v[4:7], v[208:211], v[200:203], v[4:7]
	v_mfma_f32_16x16x32_bf16 v[0:3], v[216:219], v[200:203], v[0:3]
	s_setprio 0
	s_add_i32 s4, s4, 2
	s_add_u32 s8, s8, 0x100
	s_addc_u32 s9, s9, 0
	s_add_u32 vcc_lo, vcc_lo, 0x100
	s_addc_u32 vcc_hi, vcc_hi, 0
	s_cmp_gt_u32 s4, 13
	s_cbranch_scc0 .LBB0_298
	s_lshl_b32 s4, s97, 8
	v_or_b32_e32 v128, s4, v166
	v_ashrrev_i32_e32 v129, 31, v128
	v_lshl_add_u64 v[132:133], v[128:129], 2, s[60:61]
	global_load_dwordx4 v[158:161], v[132:133], off offset:16
	global_load_dwordx4 v[154:157], v[132:133], off
	global_load_dwordx4 v[128:131], v[132:133], off offset:528
	s_nop 0
	global_load_dwordx4 v[132:135], v[132:133], off offset:512
	s_mov_b32 s6, 0x358637bd
	v_mov_b64_e32 v[162:163], s[6:7]
	s_lshl_b32 s6, s76, 8
	s_add_i32 s6, s6, s84
	s_lshr_b32 s5, s97, 3
	s_and_b32 s7, s5, 0x1fffc
	s_bfe_u32 s5, s6, 0x20008
	s_or_b32 s4, s4, s85
	s_or_b32 s5, s5, s7
	s_cmpk_lt_u32 s6, 0x400
	s_mov_b32 s97, s20
	s_mov_b32 s76, s22
	s_mov_b64 s[78:79], s[28:29]
	s_waitcnt vmcnt(0)
; DI unsigned pk_bf16(float lo, float hi) { f32x2 v = {lo, hi}; return __builtin_bit_cast(unsigned, __builtin_convertvector(v, bf16v2)); }
;     DI void operator()(AccRef acc, const Unit& u, int wr, int wc, int fr, int fq) const {
;         f32x4 ts[2][2];
; #pragma unroll
;         for (int bj = 0; bj < 2; ++bj) { const int tok = u.pn * 256 + bj * 128 + wc * 32 + 8 * fq; ts[bj][0] = *(const f32x4*)(ss + tok); ts[bj][1] = *(const f32x4*)(ss + tok + 4); }
; #pragma unroll
;         for (int bj = 0; bj < 2; ++bj)
; #pragma unroll
;             for (int n = 0; n < 2; ++n)
; #pragma unroll
;                 for (int e = 0; e < 4; ++e) ts[bj][n][e] = rsqrtf(ts[bj][n][e] * (1.0f / 1024.0f) + 1e-6f);
; #pragma unroll
;         for (int ai = 0; ai < 2; ++ai)
; #pragma unroll
;             for (int m = 0; m < 4; ++m) {
;                 const int R = u.pm * 256 + ai * 128 + wr * 64 + m * 16 + fr, X = R >> 10, hv = R & 1023;
; #pragma unroll
;                 for (int bj = 0; bj < 2; ++bj) {
;                     const int tok = u.pn * 256 + bj * 128 + wc * 32 + 8 * fq, b = tok >> 13, s = tok & (SEQ - 1);
;                     bf16_t* dst = (X ? vtB : vtA) + ((size_t)(((b * 4 + (hv >> 8)) * 128 + (s >> 6)) * 256 + (hv & 255))) * 64 + (s & 63);
;                     const f32x4 v0 = acc[ai][bj][m][0] * ts[bj][0], v1 = acc[ai][bj][m][1] * ts[bj][1];
;                     u32x4 w; w.x = pk_bf16(v0[0], v0[1]); w.y = pk_bf16(v0[2], v0[3]); w.z = pk_bf16(v1[0], v1[1]); w.w = pk_bf16(v1[2], v1[3]);
;                     *(u32x4*)dst = w;
	v_pk_fma_f32 v[158:159], v[158:159], s[16:17], v[162:163] op_sel_hi:[1,0,0]
	v_pk_fma_f32 v[154:155], v[154:155], s[16:17], v[162:163] op_sel_hi:[1,0,0]
	v_pk_fma_f32 v[156:157], v[156:157], s[16:17], v[162:163] op_sel_hi:[1,0,0]
	v_mul_f32_e32 v171, 0x4b800000, v154
	v_cmp_gt_f32_e64 s[8:9], s96, v154
	v_cmp_gt_f32_e32 vcc, s96, v155
	v_pk_fma_f32 v[160:161], v[160:161], s[16:17], v[162:163] op_sel_hi:[1,0,0]
	v_cndmask_b32_e64 v154, v154, v171, s[8:9]
	v_mul_f32_e32 v171, 0x4b800000, v155
	v_cndmask_b32_e32 v155, v155, v171, vcc
	v_rsq_f32_e32 v154, v154
	v_rsq_f32_e32 v155, v155
	v_mul_f32_e32 v171, 0x4b800000, v156
	v_pk_fma_f32 v[132:133], v[132:133], s[16:17], v[162:163] op_sel_hi:[1,0,0]
	v_pk_fma_f32 v[134:135], v[134:135], s[16:17], v[162:163] op_sel_hi:[1,0,0]
	v_pk_mul_f32 v[172:173], v[154:155], s[18:19] op_sel_hi:[1,0]
	v_pk_fma_f32 v[128:129], v[128:129], s[16:17], v[162:163] op_sel_hi:[1,0,0]
	v_cndmask_b32_e64 v154, v154, v172, s[8:9]
	v_cmp_gt_f32_e64 s[8:9], s96, v156
	v_cndmask_b32_e32 v155, v155, v173, vcc
	v_cmp_gt_f32_e32 vcc, s96, v157
	v_cndmask_b32_e64 v156, v156, v171, s[8:9]
	v_mul_f32_e32 v171, 0x4b800000, v157
	v_cndmask_b32_e32 v157, v157, v171, vcc
	v_rsq_f32_e32 v156, v156
	v_rsq_f32_e32 v157, v157
	v_mul_f32_e32 v171, 0x4b800000, v158
	v_pk_fma_f32 v[130:131], v[130:131], s[16:17], v[162:163] op_sel_hi:[1,0,0]
	v_pk_mul_f32 v[124:125], v[124:125], v[154:155]
	v_pk_mul_f32 v[172:173], v[156:157], s[18:19] op_sel_hi:[1,0]
	v_mul_f32_e32 v162, 0x4b800000, v130
	v_cndmask_b32_e64 v156, v156, v172, s[8:9]
	v_cmp_gt_f32_e64 s[8:9], s96, v158
	v_cndmask_b32_e32 v157, v157, v173, vcc
	v_cmp_gt_f32_e32 vcc, s96, v159
	v_cndmask_b32_e64 v158, v158, v171, s[8:9]
	v_mul_f32_e32 v171, 0x4b800000, v159
	v_cndmask_b32_e32 v159, v159, v171, vcc
	v_rsq_f32_e32 v158, v158
	v_rsq_f32_e32 v159, v159
	v_mul_f32_e32 v171, 0x4b800000, v160
	v_pk_mul_f32 v[126:127], v[126:127], v[156:157]
	v_pk_mul_f32 v[112:113], v[112:113], v[154:155]
	v_pk_mul_f32 v[172:173], v[158:159], s[18:19] op_sel_hi:[1,0]
	v_pk_mul_f32 v[96:97], v[96:97], v[154:155]
	v_cndmask_b32_e64 v158, v158, v172, s[8:9]
	v_cmp_gt_f32_e64 s[8:9], s96, v160
	v_cndmask_b32_e32 v159, v159, v173, vcc
	v_cmp_gt_f32_e32 vcc, s96, v161
	v_cndmask_b32_e64 v160, v160, v171, s[8:9]
	v_mul_f32_e32 v171, 0x4b800000, v161
	v_cndmask_b32_e32 v161, v161, v171, vcc
	v_rsq_f32_e32 v160, v160
	v_rsq_f32_e32 v161, v161
	v_mul_f32_e32 v171, 0x4b800000, v132
	v_pk_mul_f32 v[80:81], v[80:81], v[154:155]
	v_pk_mul_f32 v[62:63], v[62:63], v[156:157]
	v_pk_mul_f32 v[172:173], v[160:161], s[18:19] op_sel_hi:[1,0]
	v_pk_mul_f32 v[60:61], v[60:61], v[154:155]
	v_cndmask_b32_e64 v160, v160, v172, s[8:9]
	v_cmp_gt_f32_e64 s[8:9], s96, v132
	v_cndmask_b32_e32 v161, v161, v173, vcc
	v_cmp_gt_f32_e32 vcc, s96, v133
	v_cndmask_b32_e64 v132, v132, v171, s[8:9]
	v_mul_f32_e32 v171, 0x4b800000, v133
	v_cndmask_b32_e32 v133, v133, v171, vcc
	v_rsq_f32_e32 v132, v132
	v_rsq_f32_e32 v133, v133
	v_mul_f32_e32 v171, 0x4b800000, v134
	v_pk_mul_f32 v[48:49], v[48:49], v[154:155]
	v_pk_mul_f32 v[32:33], v[32:33], v[154:155]
	v_pk_mul_f32 v[172:173], v[132:133], s[18:19] op_sel_hi:[1,0]
	v_pk_mul_f32 v[16:17], v[16:17], v[154:155]
	v_cndmask_b32_e64 v132, v132, v172, s[8:9]
	v_cmp_gt_f32_e64 s[8:9], s96, v134
	v_cndmask_b32_e32 v133, v133, v173, vcc
	v_cmp_gt_f32_e32 vcc, s96, v135
	v_cndmask_b32_e64 v134, v134, v171, s[8:9]
	v_mul_f32_e32 v171, 0x4b800000, v135
	v_cndmask_b32_e32 v135, v135, v171, vcc
	v_rsq_f32_e32 v134, v134
	v_rsq_f32_e32 v135, v135
	v_mul_f32_e32 v171, 0x4b800000, v128
	v_pk_mul_f32 v[116:117], v[116:117], v[132:133]
	v_pk_mul_f32 v[100:101], v[100:101], v[132:133]
	v_pk_mul_f32 v[172:173], v[134:135], s[18:19] op_sel_hi:[1,0]
	v_pk_mul_f32 v[84:85], v[84:85], v[132:133]
	v_cndmask_b32_e64 v134, v134, v172, s[8:9]
	v_cmp_gt_f32_e64 s[8:9], s96, v128
	v_cndmask_b32_e32 v135, v135, v173, vcc
	v_cmp_gt_f32_e32 vcc, s96, v129
	v_cndmask_b32_e64 v128, v128, v171, s[8:9]
	v_mul_f32_e32 v171, 0x4b800000, v129
	v_cndmask_b32_e32 v129, v129, v171, vcc
	v_rsq_f32_e32 v128, v128
	v_rsq_f32_e32 v129, v129
	v_lshl_or_b32 v171, s5, 15, v167
	v_pk_mul_f32 v[118:119], v[118:119], v[134:135]
	v_pk_mul_f32 v[102:103], v[102:103], v[134:135]
	v_pk_mul_f32 v[172:173], v[128:129], s[18:19] op_sel_hi:[1,0]
	v_pk_mul_f32 v[86:87], v[86:87], v[134:135]
	v_cndmask_b32_e64 v128, v128, v172, s[8:9]
	v_cmp_gt_f32_e64 s[8:9], s96, v130
	v_cndmask_b32_e32 v129, v129, v173, vcc
	v_cmp_gt_f32_e32 vcc, s96, v131
	v_cndmask_b32_e64 v130, v130, v162, s[8:9]
	v_mul_f32_e32 v162, 0x4b800000, v131
	v_cndmask_b32_e32 v131, v131, v162, vcc
	v_rsq_f32_e32 v130, v130
	v_rsq_f32_e32 v131, v131
	v_pk_mul_f32 v[172:173], v[122:123], v[160:161]
	v_pk_mul_f32 v[122:123], v[120:121], v[158:159]
	v_cvt_pk_bf16_f32 v120, v124, v125
	v_pk_mul_f32 v[162:163], v[130:131], s[18:19] op_sel_hi:[1,0]
	v_cvt_pk_bf16_f32 v121, v126, v127
	v_cndmask_b32_e64 v130, v130, v162, s[8:9]
	s_cselect_b32 s9, s53, s91
	s_cselect_b32 s8, s52, s90
	s_lshl_b32 s4, s4, 2
	s_and_b32 s4, s4, 0x7d00
	v_or_b32_e32 v162, s4, v171
	v_cndmask_b32_e32 v131, v131, v163, vcc
	v_ashrrev_i32_e32 v163, 31, v162
	v_lshlrev_b64 v[162:163], 7, v[162:163]
	v_lshl_add_u64 v[162:163], s[8:9], 0, v[162:163]
	v_lshl_add_u64 v[162:163], v[162:163], 0, v[144:145]
	v_cvt_pk_bf16_f32 v122, v122, v123
	v_cvt_pk_bf16_f32 v123, v172, v173
	s_or_b32 s5, s4, 0x200
	global_store_dwordx4 v[162:163], v[120:123], off
	s_addk_i32 s6, 0x80
	v_pk_mul_f32 v[70:71], v[70:71], v[134:135]
	v_or_b32_e32 v120, s5, v171
	v_ashrrev_i32_e32 v121, 31, v120
	v_lshlrev_b64 v[120:121], 7, v[120:121]
; DI unsigned pk_bf16(float lo, float hi) { f32x2 v = {lo, hi}; return __builtin_bit_cast(unsigned, __builtin_convertvector(v, bf16v2)); }
;     DI void operator()(AccRef acc, const Unit& u, int wr, int wc, int fr, int fq) const {
;     ...
;                 const int R = u.pm * 256 + ai * 128 + wr * 64 + m * 16 + fr, X = R >> 10, hv = R & 1023;
; #pragma unroll
;                 for (int bj = 0; bj < 2; ++bj) {
;                     const int tok = u.pn * 256 + bj * 128 + wc * 32 + 8 * fq, b = tok >> 13, s = tok & (SEQ - 1);
;                     bf16_t* dst = (X ? vtB : vtA) + ((size_t)(((b * 4 + (hv >> 8)) * 128 + (s >> 6)) * 256 + (hv & 255))) * 64 + (s & 63);
;                     const f32x4 v0 = acc[ai][bj][m][0] * ts[bj][0], v1 = acc[ai][bj][m][1] * ts[bj][1];
;                     u32x4 w; w.x = pk_bf16(v0[0], v0[1]); w.y = pk_bf16(v0[2], v0[3]); w.z = pk_bf16(v1[0], v1[1]); w.w = pk_bf16(v1[2], v1[3]);
;                     *(u32x4*)dst = w;
	v_lshl_add_u64 v[120:121], s[8:9], 0, v[120:121]
	v_pk_mul_f32 v[122:123], v[110:111], v[130:131]
	v_pk_mul_f32 v[110:111], v[108:109], v[128:129]
	v_lshl_add_u64 v[120:121], v[120:121], 0, v[144:145]
	v_cvt_pk_bf16_f32 v108, v116, v117
	v_cvt_pk_bf16_f32 v109, v118, v119
	v_cvt_pk_bf16_f32 v110, v110, v111
	v_cvt_pk_bf16_f32 v111, v122, v123
	v_or_b32_e32 v116, 16, v171
	global_store_dwordx4 v[120:121], v[108:111], off
	v_pk_mul_f32 v[68:69], v[68:69], v[132:133]
	v_pk_mul_f32 v[54:55], v[54:55], v[134:135]
	v_or_b32_e32 v108, s4, v116
	v_ashrrev_i32_e32 v109, 31, v108
	v_lshlrev_b64 v[108:109], 7, v[108:109]
	v_lshl_add_u64 v[108:109], s[8:9], 0, v[108:109]
	v_pk_mul_f32 v[110:111], v[114:115], v[156:157]
	v_pk_mul_f32 v[114:115], v[106:107], v[160:161]
	v_pk_mul_f32 v[106:107], v[104:105], v[158:159]
	v_lshl_add_u64 v[108:109], v[108:109], 0, v[144:145]
	v_cvt_pk_bf16_f32 v104, v112, v113
	v_cvt_pk_bf16_f32 v105, v110, v111
	v_cvt_pk_bf16_f32 v106, v106, v107
	v_cvt_pk_bf16_f32 v107, v114, v115
	global_store_dwordx4 v[108:109], v[104:107], off
	v_pk_mul_f32 v[52:53], v[52:53], v[132:133]
	v_pk_mul_f32 v[38:39], v[38:39], v[134:135]
	v_or_b32_e32 v104, s5, v116
	v_ashrrev_i32_e32 v105, 31, v104
	v_lshlrev_b64 v[104:105], 7, v[104:105]
	v_lshl_add_u64 v[104:105], s[8:9], 0, v[104:105]
	v_pk_mul_f32 v[106:107], v[94:95], v[130:131]
	v_pk_mul_f32 v[94:95], v[92:93], v[128:129]
	v_lshl_add_u64 v[104:105], v[104:105], 0, v[144:145]
	v_cvt_pk_bf16_f32 v92, v100, v101
	v_cvt_pk_bf16_f32 v93, v102, v103
	v_cvt_pk_bf16_f32 v94, v94, v95
	v_cvt_pk_bf16_f32 v95, v106, v107
	v_or_b32_e32 v100, 32, v171
	global_store_dwordx4 v[104:105], v[92:95], off
	v_pk_mul_f32 v[36:37], v[36:37], v[132:133]
	v_pk_mul_f32 v[22:23], v[22:23], v[134:135]
	v_or_b32_e32 v92, s4, v100
	v_ashrrev_i32_e32 v93, 31, v92
	v_lshlrev_b64 v[92:93], 7, v[92:93]
	v_lshl_add_u64 v[92:93], s[8:9], 0, v[92:93]
	v_pk_mul_f32 v[94:95], v[98:99], v[156:157]
	v_pk_mul_f32 v[98:99], v[90:91], v[160:161]
	v_pk_mul_f32 v[90:91], v[88:89], v[158:159]
	v_lshl_add_u64 v[92:93], v[92:93], 0, v[144:145]
	v_cvt_pk_bf16_f32 v88, v96, v97
	v_cvt_pk_bf16_f32 v89, v94, v95
	v_cvt_pk_bf16_f32 v90, v90, v91
	v_cvt_pk_bf16_f32 v91, v98, v99
	global_store_dwordx4 v[92:93], v[88:91], off
	v_pk_mul_f32 v[20:21], v[20:21], v[132:133]
	v_pk_mul_f32 v[6:7], v[6:7], v[134:135]
	v_or_b32_e32 v88, s5, v100
	v_ashrrev_i32_e32 v89, 31, v88
	v_lshlrev_b64 v[88:89], 7, v[88:89]
	v_lshl_add_u64 v[88:89], s[8:9], 0, v[88:89]
	v_pk_mul_f32 v[90:91], v[78:79], v[130:131]
	v_pk_mul_f32 v[78:79], v[76:77], v[128:129]
	v_lshl_add_u64 v[88:89], v[88:89], 0, v[144:145]
	v_cvt_pk_bf16_f32 v76, v84, v85
	v_cvt_pk_bf16_f32 v77, v86, v87
	v_cvt_pk_bf16_f32 v78, v78, v79
	v_cvt_pk_bf16_f32 v79, v90, v91
	v_or_b32_e32 v84, 48, v171
	global_store_dwordx4 v[88:89], v[76:79], off
	v_pk_mul_f32 v[4:5], v[4:5], v[132:133]
	s_nop 0
	v_or_b32_e32 v76, s4, v84
	v_ashrrev_i32_e32 v77, 31, v76
	v_lshlrev_b64 v[76:77], 7, v[76:77]
	v_lshl_add_u64 v[76:77], s[8:9], 0, v[76:77]
	v_pk_mul_f32 v[78:79], v[82:83], v[156:157]
	v_pk_mul_f32 v[82:83], v[74:75], v[160:161]
	v_pk_mul_f32 v[74:75], v[72:73], v[158:159]
	v_lshl_add_u64 v[76:77], v[76:77], 0, v[144:145]
	v_cvt_pk_bf16_f32 v72, v80, v81
	v_cvt_pk_bf16_f32 v73, v78, v79
	v_cvt_pk_bf16_f32 v74, v74, v75
	v_cvt_pk_bf16_f32 v75, v82, v83
	global_store_dwordx4 v[76:77], v[72:75], off
	s_nop 1
	v_or_b32_e32 v72, s5, v84
	v_ashrrev_i32_e32 v73, 31, v72
	v_lshlrev_b64 v[72:73], 7, v[72:73]
	v_lshl_add_u64 v[72:73], s[8:9], 0, v[72:73]
	s_bfe_u32 s8, s6, 0x20008
	s_or_b32 s7, s8, s7
	s_lshl_b32 s7, s7, 15
	s_and_b32 s8, s6, 0xc0
	v_pk_mul_f32 v[74:75], v[66:67], v[130:131]
	v_pk_mul_f32 v[66:67], v[64:65], v[128:129]
	s_or_b32 s7, s7, s8
	v_lshl_add_u64 v[72:73], v[72:73], 0, v[144:145]
	v_cvt_pk_bf16_f32 v64, v68, v69
	v_cvt_pk_bf16_f32 v65, v70, v71
	v_cvt_pk_bf16_f32 v66, v66, v67
	v_cvt_pk_bf16_f32 v67, v74, v75
	v_or_b32_e32 v68, s7, v164
	global_store_dwordx4 v[72:73], v[64:67], off
	s_cmpk_lt_u32 s6, 0x400
	s_cselect_b32 s9, s53, s91
	v_or_b32_e32 v64, s4, v68
; DI unsigned pk_bf16(float lo, float hi) { f32x2 v = {lo, hi}; return __builtin_bit_cast(unsigned, __builtin_convertvector(v, bf16v2)); }
; #define PG8_WAIT_V(n) asm volatile("s_waitcnt vmcnt(" #n ")" ::: "memory")
; #define PG8_BAR __builtin_amdgcn_s_barrier()
; #define PG8_WAIT_V(n) asm volatile("s_waitcnt vmcnt(" #n ")" ::: "memory")
; #define PG8_BAR __builtin_amdgcn_s_barrier()
; template <class Epi>
; DI void gemm_phase(LAS unsigned char* lds, const Gemm g, const StaticOrder S, const Epi E) {
;     ...
;     PG8_WAIT_V(0);
;     if (wr == 0) PG8_BAR;
;     PG8_BAR;
;     DI void operator()(AccRef acc, const Unit& u, int wr, int wc, int fr, int fq) const {
;     ...
;                 const int R = u.pm * 256 + ai * 128 + wr * 64 + m * 16 + fr, X = R >> 10, hv = R & 1023;
; #pragma unroll
;                 for (int bj = 0; bj < 2; ++bj) {
;                     const int tok = u.pn * 256 + bj * 128 + wc * 32 + 8 * fq, b = tok >> 13, s = tok & (SEQ - 1);
;                     bf16_t* dst = (X ? vtB : vtA) + ((size_t)(((b * 4 + (hv >> 8)) * 128 + (s >> 6)) * 256 + (hv & 255))) * 64 + (s & 63);
;                     const f32x4 v0 = acc[ai][bj][m][0] * ts[bj][0], v1 = acc[ai][bj][m][1] * ts[bj][1];
;                     u32x4 w; w.x = pk_bf16(v0[0], v0[1]); w.y = pk_bf16(v0[2], v0[3]); w.z = pk_bf16(v1[0], v1[1]); w.w = pk_bf16(v1[2], v1[3]);
;                     *(u32x4*)dst = w;
	v_ashrrev_i32_e32 v65, 31, v64
	s_cselect_b32 s8, s52, s90
	v_lshlrev_b64 v[64:65], 7, v[64:65]
	v_lshl_add_u64 v[64:65], s[8:9], 0, v[64:65]
	v_pk_mul_f32 v[66:67], v[58:59], v[160:161]
	v_pk_mul_f32 v[58:59], v[56:57], v[158:159]
	v_lshl_add_u64 v[64:65], v[64:65], 0, v[144:145]
	v_cvt_pk_bf16_f32 v56, v60, v61
	v_cvt_pk_bf16_f32 v57, v62, v63
	v_cvt_pk_bf16_f32 v58, v58, v59
	v_cvt_pk_bf16_f32 v59, v66, v67
	global_store_dwordx4 v[64:65], v[56:59], off
	s_and_b64 vcc, exec, s[0:1]
	s_nop 0
	v_or_b32_e32 v56, s5, v68
	v_ashrrev_i32_e32 v57, 31, v56
	v_lshlrev_b64 v[56:57], 7, v[56:57]
	v_lshl_add_u64 v[56:57], s[8:9], 0, v[56:57]
	v_pk_mul_f32 v[58:59], v[46:47], v[130:131]
	v_pk_mul_f32 v[46:47], v[44:45], v[128:129]
	v_lshl_add_u64 v[56:57], v[56:57], 0, v[144:145]
	v_cvt_pk_bf16_f32 v44, v52, v53
	v_cvt_pk_bf16_f32 v45, v54, v55
	v_cvt_pk_bf16_f32 v46, v46, v47
	v_cvt_pk_bf16_f32 v47, v58, v59
	v_or_b32_e32 v52, 16, v68
	global_store_dwordx4 v[56:57], v[44:47], off
	s_nop 1
	v_or_b32_e32 v44, s4, v52
	v_ashrrev_i32_e32 v45, 31, v44
	v_lshlrev_b64 v[44:45], 7, v[44:45]
	v_lshl_add_u64 v[44:45], s[8:9], 0, v[44:45]
	v_pk_mul_f32 v[46:47], v[50:51], v[156:157]
	v_pk_mul_f32 v[50:51], v[42:43], v[160:161]
	v_pk_mul_f32 v[42:43], v[40:41], v[158:159]
	v_lshl_add_u64 v[44:45], v[44:45], 0, v[144:145]
	v_cvt_pk_bf16_f32 v40, v48, v49
	v_cvt_pk_bf16_f32 v41, v46, v47
	v_cvt_pk_bf16_f32 v42, v42, v43
	v_cvt_pk_bf16_f32 v43, v50, v51
	global_store_dwordx4 v[44:45], v[40:43], off
	s_nop 1
	v_or_b32_e32 v40, s5, v52
	v_ashrrev_i32_e32 v41, 31, v40
	v_lshlrev_b64 v[40:41], 7, v[40:41]
	v_lshl_add_u64 v[40:41], s[8:9], 0, v[40:41]
	v_pk_mul_f32 v[42:43], v[30:31], v[130:131]
	v_pk_mul_f32 v[30:31], v[28:29], v[128:129]
	v_lshl_add_u64 v[40:41], v[40:41], 0, v[144:145]
	v_cvt_pk_bf16_f32 v28, v36, v37
	v_cvt_pk_bf16_f32 v29, v38, v39
	v_cvt_pk_bf16_f32 v30, v30, v31
	v_cvt_pk_bf16_f32 v31, v42, v43
	v_or_b32_e32 v36, 32, v68
	global_store_dwordx4 v[40:41], v[28:31], off
	s_nop 1
	v_or_b32_e32 v28, s4, v36
	v_ashrrev_i32_e32 v29, 31, v28
	v_lshlrev_b64 v[28:29], 7, v[28:29]
	v_lshl_add_u64 v[28:29], s[8:9], 0, v[28:29]
	v_pk_mul_f32 v[30:31], v[34:35], v[156:157]
	v_pk_mul_f32 v[34:35], v[26:27], v[160:161]
	v_pk_mul_f32 v[26:27], v[24:25], v[158:159]
	v_lshl_add_u64 v[28:29], v[28:29], 0, v[144:145]
	v_cvt_pk_bf16_f32 v24, v32, v33
	v_cvt_pk_bf16_f32 v25, v30, v31
	v_cvt_pk_bf16_f32 v26, v26, v27
	v_cvt_pk_bf16_f32 v27, v34, v35
	global_store_dwordx4 v[28:29], v[24:27], off
	s_nop 1
	v_or_b32_e32 v24, s5, v36
	v_ashrrev_i32_e32 v25, 31, v24
	v_lshlrev_b64 v[24:25], 7, v[24:25]
	v_lshl_add_u64 v[24:25], s[8:9], 0, v[24:25]
	v_pk_mul_f32 v[26:27], v[14:15], v[130:131]
	v_pk_mul_f32 v[14:15], v[12:13], v[128:129]
	v_lshl_add_u64 v[24:25], v[24:25], 0, v[144:145]
	v_cvt_pk_bf16_f32 v12, v20, v21
	v_cvt_pk_bf16_f32 v13, v22, v23
	v_cvt_pk_bf16_f32 v14, v14, v15
	v_cvt_pk_bf16_f32 v15, v26, v27
	v_or_b32_e32 v20, 48, v68
	global_store_dwordx4 v[24:25], v[12:15], off
	s_nop 1
	v_or_b32_e32 v12, s4, v20
	v_ashrrev_i32_e32 v13, 31, v12
	v_lshlrev_b64 v[12:13], 7, v[12:13]
	v_lshl_add_u64 v[12:13], s[8:9], 0, v[12:13]
	v_pk_mul_f32 v[14:15], v[18:19], v[156:157]
	v_pk_mul_f32 v[18:19], v[10:11], v[160:161]
	v_pk_mul_f32 v[10:11], v[8:9], v[158:159]
	v_lshl_add_u64 v[12:13], v[12:13], 0, v[144:145]
	v_cvt_pk_bf16_f32 v8, v16, v17
	v_cvt_pk_bf16_f32 v9, v14, v15
	v_cvt_pk_bf16_f32 v10, v10, v11
	v_cvt_pk_bf16_f32 v11, v18, v19
	global_store_dwordx4 v[12:13], v[8:11], off
	s_nop 1
	v_or_b32_e32 v8, s5, v20
	v_ashrrev_i32_e32 v9, 31, v8
	v_lshlrev_b64 v[8:9], 7, v[8:9]
	v_lshl_add_u64 v[8:9], s[8:9], 0, v[8:9]
	v_pk_mul_f32 v[10:11], v[2:3], v[130:131]
	v_pk_mul_f32 v[2:3], v[0:1], v[128:129]
	v_lshl_add_u64 v[8:9], v[8:9], 0, v[144:145]
	v_cvt_pk_bf16_f32 v0, v4, v5
	v_cvt_pk_bf16_f32 v1, v6, v7
	v_cvt_pk_bf16_f32 v2, v2, v3
	v_cvt_pk_bf16_f32 v3, v10, v11
	s_mov_b64 s[8:9], s[24:25]
	global_store_dwordx4 v[8:9], v[0:3], off
	s_cbranch_vccz .LBB0_291
	s_waitcnt vmcnt(0)
	s_cmpk_gt_u32 s17, 0xff
	s_cbranch_scc1 .LBB0_302
	s_barrier

; #define PG8_STAGE(bufoff, gbase, voff) do { _Pragma("unroll") for (int _i = 0; _i < 2; ++_i) \
;         __builtin_amdgcn_global_load_lds((const unsigned*)((const char*)(gbase) + (voff)[_i]), (LAS unsigned*)(lds + (bufoff) + ldsw + _i * 8192), 16, 0, 0); } while (0)
; #define PG8_LDA(dst, b, h) do { _Pragma("unroll") for (int m = 0; m < 4; ++m) _Pragma("unroll") for (int k = 0; k < 2; ++k) dst[m][k] = *(const LAS bf16x8*)(lds + PG8_SA(b, h) + aoff + m * 2048 + k * 1024); } while (0)
; #define PG8_LDB(dst, b, h) do { _Pragma("unroll") for (int n = 0; n < 2; ++n) _Pragma("unroll") for (int k = 0; k < 2; ++k) dst[n][k] = *(const LAS bf16x8*)(lds + PG8_SB(b, h) + boff + n * 2048 + k * 1024); } while (0)
; #define PG8_WAIT_V(n) asm volatile("s_waitcnt vmcnt(" #n ")" ::: "memory")
; #define PG8_WAIT_L(n) asm volatile("s_waitcnt lgkmcnt(" #n ")" ::: "memory")
; #define PG8_BAR __builtin_amdgcn_s_barrier()
; #define PG8_SCHED __builtin_amdgcn_sched_barrier(0)
; template <class Epi0, class Epi1>
; DI void gemm_phase_dual(LAS unsigned char* lds, const Gemm g, const Gemm g1, const StaticOrder S, const Epi0 E0, const Epi1 E1) {
;     ...
;             PG8_LDB(B0, 0, 0); PG8_SCHED; PG8_LDA(At, 0, 0); PG8_STAGE(PG8_SA(1, 1), a1 + hstep, voffA);
;             PG8_WAIT_L(8); PG8_BAR; PG8_WAIT_L(0); PG8_MMA(0, 0, At, B0); PG8_BAR; PG8_SCHED;
;             PG8_LDB(B1, 0, 1); PG8_STAGE(PG8_SB(0, 0), b2, voffB);
;             PG8_BAR; PG8_WAIT_L(0); PG8_MMA(0, 1, At, B1); PG8_BAR;
;             PG8_LDA(At, 0, 1); PG8_STAGE(PG8_SA(0, 0), a2, voffA);
;             PG8_BAR; PG8_WAIT_L(0); PG8_MMA(1, 0, At, B0); PG8_BAR; PG8_SCHED;
;             PG8_STAGE(PG8_SB(0, 1), b2 + hstep, voffB);
;             PG8_WAIT_V(6); PG8_BAR; PG8_MMA(1, 1, At, B1); PG8_BAR;
;             PG8_LDB(B0, 1, 0); PG8_SCHED; PG8_LDA(At, 1, 0); PG8_STAGE(PG8_SA(0, 1), a2 + hstep, voffA);
;             PG8_WAIT_L(8); PG8_BAR; PG8_WAIT_L(0); PG8_MMA(0, 0, At, B0); PG8_BAR; PG8_SCHED;
;             PG8_LDB(B1, 1, 1); PG8_STAGE(PG8_SB(1, 0), b3, voffB);
;             PG8_BAR; PG8_WAIT_L(0); PG8_MMA(0, 1, At, B1); PG8_BAR;
;             PG8_LDA(At, 1, 1); PG8_STAGE(PG8_SA(1, 0), a3, voffA);
;             PG8_BAR; PG8_WAIT_L(0); PG8_MMA(1, 0, At, B0); PG8_BAR; PG8_SCHED;
;             PG8_STAGE(PG8_SB(1, 1), b3 + hstep, voffB);
;             PG8_WAIT_V(6); PG8_BAR; PG8_MMA(1, 1, At, B1); PG8_BAR;
.LBB0_632:
	ds_read_b128 v[128:131], v181
	ds_read_b128 v[132:135], v181 offset:1024
	ds_read_b128 v[136:139], v181 offset:2048
	ds_read_b128 v[140:143], v181 offset:3072
	s_add_u32 s12, s10, 0xfffc0080
	s_addc_u32 s13, s11, -1
	s_cmp_eq_u32 s19, 12
	s_cselect_b32 s15, s1, s13
	s_cselect_b32 s14, s6, s12
	s_cselect_b32 s13, s7, s18
	s_cselect_b32 s12, s16, s17
	v_lshl_add_u64 v[190:191], s[10:11], 0, v[168:169]
	s_add_i32 m0, s49, 0xc000
	ds_read_b128 v[144:147], v183
	ds_read_b128 v[148:151], v183 offset:1024
	ds_read_b128 v[152:155], v183 offset:2048
	ds_read_b128 v[184:187], v183 offset:3072
	ds_read_b128 v[194:197], v183 offset:4096
	ds_read_b128 v[198:201], v183 offset:5120
	ds_read_b128 v[202:205], v183 offset:6144
	ds_read_b128 v[206:209], v183 offset:7168
	global_load_lds_dwordx4 v[190:191], off
	v_lshl_add_u64 v[190:191], s[10:11], 0, v[170:171]
	s_add_i32 m0, s49, 0xe000
	s_nop 0
	global_load_lds_dwordx4 v[190:191], off
	s_waitcnt lgkmcnt(8)
	s_setprio 1
	s_barrier
	s_waitcnt lgkmcnt(0)
	v_mfma_f32_16x16x32_bf16 v[124:127], v[128:131], v[144:147], v[124:127]
	v_mfma_f32_16x16x32_bf16 v[120:123], v[136:139], v[144:147], v[120:123]
	v_mfma_f32_16x16x32_bf16 v[108:111], v[128:131], v[152:155], v[108:111]
	v_mfma_f32_16x16x32_bf16 v[104:107], v[136:139], v[152:155], v[104:107]
	v_mfma_f32_16x16x32_bf16 v[92:95], v[128:131], v[194:197], v[92:95]
	v_mfma_f32_16x16x32_bf16 v[88:91], v[136:139], v[194:197], v[88:91]
	v_mfma_f32_16x16x32_bf16 v[76:79], v[128:131], v[202:205], v[76:79]
	v_mfma_f32_16x16x32_bf16 v[72:75], v[136:139], v[202:205], v[72:75]
	v_mfma_f32_16x16x32_bf16 v[124:127], v[132:135], v[148:151], v[124:127]
	v_mfma_f32_16x16x32_bf16 v[120:123], v[140:143], v[148:151], v[120:123]
	v_mfma_f32_16x16x32_bf16 v[108:111], v[132:135], v[184:187], v[108:111]
	v_mfma_f32_16x16x32_bf16 v[104:107], v[140:143], v[184:187], v[104:107]
	v_mfma_f32_16x16x32_bf16 v[92:95], v[132:135], v[198:201], v[92:95]
	v_mfma_f32_16x16x32_bf16 v[88:91], v[140:143], v[198:201], v[88:91]
	s_setprio 2
	s_barrier
	v_mfma_f32_16x16x32_bf16 v[76:79], v[132:135], v[206:209], v[76:79]
	v_mfma_f32_16x16x32_bf16 v[72:75], v[140:143], v[206:209], v[72:75]
	s_setprio 0
	s_add_i32 s41, s78, s48
	v_lshl_add_u64 v[190:191], s[12:13], 0, v[158:159]
	s_mov_b32 m0, s41
	ds_read_b128 v[210:213], v189
	ds_read_b128 v[214:217], v189 offset:1024
	ds_read_b128 v[218:221], v189 offset:2048
	ds_read_b128 v[224:227], v189 offset:3072
	global_load_lds_dwordx4 v[190:191], off
	v_lshl_add_u64 v[228:229], s[12:13], 0, v[162:163]
	s_add_i32 m0, s41, 0x2000
	s_nop 0
	global_load_lds_dwordx4 v[228:229], off
	s_setprio 1
	s_barrier
	s_waitcnt lgkmcnt(0)
	v_mfma_f32_16x16x32_bf16 v[116:119], v[210:213], v[144:147], v[116:119]
	v_mfma_f32_16x16x32_bf16 v[112:115], v[218:221], v[144:147], v[112:115]
	v_mfma_f32_16x16x32_bf16 v[100:103], v[210:213], v[152:155], v[100:103]
	v_mfma_f32_16x16x32_bf16 v[96:99], v[218:221], v[152:155], v[96:99]
	v_mfma_f32_16x16x32_bf16 v[84:87], v[210:213], v[194:197], v[84:87]
	v_mfma_f32_16x16x32_bf16 v[80:83], v[218:221], v[194:197], v[80:83]
	v_mfma_f32_16x16x32_bf16 v[68:71], v[210:213], v[202:205], v[68:71]
	v_mfma_f32_16x16x32_bf16 v[64:67], v[218:221], v[202:205], v[64:67]
	v_mfma_f32_16x16x32_bf16 v[116:119], v[214:217], v[148:151], v[116:119]
	v_mfma_f32_16x16x32_bf16 v[112:115], v[224:227], v[148:151], v[112:115]
	v_mfma_f32_16x16x32_bf16 v[100:103], v[214:217], v[184:187], v[100:103]
	v_mfma_f32_16x16x32_bf16 v[96:99], v[224:227], v[184:187], v[96:99]
	v_mfma_f32_16x16x32_bf16 v[84:87], v[214:217], v[198:201], v[84:87]
	v_mfma_f32_16x16x32_bf16 v[80:83], v[224:227], v[198:201], v[80:83]
	s_setprio 2
	s_barrier
	v_mfma_f32_16x16x32_bf16 v[68:71], v[214:217], v[206:209], v[68:71]
	v_mfma_f32_16x16x32_bf16 v[64:67], v[224:227], v[206:209], v[64:67]
	s_setprio 0
	s_mov_b32 m0, s49
	v_lshl_add_u64 v[230:231], s[14:15], 0, v[156:157]
	ds_read_b128 v[144:147], v183 offset:16384
	ds_read_b128 v[148:151], v183 offset:17408
	ds_read_b128 v[152:155], v183 offset:18432
	ds_read_b128 v[184:187], v183 offset:19456
	ds_read_b128 v[194:197], v183 offset:20480
	ds_read_b128 v[198:201], v183 offset:21504
	ds_read_b128 v[202:205], v183 offset:22528
	ds_read_b128 v[206:209], v183 offset:23552
	global_load_lds_dwordx4 v[230:231], off
	v_lshl_add_u64 v[232:233], s[14:15], 0, v[160:161]
	s_mov_b32 m0, s50
	s_nop 0
	global_load_lds_dwordx4 v[232:233], off
	s_setprio 1
	s_barrier
	s_waitcnt lgkmcnt(0)
	v_mfma_f32_16x16x32_bf16 v[60:63], v[128:131], v[144:147], v[60:63]
	v_mfma_f32_16x16x32_bf16 v[56:59], v[136:139], v[144:147], v[56:59]
	v_mfma_f32_16x16x32_bf16 v[44:47], v[128:131], v[152:155], v[44:47]
	v_mfma_f32_16x16x32_bf16 v[40:43], v[136:139], v[152:155], v[40:43]
	v_mfma_f32_16x16x32_bf16 v[28:31], v[128:131], v[194:197], v[28:31]
	v_mfma_f32_16x16x32_bf16 v[24:27], v[136:139], v[194:197], v[24:27]
	v_mfma_f32_16x16x32_bf16 v[12:15], v[128:131], v[202:205], v[12:15]
	v_mfma_f32_16x16x32_bf16 v[8:11], v[136:139], v[202:205], v[8:11]
	v_mfma_f32_16x16x32_bf16 v[60:63], v[132:135], v[148:151], v[60:63]
	v_mfma_f32_16x16x32_bf16 v[56:59], v[140:143], v[148:151], v[56:59]
	v_mfma_f32_16x16x32_bf16 v[44:47], v[132:135], v[184:187], v[44:47]
	v_mfma_f32_16x16x32_bf16 v[40:43], v[140:143], v[184:187], v[40:43]
	v_mfma_f32_16x16x32_bf16 v[28:31], v[132:135], v[198:201], v[28:31]
	v_mfma_f32_16x16x32_bf16 v[24:27], v[140:143], v[198:201], v[24:27]
	s_setprio 2
	s_barrier
; #define PG8_STAGE(bufoff, gbase, voff) do { _Pragma("unroll") for (int _i = 0; _i < 2; ++_i) \
;         __builtin_amdgcn_global_load_lds((const unsigned*)((const char*)(gbase) + (voff)[_i]), (LAS unsigned*)(lds + (bufoff) + ldsw + _i * 8192), 16, 0, 0); } while (0)
; #define PG8_LDA(dst, b, h) do { _Pragma("unroll") for (int m = 0; m < 4; ++m) _Pragma("unroll") for (int k = 0; k < 2; ++k) dst[m][k] = *(const LAS bf16x8*)(lds + PG8_SA(b, h) + aoff + m * 2048 + k * 1024); } while (0)
; #define PG8_LDB(dst, b, h) do { _Pragma("unroll") for (int n = 0; n < 2; ++n) _Pragma("unroll") for (int k = 0; k < 2; ++k) dst[n][k] = *(const LAS bf16x8*)(lds + PG8_SB(b, h) + boff + n * 2048 + k * 1024); } while (0)
; #define PG8_MMA(ai, bj, At, Bt) do { __builtin_amdgcn_s_setprio(1); _Pragma("unroll") for (int m = 0; m < 4; ++m) _Pragma("unroll") for (int n = 0; n < 2; ++n) _Pragma("unroll") for (int k = 0; k < 2; ++k) \
;         acc[ai][bj][m][n] = __builtin_amdgcn_mfma_f32_16x16x32_bf16(Bt[n][k], At[m][k], acc[ai][bj][m][n], 0, 0, 0); __builtin_amdgcn_s_setprio(0); } while (0)
; #define PG8_WAIT_V(n) asm volatile("s_waitcnt vmcnt(" #n ")" ::: "memory")
; #define PG8_WAIT_L(n) asm volatile("s_waitcnt lgkmcnt(" #n ")" ::: "memory")
; #define PG8_BAR __builtin_amdgcn_s_barrier()
; #define PG8_SCHED __builtin_amdgcn_sched_barrier(0)
; #define PG8_STAGE(bufoff, gbase, voff) do { _Pragma("unroll") for (int _i = 0; _i < 2; ++_i) \
;         __builtin_amdgcn_global_load_lds((const unsigned*)((const char*)(gbase) + (voff)[_i]), (LAS unsigned*)(lds + (bufoff) + ldsw + _i * 8192), 16, 0, 0); } while (0)
; template <class Epi0, class Epi1>
; DI void gemm_phase_dual(LAS unsigned char* lds, const Gemm g, const Gemm g1, const StaticOrder S, const Epi0 E0, const Epi1 E1) {
;     ...
;             PG8_LDB(B0, 1, 0); PG8_SCHED; PG8_LDA(At, 1, 0); PG8_STAGE(PG8_SA(0, 1), a2 + hstep, voffA);
;             PG8_WAIT_L(8); PG8_BAR; PG8_WAIT_L(0); PG8_MMA(0, 0, At, B0); PG8_BAR; PG8_SCHED;
;             PG8_LDB(B1, 1, 1); PG8_STAGE(PG8_SB(1, 0), b3, voffB);
;             PG8_BAR; PG8_WAIT_L(0); PG8_MMA(0, 1, At, B1); PG8_BAR;
;             PG8_LDA(At, 1, 1); PG8_STAGE(PG8_SA(1, 0), a3, voffA);
;             PG8_BAR; PG8_WAIT_L(0); PG8_MMA(1, 0, At, B0); PG8_BAR; PG8_SCHED;
;             PG8_STAGE(PG8_SB(1, 1), b3 + hstep, voffB);
;             PG8_WAIT_V(6); PG8_BAR; PG8_MMA(1, 1, At, B1); PG8_BAR;
	v_mfma_f32_16x16x32_bf16 v[12:15], v[132:135], v[206:209], v[12:15]
	v_mfma_f32_16x16x32_bf16 v[8:11], v[140:143], v[206:209], v[8:11]
	s_setprio 0
	s_add_u32 s90, s12, 0x40000
	s_addc_u32 s91, s13, 0
	s_add_i32 s41, s79, s48
	v_lshl_add_u64 v[128:129], s[90:91], 0, v[158:159]
	s_mov_b32 m0, s41
	s_nop 0
	global_load_lds_dwordx4 v[128:129], off
	v_lshl_add_u64 v[128:129], s[90:91], 0, v[162:163]
	s_add_i32 m0, s41, 0x2000
	s_nop 0
	global_load_lds_dwordx4 v[128:129], off
	s_waitcnt vmcnt(6)
	s_setprio 1
	s_barrier
	v_mfma_f32_16x16x32_bf16 v[52:55], v[210:213], v[144:147], v[52:55]
	v_mfma_f32_16x16x32_bf16 v[48:51], v[218:221], v[144:147], v[48:51]
	v_mfma_f32_16x16x32_bf16 v[36:39], v[210:213], v[152:155], v[36:39]
	v_mfma_f32_16x16x32_bf16 v[32:35], v[218:221], v[152:155], v[32:35]
	v_mfma_f32_16x16x32_bf16 v[20:23], v[210:213], v[194:197], v[20:23]
	v_mfma_f32_16x16x32_bf16 v[16:19], v[218:221], v[194:197], v[16:19]
	v_mfma_f32_16x16x32_bf16 v[4:7], v[210:213], v[202:205], v[4:7]
	v_mfma_f32_16x16x32_bf16 v[0:3], v[218:221], v[202:205], v[0:3]
	v_mfma_f32_16x16x32_bf16 v[52:55], v[214:217], v[148:151], v[52:55]
	v_mfma_f32_16x16x32_bf16 v[48:51], v[224:227], v[148:151], v[48:51]
	v_mfma_f32_16x16x32_bf16 v[36:39], v[214:217], v[184:187], v[36:39]
	v_mfma_f32_16x16x32_bf16 v[32:35], v[224:227], v[184:187], v[32:35]
	v_mfma_f32_16x16x32_bf16 v[20:23], v[214:217], v[198:201], v[20:23]
	v_mfma_f32_16x16x32_bf16 v[16:19], v[224:227], v[198:201], v[16:19]
	s_setprio 2
	s_barrier
	v_mfma_f32_16x16x32_bf16 v[4:7], v[214:217], v[206:209], v[4:7]
	v_mfma_f32_16x16x32_bf16 v[0:3], v[224:227], v[206:209], v[0:3]
	s_setprio 0
	s_add_i32 s41, 0, 0x18000
	v_add_u32_e32 v140, s41, v179
	ds_read_b128 v[128:131], v140
	ds_read_b128 v[132:135], v140 offset:1024
	ds_read_b128 v[136:139], v140 offset:2048
	ds_read_b128 v[140:143], v140 offset:3072
	s_add_u32 s14, s14, 0x40000
	s_addc_u32 s15, s15, 0
	s_mov_b32 m0, s51
	v_lshl_add_u64 v[210:211], s[14:15], 0, v[156:157]
	ds_read_b128 v[144:147], v183 offset:32768
	ds_read_b128 v[148:151], v183 offset:33792
	ds_read_b128 v[152:155], v183 offset:34816
	ds_read_b128 v[184:187], v183 offset:35840
	ds_read_b128 v[194:197], v183 offset:36864
	ds_read_b128 v[198:201], v183 offset:37888
	ds_read_b128 v[202:205], v183 offset:38912
	ds_read_b128 v[206:209], v183 offset:39936
	global_load_lds_dwordx4 v[210:211], off
	v_lshl_add_u64 v[210:211], s[14:15], 0, v[160:161]
	s_mov_b32 m0, s58
	s_nop 0
	global_load_lds_dwordx4 v[210:211], off
	s_waitcnt lgkmcnt(8)
	s_setprio 1
	s_barrier
	s_waitcnt lgkmcnt(0)
	v_mfma_f32_16x16x32_bf16 v[124:127], v[128:131], v[144:147], v[124:127]
	v_mfma_f32_16x16x32_bf16 v[120:123], v[136:139], v[144:147], v[120:123]
	v_mfma_f32_16x16x32_bf16 v[108:111], v[128:131], v[152:155], v[108:111]
	v_mfma_f32_16x16x32_bf16 v[104:107], v[136:139], v[152:155], v[104:107]
	v_mfma_f32_16x16x32_bf16 v[92:95], v[128:131], v[194:197], v[92:95]
	v_mfma_f32_16x16x32_bf16 v[88:91], v[136:139], v[194:197], v[88:91]
	v_mfma_f32_16x16x32_bf16 v[76:79], v[128:131], v[202:205], v[76:79]
	v_mfma_f32_16x16x32_bf16 v[72:75], v[136:139], v[202:205], v[72:75]
	v_mfma_f32_16x16x32_bf16 v[124:127], v[132:135], v[148:151], v[124:127]
	v_mfma_f32_16x16x32_bf16 v[120:123], v[140:143], v[148:151], v[120:123]
	v_mfma_f32_16x16x32_bf16 v[108:111], v[132:135], v[184:187], v[108:111]
	v_mfma_f32_16x16x32_bf16 v[104:107], v[140:143], v[184:187], v[104:107]
	v_mfma_f32_16x16x32_bf16 v[92:95], v[132:135], v[198:201], v[92:95]
	v_mfma_f32_16x16x32_bf16 v[88:91], v[140:143], v[198:201], v[88:91]
	s_setprio 2
	s_barrier
	v_mfma_f32_16x16x32_bf16 v[76:79], v[132:135], v[206:209], v[76:79]
	v_mfma_f32_16x16x32_bf16 v[72:75], v[140:143], v[206:209], v[72:75]
	s_setprio 0
	s_add_i32 s14, 0, 0x1c000
	s_add_i32 s15, s41, s48
	v_add_u32_e32 v176, s14, v179
	v_lshl_add_u64 v[190:191], v[190:191], 0, s[22:23]
	s_mov_b32 m0, s15
	ds_read_b128 v[210:213], v176
	ds_read_b128 v[214:217], v176 offset:1024
	ds_read_b128 v[218:221], v176 offset:2048
	ds_read_b128 v[224:227], v176 offset:3072
	global_load_lds_dwordx4 v[190:191], off
	v_lshl_add_u64 v[190:191], v[228:229], 0, s[22:23]
	s_add_i32 m0, s15, 0x2000
	s_nop 0
	global_load_lds_dwordx4 v[190:191], off
	s_setprio 1
	s_barrier
	s_waitcnt lgkmcnt(0)
	v_mfma_f32_16x16x32_bf16 v[116:119], v[210:213], v[144:147], v[116:119]
	v_mfma_f32_16x16x32_bf16 v[112:115], v[218:221], v[144:147], v[112:115]
	v_mfma_f32_16x16x32_bf16 v[100:103], v[210:213], v[152:155], v[100:103]
	v_mfma_f32_16x16x32_bf16 v[96:99], v[218:221], v[152:155], v[96:99]
	v_mfma_f32_16x16x32_bf16 v[84:87], v[210:213], v[194:197], v[84:87]
	v_mfma_f32_16x16x32_bf16 v[80:83], v[218:221], v[194:197], v[80:83]
	v_mfma_f32_16x16x32_bf16 v[68:71], v[210:213], v[202:205], v[68:71]
	v_mfma_f32_16x16x32_bf16 v[64:67], v[218:221], v[202:205], v[64:67]
	v_mfma_f32_16x16x32_bf16 v[116:119], v[214:217], v[148:151], v[116:119]
	v_mfma_f32_16x16x32_bf16 v[112:115], v[224:227], v[148:151], v[112:115]
	v_mfma_f32_16x16x32_bf16 v[100:103], v[214:217], v[184:187], v[100:103]
	v_mfma_f32_16x16x32_bf16 v[96:99], v[224:227], v[184:187], v[96:99]
	v_mfma_f32_16x16x32_bf16 v[84:87], v[214:217], v[198:201], v[84:87]
	v_mfma_f32_16x16x32_bf16 v[80:83], v[224:227], v[198:201], v[80:83]
	s_setprio 2
	s_barrier
; #define PG8_STAGE(bufoff, gbase, voff) do { _Pragma("unroll") for (int _i = 0; _i < 2; ++_i) \
;         __builtin_amdgcn_global_load_lds((const unsigned*)((const char*)(gbase) + (voff)[_i]), (LAS unsigned*)(lds + (bufoff) + ldsw + _i * 8192), 16, 0, 0); } while (0)
; #define PG8_LDA(dst, b, h) do { _Pragma("unroll") for (int m = 0; m < 4; ++m) _Pragma("unroll") for (int k = 0; k < 2; ++k) dst[m][k] = *(const LAS bf16x8*)(lds + PG8_SA(b, h) + aoff + m * 2048 + k * 1024); } while (0)
; #define PG8_LDB(dst, b, h) do { _Pragma("unroll") for (int n = 0; n < 2; ++n) _Pragma("unroll") for (int k = 0; k < 2; ++k) dst[n][k] = *(const LAS bf16x8*)(lds + PG8_SB(b, h) + boff + n * 2048 + k * 1024); } while (0)
; #define PG8_MMA(ai, bj, At, Bt) do { __builtin_amdgcn_s_setprio(1); _Pragma("unroll") for (int m = 0; m < 4; ++m) _Pragma("unroll") for (int n = 0; n < 2; ++n) _Pragma("unroll") for (int k = 0; k < 2; ++k) \
;         acc[ai][bj][m][n] = __builtin_amdgcn_mfma_f32_16x16x32_bf16(Bt[n][k], At[m][k], acc[ai][bj][m][n], 0, 0, 0); __builtin_amdgcn_s_setprio(0); } while (0)
; #define PG8_WAIT_V(n) asm volatile("s_waitcnt vmcnt(" #n ")" ::: "memory")
; #define PG8_WAIT_L(n) asm volatile("s_waitcnt lgkmcnt(" #n ")" ::: "memory")
; #define PG8_BAR __builtin_amdgcn_s_barrier()
; template <class Epi0, class Epi1>
; DI void gemm_phase_dual(LAS unsigned char* lds, const Gemm g, const Gemm g1, const StaticOrder S, const Epi0 E0, const Epi1 E1) {
;     ...
;             PG8_LDB(B0, 1, 0); PG8_SCHED; PG8_LDA(At, 1, 0); PG8_STAGE(PG8_SA(0, 1), a2 + hstep, voffA);
;             PG8_WAIT_L(8); PG8_BAR; PG8_WAIT_L(0); PG8_MMA(0, 0, At, B0); PG8_BAR; PG8_SCHED;
;             PG8_LDB(B1, 1, 1); PG8_STAGE(PG8_SB(1, 0), b3, voffB);
;             PG8_BAR; PG8_WAIT_L(0); PG8_MMA(0, 1, At, B1); PG8_BAR;
;             PG8_LDA(At, 1, 1); PG8_STAGE(PG8_SA(1, 0), a3, voffA);
;             PG8_BAR; PG8_WAIT_L(0); PG8_MMA(1, 0, At, B0); PG8_BAR; PG8_SCHED;
;             PG8_STAGE(PG8_SB(1, 1), b3 + hstep, voffB);
;             PG8_WAIT_V(6); PG8_BAR; PG8_MMA(1, 1, At, B1); PG8_BAR;
;     DI void operator()(AccRef acc, const Unit& u, int wr, int wc, int fr, int fq) const {
;         const int row0 = u.pm * 256 + wr * 64 + fr;
;         bf16_t* Gp = gab + (size_t)(u.pm * 8 + u.pn) * 65536 + (wr * 64 + fr) * 256 + wc * 32 + 8 * fq;
;         const RowScales rsc = load_rowscales(ss, row0);
	v_mfma_f32_16x16x32_bf16 v[68:71], v[214:217], v[206:209], v[68:71]
	v_mfma_f32_16x16x32_bf16 v[64:67], v[224:227], v[206:209], v[64:67]
	s_setprio 0
	s_mov_b32 m0, s76
	v_lshl_add_u64 v[190:191], v[230:231], 0, s[22:23]
	ds_read_b128 v[144:147], v183 offset:49152
	ds_read_b128 v[148:151], v183 offset:50176
	ds_read_b128 v[152:155], v183 offset:51200
	ds_read_b128 v[184:187], v183 offset:52224
	ds_read_b128 v[194:197], v183 offset:53248
	ds_read_b128 v[198:201], v183 offset:54272
	ds_read_b128 v[202:205], v183 offset:55296
	ds_read_b128 v[206:209], v183 offset:56320
	global_load_lds_dwordx4 v[190:191], off
	v_lshl_add_u64 v[190:191], v[232:233], 0, s[22:23]
	s_mov_b32 m0, s77
	s_nop 0
	global_load_lds_dwordx4 v[190:191], off
	s_setprio 1
	s_barrier
	s_waitcnt lgkmcnt(0)
	v_mfma_f32_16x16x32_bf16 v[60:63], v[128:131], v[144:147], v[60:63]
	v_mfma_f32_16x16x32_bf16 v[56:59], v[136:139], v[144:147], v[56:59]
	v_mfma_f32_16x16x32_bf16 v[44:47], v[128:131], v[152:155], v[44:47]
	v_mfma_f32_16x16x32_bf16 v[40:43], v[136:139], v[152:155], v[40:43]
	v_mfma_f32_16x16x32_bf16 v[28:31], v[128:131], v[194:197], v[28:31]
	v_mfma_f32_16x16x32_bf16 v[24:27], v[136:139], v[194:197], v[24:27]
	v_mfma_f32_16x16x32_bf16 v[12:15], v[128:131], v[202:205], v[12:15]
	v_mfma_f32_16x16x32_bf16 v[8:11], v[136:139], v[202:205], v[8:11]
	v_mfma_f32_16x16x32_bf16 v[60:63], v[132:135], v[148:151], v[60:63]
	v_mfma_f32_16x16x32_bf16 v[56:59], v[140:143], v[148:151], v[56:59]
	v_mfma_f32_16x16x32_bf16 v[44:47], v[132:135], v[184:187], v[44:47]
	v_mfma_f32_16x16x32_bf16 v[40:43], v[140:143], v[184:187], v[40:43]
	v_mfma_f32_16x16x32_bf16 v[28:31], v[132:135], v[198:201], v[28:31]
	v_mfma_f32_16x16x32_bf16 v[24:27], v[140:143], v[198:201], v[24:27]
	s_setprio 2
	s_barrier
	v_mfma_f32_16x16x32_bf16 v[12:15], v[132:135], v[206:209], v[12:15]
	v_mfma_f32_16x16x32_bf16 v[8:11], v[140:143], v[206:209], v[8:11]
	s_setprio 0
	s_add_u32 s12, s12, 0x40080
	s_addc_u32 s13, s13, 0
	s_add_i32 s14, s14, s48
	v_lshl_add_u64 v[128:129], s[12:13], 0, v[158:159]
	s_mov_b32 m0, s14
	s_nop 0
	global_load_lds_dwordx4 v[128:129], off
	v_lshl_add_u64 v[128:129], s[12:13], 0, v[162:163]
	s_add_i32 m0, s14, 0x2000
	s_nop 0
	global_load_lds_dwordx4 v[128:129], off
	s_waitcnt vmcnt(6)
	s_setprio 1
	s_barrier
	v_mfma_f32_16x16x32_bf16 v[52:55], v[210:213], v[144:147], v[52:55]
	v_mfma_f32_16x16x32_bf16 v[48:51], v[218:221], v[144:147], v[48:51]
	v_mfma_f32_16x16x32_bf16 v[36:39], v[210:213], v[152:155], v[36:39]
	v_mfma_f32_16x16x32_bf16 v[32:35], v[218:221], v[152:155], v[32:35]
	v_mfma_f32_16x16x32_bf16 v[20:23], v[210:213], v[194:197], v[20:23]
	v_mfma_f32_16x16x32_bf16 v[16:19], v[218:221], v[194:197], v[16:19]
	v_mfma_f32_16x16x32_bf16 v[4:7], v[210:213], v[202:205], v[4:7]
	v_mfma_f32_16x16x32_bf16 v[0:3], v[218:221], v[202:205], v[0:3]
	v_mfma_f32_16x16x32_bf16 v[52:55], v[214:217], v[148:151], v[52:55]
	v_mfma_f32_16x16x32_bf16 v[48:51], v[224:227], v[148:151], v[48:51]
	v_mfma_f32_16x16x32_bf16 v[36:39], v[214:217], v[184:187], v[36:39]
	v_mfma_f32_16x16x32_bf16 v[32:35], v[224:227], v[184:187], v[32:35]
	v_mfma_f32_16x16x32_bf16 v[20:23], v[214:217], v[198:201], v[20:23]
	v_mfma_f32_16x16x32_bf16 v[16:19], v[224:227], v[198:201], v[16:19]
	s_setprio 2
	s_barrier
	v_mfma_f32_16x16x32_bf16 v[4:7], v[214:217], v[206:209], v[4:7]
	v_mfma_f32_16x16x32_bf16 v[0:3], v[224:227], v[206:209], v[0:3]
	s_setprio 0
	s_add_i32 s19, s19, 2
	s_add_u32 s10, s10, 0x100
	s_addc_u32 s11, s11, 0
	s_add_u32 s17, s17, 0x100
	s_addc_u32 s18, s18, 0
	s_cmp_gt_u32 s19, 13
	s_cbranch_scc0 .LBB0_632
	v_lshl_add_u32 v128, s0, 8, v177
	s_mov_b64 s[6:7], -1
	s_and_b64 vcc, exec, s[8:9]
	v_ashrrev_i32_e32 v129, 31, v128
	s_cbranch_vccz .LBB0_635
	v_lshl_add_u64 v[130:131], v[128:129], 2, s[60:61]
	global_load_dword v132, v[130:131], off
	global_load_dword v133, v[130:131], off offset:64
	global_load_dword v134, v[130:131], off offset:128
	global_load_dword v135, v[130:131], off offset:192
	global_load_dword v136, v[130:131], off offset:512
	global_load_dword v137, v[130:131], off offset:576
	global_load_dword v138, v[130:131], off offset:640
	global_load_dword v139, v[130:131], off offset:704
	s_lshl_b32 s0, s0, 3
	s_add_i32 s0, s0, s87
	s_ashr_i32 s1, s0, 31
	s_lshl_b64 s[0:1], s[0:1], 17
	v_lshl_add_u64 v[130:131], v[166:167], 0, s[0:1]
	s_mov_b64 s[6:7], 0
	s_waitcnt vmcnt(0)
; DI unsigned pk_bf16(float lo, float hi) { f32x2 v = {lo, hi}; return __builtin_bit_cast(unsigned, __builtin_convertvector(v, bf16v2)); }
; DI float fast_sigmoid(float x) { return __builtin_amdgcn_rcpf(1.0f + __expf(-x)); }
; DI RowScales load_rowscales(const float* ss, int row0) {
;     ...
;         for (int m = 0; m < 4; ++m) t.r[ai][m] = ss[row0 + ai * 128 + m * 16];
; #pragma unroll
;     for (int ai = 0; ai < 2; ++ai)
; #pragma unroll
;         for (int m = 0; m < 4; ++m) t.r[ai][m] = rsqrtf(t.r[ai][m] * (1.0f / 1024.0f) + 1e-6f);
;     DI void operator()(AccRef acc, const Unit& u, int wr, int wc, int fr, int fq) const {
;     ...
;                     const float rs = rsc.r[ai][m];
;                     const f32x4 r0 = acc[ai][bj][m][0] * rs, r1 = acc[ai][bj][m][1] * rs;
;                     u32x4 w;
;                     w.x = pk_bf16(fast_sigmoid(r0[0]), fast_sigmoid(r0[1])); w.y = pk_bf16(fast_sigmoid(r0[2]), fast_sigmoid(r0[3]));
;                     w.z = pk_bf16(fast_sigmoid(r1[0]), fast_sigmoid(r1[1])); w.w = pk_bf16(fast_sigmoid(r1[2]), fast_sigmoid(r1[3]));
;                     *(u32x4*)(Gp + (ai * 128 + m * 16) * 256 + bj * 128) = w;
	v_fmamk_f32 v132, v132, 0x3a800000, v193
	v_mul_f32_e32 v140, 0x4b800000, v132
	v_cmp_gt_f32_e32 vcc, s80, v132
	v_fmamk_f32 v134, v134, 0x3a800000, v193
	v_fmamk_f32 v136, v136, 0x3a800000, v193
	v_fmamk_f32 v137, v137, 0x3a800000, v193
	v_fmamk_f32 v138, v138, 0x3a800000, v193
	v_fmamk_f32 v139, v139, 0x3a800000, v193
	v_mul_f32_e32 v144, 0x4b800000, v136
	v_mul_f32_e32 v145, 0x4b800000, v137
	v_cndmask_b32_e32 v132, v132, v140, vcc
	v_cmp_gt_f32_e64 s[12:13], s80, v136
	v_cmp_gt_f32_e64 s[14:15], s80, v137
	v_fmamk_f32 v133, v133, 0x3a800000, v193
	v_fmamk_f32 v135, v135, 0x3a800000, v193
	v_mul_f32_e32 v142, 0x4b800000, v134
	v_mul_f32_e32 v146, 0x4b800000, v138
	v_mul_f32_e32 v147, 0x4b800000, v139
	v_cmp_gt_f32_e64 s[8:9], s80, v134
	v_cndmask_b32_e64 v136, v136, v144, s[12:13]
	v_cndmask_b32_e64 v137, v137, v145, s[14:15]
	v_cmp_gt_f32_e64 s[16:17], s80, v138
	v_cmp_gt_f32_e64 s[18:19], s80, v139
	v_rsq_f32_e32 v132, v132
	v_mul_f32_e32 v141, 0x4b800000, v133
	v_mul_f32_e32 v143, 0x4b800000, v135
	v_cmp_gt_f32_e64 s[0:1], s80, v133
	v_cndmask_b32_e64 v134, v134, v142, s[8:9]
	v_cmp_gt_f32_e64 s[10:11], s80, v135
	v_cndmask_b32_e64 v138, v138, v146, s[16:17]
	v_cndmask_b32_e64 v139, v139, v147, s[18:19]
	v_rsq_f32_e32 v136, v136
	v_rsq_f32_e32 v137, v137
	v_cndmask_b32_e64 v133, v133, v141, s[0:1]
	v_cndmask_b32_e64 v135, v135, v143, s[10:11]
	v_rsq_f32_e32 v134, v134
	v_rsq_f32_e32 v141, v138
	v_rsq_f32_e32 v139, v139
	v_rsq_f32_e32 v133, v133
	v_rsq_f32_e32 v135, v135
	v_mul_f32_e32 v138, 0x45800000, v132
	v_mul_f32_e32 v144, 0x45800000, v136
	v_mul_f32_e32 v145, 0x45800000, v137
	v_cndmask_b32_e32 v148, v132, v138, vcc
	v_mul_f32_e32 v142, 0x45800000, v134
	v_mul_f32_e32 v146, 0x45800000, v141
	v_mul_f32_e32 v147, 0x45800000, v139
	v_cndmask_b32_e64 v138, v136, v144, s[12:13]
	v_cndmask_b32_e64 v136, v137, v145, s[14:15]
	v_pk_mul_f32 v[144:145], v[126:127], v[148:149] op_sel_hi:[1,0]
	v_pk_mul_f32 v[152:153], v[122:123], v[148:149] op_sel_hi:[1,0]
	v_mul_f32_e32 v140, 0x45800000, v133
	v_mul_f32_e32 v143, 0x45800000, v135
	v_cndmask_b32_e64 v142, v134, v142, s[8:9]
	v_cndmask_b32_e64 v134, v141, v146, s[16:17]
	v_cndmask_b32_e64 v132, v139, v147, s[18:19]
	v_pk_mul_f32 v[146:147], v[124:125], v[148:149] op_sel_hi:[1,0]
	v_pk_mul_f32 v[154:155], v[120:121], v[148:149] op_sel_hi:[1,0]
	v_mul_f32_e32 v137, 0xbfb8aa3b, v144
	v_mul_f32_e32 v144, 0xbfb8aa3b, v152
	v_cndmask_b32_e64 v150, v133, v140, s[0:1]
	v_cndmask_b32_e64 v140, v135, v143, s[10:11]
	v_mul_f32_e32 v133, 0xbfb8aa3b, v146
	v_mul_f32_e32 v135, 0xbfb8aa3b, v147
	v_mul_f32_e32 v139, 0xbfb8aa3b, v145
	v_mul_f32_e32 v141, 0xbfb8aa3b, v154
	v_mul_f32_e32 v143, 0xbfb8aa3b, v155
	v_exp_f32_e32 v144, v144
	v_mul_f32_e32 v145, 0xbfb8aa3b, v153
	v_exp_f32_e32 v133, v133
	v_exp_f32_e32 v135, v135
	v_exp_f32_e32 v137, v137
	v_exp_f32_e32 v139, v139
	v_exp_f32_e32 v141, v141
	v_exp_f32_e32 v143, v143
	v_exp_f32_e32 v145, v145
	v_add_f32_e32 v144, 1.0, v144
	v_add_f32_e32 v133, 1.0, v133
	v_add_f32_e32 v135, 1.0, v135
	v_add_f32_e32 v137, 1.0, v137
	v_add_f32_e32 v139, 1.0, v139
	v_add_f32_e32 v141, 1.0, v141
	v_add_f32_e32 v143, 1.0, v143
	v_rcp_f32_e32 v147, v144
	v_add_f32_e32 v144, 1.0, v145
	v_rcp_f32_e32 v133, v133
	v_rcp_f32_e32 v135, v135
	v_rcp_f32_e32 v137, v137
	v_rcp_f32_e32 v139, v139
	v_rcp_f32_e32 v141, v141
	v_rcp_f32_e32 v143, v143
	v_rcp_f32_e32 v149, v144
	v_cvt_pk_bf16_f32 v144, v133, v135
	v_cvt_pk_bf16_f32 v145, v137, v139
	v_cvt_pk_bf16_f32 v146, v141, v143
	v_cvt_pk_bf16_f32 v147, v147, v149
	global_store_dwordx4 v[130:131], v[144:147], off
	v_pk_mul_f32 v[152:153], v[114:115], v[148:149] op_sel_hi:[1,0]
	s_nop 0
	v_pk_mul_f32 v[144:145], v[118:119], v[148:149] op_sel_hi:[1,0]
	v_pk_mul_f32 v[146:147], v[116:117], v[148:149] op_sel_hi:[1,0]
	v_mul_f32_e32 v137, 0xbfb8aa3b, v144
	v_mul_f32_e32 v133, 0xbfb8aa3b, v146
	v_mul_f32_e32 v135, 0xbfb8aa3b, v147
	v_pk_mul_f32 v[146:147], v[112:113], v[148:149] op_sel_hi:[1,0]
	v_mul_f32_e32 v144, 0xbfb8aa3b, v152
	v_mul_f32_e32 v139, 0xbfb8aa3b, v145
	v_mul_f32_e32 v141, 0xbfb8aa3b, v146
	v_mul_f32_e32 v143, 0xbfb8aa3b, v147
	v_exp_f32_e32 v144, v144
	v_mul_f32_e32 v145, 0xbfb8aa3b, v153
	v_exp_f32_e32 v133, v133
	v_exp_f32_e32 v135, v135
	v_exp_f32_e32 v137, v137
	v_exp_f32_e32 v139, v139
	v_exp_f32_e32 v141, v141
	v_exp_f32_e32 v143, v143
	v_exp_f32_e32 v145, v145
	v_add_f32_e32 v144, 1.0, v144
	v_add_f32_e32 v133, 1.0, v133
	v_add_f32_e32 v135, 1.0, v135
	v_add_f32_e32 v137, 1.0, v137
	v_add_f32_e32 v139, 1.0, v139
	v_add_f32_e32 v141, 1.0, v141
	v_add_f32_e32 v143, 1.0, v143
	v_rcp_f32_e32 v147, v144
	v_add_f32_e32 v144, 1.0, v145
	v_rcp_f32_e32 v133, v133
	v_rcp_f32_e32 v135, v135
	v_rcp_f32_e32 v137, v137
	v_rcp_f32_e32 v139, v139
	v_rcp_f32_e32 v141, v141
	v_rcp_f32_e32 v143, v143
	v_rcp_f32_e32 v148, v144
	v_cvt_pk_bf16_f32 v144, v133, v135
	v_cvt_pk_bf16_f32 v145, v137, v139
	v_cvt_pk_bf16_f32 v146, v141, v143
	v_cvt_pk_bf16_f32 v147, v147, v148
	global_store_dwordx4 v[130:131], v[144:147], off offset:256
	v_pk_mul_f32 v[148:149], v[106:107], v[150:151] op_sel_hi:[1,0]
	v_pk_mul_f32 v[152:153], v[98:99], v[150:151] op_sel_hi:[1,0]
	v_pk_mul_f32 v[144:145], v[110:111], v[150:151] op_sel_hi:[1,0]
	v_pk_mul_f32 v[146:147], v[108:109], v[150:151] op_sel_hi:[1,0]
	v_mul_f32_e32 v137, 0xbfb8aa3b, v144
	v_mul_f32_e32 v144, 0xbfb8aa3b, v148
	v_mul_f32_e32 v133, 0xbfb8aa3b, v146
	v_mul_f32_e32 v135, 0xbfb8aa3b, v147
	v_pk_mul_f32 v[146:147], v[104:105], v[150:151] op_sel_hi:[1,0]
	v_mul_f32_e32 v139, 0xbfb8aa3b, v145
	v_exp_f32_e32 v144, v144
	v_mul_f32_e32 v145, 0xbfb8aa3b, v149
	v_mul_f32_e32 v141, 0xbfb8aa3b, v146
; DI unsigned pk_bf16(float lo, float hi) { f32x2 v = {lo, hi}; return __builtin_bit_cast(unsigned, __builtin_convertvector(v, bf16v2)); }
; DI float fast_sigmoid(float x) { return __builtin_amdgcn_rcpf(1.0f + __expf(-x)); }
;     DI void operator()(AccRef acc, const Unit& u, int wr, int wc, int fr, int fq) const {
;     ...
;         for (int ai = 0; ai < 2; ++ai)
; #pragma unroll
;             for (int m = 0; m < 4; ++m)
; #pragma unroll
;                 for (int bj = 0; bj < 2; ++bj) {
;                     const float rs = rsc.r[ai][m];
;                     const f32x4 r0 = acc[ai][bj][m][0] * rs, r1 = acc[ai][bj][m][1] * rs;
;                     u32x4 w;
;                     w.x = pk_bf16(fast_sigmoid(r0[0]), fast_sigmoid(r0[1])); w.y = pk_bf16(fast_sigmoid(r0[2]), fast_sigmoid(r0[3]));
;                     w.z = pk_bf16(fast_sigmoid(r1[0]), fast_sigmoid(r1[1])); w.w = pk_bf16(fast_sigmoid(r1[2]), fast_sigmoid(r1[3]));
;                     *(u32x4*)(Gp + (ai * 128 + m * 16) * 256 + bj * 128) = w;
	v_mul_f32_e32 v143, 0xbfb8aa3b, v147
	v_exp_f32_e32 v145, v145
	v_exp_f32_e32 v133, v133
	v_exp_f32_e32 v135, v135
	v_exp_f32_e32 v137, v137
	v_exp_f32_e32 v139, v139
	v_exp_f32_e32 v141, v141
	v_exp_f32_e32 v143, v143
	v_add_f32_e32 v144, 1.0, v144
	v_rcp_f32_e32 v147, v144
	v_add_f32_e32 v144, 1.0, v145
	v_add_f32_e32 v133, 1.0, v133
	v_add_f32_e32 v135, 1.0, v135
	v_add_f32_e32 v137, 1.0, v137
	v_add_f32_e32 v139, 1.0, v139
	v_add_f32_e32 v141, 1.0, v141
	v_add_f32_e32 v143, 1.0, v143
	v_rcp_f32_e32 v148, v144
	v_rcp_f32_e32 v133, v133
	v_rcp_f32_e32 v135, v135
	v_rcp_f32_e32 v137, v137
	v_rcp_f32_e32 v139, v139
	v_rcp_f32_e32 v141, v141
	v_rcp_f32_e32 v143, v143
	v_cvt_pk_bf16_f32 v147, v147, v148
	v_add_co_u32_e32 v148, vcc, s59, v130
	v_cvt_pk_bf16_f32 v144, v133, v135
	v_cvt_pk_bf16_f32 v145, v137, v139
	v_cvt_pk_bf16_f32 v146, v141, v143
	v_addc_co_u32_e32 v149, vcc, 0, v131, vcc
	global_store_dwordx4 v[148:149], v[144:147], off
	s_nop 1
	v_pk_mul_f32 v[144:145], v[102:103], v[150:151] op_sel_hi:[1,0]
	v_pk_mul_f32 v[146:147], v[100:101], v[150:151] op_sel_hi:[1,0]
	v_mul_f32_e32 v137, 0xbfb8aa3b, v144
	v_mul_f32_e32 v133, 0xbfb8aa3b, v146
	v_mul_f32_e32 v135, 0xbfb8aa3b, v147
	v_pk_mul_f32 v[146:147], v[96:97], v[150:151] op_sel_hi:[1,0]
	v_mul_f32_e32 v144, 0xbfb8aa3b, v152
	v_mul_f32_e32 v139, 0xbfb8aa3b, v145
	v_mul_f32_e32 v141, 0xbfb8aa3b, v146
	v_mul_f32_e32 v143, 0xbfb8aa3b, v147
	v_exp_f32_e32 v144, v144
	v_mul_f32_e32 v145, 0xbfb8aa3b, v153
	v_exp_f32_e32 v133, v133
	v_exp_f32_e32 v135, v135
	v_exp_f32_e32 v137, v137
	v_exp_f32_e32 v139, v139
	v_exp_f32_e32 v141, v141
	v_exp_f32_e32 v143, v143
	v_exp_f32_e32 v145, v145
	v_add_f32_e32 v144, 1.0, v144
	v_add_f32_e32 v133, 1.0, v133
	v_add_f32_e32 v135, 1.0, v135
	v_add_f32_e32 v137, 1.0, v137
	v_add_f32_e32 v139, 1.0, v139
	v_add_f32_e32 v141, 1.0, v141
	v_add_f32_e32 v143, 1.0, v143
	v_rcp_f32_e32 v147, v144
	v_add_f32_e32 v144, 1.0, v145
	v_rcp_f32_e32 v133, v133
	v_rcp_f32_e32 v135, v135
	v_rcp_f32_e32 v137, v137
	v_rcp_f32_e32 v139, v139
	v_rcp_f32_e32 v141, v141
	v_rcp_f32_e32 v143, v143
	v_rcp_f32_e32 v150, v144
	v_cvt_pk_bf16_f32 v144, v133, v135
	v_cvt_pk_bf16_f32 v145, v137, v139
	v_cvt_pk_bf16_f32 v146, v141, v143
	v_cvt_pk_bf16_f32 v147, v147, v150
	global_store_dwordx4 v[148:149], v[144:147], off offset:256
	v_pk_mul_f32 v[148:149], v[90:91], v[142:143] op_sel_hi:[1,0]
	s_nop 0
	v_pk_mul_f32 v[144:145], v[94:95], v[142:143] op_sel_hi:[1,0]
	v_pk_mul_f32 v[146:147], v[92:93], v[142:143] op_sel_hi:[1,0]
	v_mul_f32_e32 v137, 0xbfb8aa3b, v144
	v_mul_f32_e32 v144, 0xbfb8aa3b, v148
	v_mul_f32_e32 v133, 0xbfb8aa3b, v146
	v_mul_f32_e32 v135, 0xbfb8aa3b, v147
	v_pk_mul_f32 v[146:147], v[88:89], v[142:143] op_sel_hi:[1,0]
	v_mul_f32_e32 v139, 0xbfb8aa3b, v145
	v_exp_f32_e32 v144, v144
	v_mul_f32_e32 v145, 0xbfb8aa3b, v149
	v_mul_f32_e32 v141, 0xbfb8aa3b, v146
	v_mul_f32_e32 v143, 0xbfb8aa3b, v147
	v_exp_f32_e32 v145, v145
	v_exp_f32_e32 v133, v133
	v_exp_f32_e32 v135, v135
	v_exp_f32_e32 v137, v137
	v_exp_f32_e32 v139, v139
	v_exp_f32_e32 v141, v141
	v_exp_f32_e32 v143, v143
	v_add_f32_e32 v144, 1.0, v144
	v_rcp_f32_e32 v147, v144
	v_add_f32_e32 v144, 1.0, v145
	v_add_f32_e32 v133, 1.0, v133
	v_add_f32_e32 v135, 1.0, v135
	v_add_f32_e32 v137, 1.0, v137
	v_add_f32_e32 v139, 1.0, v139
	v_add_f32_e32 v141, 1.0, v141
	v_add_f32_e32 v143, 1.0, v143
	v_rcp_f32_e32 v148, v144
	v_rcp_f32_e32 v133, v133
	v_rcp_f32_e32 v135, v135
	v_rcp_f32_e32 v137, v137
	v_rcp_f32_e32 v139, v139
	v_rcp_f32_e32 v141, v141
	v_rcp_f32_e32 v143, v143
	v_cvt_pk_bf16_f32 v147, v147, v148
	v_add_co_u32_e32 v148, vcc, s66, v130
	v_cvt_pk_bf16_f32 v144, v133, v135
	v_cvt_pk_bf16_f32 v145, v137, v139
	v_cvt_pk_bf16_f32 v146, v141, v143
	v_addc_co_u32_e32 v149, vcc, 0, v131, vcc
	global_store_dwordx4 v[148:149], v[144:147], off
	v_pk_mul_f32 v[150:151], v[82:83], v[142:143] op_sel_hi:[1,0]
	s_nop 0
	v_pk_mul_f32 v[144:145], v[86:87], v[142:143] op_sel_hi:[1,0]
	v_pk_mul_f32 v[146:147], v[84:85], v[142:143] op_sel_hi:[1,0]
	v_pk_mul_f32 v[142:143], v[80:81], v[142:143] op_sel_hi:[1,0]
	v_mul_f32_e32 v133, 0xbfb8aa3b, v146
	v_mul_f32_e32 v141, 0xbfb8aa3b, v142
	v_mul_f32_e32 v142, 0xbfb8aa3b, v143
	v_exp_f32_e32 v142, v142
	v_mul_f32_e32 v143, 0xbfb8aa3b, v150
	v_mul_f32_e32 v135, 0xbfb8aa3b, v147
	v_mul_f32_e32 v137, 0xbfb8aa3b, v144
	v_mul_f32_e32 v139, 0xbfb8aa3b, v145
	v_exp_f32_e32 v143, v143
	v_mul_f32_e32 v144, 0xbfb8aa3b, v151
	v_exp_f32_e32 v133, v133
	v_exp_f32_e32 v135, v135
	v_exp_f32_e32 v137, v137
	v_exp_f32_e32 v139, v139
	v_exp_f32_e32 v141, v141
	v_exp_f32_e32 v144, v144
	v_add_f32_e32 v142, 1.0, v142
	v_rcp_f32_e32 v145, v142
	v_add_f32_e32 v142, 1.0, v143
	v_add_f32_e32 v133, 1.0, v133
	v_add_f32_e32 v135, 1.0, v135
	v_add_f32_e32 v137, 1.0, v137
	v_add_f32_e32 v139, 1.0, v139
	v_add_f32_e32 v141, 1.0, v141
	v_rcp_f32_e32 v146, v142
	v_add_f32_e32 v142, 1.0, v144
	v_rcp_f32_e32 v133, v133
	v_rcp_f32_e32 v135, v135
	v_rcp_f32_e32 v137, v137
	v_rcp_f32_e32 v139, v139
	v_rcp_f32_e32 v141, v141
	v_rcp_f32_e32 v147, v142
	v_cvt_pk_bf16_f32 v142, v133, v135
	v_cvt_pk_bf16_f32 v143, v137, v139
	v_cvt_pk_bf16_f32 v144, v141, v145
	v_cvt_pk_bf16_f32 v145, v146, v147
	global_store_dwordx4 v[148:149], v[142:145], off offset:256
	v_pk_mul_f32 v[146:147], v[74:75], v[140:141] op_sel_hi:[1,0]
	s_nop 0
	v_pk_mul_f32 v[144:145], v[76:77], v[140:141] op_sel_hi:[1,0]
	v_pk_mul_f32 v[142:143], v[78:79], v[140:141] op_sel_hi:[1,0]
	v_mul_f32_e32 v133, 0xbfb8aa3b, v144
	v_mul_f32_e32 v135, 0xbfb8aa3b, v145
	v_pk_mul_f32 v[144:145], v[72:73], v[140:141] op_sel_hi:[1,0]
	v_mul_f32_e32 v137, 0xbfb8aa3b, v142
; DI unsigned pk_bf16(float lo, float hi) { f32x2 v = {lo, hi}; return __builtin_bit_cast(unsigned, __builtin_convertvector(v, bf16v2)); }
; DI float fast_sigmoid(float x) { return __builtin_amdgcn_rcpf(1.0f + __expf(-x)); }
;     DI void operator()(AccRef acc, const Unit& u, int wr, int wc, int fr, int fq) const {
;     ...
;         for (int ai = 0; ai < 2; ++ai)
; #pragma unroll
;             for (int m = 0; m < 4; ++m)
; #pragma unroll
;                 for (int bj = 0; bj < 2; ++bj) {
;                     const float rs = rsc.r[ai][m];
;                     const f32x4 r0 = acc[ai][bj][m][0] * rs, r1 = acc[ai][bj][m][1] * rs;
;                     u32x4 w;
;                     w.x = pk_bf16(fast_sigmoid(r0[0]), fast_sigmoid(r0[1])); w.y = pk_bf16(fast_sigmoid(r0[2]), fast_sigmoid(r0[3]));
;                     w.z = pk_bf16(fast_sigmoid(r1[0]), fast_sigmoid(r1[1])); w.w = pk_bf16(fast_sigmoid(r1[2]), fast_sigmoid(r1[3]));
;                     *(u32x4*)(Gp + (ai * 128 + m * 16) * 256 + bj * 128) = w;
	v_mul_f32_e32 v142, 0xbfb8aa3b, v145
	v_mul_f32_e32 v139, 0xbfb8aa3b, v143
	v_exp_f32_e32 v142, v142
	v_mul_f32_e32 v143, 0xbfb8aa3b, v146
	v_mul_f32_e32 v141, 0xbfb8aa3b, v144
	v_exp_f32_e32 v143, v143
	v_mul_f32_e32 v144, 0xbfb8aa3b, v147
	v_exp_f32_e32 v141, v141
	v_exp_f32_e32 v144, v144
	v_exp_f32_e32 v133, v133
	v_exp_f32_e32 v135, v135
	v_exp_f32_e32 v137, v137
	v_exp_f32_e32 v139, v139
	v_add_f32_e32 v142, 1.0, v142
	v_rcp_f32_e32 v145, v142
	v_add_f32_e32 v142, 1.0, v143
	v_add_f32_e32 v141, 1.0, v141
	v_rcp_f32_e32 v146, v142
	v_add_f32_e32 v142, 1.0, v144
	v_add_f32_e32 v133, 1.0, v133
	v_add_f32_e32 v135, 1.0, v135
	v_add_f32_e32 v137, 1.0, v137
	v_add_f32_e32 v139, 1.0, v139
	v_rcp_f32_e32 v141, v141
	v_rcp_f32_e32 v147, v142
	v_rcp_f32_e32 v133, v133
	v_rcp_f32_e32 v135, v135
	v_rcp_f32_e32 v137, v137
	v_rcp_f32_e32 v139, v139
	v_cvt_pk_bf16_f32 v144, v141, v145
	v_cvt_pk_bf16_f32 v145, v146, v147
	v_add_co_u32_e32 v146, vcc, s67, v130
	v_cvt_pk_bf16_f32 v142, v133, v135
	v_cvt_pk_bf16_f32 v143, v137, v139
	v_addc_co_u32_e32 v147, vcc, 0, v131, vcc
	global_store_dwordx4 v[146:147], v[142:145], off
	v_pk_mul_f32 v[148:149], v[66:67], v[140:141] op_sel_hi:[1,0]
	s_nop 0
	v_pk_mul_f32 v[142:143], v[70:71], v[140:141] op_sel_hi:[1,0]
	v_pk_mul_f32 v[144:145], v[68:69], v[140:141] op_sel_hi:[1,0]
	v_pk_mul_f32 v[140:141], v[64:65], v[140:141] op_sel_hi:[1,0]
	v_mul_f32_e32 v137, 0xbfb8aa3b, v142
	v_mul_f32_e32 v140, 0xbfb8aa3b, v140
	v_exp_f32_e32 v140, v140
	v_mul_f32_e32 v141, 0xbfb8aa3b, v141
	v_exp_f32_e32 v141, v141
	v_mul_f32_e32 v133, 0xbfb8aa3b, v144
	v_add_f32_e32 v140, 1.0, v140
	v_rcp_f32_e32 v142, v140
	v_add_f32_e32 v140, 1.0, v141
	v_mul_f32_e32 v141, 0xbfb8aa3b, v148
	v_mul_f32_e32 v135, 0xbfb8aa3b, v145
	v_mul_f32_e32 v139, 0xbfb8aa3b, v143
	v_exp_f32_e32 v141, v141
	v_mul_f32_e32 v143, 0xbfb8aa3b, v149
	v_exp_f32_e32 v133, v133
	v_exp_f32_e32 v135, v135
	v_exp_f32_e32 v137, v137
	v_exp_f32_e32 v139, v139
	v_exp_f32_e32 v143, v143
	v_rcp_f32_e32 v144, v140
	v_add_f32_e32 v140, 1.0, v141
	v_add_f32_e32 v133, 1.0, v133
	v_add_f32_e32 v135, 1.0, v135
	v_add_f32_e32 v137, 1.0, v137
	v_add_f32_e32 v139, 1.0, v139
	v_rcp_f32_e32 v145, v140
	v_add_f32_e32 v140, 1.0, v143
	v_rcp_f32_e32 v133, v133
	v_rcp_f32_e32 v135, v135
	v_rcp_f32_e32 v137, v137
	v_rcp_f32_e32 v139, v139
	v_rcp_f32_e32 v143, v140
	v_cvt_pk_bf16_f32 v140, v133, v135
	v_cvt_pk_bf16_f32 v142, v142, v144
	v_cvt_pk_bf16_f32 v141, v137, v139
	v_cvt_pk_bf16_f32 v143, v145, v143
	global_store_dwordx4 v[146:147], v[140:143], off offset:256
	v_pk_mul_f32 v[144:145], v[58:59], v[138:139] op_sel_hi:[1,0]
	s_nop 0
	v_pk_mul_f32 v[142:143], v[60:61], v[138:139] op_sel_hi:[1,0]
	v_pk_mul_f32 v[140:141], v[62:63], v[138:139] op_sel_hi:[1,0]
	v_mul_f32_e32 v133, 0xbfb8aa3b, v142
	v_mul_f32_e32 v135, 0xbfb8aa3b, v143
	v_pk_mul_f32 v[142:143], v[56:57], v[138:139] op_sel_hi:[1,0]
	v_mul_f32_e32 v137, 0xbfb8aa3b, v140
	v_mul_f32_e32 v140, 0xbfb8aa3b, v142
	v_mul_f32_e32 v139, 0xbfb8aa3b, v141
	v_exp_f32_e32 v140, v140
	v_mul_f32_e32 v141, 0xbfb8aa3b, v143
	v_exp_f32_e32 v141, v141
	v_mul_f32_e32 v143, 0xbfb8aa3b, v145
	v_add_f32_e32 v140, 1.0, v140
	v_rcp_f32_e32 v142, v140
	v_add_f32_e32 v140, 1.0, v141
	v_mul_f32_e32 v141, 0xbfb8aa3b, v144
	v_exp_f32_e32 v141, v141
	v_exp_f32_e32 v133, v133
	v_exp_f32_e32 v135, v135
	v_exp_f32_e32 v137, v137
	v_exp_f32_e32 v139, v139
	v_exp_f32_e32 v143, v143
	v_rcp_f32_e32 v144, v140
	v_add_f32_e32 v140, 1.0, v141
	v_add_f32_e32 v133, 1.0, v133
	v_add_f32_e32 v135, 1.0, v135
	v_add_f32_e32 v137, 1.0, v137
	v_add_f32_e32 v139, 1.0, v139
	v_rcp_f32_e32 v145, v140
	v_add_f32_e32 v140, 1.0, v143
	v_rcp_f32_e32 v133, v133
	v_rcp_f32_e32 v135, v135
	v_rcp_f32_e32 v137, v137
	v_rcp_f32_e32 v139, v139
	v_rcp_f32_e32 v143, v140
	v_cvt_pk_bf16_f32 v142, v142, v144
	v_add_co_u32_e32 v144, vcc, s62, v130
	v_cvt_pk_bf16_f32 v140, v133, v135
	v_cvt_pk_bf16_f32 v141, v137, v139
	v_cvt_pk_bf16_f32 v143, v145, v143
	v_addc_co_u32_e32 v145, vcc, 0, v131, vcc
	global_store_dwordx4 v[144:145], v[140:143], off
	v_pk_mul_f32 v[146:147], v[50:51], v[138:139] op_sel_hi:[1,0]
	s_nop 0
	v_pk_mul_f32 v[140:141], v[54:55], v[138:139] op_sel_hi:[1,0]
	v_pk_mul_f32 v[142:143], v[52:53], v[138:139] op_sel_hi:[1,0]
	v_pk_mul_f32 v[138:139], v[48:49], v[138:139] op_sel_hi:[1,0]
	v_mul_f32_e32 v137, 0xbfb8aa3b, v140
	v_mul_f32_e32 v138, 0xbfb8aa3b, v138
	v_exp_f32_e32 v138, v138
	v_mul_f32_e32 v139, 0xbfb8aa3b, v139
	v_exp_f32_e32 v139, v139
	v_mul_f32_e32 v140, 0xbfb8aa3b, v141
	v_add_f32_e32 v138, 1.0, v138
	v_rcp_f32_e32 v141, v138
	v_add_f32_e32 v138, 1.0, v139
	v_mul_f32_e32 v139, 0xbfb8aa3b, v146
	v_mul_f32_e32 v133, 0xbfb8aa3b, v142
	v_mul_f32_e32 v135, 0xbfb8aa3b, v143
	v_exp_f32_e32 v139, v139
	v_mul_f32_e32 v142, 0xbfb8aa3b, v147
	v_exp_f32_e32 v133, v133
	v_exp_f32_e32 v135, v135
	v_exp_f32_e32 v137, v137
	v_exp_f32_e32 v140, v140
	v_exp_f32_e32 v142, v142
	v_rcp_f32_e32 v143, v138
	v_add_f32_e32 v138, 1.0, v139
	v_add_f32_e32 v133, 1.0, v133
	v_add_f32_e32 v135, 1.0, v135
	v_add_f32_e32 v137, 1.0, v137
	v_add_f32_e32 v140, 1.0, v140
	v_rcp_f32_e32 v146, v138
	v_add_f32_e32 v138, 1.0, v142
	v_rcp_f32_e32 v133, v133
	v_rcp_f32_e32 v135, v135
	v_rcp_f32_e32 v137, v137
	v_rcp_f32_e32 v140, v140
	v_rcp_f32_e32 v142, v138
	v_cvt_pk_bf16_f32 v138, v133, v135
	v_cvt_pk_bf16_f32 v139, v137, v140
	v_cvt_pk_bf16_f32 v140, v141, v143
	v_cvt_pk_bf16_f32 v141, v146, v142
	global_store_dwordx4 v[144:145], v[138:141], off offset:256
	v_pk_mul_f32 v[142:143], v[42:43], v[136:137] op_sel_hi:[1,0]
	s_nop 0
	v_pk_mul_f32 v[138:139], v[46:47], v[136:137] op_sel_hi:[1,0]
; DI unsigned pk_bf16(float lo, float hi) { f32x2 v = {lo, hi}; return __builtin_bit_cast(unsigned, __builtin_convertvector(v, bf16v2)); }
; DI float fast_sigmoid(float x) { return __builtin_amdgcn_rcpf(1.0f + __expf(-x)); }
;     DI void operator()(AccRef acc, const Unit& u, int wr, int wc, int fr, int fq) const {
;     ...
;         for (int ai = 0; ai < 2; ++ai)
; #pragma unroll
;             for (int m = 0; m < 4; ++m)
; #pragma unroll
;                 for (int bj = 0; bj < 2; ++bj) {
;                     const float rs = rsc.r[ai][m];
;                     const f32x4 r0 = acc[ai][bj][m][0] * rs, r1 = acc[ai][bj][m][1] * rs;
;                     u32x4 w;
;                     w.x = pk_bf16(fast_sigmoid(r0[0]), fast_sigmoid(r0[1])); w.y = pk_bf16(fast_sigmoid(r0[2]), fast_sigmoid(r0[3]));
;                     w.z = pk_bf16(fast_sigmoid(r1[0]), fast_sigmoid(r1[1])); w.w = pk_bf16(fast_sigmoid(r1[2]), fast_sigmoid(r1[3]));
;                     *(u32x4*)(Gp + (ai * 128 + m * 16) * 256 + bj * 128) = w;
	v_pk_mul_f32 v[140:141], v[44:45], v[136:137] op_sel_hi:[1,0]
	s_nop 0
	v_mul_f32_e32 v133, 0xbfb8aa3b, v140
	v_mul_f32_e32 v135, 0xbfb8aa3b, v141
	v_pk_mul_f32 v[140:141], v[40:41], v[136:137] op_sel_hi:[1,0]
	v_mul_f32_e32 v137, 0xbfb8aa3b, v138
	v_mul_f32_e32 v138, 0xbfb8aa3b, v139
	v_exp_f32_e32 v138, v138
	v_mul_f32_e32 v139, 0xbfb8aa3b, v140
	v_exp_f32_e32 v139, v139
	v_mul_f32_e32 v140, 0xbfb8aa3b, v141
	v_exp_f32_e32 v140, v140
	v_add_f32_e32 v138, 1.0, v138
	v_rcp_f32_e32 v141, v138
	v_add_f32_e32 v138, 1.0, v139
	v_mul_f32_e32 v139, 0xbfb8aa3b, v142
	v_rcp_f32_e32 v144, v138
	v_add_f32_e32 v138, 1.0, v140
	v_exp_f32_e32 v139, v139
	v_mul_f32_e32 v140, 0xbfb8aa3b, v143
	v_exp_f32_e32 v133, v133
	v_exp_f32_e32 v135, v135
	v_exp_f32_e32 v137, v137
	v_exp_f32_e32 v140, v140
	v_rcp_f32_e32 v142, v138
	v_add_f32_e32 v138, 1.0, v139
	v_add_f32_e32 v133, 1.0, v133
	v_add_f32_e32 v135, 1.0, v135
	v_add_f32_e32 v137, 1.0, v137
	v_rcp_f32_e32 v143, v138
	v_add_f32_e32 v138, 1.0, v140
	v_rcp_f32_e32 v133, v133
	v_rcp_f32_e32 v135, v135
	v_rcp_f32_e32 v137, v137
	v_rcp_f32_e32 v145, v138
	v_cvt_pk_bf16_f32 v140, v144, v142
	v_add_co_u32_e32 v142, vcc, s63, v130
	v_cvt_pk_bf16_f32 v138, v133, v135
	v_cvt_pk_bf16_f32 v139, v137, v141
	v_cvt_pk_bf16_f32 v141, v143, v145
	v_addc_co_u32_e32 v143, vcc, 0, v131, vcc
	global_store_dwordx4 v[142:143], v[138:141], off
	v_pk_mul_f32 v[144:145], v[34:35], v[136:137] op_sel_hi:[1,0]
	s_nop 0
	v_pk_mul_f32 v[138:139], v[38:39], v[136:137] op_sel_hi:[1,0]
	v_pk_mul_f32 v[140:141], v[36:37], v[136:137] op_sel_hi:[1,0]
	v_pk_mul_f32 v[136:137], v[32:33], v[136:137] op_sel_hi:[1,0]
	v_mul_f32_e32 v133, 0xbfb8aa3b, v140
	v_mul_f32_e32 v136, 0xbfb8aa3b, v136
	v_exp_f32_e32 v136, v136
	v_mul_f32_e32 v137, 0xbfb8aa3b, v137
	v_exp_f32_e32 v137, v137
	v_mul_f32_e32 v135, 0xbfb8aa3b, v141
	v_add_f32_e32 v136, 1.0, v136
	v_rcp_f32_e32 v140, v136
	v_add_f32_e32 v136, 1.0, v137
	v_mul_f32_e32 v137, 0xbfb8aa3b, v144
	v_mul_f32_e32 v138, 0xbfb8aa3b, v138
	v_mul_f32_e32 v139, 0xbfb8aa3b, v139
	v_exp_f32_e32 v137, v137
	v_mul_f32_e32 v141, 0xbfb8aa3b, v145
	v_exp_f32_e32 v133, v133
	v_exp_f32_e32 v135, v135
	v_exp_f32_e32 v138, v138
	v_exp_f32_e32 v139, v139
	v_exp_f32_e32 v141, v141
	v_rcp_f32_e32 v144, v136
	v_add_f32_e32 v136, 1.0, v137
	v_add_f32_e32 v133, 1.0, v133
	v_add_f32_e32 v135, 1.0, v135
	v_add_f32_e32 v138, 1.0, v138
	v_add_f32_e32 v139, 1.0, v139
	v_rcp_f32_e32 v145, v136
	v_add_f32_e32 v136, 1.0, v141
	v_rcp_f32_e32 v133, v133
	v_rcp_f32_e32 v135, v135
	v_rcp_f32_e32 v138, v138
	v_rcp_f32_e32 v139, v139
	v_rcp_f32_e32 v141, v136
	v_cvt_pk_bf16_f32 v136, v133, v135
	v_cvt_pk_bf16_f32 v137, v138, v139
	v_cvt_pk_bf16_f32 v138, v140, v144
	v_cvt_pk_bf16_f32 v139, v145, v141
	global_store_dwordx4 v[142:143], v[136:139], off offset:256
	v_pk_mul_f32 v[140:141], v[26:27], v[134:135] op_sel_hi:[1,0]
	s_nop 0
	v_pk_mul_f32 v[136:137], v[30:31], v[134:135] op_sel_hi:[1,0]
	v_pk_mul_f32 v[138:139], v[28:29], v[134:135] op_sel_hi:[1,0]
	v_mul_f32_e32 v136, 0xbfb8aa3b, v136
	v_mul_f32_e32 v135, 0xbfb8aa3b, v139
	v_exp_f32_e32 v135, v135
	v_exp_f32_e32 v136, v136
	v_mul_f32_e32 v137, 0xbfb8aa3b, v137
	v_exp_f32_e32 v137, v137
	v_mul_f32_e32 v133, 0xbfb8aa3b, v138
	v_pk_mul_f32 v[138:139], v[24:25], v[134:135] op_sel_hi:[1,0]
	v_add_f32_e32 v136, 1.0, v136
	v_rcp_f32_e32 v142, v136
	v_add_f32_e32 v136, 1.0, v137
	v_mul_f32_e32 v137, 0xbfb8aa3b, v138
	v_exp_f32_e32 v137, v137
	v_mul_f32_e32 v138, 0xbfb8aa3b, v139
	v_exp_f32_e32 v138, v138
	v_rcp_f32_e32 v139, v136
	v_add_f32_e32 v136, 1.0, v137
	v_mul_f32_e32 v137, 0xbfb8aa3b, v140
	v_rcp_f32_e32 v143, v136
	v_add_f32_e32 v136, 1.0, v138
	v_exp_f32_e32 v137, v137
	v_mul_f32_e32 v138, 0xbfb8aa3b, v141
	v_exp_f32_e32 v133, v133
	v_exp_f32_e32 v138, v138
	v_rcp_f32_e32 v140, v136
	v_add_f32_e32 v136, 1.0, v137
	v_add_f32_e32 v133, 1.0, v133
	v_add_f32_e32 v135, 1.0, v135
	v_rcp_f32_e32 v141, v136
	v_add_f32_e32 v136, 1.0, v138
	v_rcp_f32_e32 v133, v133
	v_rcp_f32_e32 v135, v135
	v_rcp_f32_e32 v144, v136
	v_cvt_pk_bf16_f32 v138, v143, v140
	v_add_co_u32_e32 v140, vcc, s64, v130
	v_cvt_pk_bf16_f32 v136, v133, v135
	v_cvt_pk_bf16_f32 v137, v142, v139
	v_cvt_pk_bf16_f32 v139, v141, v144
	v_addc_co_u32_e32 v141, vcc, 0, v131, vcc
	global_store_dwordx4 v[140:141], v[136:139], off
; DI unsigned pk_bf16(float lo, float hi) { f32x2 v = {lo, hi}; return __builtin_bit_cast(unsigned, __builtin_convertvector(v, bf16v2)); }
; DI float fast_sigmoid(float x) { return __builtin_amdgcn_rcpf(1.0f + __expf(-x)); }
;     DI void operator()(AccRef acc, const Unit& u, int wr, int wc, int fr, int fq) const {
;     ...
;         for (int ai = 0; ai < 2; ++ai)
; #pragma unroll
;             for (int m = 0; m < 4; ++m)
; #pragma unroll
;                 for (int bj = 0; bj < 2; ++bj) {
;                     const float rs = rsc.r[ai][m];
;                     const f32x4 r0 = acc[ai][bj][m][0] * rs, r1 = acc[ai][bj][m][1] * rs;
;                     u32x4 w;
;                     w.x = pk_bf16(fast_sigmoid(r0[0]), fast_sigmoid(r0[1])); w.y = pk_bf16(fast_sigmoid(r0[2]), fast_sigmoid(r0[3]));
;                     w.z = pk_bf16(fast_sigmoid(r1[0]), fast_sigmoid(r1[1])); w.w = pk_bf16(fast_sigmoid(r1[2]), fast_sigmoid(r1[3]));
;                     *(u32x4*)(Gp + (ai * 128 + m * 16) * 256 + bj * 128) = w;
	v_pk_mul_f32 v[142:143], v[18:19], v[134:135] op_sel_hi:[1,0]
	s_nop 0
	v_pk_mul_f32 v[138:139], v[20:21], v[134:135] op_sel_hi:[1,0]
	v_pk_mul_f32 v[136:137], v[22:23], v[134:135] op_sel_hi:[1,0]
	v_mul_f32_e32 v135, 0xbfb8aa3b, v139
	v_mul_f32_e32 v133, 0xbfb8aa3b, v138
	v_exp_f32_e32 v138, v135
	v_pk_mul_f32 v[134:135], v[16:17], v[134:135] op_sel_hi:[1,0]
	v_mul_f32_e32 v136, 0xbfb8aa3b, v136
	v_mul_f32_e32 v134, 0xbfb8aa3b, v134
	v_exp_f32_e32 v134, v134
	v_mul_f32_e32 v135, 0xbfb8aa3b, v135
	v_exp_f32_e32 v135, v135
	v_mul_f32_e32 v137, 0xbfb8aa3b, v137
	v_add_f32_e32 v134, 1.0, v134
	v_rcp_f32_e32 v139, v134
	v_add_f32_e32 v134, 1.0, v135
	v_mul_f32_e32 v135, 0xbfb8aa3b, v142
	v_exp_f32_e32 v135, v135
	v_mul_f32_e32 v142, 0xbfb8aa3b, v143
	v_exp_f32_e32 v133, v133
	v_exp_f32_e32 v136, v136
	v_exp_f32_e32 v137, v137
	v_exp_f32_e32 v142, v142
	v_rcp_f32_e32 v143, v134
	v_add_f32_e32 v134, 1.0, v135
	v_add_f32_e32 v133, 1.0, v133
	v_add_f32_e32 v138, 1.0, v138
	v_add_f32_e32 v136, 1.0, v136
	v_add_f32_e32 v137, 1.0, v137
	v_rcp_f32_e32 v144, v134
	v_add_f32_e32 v134, 1.0, v142
	v_rcp_f32_e32 v133, v133
	v_rcp_f32_e32 v138, v138
	v_rcp_f32_e32 v136, v136
	v_rcp_f32_e32 v137, v137
	v_rcp_f32_e32 v142, v134
	v_cvt_pk_bf16_f32 v134, v133, v138
	v_cvt_pk_bf16_f32 v135, v136, v137
	v_cvt_pk_bf16_f32 v136, v139, v143
	v_cvt_pk_bf16_f32 v137, v144, v142
	global_store_dwordx4 v[140:141], v[134:137], off offset:256
	v_pk_mul_f32 v[138:139], v[10:11], v[132:133] op_sel_hi:[1,0]
	s_nop 0
	v_pk_mul_f32 v[134:135], v[14:15], v[132:133] op_sel_hi:[1,0]
	v_pk_mul_f32 v[136:137], v[12:13], v[132:133] op_sel_hi:[1,0]
	v_mul_f32_e32 v134, 0xbfb8aa3b, v134
	v_mul_f32_e32 v133, 0xbfb8aa3b, v136
	v_exp_f32_e32 v133, v133
	v_exp_f32_e32 v134, v134
	v_mul_f32_e32 v135, 0xbfb8aa3b, v135
	v_exp_f32_e32 v135, v135
	v_mul_f32_e32 v136, 0xbfb8aa3b, v137
	v_exp_f32_e32 v140, v136
	v_pk_mul_f32 v[136:137], v[8:9], v[132:133] op_sel_hi:[1,0]
	v_add_f32_e32 v134, 1.0, v134
	v_rcp_f32_e32 v141, v134
	v_add_f32_e32 v134, 1.0, v135
	v_mul_f32_e32 v135, 0xbfb8aa3b, v136
	v_exp_f32_e32 v135, v135
	v_mul_f32_e32 v136, 0xbfb8aa3b, v137
	v_exp_f32_e32 v136, v136
	v_rcp_f32_e32 v137, v134
	v_add_f32_e32 v134, 1.0, v135
	v_mul_f32_e32 v135, 0xbfb8aa3b, v138
	v_rcp_f32_e32 v142, v134
	v_add_f32_e32 v134, 1.0, v136
	v_exp_f32_e32 v135, v135
	v_mul_f32_e32 v136, 0xbfb8aa3b, v139
	v_exp_f32_e32 v136, v136
	v_rcp_f32_e32 v138, v134
	v_add_f32_e32 v134, 1.0, v135
	v_add_f32_e32 v133, 1.0, v133
	v_rcp_f32_e32 v139, v134
	v_add_f32_e32 v134, 1.0, v136
	v_rcp_f32_e32 v133, v133
	v_rcp_f32_e32 v143, v134
	v_add_f32_e32 v140, 1.0, v140
	v_rcp_f32_e32 v140, v140
	v_cvt_pk_bf16_f32 v136, v142, v138
	v_add_co_u32_e32 v138, vcc, s65, v130
	v_cvt_pk_bf16_f32 v135, v141, v137
	v_cvt_pk_bf16_f32 v137, v139, v143
	v_addc_co_u32_e32 v139, vcc, 0, v131, vcc
	v_pk_mul_f32 v[130:131], v[6:7], v[132:133] op_sel_hi:[1,0]
	v_cvt_pk_bf16_f32 v134, v133, v140
	v_mul_f32_e32 v130, 0xbfb8aa3b, v130
	v_exp_f32_e32 v130, v130
	v_mul_f32_e32 v131, 0xbfb8aa3b, v131
	global_store_dwordx4 v[138:139], v[134:137], off
	v_exp_f32_e32 v131, v131
	v_add_f32_e32 v130, 1.0, v130
	v_pk_mul_f32 v[134:135], v[4:5], v[132:133] op_sel_hi:[1,0]
	v_pk_mul_f32 v[136:137], v[2:3], v[132:133] op_sel_hi:[1,0]
	v_mul_f32_e32 v133, 0xbfb8aa3b, v134
	v_exp_f32_e32 v134, v133
	v_mul_f32_e32 v133, 0xbfb8aa3b, v135
	v_exp_f32_e32 v135, v133
	v_pk_mul_f32 v[132:133], v[0:1], v[132:133] op_sel_hi:[1,0]
	v_rcp_f32_e32 v140, v130
	v_add_f32_e32 v130, 1.0, v131
	v_mul_f32_e32 v131, 0xbfb8aa3b, v132
	v_exp_f32_e32 v131, v131
	v_mul_f32_e32 v132, 0xbfb8aa3b, v133
	v_exp_f32_e32 v132, v132
	v_rcp_f32_e32 v133, v130
	v_add_f32_e32 v130, 1.0, v131
	v_mul_f32_e32 v131, 0xbfb8aa3b, v136
	v_rcp_f32_e32 v141, v130
	v_add_f32_e32 v130, 1.0, v132
	v_exp_f32_e32 v131, v131
	v_mul_f32_e32 v132, 0xbfb8aa3b, v137
	v_exp_f32_e32 v132, v132
	v_rcp_f32_e32 v136, v130
	v_add_f32_e32 v130, 1.0, v131
	v_add_f32_e32 v134, 1.0, v134
	v_add_f32_e32 v135, 1.0, v135
	v_rcp_f32_e32 v137, v130
	v_add_f32_e32 v130, 1.0, v132
	v_rcp_f32_e32 v134, v134
	v_rcp_f32_e32 v135, v135
	v_rcp_f32_e32 v142, v130
	v_cvt_pk_bf16_f32 v131, v140, v133
	v_cvt_pk_bf16_f32 v132, v141, v136
	v_cvt_pk_bf16_f32 v130, v134, v135
	v_cvt_pk_bf16_f32 v133, v137, v142
	global_store_dwordx4 v[138:139], v[130:133], off offset:256

; #define PG8_STAGE(bufoff, gbase, voff) do { _Pragma("unroll") for (int _i = 0; _i < 2; ++_i) \
;         __builtin_amdgcn_global_load_lds((const unsigned*)((const char*)(gbase) + (voff)[_i]), (LAS unsigned*)(lds + (bufoff) + ldsw + _i * 8192), 16, 0, 0); } while (0)
; #define PG8_LDA(dst, b, h) do { _Pragma("unroll") for (int m = 0; m < 4; ++m) _Pragma("unroll") for (int k = 0; k < 2; ++k) dst[m][k] = *(const LAS bf16x8*)(lds + PG8_SA(b, h) + aoff + m * 2048 + k * 1024); } while (0)
; #define PG8_LDB(dst, b, h) do { _Pragma("unroll") for (int n = 0; n < 2; ++n) _Pragma("unroll") for (int k = 0; k < 2; ++k) dst[n][k] = *(const LAS bf16x8*)(lds + PG8_SB(b, h) + boff + n * 2048 + k * 1024); } while (0)
; #define PG8_WAIT_V(n) asm volatile("s_waitcnt vmcnt(" #n ")" ::: "memory")
; #define PG8_WAIT_L(n) asm volatile("s_waitcnt lgkmcnt(" #n ")" ::: "memory")
; #define PG8_BAR __builtin_amdgcn_s_barrier()
; #define PG8_SCHED __builtin_amdgcn_sched_barrier(0)
; template <class Epi0, class Epi1>
; DI void gemm_phase_dual(LAS unsigned char* lds, const Gemm g, const Gemm g1, const StaticOrder S, const Epi0 E0, const Epi1 E1) {
;     ...
;             PG8_LDB(B0, 0, 0); PG8_SCHED; PG8_LDA(At, 0, 0); PG8_STAGE(PG8_SA(1, 1), a1 + hstep, voffA);
;             PG8_WAIT_L(8); PG8_BAR; PG8_WAIT_L(0); PG8_MMA(0, 0, At, B0); PG8_BAR; PG8_SCHED;
;             PG8_LDB(B1, 0, 1); PG8_STAGE(PG8_SB(0, 0), b2, voffB);
;             PG8_BAR; PG8_WAIT_L(0); PG8_MMA(0, 1, At, B1); PG8_BAR;
;             PG8_LDA(At, 0, 1); PG8_STAGE(PG8_SA(0, 0), a2, voffA);
;             PG8_BAR; PG8_WAIT_L(0); PG8_MMA(1, 0, At, B0); PG8_BAR; PG8_SCHED;
;             PG8_STAGE(PG8_SB(0, 1), b2 + hstep, voffB);
;             PG8_WAIT_V(6); PG8_BAR; PG8_MMA(1, 1, At, B1); PG8_BAR;
;             PG8_LDB(B0, 1, 0); PG8_SCHED; PG8_LDA(At, 1, 0); PG8_STAGE(PG8_SA(0, 1), a2 + hstep, voffA);
;             PG8_WAIT_L(8); PG8_BAR; PG8_WAIT_L(0); PG8_MMA(0, 0, At, B0); PG8_BAR; PG8_SCHED;
;             PG8_LDB(B1, 1, 1); PG8_STAGE(PG8_SB(1, 0), b3, voffB);
;             PG8_BAR; PG8_WAIT_L(0); PG8_MMA(0, 1, At, B1); PG8_BAR;
;             PG8_LDA(At, 1, 1); PG8_STAGE(PG8_SA(1, 0), a3, voffA);
;             PG8_BAR; PG8_WAIT_L(0); PG8_MMA(1, 0, At, B0); PG8_BAR; PG8_SCHED;
;             PG8_STAGE(PG8_SB(1, 1), b3 + hstep, voffB);
;             PG8_WAIT_V(6); PG8_BAR; PG8_MMA(1, 1, At, B1); PG8_BAR;
.LBB0_708:
	ds_read_b128 v[156:159], v179
	ds_read_b128 v[160:163], v179 offset:1024
	ds_read_b128 v[164:167], v179 offset:2048
	ds_read_b128 v[168:171], v179 offset:3072
	s_add_u32 s40, s38, 0xfffc0080
	s_addc_u32 s41, s39, -1
	s_cmp_eq_u32 s69, 12
	s_cselect_b32 s43, s6, s41
	s_cselect_b32 s42, s7, s40
	s_cselect_b32 s41, s17, s68
	s_cselect_b32 s40, s19, s67
	v_lshl_add_u64 v[210:211], s[38:39], 0, v[148:149]
	s_add_i32 m0, s25, 0xc000
	ds_read_b128 v[172:175], v180
	ds_read_b128 v[182:185], v180 offset:1024
	ds_read_b128 v[186:189], v180 offset:2048
	ds_read_b128 v[190:193], v180 offset:3072
	ds_read_b128 v[194:197], v180 offset:4096
	ds_read_b128 v[198:201], v180 offset:5120
	ds_read_b128 v[202:205], v180 offset:6144
	ds_read_b128 v[206:209], v180 offset:7168
	global_load_lds_dwordx4 v[210:211], off
	v_lshl_add_u64 v[210:211], s[38:39], 0, v[150:151]
	s_add_i32 m0, s25, 0xe000
	s_nop 0
	global_load_lds_dwordx4 v[210:211], off
	s_waitcnt lgkmcnt(8)
	s_setprio 1
	s_barrier
	s_waitcnt lgkmcnt(0)
	v_mfma_f32_16x16x32_bf16 v[124:127], v[156:159], v[172:175], v[124:127]
	v_mfma_f32_16x16x32_bf16 v[120:123], v[164:167], v[172:175], v[120:123]
	v_mfma_f32_16x16x32_bf16 v[108:111], v[156:159], v[186:189], v[108:111]
	v_mfma_f32_16x16x32_bf16 v[104:107], v[164:167], v[186:189], v[104:107]
	v_mfma_f32_16x16x32_bf16 v[92:95], v[156:159], v[194:197], v[92:95]
	v_mfma_f32_16x16x32_bf16 v[88:91], v[164:167], v[194:197], v[88:91]
	v_mfma_f32_16x16x32_bf16 v[84:87], v[156:159], v[202:205], v[84:87]
	v_mfma_f32_16x16x32_bf16 v[80:83], v[164:167], v[202:205], v[80:83]
	v_mfma_f32_16x16x32_bf16 v[124:127], v[160:163], v[182:185], v[124:127]
	v_mfma_f32_16x16x32_bf16 v[120:123], v[168:171], v[182:185], v[120:123]
	v_mfma_f32_16x16x32_bf16 v[108:111], v[160:163], v[190:193], v[108:111]
	v_mfma_f32_16x16x32_bf16 v[104:107], v[168:171], v[190:193], v[104:107]
	v_mfma_f32_16x16x32_bf16 v[92:95], v[160:163], v[198:201], v[92:95]
	v_mfma_f32_16x16x32_bf16 v[88:91], v[168:171], v[198:201], v[88:91]
	s_setprio 2
	s_barrier
	v_mfma_f32_16x16x32_bf16 v[84:87], v[160:163], v[206:209], v[84:87]
	v_mfma_f32_16x16x32_bf16 v[80:83], v[168:171], v[206:209], v[80:83]
	s_setprio 0
	s_add_i32 s76, s52, s44
	v_lshl_add_u64 v[228:229], s[40:41], 0, v[130:131]
	s_mov_b32 m0, s76
	ds_read_b128 v[210:213], v181
	ds_read_b128 v[214:217], v181 offset:1024
	ds_read_b128 v[218:221], v181 offset:2048
	ds_read_b128 v[224:227], v181 offset:3072
	global_load_lds_dwordx4 v[228:229], off
	v_lshl_add_u64 v[230:231], s[40:41], 0, v[134:135]
	s_add_i32 m0, s76, 0x2000
	s_nop 0
	global_load_lds_dwordx4 v[230:231], off
	s_setprio 1
	s_barrier
	s_waitcnt lgkmcnt(0)
	v_mfma_f32_16x16x32_bf16 v[116:119], v[210:213], v[172:175], v[116:119]
	v_mfma_f32_16x16x32_bf16 v[112:115], v[218:221], v[172:175], v[112:115]
	v_mfma_f32_16x16x32_bf16 v[100:103], v[210:213], v[186:189], v[100:103]
	v_mfma_f32_16x16x32_bf16 v[96:99], v[218:221], v[186:189], v[96:99]
	v_mfma_f32_16x16x32_bf16 v[76:79], v[210:213], v[194:197], v[76:79]
	v_mfma_f32_16x16x32_bf16 v[72:75], v[218:221], v[194:197], v[72:75]
	v_mfma_f32_16x16x32_bf16 v[68:71], v[210:213], v[202:205], v[68:71]
	v_mfma_f32_16x16x32_bf16 v[64:67], v[218:221], v[202:205], v[64:67]
	v_mfma_f32_16x16x32_bf16 v[116:119], v[214:217], v[182:185], v[116:119]
	v_mfma_f32_16x16x32_bf16 v[112:115], v[224:227], v[182:185], v[112:115]
	v_mfma_f32_16x16x32_bf16 v[100:103], v[214:217], v[190:193], v[100:103]
	v_mfma_f32_16x16x32_bf16 v[96:99], v[224:227], v[190:193], v[96:99]
	v_mfma_f32_16x16x32_bf16 v[76:79], v[214:217], v[198:201], v[76:79]
	v_mfma_f32_16x16x32_bf16 v[72:75], v[224:227], v[198:201], v[72:75]
	s_setprio 2
	s_barrier
	v_mfma_f32_16x16x32_bf16 v[68:71], v[214:217], v[206:209], v[68:71]
	v_mfma_f32_16x16x32_bf16 v[64:67], v[224:227], v[206:209], v[64:67]
	s_setprio 0
	s_mov_b32 m0, s25
	v_lshl_add_u64 v[232:233], s[42:43], 0, v[128:129]
	ds_read_b128 v[172:175], v180 offset:16384
	ds_read_b128 v[182:185], v180 offset:17408
	ds_read_b128 v[186:189], v180 offset:18432
	ds_read_b128 v[190:193], v180 offset:19456
	ds_read_b128 v[194:197], v180 offset:20480
	ds_read_b128 v[198:201], v180 offset:21504
	ds_read_b128 v[202:205], v180 offset:22528
	ds_read_b128 v[206:209], v180 offset:23552
	global_load_lds_dwordx4 v[232:233], off
	v_lshl_add_u64 v[234:235], s[42:43], 0, v[132:133]
	s_mov_b32 m0, s45
	s_nop 0
	global_load_lds_dwordx4 v[234:235], off
	s_setprio 1
	s_barrier
	s_waitcnt lgkmcnt(0)
	v_mfma_f32_16x16x32_bf16 v[60:63], v[156:159], v[172:175], v[60:63]
	v_mfma_f32_16x16x32_bf16 v[56:59], v[164:167], v[172:175], v[56:59]
	v_mfma_f32_16x16x32_bf16 v[52:55], v[156:159], v[186:189], v[52:55]
	v_mfma_f32_16x16x32_bf16 v[48:51], v[164:167], v[186:189], v[48:51]
	v_mfma_f32_16x16x32_bf16 v[28:31], v[156:159], v[194:197], v[28:31]
	v_mfma_f32_16x16x32_bf16 v[24:27], v[164:167], v[194:197], v[24:27]
	v_mfma_f32_16x16x32_bf16 v[20:23], v[156:159], v[202:205], v[20:23]
	v_mfma_f32_16x16x32_bf16 v[16:19], v[164:167], v[202:205], v[16:19]
	v_mfma_f32_16x16x32_bf16 v[60:63], v[160:163], v[182:185], v[60:63]
	v_mfma_f32_16x16x32_bf16 v[56:59], v[168:171], v[182:185], v[56:59]
	v_mfma_f32_16x16x32_bf16 v[52:55], v[160:163], v[190:193], v[52:55]
	v_mfma_f32_16x16x32_bf16 v[48:51], v[168:171], v[190:193], v[48:51]
	v_mfma_f32_16x16x32_bf16 v[28:31], v[160:163], v[198:201], v[28:31]
	v_mfma_f32_16x16x32_bf16 v[24:27], v[168:171], v[198:201], v[24:27]
	s_setprio 2
	s_barrier
; #define PG8_STAGE(bufoff, gbase, voff) do { _Pragma("unroll") for (int _i = 0; _i < 2; ++_i) \
;         __builtin_amdgcn_global_load_lds((const unsigned*)((const char*)(gbase) + (voff)[_i]), (LAS unsigned*)(lds + (bufoff) + ldsw + _i * 8192), 16, 0, 0); } while (0)
; #define PG8_LDA(dst, b, h) do { _Pragma("unroll") for (int m = 0; m < 4; ++m) _Pragma("unroll") for (int k = 0; k < 2; ++k) dst[m][k] = *(const LAS bf16x8*)(lds + PG8_SA(b, h) + aoff + m * 2048 + k * 1024); } while (0)
; #define PG8_LDB(dst, b, h) do { _Pragma("unroll") for (int n = 0; n < 2; ++n) _Pragma("unroll") for (int k = 0; k < 2; ++k) dst[n][k] = *(const LAS bf16x8*)(lds + PG8_SB(b, h) + boff + n * 2048 + k * 1024); } while (0)
; #define PG8_MMA(ai, bj, At, Bt) do { __builtin_amdgcn_s_setprio(1); _Pragma("unroll") for (int m = 0; m < 4; ++m) _Pragma("unroll") for (int n = 0; n < 2; ++n) _Pragma("unroll") for (int k = 0; k < 2; ++k) \
;         acc[ai][bj][m][n] = __builtin_amdgcn_mfma_f32_16x16x32_bf16(Bt[n][k], At[m][k], acc[ai][bj][m][n], 0, 0, 0); __builtin_amdgcn_s_setprio(0); } while (0)
; #define PG8_WAIT_V(n) asm volatile("s_waitcnt vmcnt(" #n ")" ::: "memory")
; #define PG8_WAIT_L(n) asm volatile("s_waitcnt lgkmcnt(" #n ")" ::: "memory")
; #define PG8_BAR __builtin_amdgcn_s_barrier()
; #define PG8_SCHED __builtin_amdgcn_sched_barrier(0)
; #define PG8_STAGE(bufoff, gbase, voff) do { _Pragma("unroll") for (int _i = 0; _i < 2; ++_i) \
;         __builtin_amdgcn_global_load_lds((const unsigned*)((const char*)(gbase) + (voff)[_i]), (LAS unsigned*)(lds + (bufoff) + ldsw + _i * 8192), 16, 0, 0); } while (0)
; template <class Epi0, class Epi1>
; DI void gemm_phase_dual(LAS unsigned char* lds, const Gemm g, const Gemm g1, const StaticOrder S, const Epi0 E0, const Epi1 E1) {
;     ...
;             PG8_LDB(B0, 1, 0); PG8_SCHED; PG8_LDA(At, 1, 0); PG8_STAGE(PG8_SA(0, 1), a2 + hstep, voffA);
;             PG8_WAIT_L(8); PG8_BAR; PG8_WAIT_L(0); PG8_MMA(0, 0, At, B0); PG8_BAR; PG8_SCHED;
;             PG8_LDB(B1, 1, 1); PG8_STAGE(PG8_SB(1, 0), b3, voffB);
;             PG8_BAR; PG8_WAIT_L(0); PG8_MMA(0, 1, At, B1); PG8_BAR;
;             PG8_LDA(At, 1, 1); PG8_STAGE(PG8_SA(1, 0), a3, voffA);
;             PG8_BAR; PG8_WAIT_L(0); PG8_MMA(1, 0, At, B0); PG8_BAR; PG8_SCHED;
;             PG8_STAGE(PG8_SB(1, 1), b3 + hstep, voffB);
;             PG8_WAIT_V(6); PG8_BAR; PG8_MMA(1, 1, At, B1); PG8_BAR;
	v_mfma_f32_16x16x32_bf16 v[20:23], v[160:163], v[206:209], v[20:23]
	v_mfma_f32_16x16x32_bf16 v[16:19], v[168:171], v[206:209], v[16:19]
	s_setprio 0
	s_add_u32 s76, s40, 0x40000
	s_addc_u32 s77, s41, 0
	s_add_i32 s78, s53, s44
	v_lshl_add_u64 v[156:157], s[76:77], 0, v[130:131]
	s_mov_b32 m0, s78
	s_nop 0
	global_load_lds_dwordx4 v[156:157], off
	v_lshl_add_u64 v[156:157], s[76:77], 0, v[134:135]
	s_add_i32 m0, s78, 0x2000
	s_nop 0
	global_load_lds_dwordx4 v[156:157], off
	s_waitcnt vmcnt(6)
	s_setprio 1
	s_barrier
	v_mfma_f32_16x16x32_bf16 v[44:47], v[210:213], v[172:175], v[44:47]
	v_mfma_f32_16x16x32_bf16 v[40:43], v[218:221], v[172:175], v[40:43]
	v_mfma_f32_16x16x32_bf16 v[36:39], v[210:213], v[186:189], v[36:39]
	v_mfma_f32_16x16x32_bf16 v[32:35], v[218:221], v[186:189], v[32:35]
	v_mfma_f32_16x16x32_bf16 v[12:15], v[210:213], v[194:197], v[12:15]
	v_mfma_f32_16x16x32_bf16 v[8:11], v[218:221], v[194:197], v[8:11]
	v_mfma_f32_16x16x32_bf16 v[4:7], v[210:213], v[202:205], v[4:7]
	v_mfma_f32_16x16x32_bf16 v[0:3], v[218:221], v[202:205], v[0:3]
	v_mfma_f32_16x16x32_bf16 v[44:47], v[214:217], v[182:185], v[44:47]
	v_mfma_f32_16x16x32_bf16 v[40:43], v[224:227], v[182:185], v[40:43]
	v_mfma_f32_16x16x32_bf16 v[36:39], v[214:217], v[190:193], v[36:39]
	v_mfma_f32_16x16x32_bf16 v[32:35], v[224:227], v[190:193], v[32:35]
	v_mfma_f32_16x16x32_bf16 v[12:15], v[214:217], v[198:201], v[12:15]
	v_mfma_f32_16x16x32_bf16 v[8:11], v[224:227], v[198:201], v[8:11]
	s_setprio 2
	s_barrier
	v_mfma_f32_16x16x32_bf16 v[4:7], v[214:217], v[206:209], v[4:7]
	v_mfma_f32_16x16x32_bf16 v[0:3], v[224:227], v[206:209], v[0:3]
	s_setprio 0
	s_add_i32 s76, 0, 0x18000
	v_add_u32_e32 v168, s76, v177
	ds_read_b128 v[156:159], v168
	ds_read_b128 v[160:163], v168 offset:1024
	ds_read_b128 v[164:167], v168 offset:2048
	ds_read_b128 v[168:171], v168 offset:3072
	s_add_u32 s42, s42, 0x40000
	s_addc_u32 s43, s43, 0
	s_mov_b32 m0, s46
	v_lshl_add_u64 v[210:211], s[42:43], 0, v[128:129]
	ds_read_b128 v[172:175], v180 offset:32768
	ds_read_b128 v[182:185], v180 offset:33792
	ds_read_b128 v[186:189], v180 offset:34816
	ds_read_b128 v[190:193], v180 offset:35840
	ds_read_b128 v[194:197], v180 offset:36864
	ds_read_b128 v[198:201], v180 offset:37888
	ds_read_b128 v[202:205], v180 offset:38912
	ds_read_b128 v[206:209], v180 offset:39936
	global_load_lds_dwordx4 v[210:211], off
	v_lshl_add_u64 v[210:211], s[42:43], 0, v[132:133]
	s_mov_b32 m0, s47
	s_nop 0
	global_load_lds_dwordx4 v[210:211], off
	s_waitcnt lgkmcnt(8)
	s_setprio 1
	s_barrier
	s_waitcnt lgkmcnt(0)
	v_mfma_f32_16x16x32_bf16 v[124:127], v[156:159], v[172:175], v[124:127]
	v_mfma_f32_16x16x32_bf16 v[120:123], v[164:167], v[172:175], v[120:123]
	v_mfma_f32_16x16x32_bf16 v[108:111], v[156:159], v[186:189], v[108:111]
	v_mfma_f32_16x16x32_bf16 v[104:107], v[164:167], v[186:189], v[104:107]
	v_mfma_f32_16x16x32_bf16 v[92:95], v[156:159], v[194:197], v[92:95]
	v_mfma_f32_16x16x32_bf16 v[88:91], v[164:167], v[194:197], v[88:91]
	v_mfma_f32_16x16x32_bf16 v[84:87], v[156:159], v[202:205], v[84:87]
	v_mfma_f32_16x16x32_bf16 v[80:83], v[164:167], v[202:205], v[80:83]
	v_mfma_f32_16x16x32_bf16 v[124:127], v[160:163], v[182:185], v[124:127]
	v_mfma_f32_16x16x32_bf16 v[120:123], v[168:171], v[182:185], v[120:123]
	v_mfma_f32_16x16x32_bf16 v[108:111], v[160:163], v[190:193], v[108:111]
	v_mfma_f32_16x16x32_bf16 v[104:107], v[168:171], v[190:193], v[104:107]
	v_mfma_f32_16x16x32_bf16 v[92:95], v[160:163], v[198:201], v[92:95]
	v_mfma_f32_16x16x32_bf16 v[88:91], v[168:171], v[198:201], v[88:91]
	s_setprio 2
	s_barrier
	v_mfma_f32_16x16x32_bf16 v[84:87], v[160:163], v[206:209], v[84:87]
	v_mfma_f32_16x16x32_bf16 v[80:83], v[168:171], v[206:209], v[80:83]
	s_setprio 0
	s_add_i32 s42, 0, 0x1c000
	s_add_i32 s43, s76, s44
	v_add_u32_e32 v224, s42, v177
	v_lshl_add_u64 v[228:229], v[228:229], 0, s[8:9]
	s_mov_b32 m0, s43
	ds_read_b128 v[210:213], v224
	ds_read_b128 v[214:217], v224 offset:1024
	ds_read_b128 v[218:221], v224 offset:2048
	ds_read_b128 v[224:227], v224 offset:3072
	global_load_lds_dwordx4 v[228:229], off
	v_lshl_add_u64 v[228:229], v[230:231], 0, s[8:9]
	s_add_i32 m0, s43, 0x2000
	s_nop 0
	global_load_lds_dwordx4 v[228:229], off
	s_setprio 1
	s_barrier
	s_waitcnt lgkmcnt(0)
	v_mfma_f32_16x16x32_bf16 v[116:119], v[210:213], v[172:175], v[116:119]
	v_mfma_f32_16x16x32_bf16 v[112:115], v[218:221], v[172:175], v[112:115]
	v_mfma_f32_16x16x32_bf16 v[100:103], v[210:213], v[186:189], v[100:103]
	v_mfma_f32_16x16x32_bf16 v[96:99], v[218:221], v[186:189], v[96:99]
	v_mfma_f32_16x16x32_bf16 v[76:79], v[210:213], v[194:197], v[76:79]
	v_mfma_f32_16x16x32_bf16 v[72:75], v[218:221], v[194:197], v[72:75]
	v_mfma_f32_16x16x32_bf16 v[68:71], v[210:213], v[202:205], v[68:71]
	v_mfma_f32_16x16x32_bf16 v[64:67], v[218:221], v[202:205], v[64:67]
	v_mfma_f32_16x16x32_bf16 v[116:119], v[214:217], v[182:185], v[116:119]
	v_mfma_f32_16x16x32_bf16 v[112:115], v[224:227], v[182:185], v[112:115]
	v_mfma_f32_16x16x32_bf16 v[100:103], v[214:217], v[190:193], v[100:103]
	v_mfma_f32_16x16x32_bf16 v[96:99], v[224:227], v[190:193], v[96:99]
	v_mfma_f32_16x16x32_bf16 v[76:79], v[214:217], v[198:201], v[76:79]
	v_mfma_f32_16x16x32_bf16 v[72:75], v[224:227], v[198:201], v[72:75]
	s_setprio 2
	s_barrier
; #define PG8_STAGE(bufoff, gbase, voff) do { _Pragma("unroll") for (int _i = 0; _i < 2; ++_i) \
;         __builtin_amdgcn_global_load_lds((const unsigned*)((const char*)(gbase) + (voff)[_i]), (LAS unsigned*)(lds + (bufoff) + ldsw + _i * 8192), 16, 0, 0); } while (0)
; #define PG8_LDA(dst, b, h) do { _Pragma("unroll") for (int m = 0; m < 4; ++m) _Pragma("unroll") for (int k = 0; k < 2; ++k) dst[m][k] = *(const LAS bf16x8*)(lds + PG8_SA(b, h) + aoff + m * 2048 + k * 1024); } while (0)
; #define PG8_LDB(dst, b, h) do { _Pragma("unroll") for (int n = 0; n < 2; ++n) _Pragma("unroll") for (int k = 0; k < 2; ++k) dst[n][k] = *(const LAS bf16x8*)(lds + PG8_SB(b, h) + boff + n * 2048 + k * 1024); } while (0)
; #define PG8_MMA(ai, bj, At, Bt) do { __builtin_amdgcn_s_setprio(1); _Pragma("unroll") for (int m = 0; m < 4; ++m) _Pragma("unroll") for (int n = 0; n < 2; ++n) _Pragma("unroll") for (int k = 0; k < 2; ++k) \
;         acc[ai][bj][m][n] = __builtin_amdgcn_mfma_f32_16x16x32_bf16(Bt[n][k], At[m][k], acc[ai][bj][m][n], 0, 0, 0); __builtin_amdgcn_s_setprio(0); } while (0)
; template <class Epi0, class Epi1>
; DI void gemm_phase_dual(LAS unsigned char* lds, const Gemm g, const Gemm g1, const StaticOrder S, const Epi0 E0, const Epi1 E1) {
;     ...
;             PG8_LDB(B0, 1, 0); PG8_SCHED; PG8_LDA(At, 1, 0); PG8_STAGE(PG8_SA(0, 1), a2 + hstep, voffA);
;             PG8_WAIT_L(8); PG8_BAR; PG8_WAIT_L(0); PG8_MMA(0, 0, At, B0); PG8_BAR; PG8_SCHED;
;             PG8_LDB(B1, 1, 1); PG8_STAGE(PG8_SB(1, 0), b3, voffB);
;             PG8_BAR; PG8_WAIT_L(0); PG8_MMA(0, 1, At, B1); PG8_BAR;
;             PG8_LDA(At, 1, 1); PG8_STAGE(PG8_SA(1, 0), a3, voffA);
;             PG8_BAR; PG8_WAIT_L(0); PG8_MMA(1, 0, At, B0); PG8_BAR; PG8_SCHED;
;             PG8_STAGE(PG8_SB(1, 1), b3 + hstep, voffB);
;             PG8_WAIT_V(6); PG8_BAR; PG8_MMA(1, 1, At, B1); PG8_BAR;
;     DI void operator()(AccRef acc, const Unit& u, int wr, int wc, int fr, int fq) const {
;     ...
;                         const size_t row = (size_t)(row0 + ai * 128 + (mh * 2 + mm) * 16); const int col = col0 + bj * 128;
;                         gv[mm][bj] = *(const u32x4*)(gab + (size_t)(u.pm * 8 + SECOND * 4 + u.pn) * 65536 + (wr * 64 + fr + ai * 128 + (mh * 2 + mm) * 16) * 256 + wc * 32 + 8 * fq + bj * 128);
;                         if (SECOND) mv[mm][bj] = *(const u32x4*)(mrg + row * 1024 + col);
	v_mfma_f32_16x16x32_bf16 v[68:71], v[214:217], v[206:209], v[68:71]
	v_mfma_f32_16x16x32_bf16 v[64:67], v[224:227], v[206:209], v[64:67]
	s_setprio 0
	s_mov_b32 m0, s59
	v_lshl_add_u64 v[228:229], v[232:233], 0, s[8:9]
	ds_read_b128 v[172:175], v180 offset:49152
	ds_read_b128 v[182:185], v180 offset:50176
	ds_read_b128 v[186:189], v180 offset:51200
	ds_read_b128 v[190:193], v180 offset:52224
	ds_read_b128 v[194:197], v180 offset:53248
	ds_read_b128 v[198:201], v180 offset:54272
	ds_read_b128 v[202:205], v180 offset:55296
	ds_read_b128 v[206:209], v180 offset:56320
	global_load_lds_dwordx4 v[228:229], off
	v_lshl_add_u64 v[228:229], v[234:235], 0, s[8:9]
	s_mov_b32 m0, s60
	s_nop 0
	global_load_lds_dwordx4 v[228:229], off
	s_setprio 1
	s_barrier
	s_waitcnt lgkmcnt(0)
	v_mfma_f32_16x16x32_bf16 v[60:63], v[156:159], v[172:175], v[60:63]
	v_mfma_f32_16x16x32_bf16 v[56:59], v[164:167], v[172:175], v[56:59]
	v_mfma_f32_16x16x32_bf16 v[52:55], v[156:159], v[186:189], v[52:55]
	v_mfma_f32_16x16x32_bf16 v[48:51], v[164:167], v[186:189], v[48:51]
	v_mfma_f32_16x16x32_bf16 v[28:31], v[156:159], v[194:197], v[28:31]
	v_mfma_f32_16x16x32_bf16 v[24:27], v[164:167], v[194:197], v[24:27]
	v_mfma_f32_16x16x32_bf16 v[20:23], v[156:159], v[202:205], v[20:23]
	v_mfma_f32_16x16x32_bf16 v[16:19], v[164:167], v[202:205], v[16:19]
	v_mfma_f32_16x16x32_bf16 v[60:63], v[160:163], v[182:185], v[60:63]
	v_mfma_f32_16x16x32_bf16 v[56:59], v[168:171], v[182:185], v[56:59]
	v_mfma_f32_16x16x32_bf16 v[52:55], v[160:163], v[190:193], v[52:55]
	v_mfma_f32_16x16x32_bf16 v[48:51], v[168:171], v[190:193], v[48:51]
	v_mfma_f32_16x16x32_bf16 v[28:31], v[160:163], v[198:201], v[28:31]
	v_mfma_f32_16x16x32_bf16 v[24:27], v[168:171], v[198:201], v[24:27]
	s_setprio 2
	s_barrier
	v_mfma_f32_16x16x32_bf16 v[20:23], v[160:163], v[206:209], v[20:23]
	v_mfma_f32_16x16x32_bf16 v[16:19], v[168:171], v[206:209], v[16:19]
	s_setprio 0
	s_add_u32 s40, s40, 0x40080
	s_addc_u32 s41, s41, 0
	s_add_i32 s42, s42, s44
	v_lshl_add_u64 v[156:157], s[40:41], 0, v[130:131]
	s_mov_b32 m0, s42
	s_nop 0
	global_load_lds_dwordx4 v[156:157], off
	v_lshl_add_u64 v[156:157], s[40:41], 0, v[134:135]
	s_add_i32 m0, s42, 0x2000
	s_nop 0
	global_load_lds_dwordx4 v[156:157], off
	s_waitcnt vmcnt(6)
	s_setprio 1
	s_barrier
	v_mfma_f32_16x16x32_bf16 v[44:47], v[210:213], v[172:175], v[44:47]
	v_mfma_f32_16x16x32_bf16 v[40:43], v[218:221], v[172:175], v[40:43]
	v_mfma_f32_16x16x32_bf16 v[36:39], v[210:213], v[186:189], v[36:39]
	v_mfma_f32_16x16x32_bf16 v[32:35], v[218:221], v[186:189], v[32:35]
	v_mfma_f32_16x16x32_bf16 v[12:15], v[210:213], v[194:197], v[12:15]
	v_mfma_f32_16x16x32_bf16 v[8:11], v[218:221], v[194:197], v[8:11]
	v_mfma_f32_16x16x32_bf16 v[4:7], v[210:213], v[202:205], v[4:7]
	v_mfma_f32_16x16x32_bf16 v[0:3], v[218:221], v[202:205], v[0:3]
	v_mfma_f32_16x16x32_bf16 v[44:47], v[214:217], v[182:185], v[44:47]
	v_mfma_f32_16x16x32_bf16 v[40:43], v[224:227], v[182:185], v[40:43]
	v_mfma_f32_16x16x32_bf16 v[36:39], v[214:217], v[190:193], v[36:39]
	v_mfma_f32_16x16x32_bf16 v[32:35], v[224:227], v[190:193], v[32:35]
	v_mfma_f32_16x16x32_bf16 v[12:15], v[214:217], v[198:201], v[12:15]
	v_mfma_f32_16x16x32_bf16 v[8:11], v[224:227], v[198:201], v[8:11]
	s_setprio 2
	s_barrier
	v_mfma_f32_16x16x32_bf16 v[4:7], v[214:217], v[206:209], v[4:7]
	v_mfma_f32_16x16x32_bf16 v[0:3], v[224:227], v[206:209], v[0:3]
	s_setprio 0
	s_add_i32 s69, s69, 2
	s_add_u32 s38, s38, 0x100
	s_addc_u32 s39, s39, 0
	s_add_u32 s67, s67, 0x100
	s_addc_u32 s68, s68, 0
	s_cmp_gt_u32 s69, 13
	s_cbranch_scc0 .LBB0_708
	v_lshl_add_u32 v164, s24, 8, v176
	s_lshl_b32 s17, s66, 8
	v_or_b32_e32 v162, s17, v178
	v_or_b32_e32 v160, 16, v164
	s_mov_b64 s[6:7], -1
	s_and_b64 vcc, exec, s[28:29]
	v_ashrrev_i32_e32 v165, 31, v164
	v_ashrrev_i32_e32 v163, 31, v162
	v_ashrrev_i32_e32 v161, 31, v160
	v_or_b32_e32 v158, 32, v164
	v_or_b32_e32 v156, 48, v164
	s_cbranch_vccz .LBB0_711
	s_lshl_b32 s6, s24, 3
	s_add_i32 s6, s66, s6
	s_add_i32 s6, s6, 4
	v_lshlrev_b64 v[168:169], 11, v[160:161]
	s_ashr_i32 s7, s6, 31
	v_lshlrev_b64 v[166:167], 11, v[164:165]
	v_lshlrev_b64 v[170:171], 1, v[162:163]
	v_lshl_add_u64 v[168:169], s[36:37], 0, v[168:169]
	s_lshl_b64 s[6:7], s[6:7], 17
	v_lshl_add_u64 v[166:167], s[36:37], 0, v[166:167]
	v_lshl_add_u64 v[174:175], v[168:169], 0, v[170:171]
	v_lshl_add_u64 v[168:169], v[136:137], 0, s[6:7]
	v_lshl_add_u64 v[166:167], v[166:167], 0, v[170:171]
	v_lshl_add_u64 v[172:173], v[138:139], 1, v[168:169]
	global_load_dwordx4 v[182:185], v[166:167], off
	global_load_dwordx4 v[186:189], v[166:167], off offset:256
	global_load_dwordx4 v[190:193], v[174:175], off
	global_load_dwordx4 v[194:197], v[172:173], off
	global_load_dwordx4 v[198:201], v[172:173], off offset:256
	v_add_co_u32_e32 v206, vcc, s48, v172
	v_ashrrev_i32_e32 v159, 31, v158
	s_nop 0
	v_addc_co_u32_e32 v207, vcc, 0, v173, vcc
	global_load_dwordx4 v[202:205], v[206:207], off
	s_nop 0
	global_load_dwordx4 v[206:209], v[206:207], off offset:256
	s_nop 0
	global_load_dwordx4 v[210:213], v[174:175], off offset:256
	v_ashrrev_i32_e32 v157, 31, v156
	s_mov_b64 s[6:7], 0
	s_waitcnt vmcnt(0)
; DI unsigned pk_bf16(float lo, float hi) { f32x2 v = {lo, hi}; return __builtin_bit_cast(unsigned, __builtin_convertvector(v, bf16v2)); }
; DI float bf_lo(unsigned w) { return __uint_as_float(w << 16); }
; DI float bf_hi(unsigned w) { return __uint_as_float(w & 0xffff0000u); }
;     DI void operator()(AccRef acc, const Unit& u, int wr, int wc, int fr, int fq) const {
;     ...
;                         const size_t row = (size_t)(row0 + ai * 128 + (mh * 2 + mm) * 16); const int col = col0 + bj * 128;
;                         gv[mm][bj] = *(const u32x4*)(gab + (size_t)(u.pm * 8 + SECOND * 4 + u.pn) * 65536 + (wr * 64 + fr + ai * 128 + (mh * 2 + mm) * 16) * 256 + wc * 32 + 8 * fq + bj * 128);
;                         if (SECOND) mv[mm][bj] = *(const u32x4*)(mrg + row * 1024 + col);
;                     }
; #pragma unroll
;                 for (int mm = 0; mm < 2; ++mm)
; #pragma unroll
;                     for (int bj = 0; bj < 2; ++bj) {
;                         const int m = mh * 2 + mm;
;                         const size_t row = (size_t)(row0 + ai * 128 + m * 16); const int col = col0 + bj * 128;
;                         const u32x4 gt = gv[mm][bj];
;                         const f32x4 r0 = acc[ai][bj][m][0], r1 = acc[ai][bj][m][1];
;                         float v[8] = {bf_lo(gt.x) * r0[0], bf_hi(gt.x) * r0[1], bf_lo(gt.y) * r0[2], bf_hi(gt.y) * r0[3], bf_lo(gt.z) * r1[0], bf_hi(gt.z) * r1[1], bf_lo(gt.w) * r1[2], bf_hi(gt.w) * r1[3]};
;                         if (SECOND) { const u32x4 o = mv[mm][bj]; v[0] += bf_lo(o.x); v[1] += bf_hi(o.x); v[2] += bf_lo(o.y); v[3] += bf_hi(o.y); v[4] += bf_lo(o.z); v[5] += bf_hi(o.z); v[6] += bf_lo(o.w); v[7] += bf_hi(o.w); }
;                         u32x4 w; w.x = pk_bf16(v[0], v[1]); w.y = pk_bf16(v[2], v[3]); w.z = pk_bf16(v[4], v[5]); w.w = pk_bf16(v[6], v[7]);
;                         *(u32x4*)(mrg + row * 1024 + col) = w;
	v_lshlrev_b32_e32 v214, 16, v182
	v_and_b32_e32 v215, 0xffff0000, v182
	v_lshlrev_b32_e32 v182, 16, v183
	v_and_b32_e32 v183, 0xffff0000, v183
	v_lshlrev_b32_e32 v216, 16, v184
	v_and_b32_e32 v217, 0xffff0000, v184
	v_lshlrev_b32_e32 v184, 16, v185
	v_and_b32_e32 v185, 0xffff0000, v185
	v_lshlrev_b32_e32 v228, 16, v194
	v_and_b32_e32 v229, 0xffff0000, v194
	v_lshlrev_b32_e32 v194, 16, v195
	v_and_b32_e32 v195, 0xffff0000, v195
	v_lshlrev_b32_e32 v230, 16, v196
	v_and_b32_e32 v231, 0xffff0000, v196
	v_lshlrev_b32_e32 v196, 16, v197
	v_and_b32_e32 v197, 0xffff0000, v197
	v_lshlrev_b32_e32 v218, 16, v186
	v_and_b32_e32 v219, 0xffff0000, v186
	v_lshlrev_b32_e32 v186, 16, v187
	v_and_b32_e32 v187, 0xffff0000, v187
	v_lshlrev_b32_e32 v220, 16, v188
	v_and_b32_e32 v221, 0xffff0000, v188
	v_lshlrev_b32_e32 v188, 16, v189
	v_and_b32_e32 v189, 0xffff0000, v189
	v_lshlrev_b32_e32 v232, 16, v198
	v_and_b32_e32 v233, 0xffff0000, v198
	v_lshlrev_b32_e32 v198, 16, v199
	v_and_b32_e32 v199, 0xffff0000, v199
	v_lshlrev_b32_e32 v234, 16, v200
	v_and_b32_e32 v235, 0xffff0000, v200
	v_lshlrev_b32_e32 v200, 16, v201
	v_and_b32_e32 v201, 0xffff0000, v201
	v_pk_fma_f32 v[214:215], v[124:125], v[228:229], v[214:215]
	v_pk_fma_f32 v[194:195], v[126:127], v[194:195], v[182:183]
	v_pk_fma_f32 v[216:217], v[120:121], v[230:231], v[216:217]
	v_pk_fma_f32 v[196:197], v[122:123], v[196:197], v[184:185]
	v_pk_fma_f32 v[218:219], v[116:117], v[232:233], v[218:219]
	v_pk_fma_f32 v[198:199], v[118:119], v[198:199], v[186:187]
	v_pk_fma_f32 v[220:221], v[112:113], v[234:235], v[220:221]
	v_pk_fma_f32 v[200:201], v[114:115], v[200:201], v[188:189]
	v_cvt_pk_bf16_f32 v182, v214, v215
	v_cvt_pk_bf16_f32 v183, v194, v195
	v_cvt_pk_bf16_f32 v184, v216, v217
	v_cvt_pk_bf16_f32 v185, v196, v197
	v_lshlrev_b32_e32 v224, 16, v190
	v_and_b32_e32 v225, 0xffff0000, v190
	v_lshlrev_b32_e32 v190, 16, v191
	v_and_b32_e32 v191, 0xffff0000, v191
	v_lshlrev_b32_e32 v226, 16, v192
	v_and_b32_e32 v227, 0xffff0000, v192
	v_lshlrev_b32_e32 v228, 16, v202
	v_and_b32_e32 v229, 0xffff0000, v202
	v_lshlrev_b32_e32 v202, 16, v203
	v_and_b32_e32 v203, 0xffff0000, v203
	v_lshlrev_b32_e32 v230, 16, v204
	v_and_b32_e32 v231, 0xffff0000, v204
	v_cvt_pk_bf16_f32 v186, v218, v219
	v_cvt_pk_bf16_f32 v187, v198, v199
	v_cvt_pk_bf16_f32 v188, v220, v221
	v_cvt_pk_bf16_f32 v189, v200, v201
	global_store_dwordx4 v[166:167], v[182:185], off
	global_store_dwordx4 v[166:167], v[186:189], off offset:256
	v_pk_fma_f32 v[194:195], v[108:109], v[228:229], v[224:225]
	v_lshlrev_b32_e32 v182, 16, v205
	v_and_b32_e32 v183, 0xffff0000, v205
	v_lshlrev_b32_e32 v184, 16, v193
	v_and_b32_e32 v185, 0xffff0000, v193
	v_pk_fma_f32 v[190:191], v[110:111], v[202:203], v[190:191]
	v_pk_fma_f32 v[196:197], v[104:105], v[230:231], v[226:227]
	v_pk_fma_f32 v[186:187], v[106:107], v[182:183], v[184:185]
	v_cvt_pk_bf16_f32 v182, v194, v195
	v_cvt_pk_bf16_f32 v183, v190, v191
	v_cvt_pk_bf16_f32 v184, v196, v197
	v_cvt_pk_bf16_f32 v185, v186, v187
	global_store_dwordx4 v[174:175], v[182:185], off
	v_lshlrev_b32_e32 v186, 16, v211
	v_and_b32_e32 v187, 0xffff0000, v211
	v_lshlrev_b32_e32 v182, 16, v206
	v_and_b32_e32 v183, 0xffff0000, v206
	v_lshlrev_b32_e32 v184, 16, v210
	v_and_b32_e32 v185, 0xffff0000, v210
	v_pk_fma_f32 v[182:183], v[100:101], v[182:183], v[184:185]
	v_lshlrev_b32_e32 v184, 16, v207
	v_and_b32_e32 v185, 0xffff0000, v207
	v_pk_fma_f32 v[184:185], v[102:103], v[184:185], v[186:187]
	v_lshlrev_b32_e32 v186, 16, v208
	v_and_b32_e32 v187, 0xffff0000, v208
	v_lshlrev_b32_e32 v188, 16, v212
	v_and_b32_e32 v189, 0xffff0000, v212
	v_pk_fma_f32 v[190:191], v[96:97], v[186:187], v[188:189]
	v_lshlrev_b32_e32 v186, 16, v209
	v_and_b32_e32 v187, 0xffff0000, v209
	v_lshlrev_b32_e32 v188, 16, v213
	v_and_b32_e32 v189, 0xffff0000, v213
	v_cvt_pk_bf16_f32 v182, v182, v183
	v_cvt_pk_bf16_f32 v183, v184, v185
	v_lshlrev_b64 v[184:185], 11, v[158:159]
	v_pk_fma_f32 v[192:193], v[98:99], v[186:187], v[188:189]
	v_lshl_add_u64 v[184:185], s[36:37], 0, v[184:185]
	v_lshl_add_u64 v[210:211], v[184:185], 0, v[170:171]
	v_cvt_pk_bf16_f32 v184, v190, v191
	v_cvt_pk_bf16_f32 v185, v192, v193
	global_load_dwordx4 v[186:189], v[210:211], off
	s_waitcnt vmcnt(0)
	v_lshlrev_b32_e32 v214, 16, v188
	global_store_dwordx4 v[174:175], v[182:185], off offset:256
	v_add_co_u32_e32 v174, vcc, s49, v172
	v_and_b32_e32 v215, 0xffff0000, v188
	s_nop 0
	v_addc_co_u32_e32 v175, vcc, 0, v173, vcc
	global_load_dwordx4 v[182:185], v[174:175], off
	global_load_dwordx4 v[190:193], v[174:175], off offset:256
	global_load_dwordx4 v[194:197], v[210:211], off offset:256
	v_add_co_u32_e32 v202, vcc, s50, v172
	v_lshlrev_b64 v[174:175], 11, v[156:157]
	s_nop 0
	v_addc_co_u32_e32 v203, vcc, 0, v173, vcc
	v_lshl_add_u64 v[198:199], s[36:37], 0, v[174:175]
	global_load_dwordx4 v[172:175], v[202:203], off
	v_lshl_add_u64 v[212:213], v[198:199], 0, v[170:171]
	global_load_dwordx4 v[198:201], v[212:213], off
	s_nop 0
	global_load_dwordx4 v[202:205], v[202:203], off offset:256
	s_nop 0
	global_load_dwordx4 v[206:209], v[212:213], off offset:256
	v_lshlrev_b32_e32 v170, 16, v186
	v_and_b32_e32 v171, 0xffff0000, v186
	v_lshlrev_b32_e32 v186, 16, v187
	v_and_b32_e32 v187, 0xffff0000, v187
	v_lshlrev_b32_e32 v188, 16, v189
	v_and_b32_e32 v189, 0xffff0000, v189
	s_waitcnt vmcnt(0)
; DI unsigned pk_bf16(float lo, float hi) { f32x2 v = {lo, hi}; return __builtin_bit_cast(unsigned, __builtin_convertvector(v, bf16v2)); }
; DI float bf_lo(unsigned w) { return __uint_as_float(w << 16); }
; DI float bf_hi(unsigned w) { return __uint_as_float(w & 0xffff0000u); }
;     DI void operator()(AccRef acc, const Unit& u, int wr, int wc, int fr, int fq) const {
;     ...
;                         const size_t row = (size_t)(row0 + ai * 128 + (mh * 2 + mm) * 16); const int col = col0 + bj * 128;
;                         gv[mm][bj] = *(const u32x4*)(gab + (size_t)(u.pm * 8 + SECOND * 4 + u.pn) * 65536 + (wr * 64 + fr + ai * 128 + (mh * 2 + mm) * 16) * 256 + wc * 32 + 8 * fq + bj * 128);
;                         if (SECOND) mv[mm][bj] = *(const u32x4*)(mrg + row * 1024 + col);
;                     }
; #pragma unroll
;                 for (int mm = 0; mm < 2; ++mm)
; #pragma unroll
;                     for (int bj = 0; bj < 2; ++bj) {
;                         const int m = mh * 2 + mm;
;                         const size_t row = (size_t)(row0 + ai * 128 + m * 16); const int col = col0 + bj * 128;
;                         const u32x4 gt = gv[mm][bj];
;                         const f32x4 r0 = acc[ai][bj][m][0], r1 = acc[ai][bj][m][1];
;                         float v[8] = {bf_lo(gt.x) * r0[0], bf_hi(gt.x) * r0[1], bf_lo(gt.y) * r0[2], bf_hi(gt.y) * r0[3], bf_lo(gt.z) * r1[0], bf_hi(gt.z) * r1[1], bf_lo(gt.w) * r1[2], bf_hi(gt.w) * r1[3]};
;                         if (SECOND) { const u32x4 o = mv[mm][bj]; v[0] += bf_lo(o.x); v[1] += bf_hi(o.x); v[2] += bf_lo(o.y); v[3] += bf_hi(o.y); v[4] += bf_lo(o.z); v[5] += bf_hi(o.z); v[6] += bf_lo(o.w); v[7] += bf_hi(o.w); }
;                         u32x4 w; w.x = pk_bf16(v[0], v[1]); w.y = pk_bf16(v[2], v[3]); w.z = pk_bf16(v[4], v[5]); w.w = pk_bf16(v[6], v[7]);
;                         *(u32x4*)(mrg + row * 1024 + col) = w;
	v_lshlrev_b32_e32 v216, 16, v182
	v_and_b32_e32 v217, 0xffff0000, v182
	v_lshlrev_b32_e32 v182, 16, v183
	v_and_b32_e32 v183, 0xffff0000, v183
	v_lshlrev_b32_e32 v218, 16, v184
	v_and_b32_e32 v219, 0xffff0000, v184
	v_lshlrev_b32_e32 v184, 16, v185
	v_and_b32_e32 v185, 0xffff0000, v185
	v_pk_fma_f32 v[170:171], v[92:93], v[216:217], v[170:171]
	v_pk_fma_f32 v[186:187], v[94:95], v[182:183], v[186:187]
	v_pk_fma_f32 v[214:215], v[88:89], v[218:219], v[214:215]
	v_pk_fma_f32 v[188:189], v[90:91], v[184:185], v[188:189]
	v_cvt_pk_bf16_f32 v182, v170, v171
	v_cvt_pk_bf16_f32 v183, v186, v187
	v_cvt_pk_bf16_f32 v184, v214, v215
	v_cvt_pk_bf16_f32 v185, v188, v189
	global_store_dwordx4 v[210:211], v[182:185], off
	v_lshlrev_b32_e32 v186, 16, v196
	v_and_b32_e32 v187, 0xffff0000, v196
	v_lshlrev_b32_e32 v182, 16, v191
	v_and_b32_e32 v183, 0xffff0000, v191
	v_lshlrev_b32_e32 v184, 16, v195
	v_and_b32_e32 v185, 0xffff0000, v195
	v_pk_fma_f32 v[184:185], v[78:79], v[182:183], v[184:185]
	v_lshlrev_b32_e32 v182, 16, v192
	v_and_b32_e32 v183, 0xffff0000, v192
	v_lshlrev_b32_e32 v220, 16, v190
	v_and_b32_e32 v221, 0xffff0000, v190
	v_lshlrev_b32_e32 v170, 16, v194
	v_and_b32_e32 v171, 0xffff0000, v194
	v_pk_fma_f32 v[186:187], v[72:73], v[182:183], v[186:187]
	v_lshlrev_b32_e32 v182, 16, v193
	v_and_b32_e32 v183, 0xffff0000, v193
	v_lshlrev_b32_e32 v188, 16, v197
	v_and_b32_e32 v189, 0xffff0000, v197
	v_pk_fma_f32 v[170:171], v[76:77], v[220:221], v[170:171]
	v_pk_fma_f32 v[188:189], v[74:75], v[182:183], v[188:189]
	v_cvt_pk_bf16_f32 v182, v170, v171
	v_cvt_pk_bf16_f32 v183, v184, v185
	v_cvt_pk_bf16_f32 v184, v186, v187
	v_cvt_pk_bf16_f32 v185, v188, v189
	global_store_dwordx4 v[210:211], v[182:185], off offset:256
	v_lshlrev_b32_e32 v170, 16, v172
	v_and_b32_e32 v171, 0xffff0000, v172
	v_lshlrev_b32_e32 v182, 16, v198
	v_and_b32_e32 v183, 0xffff0000, v198
	v_pk_fma_f32 v[170:171], v[84:85], v[170:171], v[182:183]
	v_lshlrev_b32_e32 v172, 16, v173
	v_and_b32_e32 v173, 0xffff0000, v173
	v_lshlrev_b32_e32 v182, 16, v199
	v_and_b32_e32 v183, 0xffff0000, v199
	v_pk_fma_f32 v[172:173], v[86:87], v[172:173], v[182:183]
	v_lshlrev_b32_e32 v182, 16, v174
	v_and_b32_e32 v183, 0xffff0000, v174
	v_lshlrev_b32_e32 v184, 16, v200
	v_and_b32_e32 v185, 0xffff0000, v200
	v_pk_fma_f32 v[182:183], v[80:81], v[182:183], v[184:185]
	v_lshlrev_b32_e32 v174, 16, v175
	v_and_b32_e32 v175, 0xffff0000, v175
	v_lshlrev_b32_e32 v184, 16, v201
	v_and_b32_e32 v185, 0xffff0000, v201
	v_pk_fma_f32 v[174:175], v[82:83], v[174:175], v[184:185]
	v_cvt_pk_bf16_f32 v170, v170, v171
	v_cvt_pk_bf16_f32 v171, v172, v173
	v_cvt_pk_bf16_f32 v172, v182, v183
	v_cvt_pk_bf16_f32 v173, v174, v175
	global_store_dwordx4 v[212:213], v[170:173], off
	v_lshlrev_b32_e32 v174, 16, v207
	v_and_b32_e32 v175, 0xffff0000, v207
	v_lshlrev_b32_e32 v170, 16, v202
	v_and_b32_e32 v171, 0xffff0000, v202
	v_lshlrev_b32_e32 v172, 16, v206
	v_and_b32_e32 v173, 0xffff0000, v206
	v_pk_fma_f32 v[170:171], v[68:69], v[170:171], v[172:173]
	v_lshlrev_b32_e32 v172, 16, v203
	v_and_b32_e32 v173, 0xffff0000, v203
	v_pk_fma_f32 v[172:173], v[70:71], v[172:173], v[174:175]
	v_lshlrev_b32_e32 v174, 16, v204
	v_and_b32_e32 v175, 0xffff0000, v204
	v_lshlrev_b32_e32 v182, 16, v208
	v_and_b32_e32 v183, 0xffff0000, v208
	v_pk_fma_f32 v[174:175], v[64:65], v[174:175], v[182:183]
	v_lshlrev_b32_e32 v182, 16, v205
	v_and_b32_e32 v183, 0xffff0000, v205
	v_lshlrev_b32_e32 v184, 16, v209
	v_and_b32_e32 v185, 0xffff0000, v209
	v_pk_fma_f32 v[182:183], v[66:67], v[182:183], v[184:185]
	v_cvt_pk_bf16_f32 v170, v170, v171
	v_cvt_pk_bf16_f32 v171, v172, v173
	v_cvt_pk_bf16_f32 v172, v174, v175
	v_cvt_pk_bf16_f32 v173, v182, v183
	global_store_dwordx4 v[212:213], v[170:173], off offset:256
	v_lshl_add_u64 v[174:175], v[140:141], 1, v[168:169]
	v_add_co_u32_e32 v210, vcc, s61, v166
	global_load_dwordx4 v[170:173], v[174:175], off
	s_nop 0
	v_addc_co_u32_e32 v211, vcc, 0, v167, vcc
	global_load_dwordx4 v[182:185], v[210:211], off
	global_load_dwordx4 v[186:189], v[174:175], off offset:256
	v_lshl_add_u64 v[174:175], v[166:167], 0, s[0:1]
	global_load_dwordx4 v[190:193], v[174:175], off offset:256
	v_lshl_add_u64 v[202:203], v[142:143], 1, v[168:169]
	v_add_co_u32_e32 v212, vcc, s62, v166
	global_load_dwordx4 v[194:197], v[202:203], off
	s_nop 0
	v_addc_co_u32_e32 v213, vcc, 0, v167, vcc
	global_load_dwordx4 v[198:201], v[212:213], off
	s_nop 0
	global_load_dwordx4 v[202:205], v[202:203], off offset:256
	v_lshl_add_u64 v[214:215], v[166:167], 0, s[10:11]
	global_load_dwordx4 v[206:209], v[214:215], off offset:256
	s_waitcnt vmcnt(0)
; DI unsigned pk_bf16(float lo, float hi) { f32x2 v = {lo, hi}; return __builtin_bit_cast(unsigned, __builtin_convertvector(v, bf16v2)); }
; DI float bf_lo(unsigned w) { return __uint_as_float(w << 16); }
; DI float bf_hi(unsigned w) { return __uint_as_float(w & 0xffff0000u); }
;     DI void operator()(AccRef acc, const Unit& u, int wr, int wc, int fr, int fq) const {
;     ...
;                         const size_t row = (size_t)(row0 + ai * 128 + (mh * 2 + mm) * 16); const int col = col0 + bj * 128;
;                         gv[mm][bj] = *(const u32x4*)(gab + (size_t)(u.pm * 8 + SECOND * 4 + u.pn) * 65536 + (wr * 64 + fr + ai * 128 + (mh * 2 + mm) * 16) * 256 + wc * 32 + 8 * fq + bj * 128);
;                         if (SECOND) mv[mm][bj] = *(const u32x4*)(mrg + row * 1024 + col);
;                     }
; #pragma unroll
;                 for (int mm = 0; mm < 2; ++mm)
; #pragma unroll
;                     for (int bj = 0; bj < 2; ++bj) {
;                         const int m = mh * 2 + mm;
;                         const size_t row = (size_t)(row0 + ai * 128 + m * 16); const int col = col0 + bj * 128;
;                         const u32x4 gt = gv[mm][bj];
;                         const f32x4 r0 = acc[ai][bj][m][0], r1 = acc[ai][bj][m][1];
;                         float v[8] = {bf_lo(gt.x) * r0[0], bf_hi(gt.x) * r0[1], bf_lo(gt.y) * r0[2], bf_hi(gt.y) * r0[3], bf_lo(gt.z) * r1[0], bf_hi(gt.z) * r1[1], bf_lo(gt.w) * r1[2], bf_hi(gt.w) * r1[3]};
;                         if (SECOND) { const u32x4 o = mv[mm][bj]; v[0] += bf_lo(o.x); v[1] += bf_hi(o.x); v[2] += bf_lo(o.y); v[3] += bf_hi(o.y); v[4] += bf_lo(o.z); v[5] += bf_hi(o.z); v[6] += bf_lo(o.w); v[7] += bf_hi(o.w); }
;                         u32x4 w; w.x = pk_bf16(v[0], v[1]); w.y = pk_bf16(v[2], v[3]); w.z = pk_bf16(v[4], v[5]); w.w = pk_bf16(v[6], v[7]);
;                         *(u32x4*)(mrg + row * 1024 + col) = w;
	v_lshlrev_b32_e32 v216, 16, v170
	v_and_b32_e32 v217, 0xffff0000, v170
	v_lshlrev_b32_e32 v218, 16, v182
	v_and_b32_e32 v219, 0xffff0000, v182
	v_lshlrev_b32_e32 v170, 16, v171
	v_and_b32_e32 v171, 0xffff0000, v171
	v_lshlrev_b32_e32 v182, 16, v183
	v_and_b32_e32 v183, 0xffff0000, v183
	v_pk_fma_f32 v[216:217], v[60:61], v[216:217], v[218:219]
	v_pk_fma_f32 v[182:183], v[62:63], v[170:171], v[182:183]
	v_lshlrev_b32_e32 v170, 16, v172
	v_and_b32_e32 v171, 0xffff0000, v172
	v_lshlrev_b32_e32 v218, 16, v184
	v_and_b32_e32 v219, 0xffff0000, v184
	v_pk_fma_f32 v[218:219], v[56:57], v[170:171], v[218:219]
	v_lshlrev_b32_e32 v170, 16, v173
	v_and_b32_e32 v171, 0xffff0000, v173
	v_lshlrev_b32_e32 v172, 16, v185
	v_and_b32_e32 v173, 0xffff0000, v185
	v_pk_fma_f32 v[184:185], v[58:59], v[170:171], v[172:173]
	v_cvt_pk_bf16_f32 v170, v216, v217
	v_cvt_pk_bf16_f32 v171, v182, v183
	v_cvt_pk_bf16_f32 v172, v218, v219
	v_cvt_pk_bf16_f32 v173, v184, v185
	global_store_dwordx4 v[210:211], v[170:173], off
	v_lshlrev_b32_e32 v182, 16, v191
	v_and_b32_e32 v183, 0xffff0000, v191
	v_lshlrev_b32_e32 v170, 16, v186
	v_and_b32_e32 v171, 0xffff0000, v186
	v_lshlrev_b32_e32 v172, 16, v190
	v_and_b32_e32 v173, 0xffff0000, v190
	v_pk_fma_f32 v[170:171], v[44:45], v[170:171], v[172:173]
	v_lshlrev_b32_e32 v172, 16, v187
	v_and_b32_e32 v173, 0xffff0000, v187
	v_pk_fma_f32 v[172:173], v[46:47], v[172:173], v[182:183]
	v_lshlrev_b32_e32 v182, 16, v188
	v_and_b32_e32 v183, 0xffff0000, v188
	v_lshlrev_b32_e32 v184, 16, v192
	v_and_b32_e32 v185, 0xffff0000, v192
	v_pk_fma_f32 v[182:183], v[40:41], v[182:183], v[184:185]
	v_lshlrev_b32_e32 v184, 16, v189
	v_and_b32_e32 v185, 0xffff0000, v189
	v_lshlrev_b32_e32 v186, 16, v193
	v_and_b32_e32 v187, 0xffff0000, v193
	v_pk_fma_f32 v[184:185], v[42:43], v[184:185], v[186:187]
	v_cvt_pk_bf16_f32 v170, v170, v171
	v_cvt_pk_bf16_f32 v171, v172, v173
	v_cvt_pk_bf16_f32 v172, v182, v183
	v_cvt_pk_bf16_f32 v173, v184, v185
	global_store_dwordx4 v[174:175], v[170:173], off offset:256
	v_lshlrev_b32_e32 v174, 16, v199
	v_and_b32_e32 v175, 0xffff0000, v199
	v_lshlrev_b32_e32 v170, 16, v194
	v_and_b32_e32 v171, 0xffff0000, v194
	v_lshlrev_b32_e32 v172, 16, v198
	v_and_b32_e32 v173, 0xffff0000, v198
	v_pk_fma_f32 v[170:171], v[52:53], v[170:171], v[172:173]
	v_lshlrev_b32_e32 v172, 16, v195
	v_and_b32_e32 v173, 0xffff0000, v195
	v_pk_fma_f32 v[172:173], v[54:55], v[172:173], v[174:175]
	v_lshlrev_b32_e32 v174, 16, v196
	v_and_b32_e32 v175, 0xffff0000, v196
	v_lshlrev_b32_e32 v182, 16, v200
	v_and_b32_e32 v183, 0xffff0000, v200
	v_pk_fma_f32 v[174:175], v[48:49], v[174:175], v[182:183]
	v_lshlrev_b32_e32 v182, 16, v197
	v_and_b32_e32 v183, 0xffff0000, v197
	v_lshlrev_b32_e32 v184, 16, v201
	v_and_b32_e32 v185, 0xffff0000, v201
	v_pk_fma_f32 v[182:183], v[50:51], v[182:183], v[184:185]
	v_cvt_pk_bf16_f32 v170, v170, v171
	v_cvt_pk_bf16_f32 v171, v172, v173
	v_cvt_pk_bf16_f32 v172, v174, v175
	v_cvt_pk_bf16_f32 v173, v182, v183
	global_store_dwordx4 v[212:213], v[170:173], off
	v_lshlrev_b32_e32 v174, 16, v207
	v_and_b32_e32 v175, 0xffff0000, v207
	v_lshlrev_b32_e32 v170, 16, v202
	v_and_b32_e32 v171, 0xffff0000, v202
	v_lshlrev_b32_e32 v172, 16, v206
	v_and_b32_e32 v173, 0xffff0000, v206
	v_pk_fma_f32 v[170:171], v[36:37], v[170:171], v[172:173]
	v_lshlrev_b32_e32 v172, 16, v203
	v_and_b32_e32 v173, 0xffff0000, v203
	v_pk_fma_f32 v[172:173], v[38:39], v[172:173], v[174:175]
	v_lshlrev_b32_e32 v174, 16, v204
	v_and_b32_e32 v175, 0xffff0000, v204
	v_lshlrev_b32_e32 v182, 16, v208
	v_and_b32_e32 v183, 0xffff0000, v208
	v_pk_fma_f32 v[174:175], v[32:33], v[174:175], v[182:183]
	v_lshlrev_b32_e32 v182, 16, v205
	v_and_b32_e32 v183, 0xffff0000, v205
	v_lshlrev_b32_e32 v184, 16, v209
	v_and_b32_e32 v185, 0xffff0000, v209
	v_pk_fma_f32 v[182:183], v[34:35], v[182:183], v[184:185]
	v_cvt_pk_bf16_f32 v170, v170, v171
	v_cvt_pk_bf16_f32 v171, v172, v173
	v_cvt_pk_bf16_f32 v172, v174, v175
	v_cvt_pk_bf16_f32 v173, v182, v183
	global_store_dwordx4 v[214:215], v[170:173], off offset:256
	v_lshl_add_u64 v[174:175], v[144:145], 1, v[168:169]
	v_add_co_u32_e32 v206, vcc, s63, v166
	global_load_dwordx4 v[170:173], v[174:175], off
	s_nop 0
	v_addc_co_u32_e32 v207, vcc, 0, v167, vcc
	global_load_dwordx4 v[182:185], v[206:207], off
	global_load_dwordx4 v[186:189], v[174:175], off offset:256
	v_lshl_add_u64 v[174:175], v[166:167], 0, s[12:13]
	global_load_dwordx4 v[190:193], v[174:175], off offset:256
	v_lshl_add_u64 v[168:169], v[146:147], 1, v[168:169]
	v_add_co_u32_e32 v208, vcc, s64, v166
	global_load_dwordx4 v[194:197], v[168:169], off
	s_nop 0
	v_addc_co_u32_e32 v209, vcc, 0, v167, vcc
	global_load_dwordx4 v[198:201], v[208:209], off
	global_load_dwordx4 v[202:205], v[168:169], off offset:256
	v_lshl_add_u64 v[210:211], v[166:167], 0, s[14:15]
	global_load_dwordx4 v[166:169], v[210:211], off offset:256
	s_waitcnt vmcnt(0)
; DI unsigned pk_bf16(float lo, float hi) { f32x2 v = {lo, hi}; return __builtin_bit_cast(unsigned, __builtin_convertvector(v, bf16v2)); }
; DI float bf_lo(unsigned w) { return __uint_as_float(w << 16); }
; DI float bf_hi(unsigned w) { return __uint_as_float(w & 0xffff0000u); }
;     DI void operator()(AccRef acc, const Unit& u, int wr, int wc, int fr, int fq) const {
;     ...
;                     for (int bj = 0; bj < 2; ++bj) {
;                         const int m = mh * 2 + mm;
;                         const size_t row = (size_t)(row0 + ai * 128 + m * 16); const int col = col0 + bj * 128;
;                         const u32x4 gt = gv[mm][bj];
;                         const f32x4 r0 = acc[ai][bj][m][0], r1 = acc[ai][bj][m][1];
;                         float v[8] = {bf_lo(gt.x) * r0[0], bf_hi(gt.x) * r0[1], bf_lo(gt.y) * r0[2], bf_hi(gt.y) * r0[3], bf_lo(gt.z) * r1[0], bf_hi(gt.z) * r1[1], bf_lo(gt.w) * r1[2], bf_hi(gt.w) * r1[3]};
;                         if (SECOND) { const u32x4 o = mv[mm][bj]; v[0] += bf_lo(o.x); v[1] += bf_hi(o.x); v[2] += bf_lo(o.y); v[3] += bf_hi(o.y); v[4] += bf_lo(o.z); v[5] += bf_hi(o.z); v[6] += bf_lo(o.w); v[7] += bf_hi(o.w); }
;                         u32x4 w; w.x = pk_bf16(v[0], v[1]); w.y = pk_bf16(v[2], v[3]); w.z = pk_bf16(v[4], v[5]); w.w = pk_bf16(v[6], v[7]);
;                         *(u32x4*)(mrg + row * 1024 + col) = w;
	v_lshlrev_b32_e32 v212, 16, v170
	v_and_b32_e32 v213, 0xffff0000, v170
	v_lshlrev_b32_e32 v214, 16, v182
	v_and_b32_e32 v215, 0xffff0000, v182
	v_lshlrev_b32_e32 v170, 16, v171
	v_and_b32_e32 v171, 0xffff0000, v171
	v_lshlrev_b32_e32 v182, 16, v183
	v_and_b32_e32 v183, 0xffff0000, v183
	v_pk_fma_f32 v[212:213], v[28:29], v[212:213], v[214:215]
	v_pk_fma_f32 v[182:183], v[30:31], v[170:171], v[182:183]
	v_lshlrev_b32_e32 v170, 16, v172
	v_and_b32_e32 v171, 0xffff0000, v172
	v_lshlrev_b32_e32 v214, 16, v184
	v_and_b32_e32 v215, 0xffff0000, v184
	v_pk_fma_f32 v[214:215], v[24:25], v[170:171], v[214:215]
	v_lshlrev_b32_e32 v170, 16, v173
	v_and_b32_e32 v171, 0xffff0000, v173
	v_lshlrev_b32_e32 v172, 16, v185
	v_and_b32_e32 v173, 0xffff0000, v185
	v_pk_fma_f32 v[184:185], v[26:27], v[170:171], v[172:173]
	v_cvt_pk_bf16_f32 v170, v212, v213
	v_cvt_pk_bf16_f32 v171, v182, v183
	v_cvt_pk_bf16_f32 v172, v214, v215
	v_cvt_pk_bf16_f32 v173, v184, v185
	global_store_dwordx4 v[206:207], v[170:173], off
	v_lshlrev_b32_e32 v182, 16, v191
	v_and_b32_e32 v183, 0xffff0000, v191
	v_lshlrev_b32_e32 v170, 16, v186
	v_and_b32_e32 v171, 0xffff0000, v186
	v_lshlrev_b32_e32 v172, 16, v190
	v_and_b32_e32 v173, 0xffff0000, v190
	v_pk_fma_f32 v[170:171], v[12:13], v[170:171], v[172:173]
	v_lshlrev_b32_e32 v172, 16, v187
	v_and_b32_e32 v173, 0xffff0000, v187
	v_pk_fma_f32 v[172:173], v[14:15], v[172:173], v[182:183]
	v_lshlrev_b32_e32 v182, 16, v188
	v_and_b32_e32 v183, 0xffff0000, v188
	v_lshlrev_b32_e32 v184, 16, v192
	v_and_b32_e32 v185, 0xffff0000, v192
	v_pk_fma_f32 v[182:183], v[8:9], v[182:183], v[184:185]
	v_lshlrev_b32_e32 v184, 16, v189
	v_and_b32_e32 v185, 0xffff0000, v189
	v_lshlrev_b32_e32 v186, 16, v193
	v_and_b32_e32 v187, 0xffff0000, v193
	v_pk_fma_f32 v[184:185], v[10:11], v[184:185], v[186:187]
	v_cvt_pk_bf16_f32 v170, v170, v171
	v_cvt_pk_bf16_f32 v171, v172, v173
	v_cvt_pk_bf16_f32 v172, v182, v183
	v_cvt_pk_bf16_f32 v173, v184, v185
	global_store_dwordx4 v[174:175], v[170:173], off offset:256
	v_lshlrev_b32_e32 v174, 16, v199
	v_and_b32_e32 v175, 0xffff0000, v199
	v_lshlrev_b32_e32 v170, 16, v194
	v_and_b32_e32 v171, 0xffff0000, v194
	v_lshlrev_b32_e32 v172, 16, v198
	v_and_b32_e32 v173, 0xffff0000, v198
	v_pk_fma_f32 v[170:171], v[20:21], v[170:171], v[172:173]
	v_lshlrev_b32_e32 v172, 16, v195
	v_and_b32_e32 v173, 0xffff0000, v195
	v_pk_fma_f32 v[172:173], v[22:23], v[172:173], v[174:175]
	v_lshlrev_b32_e32 v174, 16, v196
	v_and_b32_e32 v175, 0xffff0000, v196
	v_lshlrev_b32_e32 v182, 16, v200
	v_and_b32_e32 v183, 0xffff0000, v200
	v_pk_fma_f32 v[174:175], v[16:17], v[174:175], v[182:183]
	v_lshlrev_b32_e32 v182, 16, v197
	v_and_b32_e32 v183, 0xffff0000, v197
	v_lshlrev_b32_e32 v184, 16, v201
	v_and_b32_e32 v185, 0xffff0000, v201
	v_pk_fma_f32 v[182:183], v[18:19], v[182:183], v[184:185]
	v_cvt_pk_bf16_f32 v170, v170, v171
	v_cvt_pk_bf16_f32 v171, v172, v173
	v_cvt_pk_bf16_f32 v172, v174, v175
	v_cvt_pk_bf16_f32 v173, v182, v183
	global_store_dwordx4 v[208:209], v[170:173], off
	v_lshlrev_b32_e32 v174, 16, v168
	v_and_b32_e32 v175, 0xffff0000, v168
	v_lshlrev_b32_e32 v170, 16, v202
	v_and_b32_e32 v171, 0xffff0000, v202
	v_lshlrev_b32_e32 v172, 16, v166
	v_and_b32_e32 v173, 0xffff0000, v166
	v_pk_fma_f32 v[170:171], v[4:5], v[170:171], v[172:173]
	v_lshlrev_b32_e32 v172, 16, v203
	v_and_b32_e32 v173, 0xffff0000, v203
	v_lshlrev_b32_e32 v166, 16, v167
	v_and_b32_e32 v167, 0xffff0000, v167
	v_pk_fma_f32 v[172:173], v[6:7], v[172:173], v[166:167]
	v_lshlrev_b32_e32 v166, 16, v204
	v_and_b32_e32 v167, 0xffff0000, v204
	v_pk_fma_f32 v[174:175], v[0:1], v[166:167], v[174:175]
	v_lshlrev_b32_e32 v166, 16, v205
	v_and_b32_e32 v167, 0xffff0000, v205
	v_lshlrev_b32_e32 v168, 16, v169
	v_and_b32_e32 v169, 0xffff0000, v169
	v_pk_fma_f32 v[182:183], v[2:3], v[166:167], v[168:169]
	v_cvt_pk_bf16_f32 v166, v170, v171
	v_cvt_pk_bf16_f32 v167, v172, v173
	v_cvt_pk_bf16_f32 v168, v174, v175
	v_cvt_pk_bf16_f32 v169, v182, v183
	global_store_dwordx4 v[210:211], v[166:169], off offset:256

; #define PG8_STAGE(bufoff, gbase, voff) do { _Pragma("unroll") for (int _i = 0; _i < 2; ++_i) \
;         __builtin_amdgcn_global_load_lds((const unsigned*)((const char*)(gbase) + (voff)[_i]), (LAS unsigned*)(lds + (bufoff) + ldsw + _i * 8192), 16, 0, 0); } while (0)
; #define PG8_LDA(dst, b, h) do { _Pragma("unroll") for (int m = 0; m < 4; ++m) _Pragma("unroll") for (int k = 0; k < 2; ++k) dst[m][k] = *(const LAS bf16x8*)(lds + PG8_SA(b, h) + aoff + m * 2048 + k * 1024); } while (0)
; #define PG8_LDB(dst, b, h) do { _Pragma("unroll") for (int n = 0; n < 2; ++n) _Pragma("unroll") for (int k = 0; k < 2; ++k) dst[n][k] = *(const LAS bf16x8*)(lds + PG8_SB(b, h) + boff + n * 2048 + k * 1024); } while (0)
; #define PG8_WAIT_V(n) asm volatile("s_waitcnt vmcnt(" #n ")" ::: "memory")
; #define PG8_WAIT_L(n) asm volatile("s_waitcnt lgkmcnt(" #n ")" ::: "memory")
; #define PG8_BAR __builtin_amdgcn_s_barrier()
; #define PG8_SCHED __builtin_amdgcn_sched_barrier(0)
; #define PG8_BAR __builtin_amdgcn_s_barrier()
; template <class Epi>
; DI void gemm_phase(LAS unsigned char* lds, const Gemm g, const StaticOrder S, const Epi E) {
;     ...
;             PG8_LDB(B0, 0, 0); PG8_SCHED; PG8_LDA(At, 0, 0); PG8_STAGE(PG8_SA(1, 1), a1 + hstep, voffA);
;             PG8_WAIT_L(8); PG8_BAR; PG8_WAIT_L(0); PG8_MMA(0, 0, At, B0); PG8_BAR; PG8_SCHED;
;             PG8_LDB(B1, 0, 1); PG8_STAGE(PG8_SB(0, 0), b2, voffB);
;             PG8_BAR; PG8_WAIT_L(0); PG8_MMA(0, 1, At, B1); PG8_BAR;
;             PG8_LDA(At, 0, 1); PG8_STAGE(PG8_SA(0, 0), a2, voffA);
;             PG8_BAR; PG8_WAIT_L(0); PG8_MMA(1, 0, At, B0); PG8_BAR; PG8_SCHED;
;             PG8_STAGE(PG8_SB(0, 1), b2 + hstep, voffB);
;             PG8_WAIT_V(6); PG8_BAR; PG8_MMA(1, 1, At, B1); PG8_BAR;
;             PG8_LDB(B0, 1, 0); PG8_SCHED; PG8_LDA(At, 1, 0); PG8_STAGE(PG8_SA(0, 1), a2 + hstep, voffA);
;             PG8_WAIT_L(8); PG8_BAR; PG8_WAIT_L(0); PG8_MMA(0, 0, At, B0); PG8_BAR; PG8_SCHED;
;             PG8_LDB(B1, 1, 1); PG8_STAGE(PG8_SB(1, 0), b3, voffB);
;             PG8_BAR; PG8_WAIT_L(0); PG8_MMA(0, 1, At, B1); PG8_BAR;
;             PG8_LDA(At, 1, 1); PG8_STAGE(PG8_SA(1, 0), a3, voffA);
;             PG8_BAR; PG8_WAIT_L(0); PG8_MMA(1, 0, At, B0); PG8_BAR; PG8_SCHED;
;             PG8_STAGE(PG8_SB(1, 1), b3 + hstep, voffB);
;             PG8_WAIT_V(6); PG8_BAR; PG8_MMA(1, 1, At, B1); PG8_BAR;
.LBB0_786:
	ds_read_b128 v[128:131], v187
	ds_read_b128 v[132:135], v187 offset:1024
	ds_read_b128 v[136:139], v187 offset:2048
	ds_read_b128 v[140:143], v187 offset:3072
	s_add_u32 s28, s24, 0xfffc0080
	s_addc_u32 s29, s25, -1
	s_cmp_eq_u32 s52, 12
	s_cselect_b32 s39, s6, s29
	s_cselect_b32 s38, s7, s28
	s_cselect_b32 s29, s11, s51
	s_cselect_b32 s28, s13, s50
	v_lshl_add_u64 v[200:201], s[24:25], 0, v[160:161]
	s_add_i32 m0, s19, 0xc000
	ds_read_b128 v[144:147], v188
	ds_read_b128 v[148:151], v188 offset:1024
	ds_read_b128 v[168:171], v188 offset:2048
	ds_read_b128 v[172:175], v188 offset:3072
	ds_read_b128 v[176:179], v188 offset:4096
	ds_read_b128 v[180:183], v188 offset:5120
	ds_read_b128 v[192:195], v188 offset:6144
	ds_read_b128 v[196:199], v188 offset:7168
	global_load_lds_dwordx4 v[200:201], off
	v_lshl_add_u64 v[200:201], s[24:25], 0, v[162:163]
	s_add_i32 m0, s19, 0xe000
	s_nop 0
	global_load_lds_dwordx4 v[200:201], off
	s_waitcnt lgkmcnt(8)
	s_setprio 1
	s_barrier
	s_waitcnt lgkmcnt(0)
	v_mfma_f32_16x16x32_bf16 v[124:127], v[128:131], v[144:147], v[124:127]
	v_mfma_f32_16x16x32_bf16 v[120:123], v[136:139], v[144:147], v[120:123]
	v_mfma_f32_16x16x32_bf16 v[108:111], v[128:131], v[168:171], v[108:111]
	v_mfma_f32_16x16x32_bf16 v[104:107], v[136:139], v[168:171], v[104:107]
	v_mfma_f32_16x16x32_bf16 v[92:95], v[128:131], v[176:179], v[92:95]
	v_mfma_f32_16x16x32_bf16 v[88:91], v[136:139], v[176:179], v[88:91]
	v_mfma_f32_16x16x32_bf16 v[76:79], v[128:131], v[192:195], v[76:79]
	v_mfma_f32_16x16x32_bf16 v[72:75], v[136:139], v[192:195], v[72:75]
	v_mfma_f32_16x16x32_bf16 v[124:127], v[132:135], v[148:151], v[124:127]
	v_mfma_f32_16x16x32_bf16 v[120:123], v[140:143], v[148:151], v[120:123]
	v_mfma_f32_16x16x32_bf16 v[108:111], v[132:135], v[172:175], v[108:111]
	v_mfma_f32_16x16x32_bf16 v[104:107], v[140:143], v[172:175], v[104:107]
	v_mfma_f32_16x16x32_bf16 v[92:95], v[132:135], v[180:183], v[92:95]
	v_mfma_f32_16x16x32_bf16 v[88:91], v[140:143], v[180:183], v[88:91]
	s_setprio 2
	s_barrier
	v_mfma_f32_16x16x32_bf16 v[76:79], v[132:135], v[196:199], v[76:79]
	v_mfma_f32_16x16x32_bf16 v[72:75], v[140:143], v[196:199], v[72:75]
	s_setprio 0
	s_add_i32 s53, s48, s40
	v_lshl_add_u64 v[216:217], s[28:29], 0, v[154:155]
	s_mov_b32 m0, s53
	ds_read_b128 v[200:203], v189
	ds_read_b128 v[204:207], v189 offset:1024
	ds_read_b128 v[208:211], v189 offset:2048
	ds_read_b128 v[212:215], v189 offset:3072
	global_load_lds_dwordx4 v[216:217], off
	v_lshl_add_u64 v[218:219], s[28:29], 0, v[158:159]
	s_add_i32 m0, s53, 0x2000
	s_nop 0
	global_load_lds_dwordx4 v[218:219], off
	s_setprio 1
	s_barrier
	s_waitcnt lgkmcnt(0)
	v_mfma_f32_16x16x32_bf16 v[116:119], v[200:203], v[144:147], v[116:119]
	v_mfma_f32_16x16x32_bf16 v[112:115], v[208:211], v[144:147], v[112:115]
	v_mfma_f32_16x16x32_bf16 v[100:103], v[200:203], v[168:171], v[100:103]
	v_mfma_f32_16x16x32_bf16 v[96:99], v[208:211], v[168:171], v[96:99]
	v_mfma_f32_16x16x32_bf16 v[84:87], v[200:203], v[176:179], v[84:87]
	v_mfma_f32_16x16x32_bf16 v[80:83], v[208:211], v[176:179], v[80:83]
	v_mfma_f32_16x16x32_bf16 v[68:71], v[200:203], v[192:195], v[68:71]
	v_mfma_f32_16x16x32_bf16 v[64:67], v[208:211], v[192:195], v[64:67]
	v_mfma_f32_16x16x32_bf16 v[116:119], v[204:207], v[148:151], v[116:119]
	v_mfma_f32_16x16x32_bf16 v[112:115], v[212:215], v[148:151], v[112:115]
	v_mfma_f32_16x16x32_bf16 v[100:103], v[204:207], v[172:175], v[100:103]
	v_mfma_f32_16x16x32_bf16 v[96:99], v[212:215], v[172:175], v[96:99]
	v_mfma_f32_16x16x32_bf16 v[84:87], v[204:207], v[180:183], v[84:87]
	v_mfma_f32_16x16x32_bf16 v[80:83], v[212:215], v[180:183], v[80:83]
	s_setprio 2
	s_barrier
	v_mfma_f32_16x16x32_bf16 v[68:71], v[204:207], v[196:199], v[68:71]
	v_mfma_f32_16x16x32_bf16 v[64:67], v[212:215], v[196:199], v[64:67]
	s_setprio 0
	s_mov_b32 m0, s19
	v_lshl_add_u64 v[220:221], s[38:39], 0, v[152:153]
	ds_read_b128 v[144:147], v188 offset:16384
	ds_read_b128 v[148:151], v188 offset:17408
	ds_read_b128 v[168:171], v188 offset:18432
	ds_read_b128 v[172:175], v188 offset:19456
	ds_read_b128 v[176:179], v188 offset:20480
	ds_read_b128 v[180:183], v188 offset:21504
	ds_read_b128 v[192:195], v188 offset:22528
	ds_read_b128 v[196:199], v188 offset:23552
	global_load_lds_dwordx4 v[220:221], off
	v_lshl_add_u64 v[224:225], s[38:39], 0, v[156:157]
	s_mov_b32 m0, s23
	s_nop 0
	global_load_lds_dwordx4 v[224:225], off
	s_setprio 1
	s_barrier
	s_waitcnt lgkmcnt(0)
	v_mfma_f32_16x16x32_bf16 v[60:63], v[128:131], v[144:147], v[60:63]
	v_mfma_f32_16x16x32_bf16 v[56:59], v[136:139], v[144:147], v[56:59]
	v_mfma_f32_16x16x32_bf16 v[44:47], v[128:131], v[168:171], v[44:47]
	v_mfma_f32_16x16x32_bf16 v[40:43], v[136:139], v[168:171], v[40:43]
	v_mfma_f32_16x16x32_bf16 v[28:31], v[128:131], v[176:179], v[28:31]
	v_mfma_f32_16x16x32_bf16 v[24:27], v[136:139], v[176:179], v[24:27]
	v_mfma_f32_16x16x32_bf16 v[12:15], v[128:131], v[192:195], v[12:15]
	v_mfma_f32_16x16x32_bf16 v[8:11], v[136:139], v[192:195], v[8:11]
	v_mfma_f32_16x16x32_bf16 v[60:63], v[132:135], v[148:151], v[60:63]
	v_mfma_f32_16x16x32_bf16 v[56:59], v[140:143], v[148:151], v[56:59]
	v_mfma_f32_16x16x32_bf16 v[44:47], v[132:135], v[172:175], v[44:47]
	v_mfma_f32_16x16x32_bf16 v[40:43], v[140:143], v[172:175], v[40:43]
	v_mfma_f32_16x16x32_bf16 v[28:31], v[132:135], v[180:183], v[28:31]
	v_mfma_f32_16x16x32_bf16 v[24:27], v[140:143], v[180:183], v[24:27]
	s_setprio 2
	s_barrier
; #define PG8_STAGE(bufoff, gbase, voff) do { _Pragma("unroll") for (int _i = 0; _i < 2; ++_i) \
;         __builtin_amdgcn_global_load_lds((const unsigned*)((const char*)(gbase) + (voff)[_i]), (LAS unsigned*)(lds + (bufoff) + ldsw + _i * 8192), 16, 0, 0); } while (0)
; #define PG8_LDA(dst, b, h) do { _Pragma("unroll") for (int m = 0; m < 4; ++m) _Pragma("unroll") for (int k = 0; k < 2; ++k) dst[m][k] = *(const LAS bf16x8*)(lds + PG8_SA(b, h) + aoff + m * 2048 + k * 1024); } while (0)
; #define PG8_LDB(dst, b, h) do { _Pragma("unroll") for (int n = 0; n < 2; ++n) _Pragma("unroll") for (int k = 0; k < 2; ++k) dst[n][k] = *(const LAS bf16x8*)(lds + PG8_SB(b, h) + boff + n * 2048 + k * 1024); } while (0)
; #define PG8_MMA(ai, bj, At, Bt) do { __builtin_amdgcn_s_setprio(1); _Pragma("unroll") for (int m = 0; m < 4; ++m) _Pragma("unroll") for (int n = 0; n < 2; ++n) _Pragma("unroll") for (int k = 0; k < 2; ++k) \
;         acc[ai][bj][m][n] = __builtin_amdgcn_mfma_f32_16x16x32_bf16(Bt[n][k], At[m][k], acc[ai][bj][m][n], 0, 0, 0); __builtin_amdgcn_s_setprio(0); } while (0)
; #define PG8_WAIT_V(n) asm volatile("s_waitcnt vmcnt(" #n ")" ::: "memory")
; #define PG8_WAIT_L(n) asm volatile("s_waitcnt lgkmcnt(" #n ")" ::: "memory")
; #define PG8_BAR __builtin_amdgcn_s_barrier()
; #define PG8_SCHED __builtin_amdgcn_sched_barrier(0)
; #define PG8_STAGE(bufoff, gbase, voff) do { _Pragma("unroll") for (int _i = 0; _i < 2; ++_i) \
;         __builtin_amdgcn_global_load_lds((const unsigned*)((const char*)(gbase) + (voff)[_i]), (LAS unsigned*)(lds + (bufoff) + ldsw + _i * 8192), 16, 0, 0); } while (0)
; #define PG8_BAR __builtin_amdgcn_s_barrier()
; template <class Epi>
; DI void gemm_phase(LAS unsigned char* lds, const Gemm g, const StaticOrder S, const Epi E) {
;     ...
;             PG8_LDB(B0, 1, 0); PG8_SCHED; PG8_LDA(At, 1, 0); PG8_STAGE(PG8_SA(0, 1), a2 + hstep, voffA);
;             PG8_WAIT_L(8); PG8_BAR; PG8_WAIT_L(0); PG8_MMA(0, 0, At, B0); PG8_BAR; PG8_SCHED;
;             PG8_LDB(B1, 1, 1); PG8_STAGE(PG8_SB(1, 0), b3, voffB);
;             PG8_BAR; PG8_WAIT_L(0); PG8_MMA(0, 1, At, B1); PG8_BAR;
;             PG8_LDA(At, 1, 1); PG8_STAGE(PG8_SA(1, 0), a3, voffA);
;             PG8_BAR; PG8_WAIT_L(0); PG8_MMA(1, 0, At, B0); PG8_BAR; PG8_SCHED;
;             PG8_STAGE(PG8_SB(1, 1), b3 + hstep, voffB);
;             PG8_WAIT_V(6); PG8_BAR; PG8_MMA(1, 1, At, B1); PG8_BAR;
	v_mfma_f32_16x16x32_bf16 v[12:15], v[132:135], v[196:199], v[12:15]
	v_mfma_f32_16x16x32_bf16 v[8:11], v[140:143], v[196:199], v[8:11]
	s_setprio 0
	s_add_u32 s58, s28, 0x40000
	s_addc_u32 s59, s29, 0
	s_add_i32 s53, s49, s40
	v_lshl_add_u64 v[128:129], s[58:59], 0, v[154:155]
	s_mov_b32 m0, s53
	s_nop 0
	global_load_lds_dwordx4 v[128:129], off
	v_lshl_add_u64 v[128:129], s[58:59], 0, v[158:159]
	s_add_i32 m0, s53, 0x2000
	s_nop 0
	global_load_lds_dwordx4 v[128:129], off
	s_waitcnt vmcnt(6)
	s_setprio 1
	s_barrier
	v_mfma_f32_16x16x32_bf16 v[52:55], v[200:203], v[144:147], v[52:55]
	v_mfma_f32_16x16x32_bf16 v[48:51], v[208:211], v[144:147], v[48:51]
	v_mfma_f32_16x16x32_bf16 v[36:39], v[200:203], v[168:171], v[36:39]
	v_mfma_f32_16x16x32_bf16 v[32:35], v[208:211], v[168:171], v[32:35]
	v_mfma_f32_16x16x32_bf16 v[20:23], v[200:203], v[176:179], v[20:23]
	v_mfma_f32_16x16x32_bf16 v[16:19], v[208:211], v[176:179], v[16:19]
	v_mfma_f32_16x16x32_bf16 v[4:7], v[200:203], v[192:195], v[4:7]
	v_mfma_f32_16x16x32_bf16 v[0:3], v[208:211], v[192:195], v[0:3]
	v_mfma_f32_16x16x32_bf16 v[52:55], v[204:207], v[148:151], v[52:55]
	v_mfma_f32_16x16x32_bf16 v[48:51], v[212:215], v[148:151], v[48:51]
	v_mfma_f32_16x16x32_bf16 v[36:39], v[204:207], v[172:175], v[36:39]
	v_mfma_f32_16x16x32_bf16 v[32:35], v[212:215], v[172:175], v[32:35]
	v_mfma_f32_16x16x32_bf16 v[20:23], v[204:207], v[180:183], v[20:23]
	v_mfma_f32_16x16x32_bf16 v[16:19], v[212:215], v[180:183], v[16:19]
	s_setprio 2
	s_barrier
	v_mfma_f32_16x16x32_bf16 v[4:7], v[204:207], v[196:199], v[4:7]
	v_mfma_f32_16x16x32_bf16 v[0:3], v[212:215], v[196:199], v[0:3]
	s_setprio 0
	s_add_i32 s53, 0, 0x18000
	v_add_u32_e32 v140, s53, v185
	ds_read_b128 v[128:131], v140
	ds_read_b128 v[132:135], v140 offset:1024
	ds_read_b128 v[136:139], v140 offset:2048
	ds_read_b128 v[140:143], v140 offset:3072
	s_add_u32 s38, s38, 0x40000
	s_addc_u32 s39, s39, 0
	s_mov_b32 m0, s41
	v_lshl_add_u64 v[200:201], s[38:39], 0, v[152:153]
	ds_read_b128 v[144:147], v188 offset:32768
	ds_read_b128 v[148:151], v188 offset:33792
	ds_read_b128 v[168:171], v188 offset:34816
	ds_read_b128 v[172:175], v188 offset:35840
	ds_read_b128 v[176:179], v188 offset:36864
	ds_read_b128 v[180:183], v188 offset:37888
	ds_read_b128 v[192:195], v188 offset:38912
	ds_read_b128 v[196:199], v188 offset:39936
	global_load_lds_dwordx4 v[200:201], off
	v_lshl_add_u64 v[200:201], s[38:39], 0, v[156:157]
	s_mov_b32 m0, s42
	s_nop 0
	global_load_lds_dwordx4 v[200:201], off
	s_waitcnt lgkmcnt(8)
	s_setprio 1
	s_barrier
	s_waitcnt lgkmcnt(0)
	v_mfma_f32_16x16x32_bf16 v[124:127], v[128:131], v[144:147], v[124:127]
	v_mfma_f32_16x16x32_bf16 v[120:123], v[136:139], v[144:147], v[120:123]
	v_mfma_f32_16x16x32_bf16 v[108:111], v[128:131], v[168:171], v[108:111]
	v_mfma_f32_16x16x32_bf16 v[104:107], v[136:139], v[168:171], v[104:107]
	v_mfma_f32_16x16x32_bf16 v[92:95], v[128:131], v[176:179], v[92:95]
	v_mfma_f32_16x16x32_bf16 v[88:91], v[136:139], v[176:179], v[88:91]
	v_mfma_f32_16x16x32_bf16 v[76:79], v[128:131], v[192:195], v[76:79]
	v_mfma_f32_16x16x32_bf16 v[72:75], v[136:139], v[192:195], v[72:75]
	v_mfma_f32_16x16x32_bf16 v[124:127], v[132:135], v[148:151], v[124:127]
	v_mfma_f32_16x16x32_bf16 v[120:123], v[140:143], v[148:151], v[120:123]
	v_mfma_f32_16x16x32_bf16 v[108:111], v[132:135], v[172:175], v[108:111]
	v_mfma_f32_16x16x32_bf16 v[104:107], v[140:143], v[172:175], v[104:107]
	v_mfma_f32_16x16x32_bf16 v[92:95], v[132:135], v[180:183], v[92:95]
	v_mfma_f32_16x16x32_bf16 v[88:91], v[140:143], v[180:183], v[88:91]
	s_setprio 2
	s_barrier
	v_mfma_f32_16x16x32_bf16 v[76:79], v[132:135], v[196:199], v[76:79]
	v_mfma_f32_16x16x32_bf16 v[72:75], v[140:143], v[196:199], v[72:75]
	s_setprio 0
	s_add_i32 s38, 0, 0x1c000
	s_add_i32 s39, s53, s40
	v_add_u32_e32 v191, s38, v185
	v_lshl_add_u64 v[216:217], v[216:217], 0, s[8:9]
	s_mov_b32 m0, s39
	ds_read_b128 v[200:203], v191
	ds_read_b128 v[204:207], v191 offset:1024
	ds_read_b128 v[208:211], v191 offset:2048
	ds_read_b128 v[212:215], v191 offset:3072
	global_load_lds_dwordx4 v[216:217], off
	v_lshl_add_u64 v[216:217], v[218:219], 0, s[8:9]
	s_add_i32 m0, s39, 0x2000
	s_nop 0
	global_load_lds_dwordx4 v[216:217], off
	s_setprio 1
	s_barrier
	s_waitcnt lgkmcnt(0)
	v_mfma_f32_16x16x32_bf16 v[116:119], v[200:203], v[144:147], v[116:119]
	v_mfma_f32_16x16x32_bf16 v[112:115], v[208:211], v[144:147], v[112:115]
	v_mfma_f32_16x16x32_bf16 v[100:103], v[200:203], v[168:171], v[100:103]
	v_mfma_f32_16x16x32_bf16 v[96:99], v[208:211], v[168:171], v[96:99]
	v_mfma_f32_16x16x32_bf16 v[84:87], v[200:203], v[176:179], v[84:87]
	v_mfma_f32_16x16x32_bf16 v[80:83], v[208:211], v[176:179], v[80:83]
	v_mfma_f32_16x16x32_bf16 v[68:71], v[200:203], v[192:195], v[68:71]
	v_mfma_f32_16x16x32_bf16 v[64:67], v[208:211], v[192:195], v[64:67]
	v_mfma_f32_16x16x32_bf16 v[116:119], v[204:207], v[148:151], v[116:119]
	v_mfma_f32_16x16x32_bf16 v[112:115], v[212:215], v[148:151], v[112:115]
	v_mfma_f32_16x16x32_bf16 v[100:103], v[204:207], v[172:175], v[100:103]
	v_mfma_f32_16x16x32_bf16 v[96:99], v[212:215], v[172:175], v[96:99]
	v_mfma_f32_16x16x32_bf16 v[84:87], v[204:207], v[180:183], v[84:87]
	v_mfma_f32_16x16x32_bf16 v[80:83], v[212:215], v[180:183], v[80:83]
	s_setprio 2
	s_barrier
; #define PG8_STAGE(bufoff, gbase, voff) do { _Pragma("unroll") for (int _i = 0; _i < 2; ++_i) \
;         __builtin_amdgcn_global_load_lds((const unsigned*)((const char*)(gbase) + (voff)[_i]), (LAS unsigned*)(lds + (bufoff) + ldsw + _i * 8192), 16, 0, 0); } while (0)
; #define PG8_LDA(dst, b, h) do { _Pragma("unroll") for (int m = 0; m < 4; ++m) _Pragma("unroll") for (int k = 0; k < 2; ++k) dst[m][k] = *(const LAS bf16x8*)(lds + PG8_SA(b, h) + aoff + m * 2048 + k * 1024); } while (0)
; #define PG8_LDB(dst, b, h) do { _Pragma("unroll") for (int n = 0; n < 2; ++n) _Pragma("unroll") for (int k = 0; k < 2; ++k) dst[n][k] = *(const LAS bf16x8*)(lds + PG8_SB(b, h) + boff + n * 2048 + k * 1024); } while (0)
; #define PG8_MMA(ai, bj, At, Bt) do { __builtin_amdgcn_s_setprio(1); _Pragma("unroll") for (int m = 0; m < 4; ++m) _Pragma("unroll") for (int n = 0; n < 2; ++n) _Pragma("unroll") for (int k = 0; k < 2; ++k) \
;         acc[ai][bj][m][n] = __builtin_amdgcn_mfma_f32_16x16x32_bf16(Bt[n][k], At[m][k], acc[ai][bj][m][n], 0, 0, 0); __builtin_amdgcn_s_setprio(0); } while (0)
; #define PG8_WAIT_V(n) asm volatile("s_waitcnt vmcnt(" #n ")" ::: "memory")
; #define PG8_WAIT_L(n) asm volatile("s_waitcnt lgkmcnt(" #n ")" ::: "memory")
; #define PG8_BAR __builtin_amdgcn_s_barrier()
; #define PG8_SCHED __builtin_amdgcn_sched_barrier(0)
; #define PG8_STAGE(bufoff, gbase, voff) do { _Pragma("unroll") for (int _i = 0; _i < 2; ++_i) \
;         __builtin_amdgcn_global_load_lds((const unsigned*)((const char*)(gbase) + (voff)[_i]), (LAS unsigned*)(lds + (bufoff) + ldsw + _i * 8192), 16, 0, 0); } while (0)
; #define PG8_BAR __builtin_amdgcn_s_barrier()
; template <class Epi>
; DI void gemm_phase(LAS unsigned char* lds, const Gemm g, const StaticOrder S, const Epi E) {
;     ...
;             PG8_LDB(B0, 1, 0); PG8_SCHED; PG8_LDA(At, 1, 0); PG8_STAGE(PG8_SA(0, 1), a2 + hstep, voffA);
;             PG8_WAIT_L(8); PG8_BAR; PG8_WAIT_L(0); PG8_MMA(0, 0, At, B0); PG8_BAR; PG8_SCHED;
;             PG8_LDB(B1, 1, 1); PG8_STAGE(PG8_SB(1, 0), b3, voffB);
;             PG8_BAR; PG8_WAIT_L(0); PG8_MMA(0, 1, At, B1); PG8_BAR;
;             PG8_LDA(At, 1, 1); PG8_STAGE(PG8_SA(1, 0), a3, voffA);
;             PG8_BAR; PG8_WAIT_L(0); PG8_MMA(1, 0, At, B0); PG8_BAR; PG8_SCHED;
;             PG8_STAGE(PG8_SB(1, 1), b3 + hstep, voffB);
;             PG8_WAIT_V(6); PG8_BAR; PG8_MMA(1, 1, At, B1); PG8_BAR;
	v_mfma_f32_16x16x32_bf16 v[68:71], v[204:207], v[196:199], v[68:71]
	v_mfma_f32_16x16x32_bf16 v[64:67], v[212:215], v[196:199], v[64:67]
	s_setprio 0
	s_mov_b32 m0, s44
	v_lshl_add_u64 v[216:217], v[220:221], 0, s[8:9]
	ds_read_b128 v[144:147], v188 offset:49152
	ds_read_b128 v[148:151], v188 offset:50176
	ds_read_b128 v[168:171], v188 offset:51200
	ds_read_b128 v[172:175], v188 offset:52224
	ds_read_b128 v[176:179], v188 offset:53248
	ds_read_b128 v[180:183], v188 offset:54272
	ds_read_b128 v[192:195], v188 offset:55296
	ds_read_b128 v[196:199], v188 offset:56320
	global_load_lds_dwordx4 v[216:217], off
	v_lshl_add_u64 v[216:217], v[224:225], 0, s[8:9]
	s_mov_b32 m0, s45
	s_nop 0
	global_load_lds_dwordx4 v[216:217], off
	s_setprio 1
	s_barrier
	s_waitcnt lgkmcnt(0)
	v_mfma_f32_16x16x32_bf16 v[60:63], v[128:131], v[144:147], v[60:63]
	v_mfma_f32_16x16x32_bf16 v[56:59], v[136:139], v[144:147], v[56:59]
	v_mfma_f32_16x16x32_bf16 v[44:47], v[128:131], v[168:171], v[44:47]
	v_mfma_f32_16x16x32_bf16 v[40:43], v[136:139], v[168:171], v[40:43]
	v_mfma_f32_16x16x32_bf16 v[28:31], v[128:131], v[176:179], v[28:31]
	v_mfma_f32_16x16x32_bf16 v[24:27], v[136:139], v[176:179], v[24:27]
	v_mfma_f32_16x16x32_bf16 v[12:15], v[128:131], v[192:195], v[12:15]
	v_mfma_f32_16x16x32_bf16 v[8:11], v[136:139], v[192:195], v[8:11]
	v_mfma_f32_16x16x32_bf16 v[60:63], v[132:135], v[148:151], v[60:63]
	v_mfma_f32_16x16x32_bf16 v[56:59], v[140:143], v[148:151], v[56:59]
	v_mfma_f32_16x16x32_bf16 v[44:47], v[132:135], v[172:175], v[44:47]
	v_mfma_f32_16x16x32_bf16 v[40:43], v[140:143], v[172:175], v[40:43]
	v_mfma_f32_16x16x32_bf16 v[28:31], v[132:135], v[180:183], v[28:31]
	v_mfma_f32_16x16x32_bf16 v[24:27], v[140:143], v[180:183], v[24:27]
	s_setprio 2
	s_barrier
	v_mfma_f32_16x16x32_bf16 v[12:15], v[132:135], v[196:199], v[12:15]
	v_mfma_f32_16x16x32_bf16 v[8:11], v[140:143], v[196:199], v[8:11]
	s_setprio 0
	s_add_u32 s28, s28, 0x40080
	s_addc_u32 s29, s29, 0
	s_add_i32 s38, s38, s40
	v_lshl_add_u64 v[128:129], s[28:29], 0, v[154:155]
	s_mov_b32 m0, s38
	s_nop 0
	global_load_lds_dwordx4 v[128:129], off
	v_lshl_add_u64 v[128:129], s[28:29], 0, v[158:159]
	s_add_i32 m0, s38, 0x2000
	s_nop 0
	global_load_lds_dwordx4 v[128:129], off
	s_waitcnt vmcnt(6)
	s_setprio 1
	s_barrier
	v_mfma_f32_16x16x32_bf16 v[52:55], v[200:203], v[144:147], v[52:55]
	v_mfma_f32_16x16x32_bf16 v[48:51], v[208:211], v[144:147], v[48:51]
	v_mfma_f32_16x16x32_bf16 v[36:39], v[200:203], v[168:171], v[36:39]
	v_mfma_f32_16x16x32_bf16 v[32:35], v[208:211], v[168:171], v[32:35]
	v_mfma_f32_16x16x32_bf16 v[20:23], v[200:203], v[176:179], v[20:23]
	v_mfma_f32_16x16x32_bf16 v[16:19], v[208:211], v[176:179], v[16:19]
	v_mfma_f32_16x16x32_bf16 v[4:7], v[200:203], v[192:195], v[4:7]
	v_mfma_f32_16x16x32_bf16 v[0:3], v[208:211], v[192:195], v[0:3]
	v_mfma_f32_16x16x32_bf16 v[52:55], v[204:207], v[148:151], v[52:55]
	v_mfma_f32_16x16x32_bf16 v[48:51], v[212:215], v[148:151], v[48:51]
	v_mfma_f32_16x16x32_bf16 v[36:39], v[204:207], v[172:175], v[36:39]
	v_mfma_f32_16x16x32_bf16 v[32:35], v[212:215], v[172:175], v[32:35]
	v_mfma_f32_16x16x32_bf16 v[20:23], v[204:207], v[180:183], v[20:23]
	v_mfma_f32_16x16x32_bf16 v[16:19], v[212:215], v[180:183], v[16:19]
	s_setprio 2
	s_barrier
	v_mfma_f32_16x16x32_bf16 v[4:7], v[204:207], v[196:199], v[4:7]
	v_mfma_f32_16x16x32_bf16 v[0:3], v[212:215], v[196:199], v[0:3]
	s_setprio 0
	s_add_i32 s52, s52, 2
	s_add_u32 s24, s24, 0x100
	s_addc_u32 s25, s25, 0
	s_add_u32 s50, s50, 0x100
	s_addc_u32 s51, s51, 0
	s_cmp_gt_u32 s52, 13
	s_cbranch_scc0 .LBB0_786
; DI unsigned pk_bf16(float lo, float hi) { f32x2 v = {lo, hi}; return __builtin_bit_cast(unsigned, __builtin_convertvector(v, bf16v2)); }
; DI f32x4 bf_lo4(u32x4 w) { f32x4 r; r[0] = bf_lo(w.x); r[1] = bf_hi(w.x); r[2] = bf_lo(w.y); r[3] = bf_hi(w.y); return r; }
; DI f32x4 bf_hi4(u32x4 w) { f32x4 r; r[0] = bf_lo(w.z); r[1] = bf_hi(w.z); r[2] = bf_lo(w.w); r[3] = bf_hi(w.w); return r; }
;     DI void operator()(AccRef acc, const Unit& u, int wr, int wc, int fr, int fq) const {
;     ...
;         const int row0 = u.pm * 256 + wr * 64 + fr, col0 = u.pn * 256 + wc * 32 + 8 * fq;
; #pragma unroll
;         for (int ai = 0; ai < 2; ++ai) {
;             f32x4 bv[4][2][2];
; #pragma unroll
;             for (int m = 0; m < 4; ++m)
; #pragma unroll
;                 for (int bj = 0; bj < 2; ++bj) {
;                     const size_t o = (size_t)(row0 + ai * 128 + m * 16) * DM + col0 + bj * 128;
;                     if (BASEF32) { bv[m][bj][0] = *(const f32x4*)(basef + o); bv[m][bj][1] = *(const f32x4*)(basef + o + 4); }
;                     else { const u32x4 h = *(const u32x4*)(xnb + o); bv[m][bj][0] = bf_lo4(h); bv[m][bj][1] = bf_hi4(h); }
;                 }
; #pragma unroll
;             for (int m = 0; m < 4; ++m) {
;                 const int row = row0 + ai * 128 + m * 16;
;                 float q = 0.f;
; #pragma unroll
;                 for (int bj = 0; bj < 2; ++bj) {
;                     const size_t o = (size_t)row * DM + col0 + bj * 128;
;                     const f32x4 r0 = bv[m][bj][0] + scale * acc[ai][bj][m][0], r1 = bv[m][bj][1] + scale * acc[ai][bj][m][1];
;                     u32x4 w; w.x = pk_bf16(r0[0], r0[1]); w.y = pk_bf16(r0[2], r0[3]); w.z = pk_bf16(r1[0], r1[1]); w.w = pk_bf16(r1[2], r1[3]);
;                     *(u32x4*)(xnb + o) = w;
;                     if (STATS) q += r0[0] * r0[0] + r0[1] * r0[1] + r0[2] * r0[2] + r0[3] * r0[3] + r1[0] * r1[0] + r1[1] * r1[1] + r1[2] * r1[2] + r1[3] * r1[3];
;                 }
;                 if (STATS) { q += __shfl_xor(q, 16); q += __shfl_xor(q, 32); if (fq == 0) atomicAdd(ss + row, q); }
	v_lshl_add_u32 v170, s18, 8, v184
	v_lshl_or_b32 v128, s22, 8, v186
	v_ashrrev_i32_e32 v129, 31, v128
	v_ashrrev_i32_e32 v171, 31, v170
	v_lshl_add_u64 v[168:169], v[128:129], 1, s[56:57]
	v_lshlrev_b64 v[128:129], 11, v[170:171]
	v_lshl_add_u64 v[202:203], v[168:169], 0, v[128:129]
	global_load_dwordx4 v[194:197], v[202:203], off
	global_load_dwordx4 v[198:201], v[202:203], off offset:256
	v_or_b32_e32 v180, 16, v170
	v_or_b32_e32 v176, 32, v170
	v_or_b32_e32 v172, 48, v170
	v_ashrrev_i32_e32 v181, 31, v180
	v_ashrrev_i32_e32 v177, 31, v176
	v_ashrrev_i32_e32 v173, 31, v172
	v_lshlrev_b64 v[128:129], 11, v[180:181]
	v_lshlrev_b64 v[130:131], 11, v[176:177]
	v_lshlrev_b64 v[132:133], 11, v[172:173]
	v_lshl_add_u64 v[182:183], v[168:169], 0, v[128:129]
	v_lshl_add_u64 v[178:179], v[168:169], 0, v[130:131]
	v_lshl_add_u64 v[174:175], v[168:169], 0, v[132:133]
	global_load_dwordx4 v[148:151], v[182:183], off
	global_load_dwordx4 v[144:147], v[182:183], off offset:256
	global_load_dwordx4 v[140:143], v[178:179], off
	global_load_dwordx4 v[136:139], v[178:179], off offset:256
	global_load_dwordx4 v[132:135], v[174:175], off
	global_load_dwordx4 v[128:131], v[174:175], off offset:256
	v_and_b32_e32 v192, 64, v190
	v_xor_b32_e32 v191, 16, v190
	v_add_u32_e32 v192, 64, v192
	v_cmp_lt_i32_e32 vcc, v191, v192
	v_xor_b32_e32 v193, 32, v190
	s_waitcnt vmcnt(0)
	v_lshlrev_b32_e32 v204, 16, v194
	v_and_b32_e32 v205, 0xffff0000, v194
	v_lshlrev_b32_e32 v208, 16, v198
	v_and_b32_e32 v209, 0xffff0000, v198
	v_lshlrev_b32_e32 v194, 16, v195
	v_and_b32_e32 v195, 0xffff0000, v195
	v_lshlrev_b32_e32 v210, 16, v200
	v_and_b32_e32 v211, 0xffff0000, v200
	v_lshlrev_b32_e32 v200, 16, v201
	v_and_b32_e32 v201, 0xffff0000, v201
	v_pk_add_f32 v[124:125], v[124:125], v[204:205]
	v_pk_add_f32 v[116:117], v[116:117], v[208:209]
	v_lshlrev_b32_e32 v198, 16, v199
	v_and_b32_e32 v199, 0xffff0000, v199
	v_pk_add_f32 v[126:127], v[126:127], v[194:195]
	v_pk_add_f32 v[194:195], v[114:115], v[200:201]
	v_mul_f32_e32 v114, v125, v125
	v_mul_f32_e32 v115, v117, v117
	v_pk_add_f32 v[118:119], v[118:119], v[198:199]
	v_fmac_f32_e32 v114, v124, v124
	v_fmac_f32_e32 v115, v116, v116
	v_lshlrev_b32_e32 v206, 16, v196
	v_and_b32_e32 v207, 0xffff0000, v196
	v_lshlrev_b32_e32 v196, 16, v197
	v_and_b32_e32 v197, 0xffff0000, v197
	v_fmac_f32_e32 v114, v126, v126
	v_fmac_f32_e32 v115, v118, v118
	v_pk_add_f32 v[122:123], v[122:123], v[196:197]
	v_pk_add_f32 v[120:121], v[120:121], v[206:207]
	v_pk_add_f32 v[196:197], v[112:113], v[210:211]
	v_fmac_f32_e32 v114, v127, v127
	v_fmac_f32_e32 v115, v119, v119
	v_fmac_f32_e32 v114, v120, v120
	v_fmac_f32_e32 v115, v196, v196
	v_fmac_f32_e32 v114, v121, v121
	v_fmac_f32_e32 v115, v197, v197
	v_fmac_f32_e32 v114, v122, v122
	v_fmac_f32_e32 v115, v194, v194
	v_cndmask_b32_e32 v191, v190, v191, vcc
	v_fmac_f32_e32 v114, v123, v123
	v_fmac_f32_e32 v115, v195, v195
	v_cmp_lt_i32_e32 vcc, v193, v192
	v_lshlrev_b32_e32 v192, 2, v191
	v_cvt_pk_bf16_f32 v112, v124, v125
	v_add_f32_e32 v124, v114, v115
	ds_bpermute_b32 v125, v192, v124
	v_cndmask_b32_e32 v193, v190, v193, vcc
	v_cvt_pk_bf16_f32 v113, v126, v127
	v_cvt_pk_bf16_f32 v114, v120, v121
	v_cvt_pk_bf16_f32 v115, v122, v123
	v_lshlrev_b32_e32 v191, 2, v193
	global_store_dwordx4 v[202:203], v[112:115], off
	s_waitcnt lgkmcnt(0)
	s_nop 0
	v_add_f32_e32 v112, v124, v125
	ds_bpermute_b32 v113, v191, v112
	v_cvt_pk_bf16_f32 v114, v116, v117
	v_cvt_pk_bf16_f32 v115, v118, v119
	v_cvt_pk_bf16_f32 v116, v196, v197
	v_cvt_pk_bf16_f32 v117, v194, v195
	global_store_dwordx4 v[202:203], v[114:117], off offset:256
	s_and_saveexec_b64 s[6:7], s[0:1]
	s_cbranch_execz .LBB0_789
	s_waitcnt lgkmcnt(0)
	v_add_f32_e32 v114, v112, v113
	v_lshl_add_u64 v[112:113], v[170:171], 2, s[20:21]
	global_atomic_add_f32 v[112:113], v114, off

; #define PG8_STAGE(bufoff, gbase, voff) do { _Pragma("unroll") for (int _i = 0; _i < 2; ++_i) \
;         __builtin_amdgcn_global_load_lds((const unsigned*)((const char*)(gbase) + (voff)[_i]), (LAS unsigned*)(lds + (bufoff) + ldsw + _i * 8192), 16, 0, 0); } while (0)
; #define PG8_LDA(dst, b, h) do { _Pragma("unroll") for (int m = 0; m < 4; ++m) _Pragma("unroll") for (int k = 0; k < 2; ++k) dst[m][k] = *(const LAS bf16x8*)(lds + PG8_SA(b, h) + aoff + m * 2048 + k * 1024); } while (0)
; #define PG8_LDB(dst, b, h) do { _Pragma("unroll") for (int n = 0; n < 2; ++n) _Pragma("unroll") for (int k = 0; k < 2; ++k) dst[n][k] = *(const LAS bf16x8*)(lds + PG8_SB(b, h) + boff + n * 2048 + k * 1024); } while (0)
; #define PG8_WAIT_V(n) asm volatile("s_waitcnt vmcnt(" #n ")" ::: "memory")
; #define PG8_WAIT_L(n) asm volatile("s_waitcnt lgkmcnt(" #n ")" ::: "memory")
; #define PG8_BAR __builtin_amdgcn_s_barrier()
; #define PG8_SCHED __builtin_amdgcn_sched_barrier(0)
; #define PG8_BAR __builtin_amdgcn_s_barrier()
; template <class Epi>
; DI void gemm_phase(LAS unsigned char* lds, const Gemm g, const StaticOrder S, const Epi E) {
;     ...
;             PG8_LDB(B0, 0, 0); PG8_SCHED; PG8_LDA(At, 0, 0); PG8_STAGE(PG8_SA(1, 1), a1 + hstep, voffA);
;             PG8_WAIT_L(8); PG8_BAR; PG8_WAIT_L(0); PG8_MMA(0, 0, At, B0); PG8_BAR; PG8_SCHED;
;             PG8_LDB(B1, 0, 1); PG8_STAGE(PG8_SB(0, 0), b2, voffB);
;             PG8_BAR; PG8_WAIT_L(0); PG8_MMA(0, 1, At, B1); PG8_BAR;
;             PG8_LDA(At, 0, 1); PG8_STAGE(PG8_SA(0, 0), a2, voffA);
;             PG8_BAR; PG8_WAIT_L(0); PG8_MMA(1, 0, At, B0); PG8_BAR; PG8_SCHED;
;             PG8_STAGE(PG8_SB(0, 1), b2 + hstep, voffB);
;             PG8_WAIT_V(6); PG8_BAR; PG8_MMA(1, 1, At, B1); PG8_BAR;
;             PG8_LDB(B0, 1, 0); PG8_SCHED; PG8_LDA(At, 1, 0); PG8_STAGE(PG8_SA(0, 1), a2 + hstep, voffA);
;             PG8_WAIT_L(8); PG8_BAR; PG8_WAIT_L(0); PG8_MMA(0, 0, At, B0); PG8_BAR; PG8_SCHED;
;             PG8_LDB(B1, 1, 1); PG8_STAGE(PG8_SB(1, 0), b3, voffB);
;             PG8_BAR; PG8_WAIT_L(0); PG8_MMA(0, 1, At, B1); PG8_BAR;
;             PG8_LDA(At, 1, 1); PG8_STAGE(PG8_SA(1, 0), a3, voffA);
;             PG8_BAR; PG8_WAIT_L(0); PG8_MMA(1, 0, At, B0); PG8_BAR; PG8_SCHED;
;             PG8_STAGE(PG8_SB(1, 1), b3 + hstep, voffB);
;             PG8_WAIT_V(6); PG8_BAR; PG8_MMA(1, 1, At, B1); PG8_BAR;
.LBB0_865:
	ds_read_b128 v[144:147], v155
	ds_read_b128 v[160:163], v155 offset:1024
	ds_read_b128 v[164:167], v155 offset:2048
	ds_read_b128 v[168:171], v155 offset:3072
	s_add_u32 s10, s8, 0xfffc0080
	s_addc_u32 s11, s9, -1
	s_cmp_eq_u32 s25, 12
	s_cselect_b32 s13, s14, s11
	s_cselect_b32 s12, s15, s10
	s_cselect_b32 s11, s16, s19
	s_cselect_b32 s10, s17, s18
	v_lshl_add_u64 v[204:205], s[8:9], 0, v[136:137]
	s_add_i32 m0, s40, 0xc000
	ds_read_b128 v[172:175], v157
	ds_read_b128 v[176:179], v157 offset:1024
	ds_read_b128 v[180:183], v157 offset:2048
	ds_read_b128 v[184:187], v157 offset:3072
	ds_read_b128 v[188:191], v157 offset:4096
	ds_read_b128 v[192:195], v157 offset:5120
	ds_read_b128 v[196:199], v157 offset:6144
	ds_read_b128 v[200:203], v157 offset:7168
	global_load_lds_dwordx4 v[204:205], off
	v_lshl_add_u64 v[204:205], s[8:9], 0, v[138:139]
	s_add_i32 m0, s40, 0xe000
	s_nop 0
	global_load_lds_dwordx4 v[204:205], off
	s_waitcnt lgkmcnt(8)
	s_setprio 1
	s_barrier
	s_waitcnt lgkmcnt(0)
	v_mfma_f32_16x16x32_bf16 v[124:127], v[144:147], v[172:175], v[124:127]
	v_mfma_f32_16x16x32_bf16 v[120:123], v[164:167], v[172:175], v[120:123]
	v_mfma_f32_16x16x32_bf16 v[108:111], v[144:147], v[180:183], v[108:111]
	v_mfma_f32_16x16x32_bf16 v[104:107], v[164:167], v[180:183], v[104:107]
	v_mfma_f32_16x16x32_bf16 v[92:95], v[144:147], v[188:191], v[92:95]
	v_mfma_f32_16x16x32_bf16 v[88:91], v[164:167], v[188:191], v[88:91]
	v_mfma_f32_16x16x32_bf16 v[76:79], v[144:147], v[196:199], v[76:79]
	v_mfma_f32_16x16x32_bf16 v[72:75], v[164:167], v[196:199], v[72:75]
	v_mfma_f32_16x16x32_bf16 v[124:127], v[160:163], v[176:179], v[124:127]
	v_mfma_f32_16x16x32_bf16 v[120:123], v[168:171], v[176:179], v[120:123]
	v_mfma_f32_16x16x32_bf16 v[108:111], v[160:163], v[184:187], v[108:111]
	v_mfma_f32_16x16x32_bf16 v[104:107], v[168:171], v[184:187], v[104:107]
	v_mfma_f32_16x16x32_bf16 v[92:95], v[160:163], v[192:195], v[92:95]
	v_mfma_f32_16x16x32_bf16 v[88:91], v[168:171], v[192:195], v[88:91]
	s_setprio 2
	s_barrier
	v_mfma_f32_16x16x32_bf16 v[76:79], v[160:163], v[200:203], v[76:79]
	v_mfma_f32_16x16x32_bf16 v[72:75], v[168:171], v[200:203], v[72:75]
	s_setprio 0
	s_add_i32 s29, s49, s34
	v_lshl_add_u64 v[220:221], s[10:11], 0, v[132:133]
	s_mov_b32 m0, s29
	ds_read_b128 v[204:207], v158
	ds_read_b128 v[208:211], v158 offset:1024
	ds_read_b128 v[212:215], v158 offset:2048
	ds_read_b128 v[216:219], v158 offset:3072
	global_load_lds_dwordx4 v[220:221], off
	v_lshl_add_u64 v[224:225], s[10:11], 0, v[128:129]
	s_add_i32 m0, s29, 0x2000
	s_nop 0
	global_load_lds_dwordx4 v[224:225], off
	s_setprio 1
	s_barrier
	s_waitcnt lgkmcnt(0)
	v_mfma_f32_16x16x32_bf16 v[116:119], v[204:207], v[172:175], v[116:119]
	v_mfma_f32_16x16x32_bf16 v[112:115], v[212:215], v[172:175], v[112:115]
	v_mfma_f32_16x16x32_bf16 v[100:103], v[204:207], v[180:183], v[100:103]
	v_mfma_f32_16x16x32_bf16 v[96:99], v[212:215], v[180:183], v[96:99]
	v_mfma_f32_16x16x32_bf16 v[84:87], v[204:207], v[188:191], v[84:87]
	v_mfma_f32_16x16x32_bf16 v[80:83], v[212:215], v[188:191], v[80:83]
	v_mfma_f32_16x16x32_bf16 v[68:71], v[204:207], v[196:199], v[68:71]
	v_mfma_f32_16x16x32_bf16 v[64:67], v[212:215], v[196:199], v[64:67]
	v_mfma_f32_16x16x32_bf16 v[116:119], v[208:211], v[176:179], v[116:119]
	v_mfma_f32_16x16x32_bf16 v[112:115], v[216:219], v[176:179], v[112:115]
	v_mfma_f32_16x16x32_bf16 v[100:103], v[208:211], v[184:187], v[100:103]
	v_mfma_f32_16x16x32_bf16 v[96:99], v[216:219], v[184:187], v[96:99]
	v_mfma_f32_16x16x32_bf16 v[84:87], v[208:211], v[192:195], v[84:87]
	v_mfma_f32_16x16x32_bf16 v[80:83], v[216:219], v[192:195], v[80:83]
	s_setprio 2
	s_barrier
	v_mfma_f32_16x16x32_bf16 v[68:71], v[208:211], v[200:203], v[68:71]
	v_mfma_f32_16x16x32_bf16 v[64:67], v[216:219], v[200:203], v[64:67]
	s_setprio 0
	s_mov_b32 m0, s40
	v_lshl_add_u64 v[226:227], s[12:13], 0, v[134:135]
	ds_read_b128 v[172:175], v157 offset:16384
	ds_read_b128 v[176:179], v157 offset:17408
	ds_read_b128 v[180:183], v157 offset:18432
	ds_read_b128 v[184:187], v157 offset:19456
	ds_read_b128 v[188:191], v157 offset:20480
	ds_read_b128 v[192:195], v157 offset:21504
	ds_read_b128 v[196:199], v157 offset:22528
	ds_read_b128 v[200:203], v157 offset:23552
	global_load_lds_dwordx4 v[226:227], off
	v_lshl_add_u64 v[228:229], s[12:13], 0, v[130:131]
	s_mov_b32 m0, s41
	s_nop 0
	global_load_lds_dwordx4 v[228:229], off
	s_setprio 1
	s_barrier
	s_waitcnt lgkmcnt(0)
	v_mfma_f32_16x16x32_bf16 v[60:63], v[144:147], v[172:175], v[60:63]
	v_mfma_f32_16x16x32_bf16 v[56:59], v[164:167], v[172:175], v[56:59]
	v_mfma_f32_16x16x32_bf16 v[44:47], v[144:147], v[180:183], v[44:47]
	v_mfma_f32_16x16x32_bf16 v[40:43], v[164:167], v[180:183], v[40:43]
	v_mfma_f32_16x16x32_bf16 v[28:31], v[144:147], v[188:191], v[28:31]
	v_mfma_f32_16x16x32_bf16 v[24:27], v[164:167], v[188:191], v[24:27]
	v_mfma_f32_16x16x32_bf16 v[12:15], v[144:147], v[196:199], v[12:15]
	v_mfma_f32_16x16x32_bf16 v[8:11], v[164:167], v[196:199], v[8:11]
	v_mfma_f32_16x16x32_bf16 v[60:63], v[160:163], v[176:179], v[60:63]
	v_mfma_f32_16x16x32_bf16 v[56:59], v[168:171], v[176:179], v[56:59]
	v_mfma_f32_16x16x32_bf16 v[44:47], v[160:163], v[184:187], v[44:47]
	v_mfma_f32_16x16x32_bf16 v[40:43], v[168:171], v[184:187], v[40:43]
	v_mfma_f32_16x16x32_bf16 v[28:31], v[160:163], v[192:195], v[28:31]
	v_mfma_f32_16x16x32_bf16 v[24:27], v[168:171], v[192:195], v[24:27]
	s_setprio 2
	s_barrier
; #define PG8_STAGE(bufoff, gbase, voff) do { _Pragma("unroll") for (int _i = 0; _i < 2; ++_i) \
;         __builtin_amdgcn_global_load_lds((const unsigned*)((const char*)(gbase) + (voff)[_i]), (LAS unsigned*)(lds + (bufoff) + ldsw + _i * 8192), 16, 0, 0); } while (0)
; #define PG8_LDA(dst, b, h) do { _Pragma("unroll") for (int m = 0; m < 4; ++m) _Pragma("unroll") for (int k = 0; k < 2; ++k) dst[m][k] = *(const LAS bf16x8*)(lds + PG8_SA(b, h) + aoff + m * 2048 + k * 1024); } while (0)
; #define PG8_LDB(dst, b, h) do { _Pragma("unroll") for (int n = 0; n < 2; ++n) _Pragma("unroll") for (int k = 0; k < 2; ++k) dst[n][k] = *(const LAS bf16x8*)(lds + PG8_SB(b, h) + boff + n * 2048 + k * 1024); } while (0)
; #define PG8_MMA(ai, bj, At, Bt) do { __builtin_amdgcn_s_setprio(1); _Pragma("unroll") for (int m = 0; m < 4; ++m) _Pragma("unroll") for (int n = 0; n < 2; ++n) _Pragma("unroll") for (int k = 0; k < 2; ++k) \
;         acc[ai][bj][m][n] = __builtin_amdgcn_mfma_f32_16x16x32_bf16(Bt[n][k], At[m][k], acc[ai][bj][m][n], 0, 0, 0); __builtin_amdgcn_s_setprio(0); } while (0)
; #define PG8_WAIT_V(n) asm volatile("s_waitcnt vmcnt(" #n ")" ::: "memory")
; #define PG8_WAIT_L(n) asm volatile("s_waitcnt lgkmcnt(" #n ")" ::: "memory")
; #define PG8_BAR __builtin_amdgcn_s_barrier()
; #define PG8_SCHED __builtin_amdgcn_sched_barrier(0)
; #define PG8_STAGE(bufoff, gbase, voff) do { _Pragma("unroll") for (int _i = 0; _i < 2; ++_i) \
;         __builtin_amdgcn_global_load_lds((const unsigned*)((const char*)(gbase) + (voff)[_i]), (LAS unsigned*)(lds + (bufoff) + ldsw + _i * 8192), 16, 0, 0); } while (0)
; #define PG8_BAR __builtin_amdgcn_s_barrier()
; template <class Epi>
; DI void gemm_phase(LAS unsigned char* lds, const Gemm g, const StaticOrder S, const Epi E) {
;     ...
;             PG8_LDB(B0, 1, 0); PG8_SCHED; PG8_LDA(At, 1, 0); PG8_STAGE(PG8_SA(0, 1), a2 + hstep, voffA);
;             PG8_WAIT_L(8); PG8_BAR; PG8_WAIT_L(0); PG8_MMA(0, 0, At, B0); PG8_BAR; PG8_SCHED;
;             PG8_LDB(B1, 1, 1); PG8_STAGE(PG8_SB(1, 0), b3, voffB);
;             PG8_BAR; PG8_WAIT_L(0); PG8_MMA(0, 1, At, B1); PG8_BAR;
;             PG8_LDA(At, 1, 1); PG8_STAGE(PG8_SA(1, 0), a3, voffA);
;             PG8_BAR; PG8_WAIT_L(0); PG8_MMA(1, 0, At, B0); PG8_BAR; PG8_SCHED;
;             PG8_STAGE(PG8_SB(1, 1), b3 + hstep, voffB);
;             PG8_WAIT_V(6); PG8_BAR; PG8_MMA(1, 1, At, B1); PG8_BAR;
	v_mfma_f32_16x16x32_bf16 v[12:15], v[160:163], v[200:203], v[12:15]
	v_mfma_f32_16x16x32_bf16 v[8:11], v[168:171], v[200:203], v[8:11]
	s_setprio 0
	s_add_u32 s58, s10, 0x40000
	s_addc_u32 s59, s11, 0
	s_add_i32 s29, s50, s34
	v_lshl_add_u64 v[144:145], s[58:59], 0, v[132:133]
	s_mov_b32 m0, s29
	s_nop 0
	global_load_lds_dwordx4 v[144:145], off
	v_lshl_add_u64 v[144:145], s[58:59], 0, v[128:129]
	s_add_i32 m0, s29, 0x2000
	s_nop 0
	global_load_lds_dwordx4 v[144:145], off
	s_waitcnt vmcnt(6)
	s_setprio 1
	s_barrier
	v_mfma_f32_16x16x32_bf16 v[52:55], v[204:207], v[172:175], v[52:55]
	v_mfma_f32_16x16x32_bf16 v[48:51], v[212:215], v[172:175], v[48:51]
	v_mfma_f32_16x16x32_bf16 v[36:39], v[204:207], v[180:183], v[36:39]
	v_mfma_f32_16x16x32_bf16 v[32:35], v[212:215], v[180:183], v[32:35]
	v_mfma_f32_16x16x32_bf16 v[20:23], v[204:207], v[188:191], v[20:23]
	v_mfma_f32_16x16x32_bf16 v[16:19], v[212:215], v[188:191], v[16:19]
	v_mfma_f32_16x16x32_bf16 v[4:7], v[204:207], v[196:199], v[4:7]
	v_mfma_f32_16x16x32_bf16 v[0:3], v[212:215], v[196:199], v[0:3]
	v_mfma_f32_16x16x32_bf16 v[52:55], v[208:211], v[176:179], v[52:55]
	v_mfma_f32_16x16x32_bf16 v[48:51], v[216:219], v[176:179], v[48:51]
	v_mfma_f32_16x16x32_bf16 v[36:39], v[208:211], v[184:187], v[36:39]
	v_mfma_f32_16x16x32_bf16 v[32:35], v[216:219], v[184:187], v[32:35]
	v_mfma_f32_16x16x32_bf16 v[20:23], v[208:211], v[192:195], v[20:23]
	v_mfma_f32_16x16x32_bf16 v[16:19], v[216:219], v[192:195], v[16:19]
	s_setprio 2
	s_barrier
	v_mfma_f32_16x16x32_bf16 v[4:7], v[208:211], v[200:203], v[4:7]
	v_mfma_f32_16x16x32_bf16 v[0:3], v[216:219], v[200:203], v[0:3]
	s_setprio 0
	s_add_i32 s29, 0, 0x18000
	v_add_u32_e32 v148, s29, v151
	ds_read_b128 v[144:147], v148
	ds_read_b128 v[160:163], v148 offset:1024
	ds_read_b128 v[164:167], v148 offset:2048
	ds_read_b128 v[168:171], v148 offset:3072
	s_add_u32 s12, s12, 0x40000
	s_addc_u32 s13, s13, 0
	s_mov_b32 m0, s42
	v_lshl_add_u64 v[204:205], s[12:13], 0, v[134:135]
	ds_read_b128 v[172:175], v157 offset:32768
	ds_read_b128 v[176:179], v157 offset:33792
	ds_read_b128 v[180:183], v157 offset:34816
	ds_read_b128 v[184:187], v157 offset:35840
	ds_read_b128 v[188:191], v157 offset:36864
	ds_read_b128 v[192:195], v157 offset:37888
	ds_read_b128 v[196:199], v157 offset:38912
	ds_read_b128 v[200:203], v157 offset:39936
	global_load_lds_dwordx4 v[204:205], off
	v_lshl_add_u64 v[204:205], s[12:13], 0, v[130:131]
	s_mov_b32 m0, s43
	s_nop 0
	global_load_lds_dwordx4 v[204:205], off
	s_waitcnt lgkmcnt(8)
	s_setprio 1
	s_barrier
	s_waitcnt lgkmcnt(0)
	v_mfma_f32_16x16x32_bf16 v[124:127], v[144:147], v[172:175], v[124:127]
	v_mfma_f32_16x16x32_bf16 v[120:123], v[164:167], v[172:175], v[120:123]
	v_mfma_f32_16x16x32_bf16 v[108:111], v[144:147], v[180:183], v[108:111]
	v_mfma_f32_16x16x32_bf16 v[104:107], v[164:167], v[180:183], v[104:107]
	v_mfma_f32_16x16x32_bf16 v[92:95], v[144:147], v[188:191], v[92:95]
	v_mfma_f32_16x16x32_bf16 v[88:91], v[164:167], v[188:191], v[88:91]
	v_mfma_f32_16x16x32_bf16 v[76:79], v[144:147], v[196:199], v[76:79]
	v_mfma_f32_16x16x32_bf16 v[72:75], v[164:167], v[196:199], v[72:75]
	v_mfma_f32_16x16x32_bf16 v[124:127], v[160:163], v[176:179], v[124:127]
	v_mfma_f32_16x16x32_bf16 v[120:123], v[168:171], v[176:179], v[120:123]
	v_mfma_f32_16x16x32_bf16 v[108:111], v[160:163], v[184:187], v[108:111]
	v_mfma_f32_16x16x32_bf16 v[104:107], v[168:171], v[184:187], v[104:107]
	v_mfma_f32_16x16x32_bf16 v[92:95], v[160:163], v[192:195], v[92:95]
	v_mfma_f32_16x16x32_bf16 v[88:91], v[168:171], v[192:195], v[88:91]
	s_setprio 2
	s_barrier
	v_mfma_f32_16x16x32_bf16 v[76:79], v[160:163], v[200:203], v[76:79]
	v_mfma_f32_16x16x32_bf16 v[72:75], v[168:171], v[200:203], v[72:75]
	s_setprio 0
	s_add_i32 s12, 0, 0x1c000
	s_add_i32 s13, s29, s34
	v_add_u32_e32 v148, s12, v151
	v_lshl_add_u64 v[220:221], v[220:221], 0, s[22:23]
	s_mov_b32 m0, s13
	ds_read_b128 v[204:207], v148
	ds_read_b128 v[208:211], v148 offset:1024
	ds_read_b128 v[212:215], v148 offset:2048
	ds_read_b128 v[216:219], v148 offset:3072
	global_load_lds_dwordx4 v[220:221], off
	v_lshl_add_u64 v[220:221], v[224:225], 0, s[22:23]
	s_add_i32 m0, s13, 0x2000
	s_nop 0
	global_load_lds_dwordx4 v[220:221], off
	s_setprio 1
	s_barrier
	s_waitcnt lgkmcnt(0)
	v_mfma_f32_16x16x32_bf16 v[116:119], v[204:207], v[172:175], v[116:119]
	v_mfma_f32_16x16x32_bf16 v[112:115], v[212:215], v[172:175], v[112:115]
	v_mfma_f32_16x16x32_bf16 v[100:103], v[204:207], v[180:183], v[100:103]
	v_mfma_f32_16x16x32_bf16 v[96:99], v[212:215], v[180:183], v[96:99]
	v_mfma_f32_16x16x32_bf16 v[84:87], v[204:207], v[188:191], v[84:87]
	v_mfma_f32_16x16x32_bf16 v[80:83], v[212:215], v[188:191], v[80:83]
	v_mfma_f32_16x16x32_bf16 v[68:71], v[204:207], v[196:199], v[68:71]
	v_mfma_f32_16x16x32_bf16 v[64:67], v[212:215], v[196:199], v[64:67]
	v_mfma_f32_16x16x32_bf16 v[116:119], v[208:211], v[176:179], v[116:119]
	v_mfma_f32_16x16x32_bf16 v[112:115], v[216:219], v[176:179], v[112:115]
	v_mfma_f32_16x16x32_bf16 v[100:103], v[208:211], v[184:187], v[100:103]
	v_mfma_f32_16x16x32_bf16 v[96:99], v[216:219], v[184:187], v[96:99]
	v_mfma_f32_16x16x32_bf16 v[84:87], v[208:211], v[192:195], v[84:87]
	v_mfma_f32_16x16x32_bf16 v[80:83], v[216:219], v[192:195], v[80:83]
	s_setprio 2
	s_barrier
; #define PG8_STAGE(bufoff, gbase, voff) do { _Pragma("unroll") for (int _i = 0; _i < 2; ++_i) \
;         __builtin_amdgcn_global_load_lds((const unsigned*)((const char*)(gbase) + (voff)[_i]), (LAS unsigned*)(lds + (bufoff) + ldsw + _i * 8192), 16, 0, 0); } while (0)
; #define PG8_LDA(dst, b, h) do { _Pragma("unroll") for (int m = 0; m < 4; ++m) _Pragma("unroll") for (int k = 0; k < 2; ++k) dst[m][k] = *(const LAS bf16x8*)(lds + PG8_SA(b, h) + aoff + m * 2048 + k * 1024); } while (0)
; #define PG8_LDB(dst, b, h) do { _Pragma("unroll") for (int n = 0; n < 2; ++n) _Pragma("unroll") for (int k = 0; k < 2; ++k) dst[n][k] = *(const LAS bf16x8*)(lds + PG8_SB(b, h) + boff + n * 2048 + k * 1024); } while (0)
; #define PG8_MMA(ai, bj, At, Bt) do { __builtin_amdgcn_s_setprio(1); _Pragma("unroll") for (int m = 0; m < 4; ++m) _Pragma("unroll") for (int n = 0; n < 2; ++n) _Pragma("unroll") for (int k = 0; k < 2; ++k) \
;         acc[ai][bj][m][n] = __builtin_amdgcn_mfma_f32_16x16x32_bf16(Bt[n][k], At[m][k], acc[ai][bj][m][n], 0, 0, 0); __builtin_amdgcn_s_setprio(0); } while (0)
; #define PG8_WAIT_V(n) asm volatile("s_waitcnt vmcnt(" #n ")" ::: "memory")
; #define PG8_WAIT_L(n) asm volatile("s_waitcnt lgkmcnt(" #n ")" ::: "memory")
; #define PG8_BAR __builtin_amdgcn_s_barrier()
; #define PG8_SCHED __builtin_amdgcn_sched_barrier(0)
; #define PG8_BAR __builtin_amdgcn_s_barrier()
; template <class Epi>
; DI void gemm_phase(LAS unsigned char* lds, const Gemm g, const StaticOrder S, const Epi E) {
;     ...
;             PG8_LDB(B0, 1, 0); PG8_SCHED; PG8_LDA(At, 1, 0); PG8_STAGE(PG8_SA(0, 1), a2 + hstep, voffA);
;             PG8_WAIT_L(8); PG8_BAR; PG8_WAIT_L(0); PG8_MMA(0, 0, At, B0); PG8_BAR; PG8_SCHED;
;             PG8_LDB(B1, 1, 1); PG8_STAGE(PG8_SB(1, 0), b3, voffB);
;             PG8_BAR; PG8_WAIT_L(0); PG8_MMA(0, 1, At, B1); PG8_BAR;
;             PG8_LDA(At, 1, 1); PG8_STAGE(PG8_SA(1, 0), a3, voffA);
;             PG8_BAR; PG8_WAIT_L(0); PG8_MMA(1, 0, At, B0); PG8_BAR; PG8_SCHED;
;             PG8_STAGE(PG8_SB(1, 1), b3 + hstep, voffB);
;             PG8_WAIT_V(6); PG8_BAR; PG8_MMA(1, 1, At, B1); PG8_BAR;
;     DI void operator()(AccRef acc, const Unit& u, int wr, int wc, int fr, int fq) const {
;         const int row0 = u.pm * 256 + wr * 64 + fr, col = u.pn * 128 + wc * 32 + 8 * fq;
;         RowScales rsc; if (RS) rsc = load_rowscales(ss, row0);
	v_mfma_f32_16x16x32_bf16 v[68:71], v[208:211], v[200:203], v[68:71]
	v_mfma_f32_16x16x32_bf16 v[64:67], v[216:219], v[200:203], v[64:67]
	s_setprio 0
	s_mov_b32 m0, s45
	v_lshl_add_u64 v[220:221], v[226:227], 0, s[22:23]
	ds_read_b128 v[172:175], v157 offset:49152
	ds_read_b128 v[176:179], v157 offset:50176
	ds_read_b128 v[180:183], v157 offset:51200
	ds_read_b128 v[184:187], v157 offset:52224
	ds_read_b128 v[188:191], v157 offset:53248
	ds_read_b128 v[192:195], v157 offset:54272
	ds_read_b128 v[196:199], v157 offset:55296
	ds_read_b128 v[200:203], v157 offset:56320
	global_load_lds_dwordx4 v[220:221], off
	v_lshl_add_u64 v[220:221], v[228:229], 0, s[22:23]
	s_mov_b32 m0, s46
	s_nop 0
	global_load_lds_dwordx4 v[220:221], off
	s_setprio 1
	s_barrier
	s_waitcnt lgkmcnt(0)
	v_mfma_f32_16x16x32_bf16 v[60:63], v[144:147], v[172:175], v[60:63]
	v_mfma_f32_16x16x32_bf16 v[56:59], v[164:167], v[172:175], v[56:59]
	v_mfma_f32_16x16x32_bf16 v[44:47], v[144:147], v[180:183], v[44:47]
	v_mfma_f32_16x16x32_bf16 v[40:43], v[164:167], v[180:183], v[40:43]
	v_mfma_f32_16x16x32_bf16 v[28:31], v[144:147], v[188:191], v[28:31]
	v_mfma_f32_16x16x32_bf16 v[24:27], v[164:167], v[188:191], v[24:27]
	v_mfma_f32_16x16x32_bf16 v[12:15], v[144:147], v[196:199], v[12:15]
	v_mfma_f32_16x16x32_bf16 v[8:11], v[164:167], v[196:199], v[8:11]
	v_mfma_f32_16x16x32_bf16 v[60:63], v[160:163], v[176:179], v[60:63]
	v_mfma_f32_16x16x32_bf16 v[56:59], v[168:171], v[176:179], v[56:59]
	v_mfma_f32_16x16x32_bf16 v[44:47], v[160:163], v[184:187], v[44:47]
	v_mfma_f32_16x16x32_bf16 v[40:43], v[168:171], v[184:187], v[40:43]
	v_mfma_f32_16x16x32_bf16 v[28:31], v[160:163], v[192:195], v[28:31]
	v_mfma_f32_16x16x32_bf16 v[24:27], v[168:171], v[192:195], v[24:27]
	s_setprio 2
	s_barrier
	v_mfma_f32_16x16x32_bf16 v[12:15], v[160:163], v[200:203], v[12:15]
	v_mfma_f32_16x16x32_bf16 v[8:11], v[168:171], v[200:203], v[8:11]
	s_setprio 0
	s_add_u32 s10, s10, 0x40080
	s_addc_u32 s11, s11, 0
	s_add_i32 s12, s12, s34
	v_lshl_add_u64 v[144:145], s[10:11], 0, v[132:133]
	s_mov_b32 m0, s12
	s_nop 0
	global_load_lds_dwordx4 v[144:145], off
	v_lshl_add_u64 v[144:145], s[10:11], 0, v[128:129]
	s_add_i32 m0, s12, 0x2000
	s_nop 0
	global_load_lds_dwordx4 v[144:145], off
	s_waitcnt vmcnt(6)
	s_setprio 1
	s_barrier
	v_mfma_f32_16x16x32_bf16 v[52:55], v[204:207], v[172:175], v[52:55]
	v_mfma_f32_16x16x32_bf16 v[48:51], v[212:215], v[172:175], v[48:51]
	v_mfma_f32_16x16x32_bf16 v[36:39], v[204:207], v[180:183], v[36:39]
	v_mfma_f32_16x16x32_bf16 v[32:35], v[212:215], v[180:183], v[32:35]
	v_mfma_f32_16x16x32_bf16 v[20:23], v[204:207], v[188:191], v[20:23]
	v_mfma_f32_16x16x32_bf16 v[16:19], v[212:215], v[188:191], v[16:19]
	v_mfma_f32_16x16x32_bf16 v[4:7], v[204:207], v[196:199], v[4:7]
	v_mfma_f32_16x16x32_bf16 v[0:3], v[212:215], v[196:199], v[0:3]
	v_mfma_f32_16x16x32_bf16 v[52:55], v[208:211], v[176:179], v[52:55]
	v_mfma_f32_16x16x32_bf16 v[48:51], v[216:219], v[176:179], v[48:51]
	v_mfma_f32_16x16x32_bf16 v[36:39], v[208:211], v[184:187], v[36:39]
	v_mfma_f32_16x16x32_bf16 v[32:35], v[216:219], v[184:187], v[32:35]
	v_mfma_f32_16x16x32_bf16 v[20:23], v[208:211], v[192:195], v[20:23]
	v_mfma_f32_16x16x32_bf16 v[16:19], v[216:219], v[192:195], v[16:19]
	s_setprio 2
	s_barrier
	v_mfma_f32_16x16x32_bf16 v[4:7], v[208:211], v[200:203], v[4:7]
	v_mfma_f32_16x16x32_bf16 v[0:3], v[216:219], v[200:203], v[0:3]
	s_setprio 0
	s_add_i32 s25, s25, 2
	s_add_u32 s8, s8, 0x100
	s_addc_u32 s9, s9, 0
	s_add_u32 s18, s18, 0x100
	s_addc_u32 s19, s19, 0
	s_cmp_gt_u32 s25, 13
	s_cbranch_scc0 .LBB0_865
	v_lshl_add_u32 v146, s4, 8, v149
	v_ashrrev_i32_e32 v147, 31, v146
	v_lshl_add_u64 v[144:145], v[146:147], 2, s[20:21]
	global_load_dword v147, v[144:145], off
	global_load_dword v148, v[144:145], off offset:64
	global_load_dword v150, v[144:145], off offset:128
	global_load_dword v152, v[144:145], off offset:192
	global_load_dword v154, v[144:145], off offset:512
	global_load_dword v156, v[144:145], off offset:576
	global_load_dword v160, v[144:145], off offset:640
	global_load_dword v161, v[144:145], off offset:704
	v_lshl_or_b32 v144, s5, 7, v153
	v_ashrrev_i32_e32 v145, 31, v144
	v_lshl_add_u64 v[144:145], v[144:145], 1, s[54:55]
	s_waitcnt vmcnt(0)
; DI unsigned pk_bf16(float lo, float hi) { f32x2 v = {lo, hi}; return __builtin_bit_cast(unsigned, __builtin_convertvector(v, bf16v2)); }
; DI float fast_silu(float x) { return x * fast_sigmoid(x); }
; DI RowScales load_rowscales(const float* ss, int row0) {
;     ...
;         for (int m = 0; m < 4; ++m) t.r[ai][m] = ss[row0 + ai * 128 + m * 16];
; #pragma unroll
;     for (int ai = 0; ai < 2; ++ai)
; #pragma unroll
;         for (int m = 0; m < 4; ++m) t.r[ai][m] = rsqrtf(t.r[ai][m] * (1.0f / 1024.0f) + 1e-6f);
;     DI void operator()(AccRef acc, const Unit& u, int wr, int wc, int fr, int fq) const {
;     ...
;                 const int row = row0 + ai * 128 + m * 16;
;                 const float r = RS ? rsc.r[ai][m] : 1.0f;
;                 const f32x4 a0 = acc[ai][0][m][0] * r, a1 = acc[ai][0][m][1] * r, b0 = acc[ai][1][m][0] * r, b1 = acc[ai][1][m][1] * r;
;                 u32x4 w;
;                 w.x = pk_bf16(fast_silu(a0[0]) * b0[0], fast_silu(a0[1]) * b0[1]); w.y = pk_bf16(fast_silu(a0[2]) * b0[2], fast_silu(a0[3]) * b0[3]);
;                 w.z = pk_bf16(fast_silu(a1[0]) * b1[0], fast_silu(a1[1]) * b1[1]); w.w = pk_bf16(fast_silu(a1[2]) * b1[2], fast_silu(a1[3]) * b1[3]);
;                 *(u32x4*)(G + (size_t)row * DFF + col) = w;
	v_fmamk_f32 v147, v147, 0x3a800000, v159
	v_mul_f32_e32 v162, 0x4b800000, v147
	v_cmp_gt_f32_e32 vcc, s51, v147
	v_fmamk_f32 v152, v152, 0x3a800000, v159
	v_fmamk_f32 v154, v154, 0x3a800000, v159
	v_cndmask_b32_e32 v147, v147, v162, vcc
	v_mul_f32_e32 v165, 0x4b800000, v152
	v_fmamk_f32 v161, v161, 0x3a800000, v159
	v_mul_f32_e32 v166, 0x4b800000, v154
	v_mul_f32_e32 v169, 0x4b800000, v161
	v_cmp_gt_f32_e64 s[10:11], s51, v152
	v_cmp_gt_f32_e64 s[12:13], s51, v154
	v_cmp_gt_f32_e64 s[18:19], s51, v161
	v_rsq_f32_e32 v147, v147
	v_fmamk_f32 v156, v156, 0x3a800000, v159
	v_cndmask_b32_e64 v152, v152, v165, s[10:11]
	v_cndmask_b32_e64 v154, v154, v166, s[12:13]
	v_cndmask_b32_e64 v161, v161, v169, s[18:19]
	v_fmamk_f32 v148, v148, 0x3a800000, v159
	v_fmamk_f32 v160, v160, 0x3a800000, v159
	v_mul_f32_e32 v167, 0x4b800000, v156
	v_cmp_gt_f32_e64 s[14:15], s51, v156
	v_rsq_f32_e32 v152, v152
	v_rsq_f32_e32 v154, v154
	v_rsq_f32_e32 v161, v161
	v_mul_f32_e32 v163, 0x4b800000, v148
	v_mul_f32_e32 v168, 0x4b800000, v160
	v_cmp_gt_f32_e64 s[4:5], s51, v148
	v_cndmask_b32_e64 v156, v156, v167, s[14:15]
	v_cmp_gt_f32_e64 s[16:17], s51, v160
	v_fmamk_f32 v150, v150, 0x3a800000, v159
	v_cndmask_b32_e64 v148, v148, v163, s[4:5]
	v_cndmask_b32_e64 v160, v160, v168, s[16:17]
	v_rsq_f32_e32 v163, v156
	v_mul_f32_e32 v156, 0x45800000, v147
	v_mul_f32_e32 v164, 0x4b800000, v150
	v_cmp_gt_f32_e64 s[8:9], s51, v150
	v_rsq_f32_e32 v165, v160
	v_cndmask_b32_e32 v160, v147, v156, vcc
	v_cndmask_b32_e64 v150, v150, v164, s[8:9]
	v_rsq_f32_e32 v148, v148
	v_mul_f32_e32 v166, 0x45800000, v152
	v_mul_f32_e32 v167, 0x45800000, v154
	v_pk_mul_f32 v[126:127], v[126:127], v[160:161] op_sel_hi:[1,0]
	v_pk_mul_f32 v[124:125], v[124:125], v[160:161] op_sel_hi:[1,0]
	v_rsq_f32_e32 v150, v150
	v_cndmask_b32_e64 v156, v152, v166, s[10:11]
	v_cndmask_b32_e64 v154, v154, v167, s[12:13]
	v_pk_mul_f32 v[122:123], v[122:123], v[160:161] op_sel_hi:[1,0]
	v_pk_mul_f32 v[120:121], v[120:121], v[160:161] op_sel_hi:[1,0]
	v_pk_mul_f32 v[118:119], v[118:119], v[160:161] op_sel_hi:[1,0]
	v_pk_mul_f32 v[116:117], v[116:117], v[160:161] op_sel_hi:[1,0]
	v_pk_mul_f32 v[166:167], v[114:115], v[160:161] op_sel_hi:[1,0]
	v_pk_mul_f32 v[114:115], v[112:113], v[160:161] op_sel_hi:[1,0]
	v_mul_f32_e32 v112, 0xbfb8aa3b, v124
	v_mul_f32_e32 v113, 0xbfb8aa3b, v125
	v_mul_f32_e32 v147, 0xbfb8aa3b, v126
	v_mul_f32_e32 v160, 0xbfb8aa3b, v127
	v_exp_f32_e32 v112, v112
	v_exp_f32_e32 v113, v113
	v_exp_f32_e32 v147, v147
	v_exp_f32_e32 v160, v160
	v_mul_f32_e32 v162, 0x45800000, v148
	v_mul_f32_e32 v170, 0x45800000, v161
	v_mul_f32_e32 v164, 0x45800000, v150
	v_mul_f32_e32 v169, 0x45800000, v165
	v_cndmask_b32_e64 v162, v148, v162, s[4:5]
	v_cndmask_b32_e64 v148, v161, v170, s[18:19]
	v_mul_f32_e32 v161, 0xbfb8aa3b, v120
	v_cndmask_b32_e64 v164, v150, v164, s[8:9]
	v_cndmask_b32_e64 v150, v165, v169, s[16:17]
	v_exp_f32_e32 v165, v161
	v_add_f32_e32 v112, 1.0, v112
	v_add_f32_e32 v113, 1.0, v113
	v_add_f32_e32 v147, 1.0, v147
	v_add_f32_e32 v161, 1.0, v160
	v_rcp_f32_e32 v112, v112
	v_rcp_f32_e32 v113, v113
	v_rcp_f32_e32 v160, v147
	v_rcp_f32_e32 v161, v161
	v_mul_f32_e32 v168, 0x45800000, v163
	v_pk_mul_f32 v[112:113], v[124:125], v[112:113]
	v_cndmask_b32_e64 v152, v163, v168, s[14:15]
	v_pk_mul_f32 v[124:125], v[126:127], v[160:161]
	v_mul_f32_e32 v163, 0xbfb8aa3b, v121
	v_pk_mul_f32 v[112:113], v[116:117], v[112:113]
	v_pk_mul_f32 v[116:117], v[118:119], v[124:125]
	v_exp_f32_e32 v163, v163
	v_cvt_pk_bf16_f32 v112, v112, v113
	v_cvt_pk_bf16_f32 v113, v116, v117
	v_mul_f32_e32 v117, 0xbfb8aa3b, v122
	v_mul_f32_e32 v118, 0xbfb8aa3b, v123
	v_exp_f32_e32 v117, v117
	v_exp_f32_e32 v118, v118
	v_add_f32_e32 v116, 1.0, v163
	v_add_f32_e32 v147, 1.0, v165
	v_rcp_f32_e32 v169, v116
	v_add_f32_e32 v116, 1.0, v117
	v_add_f32_e32 v117, 1.0, v118
	v_rcp_f32_e32 v168, v147
	v_rcp_f32_e32 v116, v116
	v_rcp_f32_e32 v117, v117
	v_pk_mul_f32 v[108:109], v[108:109], v[162:163] op_sel_hi:[1,0]
	v_pk_mul_f32 v[118:119], v[120:121], v[168:169]
	v_pk_mul_f32 v[110:111], v[110:111], v[162:163] op_sel_hi:[1,0]
	v_pk_mul_f32 v[116:117], v[122:123], v[116:117]
	v_pk_mul_f32 v[114:115], v[114:115], v[118:119]
	v_pk_mul_f32 v[116:117], v[166:167], v[116:117]
	v_cvt_pk_bf16_f32 v114, v114, v115
	v_cvt_pk_bf16_f32 v115, v116, v117
	v_mad_i64_i32 v[116:117], s[4:5], v146, s52, v[144:145]
	global_store_dwordx4 v[116:117], v[112:115], off
	v_pk_mul_f32 v[100:101], v[100:101], v[162:163] op_sel_hi:[1,0]
	v_pk_mul_f32 v[104:105], v[104:105], v[162:163] op_sel_hi:[1,0]
	v_pk_mul_f32 v[112:113], v[98:99], v[162:163] op_sel_hi:[1,0]
	v_mul_f32_e32 v98, 0xbfb8aa3b, v108
	v_exp_f32_e32 v114, v98
	v_mul_f32_e32 v98, 0xbfb8aa3b, v109
	v_exp_f32_e32 v115, v98
	v_pk_mul_f32 v[98:99], v[96:97], v[162:163] op_sel_hi:[1,0]
	v_add_f32_e32 v96, 1.0, v114
	v_mul_f32_e32 v114, 0xbfb8aa3b, v110
	v_add_f32_e32 v97, 1.0, v115
	v_mul_f32_e32 v115, 0xbfb8aa3b, v111
	v_exp_f32_e32 v114, v114
	v_exp_f32_e32 v115, v115
	v_rcp_f32_e32 v96, v96
	v_rcp_f32_e32 v97, v97
	v_add_f32_e32 v114, 1.0, v114
	v_add_f32_e32 v115, 1.0, v115
	v_rcp_f32_e32 v114, v114
	v_rcp_f32_e32 v115, v115
	v_pk_mul_f32 v[96:97], v[108:109], v[96:97]
	v_pk_mul_f32 v[102:103], v[102:103], v[162:163] op_sel_hi:[1,0]
	v_pk_mul_f32 v[96:97], v[100:101], v[96:97]
	v_pk_mul_f32 v[100:101], v[110:111], v[114:115]
	v_cvt_pk_bf16_f32 v96, v96, v97
	v_mul_f32_e32 v97, 0xbfb8aa3b, v104
	v_pk_mul_f32 v[100:101], v[102:103], v[100:101]
	v_exp_f32_e32 v102, v97
	v_mul_f32_e32 v97, 0xbfb8aa3b, v105
	v_exp_f32_e32 v103, v97
	v_pk_mul_f32 v[106:107], v[106:107], v[162:163] op_sel_hi:[1,0]
; DI unsigned pk_bf16(float lo, float hi) { f32x2 v = {lo, hi}; return __builtin_bit_cast(unsigned, __builtin_convertvector(v, bf16v2)); }
; DI float fast_silu(float x) { return x * fast_sigmoid(x); }
;     DI void operator()(AccRef acc, const Unit& u, int wr, int wc, int fr, int fq) const {
;     ...
;                 const int row = row0 + ai * 128 + m * 16;
;                 const float r = RS ? rsc.r[ai][m] : 1.0f;
;                 const f32x4 a0 = acc[ai][0][m][0] * r, a1 = acc[ai][0][m][1] * r, b0 = acc[ai][1][m][0] * r, b1 = acc[ai][1][m][1] * r;
;                 u32x4 w;
;                 w.x = pk_bf16(fast_silu(a0[0]) * b0[0], fast_silu(a0[1]) * b0[1]); w.y = pk_bf16(fast_silu(a0[2]) * b0[2], fast_silu(a0[3]) * b0[3]);
;                 w.z = pk_bf16(fast_silu(a1[0]) * b1[0], fast_silu(a1[1]) * b1[1]); w.w = pk_bf16(fast_silu(a1[2]) * b1[2], fast_silu(a1[3]) * b1[3]);
;                 *(u32x4*)(G + (size_t)row * DFF + col) = w;
	v_cvt_pk_bf16_f32 v97, v100, v101
	v_add_f32_e32 v100, 1.0, v102
	v_add_f32_e32 v101, 1.0, v103
	v_mul_f32_e32 v102, 0xbfb8aa3b, v106
	v_mul_f32_e32 v103, 0xbfb8aa3b, v107
	v_exp_f32_e32 v102, v102
	v_exp_f32_e32 v103, v103
	v_rcp_f32_e32 v100, v100
	v_rcp_f32_e32 v101, v101
	v_add_f32_e32 v102, 1.0, v102
	v_add_f32_e32 v103, 1.0, v103
	v_rcp_f32_e32 v102, v102
	v_rcp_f32_e32 v103, v103
	v_pk_mul_f32 v[100:101], v[104:105], v[100:101]
	v_or_b32_e32 v116, 16, v146
	v_pk_mul_f32 v[98:99], v[98:99], v[100:101]
	v_pk_mul_f32 v[100:101], v[106:107], v[102:103]
	v_cvt_pk_bf16_f32 v98, v98, v99
	v_pk_mul_f32 v[100:101], v[112:113], v[100:101]
	v_pk_mul_f32 v[92:93], v[92:93], v[164:165] op_sel_hi:[1,0]
	v_cvt_pk_bf16_f32 v99, v100, v101
	v_mad_i64_i32 v[100:101], s[4:5], v116, s52, v[144:145]
	global_store_dwordx4 v[100:101], v[96:99], off
	v_pk_mul_f32 v[94:95], v[94:95], v[164:165] op_sel_hi:[1,0]
	v_pk_mul_f32 v[84:85], v[84:85], v[164:165] op_sel_hi:[1,0]
	v_pk_mul_f32 v[96:97], v[82:83], v[164:165] op_sel_hi:[1,0]
	v_mul_f32_e32 v82, 0xbfb8aa3b, v92
	v_exp_f32_e32 v98, v82
	v_mul_f32_e32 v82, 0xbfb8aa3b, v93
	v_exp_f32_e32 v99, v82
	v_pk_mul_f32 v[82:83], v[80:81], v[164:165] op_sel_hi:[1,0]
	v_add_f32_e32 v80, 1.0, v98
	v_mul_f32_e32 v98, 0xbfb8aa3b, v94
	v_add_f32_e32 v81, 1.0, v99
	v_mul_f32_e32 v99, 0xbfb8aa3b, v95
	v_exp_f32_e32 v98, v98
	v_exp_f32_e32 v99, v99
	v_rcp_f32_e32 v80, v80
	v_rcp_f32_e32 v81, v81
	v_add_f32_e32 v98, 1.0, v98
	v_add_f32_e32 v99, 1.0, v99
	v_rcp_f32_e32 v98, v98
	v_rcp_f32_e32 v99, v99
	v_pk_mul_f32 v[80:81], v[92:93], v[80:81]
	v_pk_mul_f32 v[88:89], v[88:89], v[164:165] op_sel_hi:[1,0]
	v_pk_mul_f32 v[80:81], v[84:85], v[80:81]
	v_pk_mul_f32 v[86:87], v[86:87], v[164:165] op_sel_hi:[1,0]
	v_cvt_pk_bf16_f32 v80, v80, v81
	v_pk_mul_f32 v[84:85], v[94:95], v[98:99]
	v_mul_f32_e32 v81, 0xbfb8aa3b, v88
	v_pk_mul_f32 v[84:85], v[86:87], v[84:85]
	v_exp_f32_e32 v86, v81
	v_mul_f32_e32 v81, 0xbfb8aa3b, v89
	v_exp_f32_e32 v87, v81
	v_pk_mul_f32 v[90:91], v[90:91], v[164:165] op_sel_hi:[1,0]
	v_cvt_pk_bf16_f32 v81, v84, v85
	v_add_f32_e32 v84, 1.0, v86
	v_add_f32_e32 v85, 1.0, v87
	v_mul_f32_e32 v86, 0xbfb8aa3b, v90
	v_mul_f32_e32 v87, 0xbfb8aa3b, v91
	v_exp_f32_e32 v86, v86
	v_exp_f32_e32 v87, v87
	v_rcp_f32_e32 v84, v84
	v_rcp_f32_e32 v85, v85
	v_add_f32_e32 v86, 1.0, v86
	v_add_f32_e32 v87, 1.0, v87
	v_rcp_f32_e32 v86, v86
	v_rcp_f32_e32 v87, v87
	v_pk_mul_f32 v[84:85], v[88:89], v[84:85]
	v_or_b32_e32 v100, 32, v146
	v_pk_mul_f32 v[82:83], v[82:83], v[84:85]
	v_pk_mul_f32 v[84:85], v[90:91], v[86:87]
	v_cvt_pk_bf16_f32 v82, v82, v83
	v_pk_mul_f32 v[84:85], v[96:97], v[84:85]
	v_pk_mul_f32 v[76:77], v[76:77], v[156:157] op_sel_hi:[1,0]
	v_cvt_pk_bf16_f32 v83, v84, v85
	v_mad_i64_i32 v[84:85], s[4:5], v100, s52, v[144:145]
	global_store_dwordx4 v[84:85], v[80:83], off
	v_pk_mul_f32 v[78:79], v[78:79], v[156:157] op_sel_hi:[1,0]
	v_pk_mul_f32 v[68:69], v[68:69], v[156:157] op_sel_hi:[1,0]
	v_pk_mul_f32 v[80:81], v[66:67], v[156:157] op_sel_hi:[1,0]
	v_mul_f32_e32 v66, 0xbfb8aa3b, v76
	v_exp_f32_e32 v82, v66
	v_mul_f32_e32 v66, 0xbfb8aa3b, v77
	v_exp_f32_e32 v83, v66
	v_pk_mul_f32 v[66:67], v[64:65], v[156:157] op_sel_hi:[1,0]
	v_add_f32_e32 v64, 1.0, v82
	v_mul_f32_e32 v82, 0xbfb8aa3b, v78
	v_add_f32_e32 v65, 1.0, v83
	v_mul_f32_e32 v83, 0xbfb8aa3b, v79
	v_exp_f32_e32 v82, v82
	v_exp_f32_e32 v83, v83
	v_rcp_f32_e32 v64, v64
	v_rcp_f32_e32 v65, v65
	v_add_f32_e32 v82, 1.0, v82
	v_add_f32_e32 v83, 1.0, v83
	v_rcp_f32_e32 v82, v82
	v_rcp_f32_e32 v83, v83
	v_pk_mul_f32 v[64:65], v[76:77], v[64:65]
	v_pk_mul_f32 v[72:73], v[72:73], v[156:157] op_sel_hi:[1,0]
	v_pk_mul_f32 v[64:65], v[68:69], v[64:65]
	v_pk_mul_f32 v[70:71], v[70:71], v[156:157] op_sel_hi:[1,0]
	v_cvt_pk_bf16_f32 v64, v64, v65
	v_pk_mul_f32 v[68:69], v[78:79], v[82:83]
	v_mul_f32_e32 v65, 0xbfb8aa3b, v72
	v_pk_mul_f32 v[68:69], v[70:71], v[68:69]
	v_exp_f32_e32 v70, v65
	v_mul_f32_e32 v65, 0xbfb8aa3b, v73
	v_exp_f32_e32 v71, v65
	v_pk_mul_f32 v[74:75], v[74:75], v[156:157] op_sel_hi:[1,0]
	v_cvt_pk_bf16_f32 v65, v68, v69
	v_add_f32_e32 v68, 1.0, v70
	v_add_f32_e32 v69, 1.0, v71
	v_mul_f32_e32 v70, 0xbfb8aa3b, v74
	v_mul_f32_e32 v71, 0xbfb8aa3b, v75
	v_exp_f32_e32 v70, v70
	v_exp_f32_e32 v71, v71
	v_rcp_f32_e32 v68, v68
	v_rcp_f32_e32 v69, v69
	v_add_f32_e32 v70, 1.0, v70
	v_add_f32_e32 v71, 1.0, v71
	v_rcp_f32_e32 v70, v70
	v_rcp_f32_e32 v71, v71
	v_pk_mul_f32 v[68:69], v[72:73], v[68:69]
	v_or_b32_e32 v84, 48, v146
	v_pk_mul_f32 v[66:67], v[66:67], v[68:69]
	v_pk_mul_f32 v[68:69], v[74:75], v[70:71]
	v_cvt_pk_bf16_f32 v66, v66, v67
	v_pk_mul_f32 v[68:69], v[80:81], v[68:69]
	v_pk_mul_f32 v[60:61], v[60:61], v[154:155] op_sel_hi:[1,0]
	v_cvt_pk_bf16_f32 v67, v68, v69
	v_mad_i64_i32 v[68:69], s[4:5], v84, s52, v[144:145]
	global_store_dwordx4 v[68:69], v[64:67], off
	v_pk_mul_f32 v[62:63], v[62:63], v[154:155] op_sel_hi:[1,0]
	v_pk_mul_f32 v[52:53], v[52:53], v[154:155] op_sel_hi:[1,0]
	v_pk_mul_f32 v[64:65], v[50:51], v[154:155] op_sel_hi:[1,0]
	v_mul_f32_e32 v50, 0xbfb8aa3b, v60
	v_exp_f32_e32 v66, v50
	v_mul_f32_e32 v50, 0xbfb8aa3b, v61
	v_exp_f32_e32 v67, v50
	v_pk_mul_f32 v[50:51], v[48:49], v[154:155] op_sel_hi:[1,0]
	v_add_f32_e32 v48, 1.0, v66
	v_mul_f32_e32 v66, 0xbfb8aa3b, v62
	v_add_f32_e32 v49, 1.0, v67
	v_mul_f32_e32 v67, 0xbfb8aa3b, v63
	v_exp_f32_e32 v66, v66
	v_exp_f32_e32 v67, v67
	v_rcp_f32_e32 v48, v48
	v_rcp_f32_e32 v49, v49
	v_add_f32_e32 v66, 1.0, v66
	v_add_f32_e32 v67, 1.0, v67
	v_rcp_f32_e32 v66, v66
	v_rcp_f32_e32 v67, v67
	v_pk_mul_f32 v[48:49], v[60:61], v[48:49]
	v_pk_mul_f32 v[56:57], v[56:57], v[154:155] op_sel_hi:[1,0]
; DI unsigned pk_bf16(float lo, float hi) { f32x2 v = {lo, hi}; return __builtin_bit_cast(unsigned, __builtin_convertvector(v, bf16v2)); }
; DI float fast_silu(float x) { return x * fast_sigmoid(x); }
;     DI void operator()(AccRef acc, const Unit& u, int wr, int wc, int fr, int fq) const {
;     ...
;                 const int row = row0 + ai * 128 + m * 16;
;                 const float r = RS ? rsc.r[ai][m] : 1.0f;
;                 const f32x4 a0 = acc[ai][0][m][0] * r, a1 = acc[ai][0][m][1] * r, b0 = acc[ai][1][m][0] * r, b1 = acc[ai][1][m][1] * r;
;                 u32x4 w;
;                 w.x = pk_bf16(fast_silu(a0[0]) * b0[0], fast_silu(a0[1]) * b0[1]); w.y = pk_bf16(fast_silu(a0[2]) * b0[2], fast_silu(a0[3]) * b0[3]);
;                 w.z = pk_bf16(fast_silu(a1[0]) * b1[0], fast_silu(a1[1]) * b1[1]); w.w = pk_bf16(fast_silu(a1[2]) * b1[2], fast_silu(a1[3]) * b1[3]);
;                 *(u32x4*)(G + (size_t)row * DFF + col) = w;
	v_pk_mul_f32 v[48:49], v[52:53], v[48:49]
	v_pk_mul_f32 v[54:55], v[54:55], v[154:155] op_sel_hi:[1,0]
	v_cvt_pk_bf16_f32 v48, v48, v49
	v_pk_mul_f32 v[52:53], v[62:63], v[66:67]
	v_mul_f32_e32 v49, 0xbfb8aa3b, v56
	v_pk_mul_f32 v[52:53], v[54:55], v[52:53]
	v_exp_f32_e32 v54, v49
	v_mul_f32_e32 v49, 0xbfb8aa3b, v57
	v_exp_f32_e32 v55, v49
	v_pk_mul_f32 v[58:59], v[58:59], v[154:155] op_sel_hi:[1,0]
	v_cvt_pk_bf16_f32 v49, v52, v53
	v_add_f32_e32 v52, 1.0, v54
	v_add_f32_e32 v53, 1.0, v55
	v_mul_f32_e32 v54, 0xbfb8aa3b, v58
	v_mul_f32_e32 v55, 0xbfb8aa3b, v59
	v_exp_f32_e32 v54, v54
	v_exp_f32_e32 v55, v55
	v_rcp_f32_e32 v52, v52
	v_rcp_f32_e32 v53, v53
	v_add_f32_e32 v54, 1.0, v54
	v_add_f32_e32 v55, 1.0, v55
	v_rcp_f32_e32 v54, v54
	v_rcp_f32_e32 v55, v55
	v_pk_mul_f32 v[52:53], v[56:57], v[52:53]
	v_add_u32_e32 v68, 0x80, v146
	v_pk_mul_f32 v[50:51], v[50:51], v[52:53]
	v_pk_mul_f32 v[52:53], v[58:59], v[54:55]
	v_cvt_pk_bf16_f32 v50, v50, v51
	v_pk_mul_f32 v[52:53], v[64:65], v[52:53]
	v_pk_mul_f32 v[44:45], v[44:45], v[152:153] op_sel_hi:[1,0]
	v_cvt_pk_bf16_f32 v51, v52, v53
	v_mad_i64_i32 v[52:53], s[4:5], v68, s52, v[144:145]
	global_store_dwordx4 v[52:53], v[48:51], off
	v_pk_mul_f32 v[46:47], v[46:47], v[152:153] op_sel_hi:[1,0]
	v_pk_mul_f32 v[36:37], v[36:37], v[152:153] op_sel_hi:[1,0]
	v_pk_mul_f32 v[48:49], v[34:35], v[152:153] op_sel_hi:[1,0]
	v_mul_f32_e32 v34, 0xbfb8aa3b, v44
	v_exp_f32_e32 v50, v34
	v_mul_f32_e32 v34, 0xbfb8aa3b, v45
	v_exp_f32_e32 v51, v34
	v_pk_mul_f32 v[34:35], v[32:33], v[152:153] op_sel_hi:[1,0]
	v_add_f32_e32 v32, 1.0, v50
	v_mul_f32_e32 v50, 0xbfb8aa3b, v46
	v_add_f32_e32 v33, 1.0, v51
	v_mul_f32_e32 v51, 0xbfb8aa3b, v47
	v_exp_f32_e32 v50, v50
	v_exp_f32_e32 v51, v51
	v_rcp_f32_e32 v32, v32
	v_rcp_f32_e32 v33, v33
	v_add_f32_e32 v50, 1.0, v50
	v_add_f32_e32 v51, 1.0, v51
	v_rcp_f32_e32 v50, v50
	v_rcp_f32_e32 v51, v51
	v_pk_mul_f32 v[32:33], v[44:45], v[32:33]
	v_pk_mul_f32 v[40:41], v[40:41], v[152:153] op_sel_hi:[1,0]
	v_pk_mul_f32 v[32:33], v[36:37], v[32:33]
	v_pk_mul_f32 v[38:39], v[38:39], v[152:153] op_sel_hi:[1,0]
	v_cvt_pk_bf16_f32 v32, v32, v33
	v_pk_mul_f32 v[36:37], v[46:47], v[50:51]
	v_mul_f32_e32 v33, 0xbfb8aa3b, v40
	v_pk_mul_f32 v[36:37], v[38:39], v[36:37]
	v_exp_f32_e32 v38, v33
	v_mul_f32_e32 v33, 0xbfb8aa3b, v41
	v_exp_f32_e32 v39, v33
	v_pk_mul_f32 v[42:43], v[42:43], v[152:153] op_sel_hi:[1,0]
	v_cvt_pk_bf16_f32 v33, v36, v37
	v_add_f32_e32 v36, 1.0, v38
	v_add_f32_e32 v37, 1.0, v39
	v_mul_f32_e32 v38, 0xbfb8aa3b, v42
	v_mul_f32_e32 v39, 0xbfb8aa3b, v43
	v_exp_f32_e32 v38, v38
	v_exp_f32_e32 v39, v39
	v_rcp_f32_e32 v36, v36
	v_rcp_f32_e32 v37, v37
	v_add_f32_e32 v38, 1.0, v38
	v_add_f32_e32 v39, 1.0, v39
	v_rcp_f32_e32 v38, v38
	v_rcp_f32_e32 v39, v39
	v_pk_mul_f32 v[36:37], v[40:41], v[36:37]
	v_add_u32_e32 v52, 0x90, v146
	v_pk_mul_f32 v[34:35], v[34:35], v[36:37]
	v_pk_mul_f32 v[36:37], v[42:43], v[38:39]
	v_cvt_pk_bf16_f32 v34, v34, v35
	v_pk_mul_f32 v[36:37], v[48:49], v[36:37]
	v_pk_mul_f32 v[28:29], v[28:29], v[150:151] op_sel_hi:[1,0]
	v_cvt_pk_bf16_f32 v35, v36, v37
	v_mad_i64_i32 v[36:37], s[4:5], v52, s52, v[144:145]
	global_store_dwordx4 v[36:37], v[32:35], off
	v_pk_mul_f32 v[30:31], v[30:31], v[150:151] op_sel_hi:[1,0]
	v_pk_mul_f32 v[20:21], v[20:21], v[150:151] op_sel_hi:[1,0]
	v_pk_mul_f32 v[32:33], v[18:19], v[150:151] op_sel_hi:[1,0]
	v_mul_f32_e32 v18, 0xbfb8aa3b, v28
	v_exp_f32_e32 v34, v18
	v_mul_f32_e32 v18, 0xbfb8aa3b, v29
	v_exp_f32_e32 v35, v18
	v_pk_mul_f32 v[18:19], v[16:17], v[150:151] op_sel_hi:[1,0]
	v_add_f32_e32 v16, 1.0, v34
	v_mul_f32_e32 v34, 0xbfb8aa3b, v30
; DI unsigned pk_bf16(float lo, float hi) { f32x2 v = {lo, hi}; return __builtin_bit_cast(unsigned, __builtin_convertvector(v, bf16v2)); }
; DI float fast_silu(float x) { return x * fast_sigmoid(x); }
; #define PG8_WAIT_V(n) asm volatile("s_waitcnt vmcnt(" #n ")" ::: "memory")
; #define PG8_BAR __builtin_amdgcn_s_barrier()
; #define PG8_WAIT_V(n) asm volatile("s_waitcnt vmcnt(" #n ")" ::: "memory")
; #define PG8_BAR __builtin_amdgcn_s_barrier()
; template <class Epi>
; DI void gemm_phase(LAS unsigned char* lds, const Gemm g, const StaticOrder S, const Epi E) {
;     ...
;         if (!has_next) break;
; #pragma unroll
;         for (int a = 0; a < 2; ++a)
; #pragma unroll
;             for (int b = 0; b < 2; ++b)
; #pragma unroll
;                 for (int m = 0; m < 4; ++m)
; #pragma unroll
;                     for (int n = 0; n < 2; ++n) acc[a][b][m][n] = (f32x4){0.f, 0.f, 0.f, 0.f};
;         cur = nxt; cA = nA; cB = nB; ++ui;
;     }
;     PG8_WAIT_V(0);
;     if (wr == 0) PG8_BAR;
;     PG8_BAR;
;     DI void operator()(AccRef acc, const Unit& u, int wr, int wc, int fr, int fq) const {
;     ...
;                 const int row = row0 + ai * 128 + m * 16;
;                 const float r = RS ? rsc.r[ai][m] : 1.0f;
;                 const f32x4 a0 = acc[ai][0][m][0] * r, a1 = acc[ai][0][m][1] * r, b0 = acc[ai][1][m][0] * r, b1 = acc[ai][1][m][1] * r;
;                 u32x4 w;
;                 w.x = pk_bf16(fast_silu(a0[0]) * b0[0], fast_silu(a0[1]) * b0[1]); w.y = pk_bf16(fast_silu(a0[2]) * b0[2], fast_silu(a0[3]) * b0[3]);
;                 w.z = pk_bf16(fast_silu(a1[0]) * b1[0], fast_silu(a1[1]) * b1[1]); w.w = pk_bf16(fast_silu(a1[2]) * b1[2], fast_silu(a1[3]) * b1[3]);
;                 *(u32x4*)(G + (size_t)row * DFF + col) = w;
;             }
	v_add_f32_e32 v17, 1.0, v35
	v_mul_f32_e32 v35, 0xbfb8aa3b, v31
	v_exp_f32_e32 v34, v34
	v_exp_f32_e32 v35, v35
	v_rcp_f32_e32 v16, v16
	v_rcp_f32_e32 v17, v17
	v_add_f32_e32 v34, 1.0, v34
	v_add_f32_e32 v35, 1.0, v35
	v_rcp_f32_e32 v34, v34
	v_rcp_f32_e32 v35, v35
	v_pk_mul_f32 v[16:17], v[28:29], v[16:17]
	v_pk_mul_f32 v[24:25], v[24:25], v[150:151] op_sel_hi:[1,0]
	v_pk_mul_f32 v[16:17], v[20:21], v[16:17]
	v_pk_mul_f32 v[22:23], v[22:23], v[150:151] op_sel_hi:[1,0]
	v_cvt_pk_bf16_f32 v16, v16, v17
	v_pk_mul_f32 v[20:21], v[30:31], v[34:35]
	v_mul_f32_e32 v17, 0xbfb8aa3b, v24
	v_pk_mul_f32 v[20:21], v[22:23], v[20:21]
	v_exp_f32_e32 v22, v17
	v_mul_f32_e32 v17, 0xbfb8aa3b, v25
	v_exp_f32_e32 v23, v17
	v_pk_mul_f32 v[26:27], v[26:27], v[150:151] op_sel_hi:[1,0]
	v_cvt_pk_bf16_f32 v17, v20, v21
	v_add_f32_e32 v20, 1.0, v22
	v_add_f32_e32 v21, 1.0, v23
	v_mul_f32_e32 v22, 0xbfb8aa3b, v26
	v_mul_f32_e32 v23, 0xbfb8aa3b, v27
	v_exp_f32_e32 v22, v22
	v_exp_f32_e32 v23, v23
	v_rcp_f32_e32 v20, v20
	v_rcp_f32_e32 v21, v21
	v_add_f32_e32 v22, 1.0, v22
	v_add_f32_e32 v23, 1.0, v23
	v_rcp_f32_e32 v22, v22
	v_rcp_f32_e32 v23, v23
	v_pk_mul_f32 v[20:21], v[24:25], v[20:21]
	v_add_u32_e32 v36, 0xa0, v146
	v_pk_mul_f32 v[18:19], v[18:19], v[20:21]
	v_pk_mul_f32 v[20:21], v[26:27], v[22:23]
	v_cvt_pk_bf16_f32 v18, v18, v19
	v_pk_mul_f32 v[20:21], v[32:33], v[20:21]
	v_pk_mul_f32 v[12:13], v[12:13], v[148:149] op_sel_hi:[1,0]
	v_cvt_pk_bf16_f32 v19, v20, v21
	v_mad_i64_i32 v[20:21], s[4:5], v36, s52, v[144:145]
	global_store_dwordx4 v[20:21], v[16:19], off
	v_pk_mul_f32 v[14:15], v[14:15], v[148:149] op_sel_hi:[1,0]
	v_pk_mul_f32 v[4:5], v[4:5], v[148:149] op_sel_hi:[1,0]
	v_pk_mul_f32 v[16:17], v[2:3], v[148:149] op_sel_hi:[1,0]
	v_mul_f32_e32 v2, 0xbfb8aa3b, v12
	v_exp_f32_e32 v18, v2
	v_mul_f32_e32 v2, 0xbfb8aa3b, v13
	v_exp_f32_e32 v19, v2
	v_pk_mul_f32 v[2:3], v[0:1], v[148:149] op_sel_hi:[1,0]
	v_add_f32_e32 v0, 1.0, v18
	v_mul_f32_e32 v18, 0xbfb8aa3b, v14
	v_add_f32_e32 v1, 1.0, v19
	v_mul_f32_e32 v19, 0xbfb8aa3b, v15
	v_exp_f32_e32 v18, v18
	v_exp_f32_e32 v19, v19
	v_rcp_f32_e32 v0, v0
	v_rcp_f32_e32 v1, v1
	v_add_f32_e32 v18, 1.0, v18
	v_add_f32_e32 v19, 1.0, v19
	v_rcp_f32_e32 v18, v18
	v_rcp_f32_e32 v19, v19
	v_pk_mul_f32 v[0:1], v[12:13], v[0:1]
	v_pk_mul_f32 v[8:9], v[8:9], v[148:149] op_sel_hi:[1,0]
	v_pk_mul_f32 v[0:1], v[4:5], v[0:1]
	v_pk_mul_f32 v[6:7], v[6:7], v[148:149] op_sel_hi:[1,0]
	v_cvt_pk_bf16_f32 v0, v0, v1
	v_pk_mul_f32 v[4:5], v[14:15], v[18:19]
	v_mul_f32_e32 v1, 0xbfb8aa3b, v8
	v_pk_mul_f32 v[4:5], v[6:7], v[4:5]
	v_exp_f32_e32 v6, v1
	v_mul_f32_e32 v1, 0xbfb8aa3b, v9
	v_exp_f32_e32 v7, v1
	v_pk_mul_f32 v[10:11], v[10:11], v[148:149] op_sel_hi:[1,0]
	v_cvt_pk_bf16_f32 v1, v4, v5
	v_add_f32_e32 v4, 1.0, v6
	v_add_f32_e32 v5, 1.0, v7
	v_mul_f32_e32 v6, 0xbfb8aa3b, v10
	v_mul_f32_e32 v7, 0xbfb8aa3b, v11
	v_exp_f32_e32 v6, v6
	v_exp_f32_e32 v7, v7
	v_rcp_f32_e32 v4, v4
	v_rcp_f32_e32 v5, v5
	v_add_f32_e32 v6, 1.0, v6
	v_add_f32_e32 v7, 1.0, v7
	v_rcp_f32_e32 v6, v6
	v_rcp_f32_e32 v7, v7
	v_pk_mul_f32 v[4:5], v[8:9], v[4:5]
	v_add_u32_e32 v20, 0xb0, v146
	v_pk_mul_f32 v[2:3], v[2:3], v[4:5]
	v_pk_mul_f32 v[4:5], v[10:11], v[6:7]
	v_cvt_pk_bf16_f32 v2, v2, v3
	v_pk_mul_f32 v[4:5], v[16:17], v[4:5]
	s_and_b64 vcc, exec, s[0:1]
	v_cvt_pk_bf16_f32 v3, v4, v5
	v_mad_i64_i32 v[4:5], s[4:5], v20, s52, v[144:145]
	s_mov_b32 s5, s24
	s_mov_b32 s4, s28
	s_mov_b64 s[10:11], s[38:39]
	s_mov_b64 s[8:9], s[36:37]
	global_store_dwordx4 v[4:5], v[0:3], off
	s_cbranch_vccz .LBB0_862
	s_waitcnt vmcnt(0)
	s_cmpk_gt_u32 s6, 0xff
	s_cbranch_scc1 .LBB0_869
	s_barrier

; #define PG8_STAGE(bufoff, gbase, voff) do { _Pragma("unroll") for (int _i = 0; _i < 2; ++_i) \
;         __builtin_amdgcn_global_load_lds((const unsigned*)((const char*)(gbase) + (voff)[_i]), (LAS unsigned*)(lds + (bufoff) + ldsw + _i * 8192), 16, 0, 0); } while (0)
; #define PG8_LDA(dst, b, h) do { _Pragma("unroll") for (int m = 0; m < 4; ++m) _Pragma("unroll") for (int k = 0; k < 2; ++k) dst[m][k] = *(const LAS bf16x8*)(lds + PG8_SA(b, h) + aoff + m * 2048 + k * 1024); } while (0)
; #define PG8_LDB(dst, b, h) do { _Pragma("unroll") for (int n = 0; n < 2; ++n) _Pragma("unroll") for (int k = 0; k < 2; ++k) dst[n][k] = *(const LAS bf16x8*)(lds + PG8_SB(b, h) + boff + n * 2048 + k * 1024); } while (0)
; #define PG8_MMA(ai, bj, At, Bt) do { __builtin_amdgcn_s_setprio(1); _Pragma("unroll") for (int m = 0; m < 4; ++m) _Pragma("unroll") for (int n = 0; n < 2; ++n) _Pragma("unroll") for (int k = 0; k < 2; ++k) \
;         acc[ai][bj][m][n] = __builtin_amdgcn_mfma_f32_16x16x32_bf16(Bt[n][k], At[m][k], acc[ai][bj][m][n], 0, 0, 0); __builtin_amdgcn_s_setprio(0); } while (0)
; #define PG8_WAIT_V(n) asm volatile("s_waitcnt vmcnt(" #n ")" ::: "memory")
; #define PG8_WAIT_L(n) asm volatile("s_waitcnt lgkmcnt(" #n ")" ::: "memory")
; #define PG8_BAR __builtin_amdgcn_s_barrier()
; #define PG8_SCHED __builtin_amdgcn_sched_barrier(0)
; #define PG8_STAGE(bufoff, gbase, voff) do { _Pragma("unroll") for (int _i = 0; _i < 2; ++_i) \
;         __builtin_amdgcn_global_load_lds((const unsigned*)((const char*)(gbase) + (voff)[_i]), (LAS unsigned*)(lds + (bufoff) + ldsw + _i * 8192), 16, 0, 0); } while (0)
; template <class Epi0, class Epi1>
; DI void gemm_phase_dual(LAS unsigned char* lds, const Gemm g, const Gemm g1, const StaticOrder S, const Epi0 E0, const Epi1 E1) {
;     ...
;             PG8_LDB(B0, 0, 0); PG8_SCHED; PG8_LDA(At, 0, 0); PG8_STAGE(PG8_SA(1, 1), a1 + hstep, voffA);
;             PG8_WAIT_L(8); PG8_BAR; PG8_WAIT_L(0); PG8_MMA(0, 0, At, B0); PG8_BAR; PG8_SCHED;
;             PG8_LDB(B1, 0, 1); PG8_STAGE(PG8_SB(0, 0), b2, voffB);
;             PG8_BAR; PG8_WAIT_L(0); PG8_MMA(0, 1, At, B1); PG8_BAR;
;             PG8_LDA(At, 0, 1); PG8_STAGE(PG8_SA(0, 0), a2, voffA);
;             PG8_BAR; PG8_WAIT_L(0); PG8_MMA(1, 0, At, B0); PG8_BAR; PG8_SCHED;
;             PG8_STAGE(PG8_SB(0, 1), b2 + hstep, voffB);
;             PG8_WAIT_V(6); PG8_BAR; PG8_MMA(1, 1, At, B1); PG8_BAR;
.LBB0_941:
	ds_read_b128 v[144:147], v199
	ds_read_b128 v[148:151], v199 offset:1024
	ds_read_b128 v[152:155], v199 offset:2048
	ds_read_b128 v[156:159], v199 offset:3072
	s_add_u32 s22, s20, 0x100
	s_addc_u32 s23, s21, 0
	s_cmp_eq_u32 s58, 40
	s_cselect_b32 s27, s9, s23
	s_cselect_b32 s26, s8, s22
	s_cselect_b32 s25, s5, s53
	s_cselect_b32 s24, s4, s52
	v_lshl_add_u64 v[192:193], s[20:21], 0, v[136:137]
	s_add_i32 m0, s33, 0xc000
	ds_read_b128 v[160:163], v200
	ds_read_b128 v[164:167], v200 offset:1024
	ds_read_b128 v[168:171], v200 offset:2048
	ds_read_b128 v[172:175], v200 offset:3072
	ds_read_b128 v[176:179], v200 offset:4096
	ds_read_b128 v[180:183], v200 offset:5120
	ds_read_b128 v[184:187], v200 offset:6144
	ds_read_b128 v[188:191], v200 offset:7168
	global_load_lds_dwordx4 v[192:193], off
	v_lshl_add_u64 v[192:193], s[20:21], 0, v[138:139]
	s_add_i32 m0, s33, 0xe000
	s_nop 0
	global_load_lds_dwordx4 v[192:193], off
	s_waitcnt lgkmcnt(8)
	s_setprio 1
	s_barrier
	s_waitcnt lgkmcnt(0)
	v_mfma_f32_16x16x32_bf16 v[124:127], v[144:147], v[160:163], v[124:127]
	v_mfma_f32_16x16x32_bf16 v[120:123], v[152:155], v[160:163], v[120:123]
	v_mfma_f32_16x16x32_bf16 v[108:111], v[144:147], v[168:171], v[108:111]
	v_mfma_f32_16x16x32_bf16 v[104:107], v[152:155], v[168:171], v[104:107]
	v_mfma_f32_16x16x32_bf16 v[92:95], v[144:147], v[176:179], v[92:95]
	v_mfma_f32_16x16x32_bf16 v[88:91], v[152:155], v[176:179], v[88:91]
	v_mfma_f32_16x16x32_bf16 v[84:87], v[144:147], v[184:187], v[84:87]
	v_mfma_f32_16x16x32_bf16 v[76:79], v[152:155], v[184:187], v[76:79]
	v_mfma_f32_16x16x32_bf16 v[124:127], v[148:151], v[164:167], v[124:127]
	v_mfma_f32_16x16x32_bf16 v[120:123], v[156:159], v[164:167], v[120:123]
	v_mfma_f32_16x16x32_bf16 v[108:111], v[148:151], v[172:175], v[108:111]
	v_mfma_f32_16x16x32_bf16 v[104:107], v[156:159], v[172:175], v[104:107]
	v_mfma_f32_16x16x32_bf16 v[92:95], v[148:151], v[180:183], v[92:95]
	v_mfma_f32_16x16x32_bf16 v[88:91], v[156:159], v[180:183], v[88:91]
	s_setprio 2
	s_barrier
	v_mfma_f32_16x16x32_bf16 v[84:87], v[148:151], v[188:191], v[84:87]
	v_mfma_f32_16x16x32_bf16 v[76:79], v[156:159], v[188:191], v[76:79]
	s_setprio 0
	s_add_i32 s20, s42, s29
	v_lshl_add_u64 v[214:215], s[24:25], 0, v[130:131]
	s_mov_b32 m0, s20
	ds_read_b128 v[192:195], v201
	ds_read_b128 v[202:205], v201 offset:1024
	ds_read_b128 v[206:209], v201 offset:2048
	ds_read_b128 v[210:213], v201 offset:3072
	global_load_lds_dwordx4 v[214:215], off
	v_lshl_add_u64 v[216:217], s[24:25], 0, v[134:135]
	s_add_i32 m0, s20, 0x2000
	s_nop 0
	global_load_lds_dwordx4 v[216:217], off
	s_setprio 1
	s_barrier
	s_waitcnt lgkmcnt(0)
	v_mfma_f32_16x16x32_bf16 v[116:119], v[192:195], v[160:163], v[116:119]
	v_mfma_f32_16x16x32_bf16 v[112:115], v[206:209], v[160:163], v[112:115]
	v_mfma_f32_16x16x32_bf16 v[100:103], v[192:195], v[168:171], v[100:103]
	v_mfma_f32_16x16x32_bf16 v[96:99], v[206:209], v[168:171], v[96:99]
	v_mfma_f32_16x16x32_bf16 v[80:83], v[192:195], v[176:179], v[80:83]
	v_mfma_f32_16x16x32_bf16 v[72:75], v[206:209], v[176:179], v[72:75]
	v_mfma_f32_16x16x32_bf16 v[68:71], v[192:195], v[184:187], v[68:71]
	v_mfma_f32_16x16x32_bf16 v[64:67], v[206:209], v[184:187], v[64:67]
	v_mfma_f32_16x16x32_bf16 v[116:119], v[202:205], v[164:167], v[116:119]
	v_mfma_f32_16x16x32_bf16 v[112:115], v[210:213], v[164:167], v[112:115]
	v_mfma_f32_16x16x32_bf16 v[100:103], v[202:205], v[172:175], v[100:103]
	v_mfma_f32_16x16x32_bf16 v[96:99], v[210:213], v[172:175], v[96:99]
	v_mfma_f32_16x16x32_bf16 v[80:83], v[202:205], v[180:183], v[80:83]
	v_mfma_f32_16x16x32_bf16 v[72:75], v[210:213], v[180:183], v[72:75]
	s_setprio 2
	s_barrier
	v_mfma_f32_16x16x32_bf16 v[68:71], v[202:205], v[188:191], v[68:71]
	v_mfma_f32_16x16x32_bf16 v[64:67], v[210:213], v[188:191], v[64:67]
	s_setprio 0
	s_mov_b32 m0, s33
	v_lshl_add_u64 v[218:219], s[26:27], 0, v[128:129]
	ds_read_b128 v[160:163], v200 offset:16384
	ds_read_b128 v[164:167], v200 offset:17408
	ds_read_b128 v[168:171], v200 offset:18432
	ds_read_b128 v[172:175], v200 offset:19456
	ds_read_b128 v[176:179], v200 offset:20480
	ds_read_b128 v[180:183], v200 offset:21504
	ds_read_b128 v[184:187], v200 offset:22528
	ds_read_b128 v[188:191], v200 offset:23552
	global_load_lds_dwordx4 v[218:219], off
	v_lshl_add_u64 v[220:221], s[26:27], 0, v[132:133]
	s_mov_b32 m0, s34
	s_nop 0
	global_load_lds_dwordx4 v[220:221], off
	s_setprio 1
	s_barrier
	s_waitcnt lgkmcnt(0)
	v_mfma_f32_16x16x32_bf16 v[60:63], v[144:147], v[160:163], v[60:63]
	v_mfma_f32_16x16x32_bf16 v[56:59], v[152:155], v[160:163], v[56:59]
	v_mfma_f32_16x16x32_bf16 v[48:51], v[144:147], v[168:171], v[48:51]
	v_mfma_f32_16x16x32_bf16 v[40:43], v[152:155], v[168:171], v[40:43]
	v_mfma_f32_16x16x32_bf16 v[32:35], v[144:147], v[176:179], v[32:35]
	v_mfma_f32_16x16x32_bf16 v[24:27], v[152:155], v[176:179], v[24:27]
	v_mfma_f32_16x16x32_bf16 v[16:19], v[144:147], v[184:187], v[16:19]
	v_mfma_f32_16x16x32_bf16 v[8:11], v[152:155], v[184:187], v[8:11]
	v_mfma_f32_16x16x32_bf16 v[60:63], v[148:151], v[164:167], v[60:63]
	v_mfma_f32_16x16x32_bf16 v[56:59], v[156:159], v[164:167], v[56:59]
	v_mfma_f32_16x16x32_bf16 v[48:51], v[148:151], v[172:175], v[48:51]
	v_mfma_f32_16x16x32_bf16 v[40:43], v[156:159], v[172:175], v[40:43]
	v_mfma_f32_16x16x32_bf16 v[32:35], v[148:151], v[180:183], v[32:35]
	v_mfma_f32_16x16x32_bf16 v[24:27], v[156:159], v[180:183], v[24:27]
	s_setprio 2
	s_barrier
; #define PG8_STAGE(bufoff, gbase, voff) do { _Pragma("unroll") for (int _i = 0; _i < 2; ++_i) \
;         __builtin_amdgcn_global_load_lds((const unsigned*)((const char*)(gbase) + (voff)[_i]), (LAS unsigned*)(lds + (bufoff) + ldsw + _i * 8192), 16, 0, 0); } while (0)
; #define PG8_LDA(dst, b, h) do { _Pragma("unroll") for (int m = 0; m < 4; ++m) _Pragma("unroll") for (int k = 0; k < 2; ++k) dst[m][k] = *(const LAS bf16x8*)(lds + PG8_SA(b, h) + aoff + m * 2048 + k * 1024); } while (0)
; #define PG8_LDB(dst, b, h) do { _Pragma("unroll") for (int n = 0; n < 2; ++n) _Pragma("unroll") for (int k = 0; k < 2; ++k) dst[n][k] = *(const LAS bf16x8*)(lds + PG8_SB(b, h) + boff + n * 2048 + k * 1024); } while (0)
; #define PG8_MMA(ai, bj, At, Bt) do { __builtin_amdgcn_s_setprio(1); _Pragma("unroll") for (int m = 0; m < 4; ++m) _Pragma("unroll") for (int n = 0; n < 2; ++n) _Pragma("unroll") for (int k = 0; k < 2; ++k) \
;         acc[ai][bj][m][n] = __builtin_amdgcn_mfma_f32_16x16x32_bf16(Bt[n][k], At[m][k], acc[ai][bj][m][n], 0, 0, 0); __builtin_amdgcn_s_setprio(0); } while (0)
; #define PG8_WAIT_V(n) asm volatile("s_waitcnt vmcnt(" #n ")" ::: "memory")
; #define PG8_WAIT_L(n) asm volatile("s_waitcnt lgkmcnt(" #n ")" ::: "memory")
; #define PG8_BAR __builtin_amdgcn_s_barrier()
; #define PG8_SCHED __builtin_amdgcn_sched_barrier(0)
; #define PG8_STAGE(bufoff, gbase, voff) do { _Pragma("unroll") for (int _i = 0; _i < 2; ++_i) \
;         __builtin_amdgcn_global_load_lds((const unsigned*)((const char*)(gbase) + (voff)[_i]), (LAS unsigned*)(lds + (bufoff) + ldsw + _i * 8192), 16, 0, 0); } while (0)
; #define PG8_BAR __builtin_amdgcn_s_barrier()
; template <class Epi0, class Epi1>
; DI void gemm_phase_dual(LAS unsigned char* lds, const Gemm g, const Gemm g1, const StaticOrder S, const Epi0 E0, const Epi1 E1) {
;     ...
;             PG8_WAIT_V(6); PG8_BAR; PG8_MMA(1, 1, At, B1); PG8_BAR;
;             PG8_LDB(B0, 1, 0); PG8_SCHED; PG8_LDA(At, 1, 0); PG8_STAGE(PG8_SA(0, 1), a2 + hstep, voffA);
;             PG8_WAIT_L(8); PG8_BAR; PG8_WAIT_L(0); PG8_MMA(0, 0, At, B0); PG8_BAR; PG8_SCHED;
;             PG8_LDB(B1, 1, 1); PG8_STAGE(PG8_SB(1, 0), b3, voffB);
;             PG8_BAR; PG8_WAIT_L(0); PG8_MMA(0, 1, At, B1); PG8_BAR;
;             PG8_LDA(At, 1, 1); PG8_STAGE(PG8_SA(1, 0), a3, voffA);
;             PG8_BAR; PG8_WAIT_L(0); PG8_MMA(1, 0, At, B0); PG8_BAR; PG8_SCHED;
	v_mfma_f32_16x16x32_bf16 v[16:19], v[148:151], v[188:191], v[16:19]
	v_mfma_f32_16x16x32_bf16 v[8:11], v[156:159], v[188:191], v[8:11]
	s_setprio 0
	s_add_u32 s20, s24, 0xb0000
	s_addc_u32 s21, s25, 0
	s_add_i32 s59, s43, s29
	v_lshl_add_u64 v[144:145], s[20:21], 0, v[130:131]
	s_mov_b32 m0, s59
	s_nop 0
	global_load_lds_dwordx4 v[144:145], off
	v_lshl_add_u64 v[144:145], s[20:21], 0, v[134:135]
	s_add_i32 m0, s59, 0x2000
	s_nop 0
	global_load_lds_dwordx4 v[144:145], off
	s_waitcnt vmcnt(6)
	s_setprio 1
	s_barrier
	v_mfma_f32_16x16x32_bf16 v[52:55], v[192:195], v[160:163], v[52:55]
	v_mfma_f32_16x16x32_bf16 v[44:47], v[206:209], v[160:163], v[44:47]
	v_mfma_f32_16x16x32_bf16 v[36:39], v[192:195], v[168:171], v[36:39]
	v_mfma_f32_16x16x32_bf16 v[28:31], v[206:209], v[168:171], v[28:31]
	v_mfma_f32_16x16x32_bf16 v[20:23], v[192:195], v[176:179], v[20:23]
	v_mfma_f32_16x16x32_bf16 v[12:15], v[206:209], v[176:179], v[12:15]
	v_mfma_f32_16x16x32_bf16 v[4:7], v[192:195], v[184:187], v[4:7]
	v_mfma_f32_16x16x32_bf16 v[0:3], v[206:209], v[184:187], v[0:3]
	v_mfma_f32_16x16x32_bf16 v[52:55], v[202:205], v[164:167], v[52:55]
	v_mfma_f32_16x16x32_bf16 v[44:47], v[210:213], v[164:167], v[44:47]
	v_mfma_f32_16x16x32_bf16 v[36:39], v[202:205], v[172:175], v[36:39]
	v_mfma_f32_16x16x32_bf16 v[28:31], v[210:213], v[172:175], v[28:31]
	v_mfma_f32_16x16x32_bf16 v[20:23], v[202:205], v[180:183], v[20:23]
	v_mfma_f32_16x16x32_bf16 v[12:15], v[210:213], v[180:183], v[12:15]
	s_setprio 2
	s_barrier
	v_mfma_f32_16x16x32_bf16 v[4:7], v[202:205], v[188:191], v[4:7]
	v_mfma_f32_16x16x32_bf16 v[0:3], v[210:213], v[188:191], v[0:3]
	s_setprio 0
	s_add_i32 s59, 0, 0x18000
	v_add_u32_e32 v156, s59, v197
	ds_read_b128 v[144:147], v156
	ds_read_b128 v[148:151], v156 offset:1024
	ds_read_b128 v[152:155], v156 offset:2048
	ds_read_b128 v[156:159], v156 offset:3072
	s_add_u32 s20, s26, 0xb0000
	s_addc_u32 s21, s27, 0
	s_mov_b32 m0, s35
	v_lshl_add_u64 v[192:193], s[20:21], 0, v[128:129]
	ds_read_b128 v[160:163], v200 offset:32768
	ds_read_b128 v[164:167], v200 offset:33792
	ds_read_b128 v[168:171], v200 offset:34816
	ds_read_b128 v[172:175], v200 offset:35840
	ds_read_b128 v[176:179], v200 offset:36864
	ds_read_b128 v[180:183], v200 offset:37888
	ds_read_b128 v[184:187], v200 offset:38912
	ds_read_b128 v[188:191], v200 offset:39936
	global_load_lds_dwordx4 v[192:193], off
	v_lshl_add_u64 v[192:193], s[20:21], 0, v[132:133]
	s_mov_b32 m0, s36
	s_nop 0
	global_load_lds_dwordx4 v[192:193], off
	s_waitcnt lgkmcnt(8)
	s_setprio 1
	s_barrier
	s_waitcnt lgkmcnt(0)
	v_mfma_f32_16x16x32_bf16 v[124:127], v[144:147], v[160:163], v[124:127]
	v_mfma_f32_16x16x32_bf16 v[120:123], v[152:155], v[160:163], v[120:123]
	v_mfma_f32_16x16x32_bf16 v[108:111], v[144:147], v[168:171], v[108:111]
	v_mfma_f32_16x16x32_bf16 v[104:107], v[152:155], v[168:171], v[104:107]
	v_mfma_f32_16x16x32_bf16 v[92:95], v[144:147], v[176:179], v[92:95]
	v_mfma_f32_16x16x32_bf16 v[88:91], v[152:155], v[176:179], v[88:91]
	v_mfma_f32_16x16x32_bf16 v[84:87], v[144:147], v[184:187], v[84:87]
	v_mfma_f32_16x16x32_bf16 v[76:79], v[152:155], v[184:187], v[76:79]
	v_mfma_f32_16x16x32_bf16 v[124:127], v[148:151], v[164:167], v[124:127]
	v_mfma_f32_16x16x32_bf16 v[120:123], v[156:159], v[164:167], v[120:123]
	v_mfma_f32_16x16x32_bf16 v[108:111], v[148:151], v[172:175], v[108:111]
	v_mfma_f32_16x16x32_bf16 v[104:107], v[156:159], v[172:175], v[104:107]
	v_mfma_f32_16x16x32_bf16 v[92:95], v[148:151], v[180:183], v[92:95]
	v_mfma_f32_16x16x32_bf16 v[88:91], v[156:159], v[180:183], v[88:91]
	s_setprio 2
	s_barrier
	v_mfma_f32_16x16x32_bf16 v[84:87], v[148:151], v[188:191], v[84:87]
	v_mfma_f32_16x16x32_bf16 v[76:79], v[156:159], v[188:191], v[76:79]
	s_setprio 0
	s_add_i32 s26, 0, 0x1c000
	s_add_i32 s20, s59, s29
	v_add_u32_e32 v210, s26, v197
	v_lshl_add_u64 v[214:215], v[214:215], 0, s[10:11]
	s_mov_b32 m0, s20
	ds_read_b128 v[192:195], v210
	ds_read_b128 v[202:205], v210 offset:1024
	ds_read_b128 v[206:209], v210 offset:2048
	ds_read_b128 v[210:213], v210 offset:3072
	global_load_lds_dwordx4 v[214:215], off
	v_lshl_add_u64 v[214:215], v[216:217], 0, s[10:11]
	s_add_i32 m0, s20, 0x2000
	s_nop 0
	global_load_lds_dwordx4 v[214:215], off
	s_setprio 1
	s_barrier
	s_waitcnt lgkmcnt(0)
	v_mfma_f32_16x16x32_bf16 v[116:119], v[192:195], v[160:163], v[116:119]
	v_mfma_f32_16x16x32_bf16 v[112:115], v[206:209], v[160:163], v[112:115]
	v_mfma_f32_16x16x32_bf16 v[100:103], v[192:195], v[168:171], v[100:103]
	v_mfma_f32_16x16x32_bf16 v[96:99], v[206:209], v[168:171], v[96:99]
	v_mfma_f32_16x16x32_bf16 v[80:83], v[192:195], v[176:179], v[80:83]
	v_mfma_f32_16x16x32_bf16 v[72:75], v[206:209], v[176:179], v[72:75]
	v_mfma_f32_16x16x32_bf16 v[68:71], v[192:195], v[184:187], v[68:71]
	v_mfma_f32_16x16x32_bf16 v[64:67], v[206:209], v[184:187], v[64:67]
	v_mfma_f32_16x16x32_bf16 v[116:119], v[202:205], v[164:167], v[116:119]
	v_mfma_f32_16x16x32_bf16 v[112:115], v[210:213], v[164:167], v[112:115]
	v_mfma_f32_16x16x32_bf16 v[100:103], v[202:205], v[172:175], v[100:103]
	v_mfma_f32_16x16x32_bf16 v[96:99], v[210:213], v[172:175], v[96:99]
	v_mfma_f32_16x16x32_bf16 v[80:83], v[202:205], v[180:183], v[80:83]
	v_mfma_f32_16x16x32_bf16 v[72:75], v[210:213], v[180:183], v[72:75]
	s_setprio 2
	s_barrier
; DI f32x4 bf_lo4(u32x4 w) { f32x4 r; r[0] = bf_lo(w.x); r[1] = bf_hi(w.x); r[2] = bf_lo(w.y); r[3] = bf_hi(w.y); return r; }
; DI f32x4 bf_hi4(u32x4 w) { f32x4 r; r[0] = bf_lo(w.z); r[1] = bf_hi(w.z); r[2] = bf_lo(w.w); r[3] = bf_hi(w.w); return r; }
; #define PG8_STAGE(bufoff, gbase, voff) do { _Pragma("unroll") for (int _i = 0; _i < 2; ++_i) \
;         __builtin_amdgcn_global_load_lds((const unsigned*)((const char*)(gbase) + (voff)[_i]), (LAS unsigned*)(lds + (bufoff) + ldsw + _i * 8192), 16, 0, 0); } while (0)
; #define PG8_MMA(ai, bj, At, Bt) do { __builtin_amdgcn_s_setprio(1); _Pragma("unroll") for (int m = 0; m < 4; ++m) _Pragma("unroll") for (int n = 0; n < 2; ++n) _Pragma("unroll") for (int k = 0; k < 2; ++k) \
;         acc[ai][bj][m][n] = __builtin_amdgcn_mfma_f32_16x16x32_bf16(Bt[n][k], At[m][k], acc[ai][bj][m][n], 0, 0, 0); __builtin_amdgcn_s_setprio(0); } while (0)
; #define PG8_WAIT_V(n) asm volatile("s_waitcnt vmcnt(" #n ")" ::: "memory")
; #define PG8_WAIT_L(n) asm volatile("s_waitcnt lgkmcnt(" #n ")" ::: "memory")
; #define PG8_BAR __builtin_amdgcn_s_barrier()
; #define PG8_SCHED __builtin_amdgcn_sched_barrier(0)
; #define PG8_WAIT_V(n) asm volatile("s_waitcnt vmcnt(" #n ")" ::: "memory")
; template <class Epi0, class Epi1>
; DI void gemm_phase_dual(LAS unsigned char* lds, const Gemm g, const Gemm g1, const StaticOrder S, const Epi0 E0, const Epi1 E1) {
;     ...
;             PG8_BAR; PG8_WAIT_L(0); PG8_MMA(1, 0, At, B0); PG8_BAR; PG8_SCHED;
;             PG8_STAGE(PG8_SB(1, 1), b3 + hstep, voffB);
;             PG8_WAIT_V(6); PG8_BAR; PG8_MMA(1, 1, At, B1); PG8_BAR;
;     DI void operator()(AccRef acc, const Unit& u, int wr, int wc, int fr, int fq) const {
;     ...
;         const int row0 = u.pm * 256 + wr * 64 + fr, col0 = u.pn * 256 + wc * 32 + 8 * fq;
; #pragma unroll
;         for (int ai = 0; ai < 2; ++ai) {
;             f32x4 bv[4][2][2];
; #pragma unroll
;             for (int m = 0; m < 4; ++m)
; #pragma unroll
;                 for (int bj = 0; bj < 2; ++bj) {
;                     const size_t o = (size_t)(row0 + ai * 128 + m * 16) * DM + col0 + bj * 128;
;                     if (BASEF32) { bv[m][bj][0] = *(const f32x4*)(basef + o); bv[m][bj][1] = *(const f32x4*)(basef + o + 4); }
;                     else { const u32x4 h = *(const u32x4*)(xnb + o); bv[m][bj][0] = bf_lo4(h); bv[m][bj][1] = bf_hi4(h); }
;                 }
	v_mfma_f32_16x16x32_bf16 v[68:71], v[202:205], v[188:191], v[68:71]
	v_mfma_f32_16x16x32_bf16 v[64:67], v[210:213], v[188:191], v[64:67]
	s_setprio 0
	s_mov_b32 m0, s38
	v_lshl_add_u64 v[214:215], v[218:219], 0, s[10:11]
	ds_read_b128 v[160:163], v200 offset:49152
	ds_read_b128 v[164:167], v200 offset:50176
	ds_read_b128 v[168:171], v200 offset:51200
	ds_read_b128 v[172:175], v200 offset:52224
	ds_read_b128 v[176:179], v200 offset:53248
	ds_read_b128 v[180:183], v200 offset:54272
	ds_read_b128 v[184:187], v200 offset:55296
	ds_read_b128 v[188:191], v200 offset:56320
	global_load_lds_dwordx4 v[214:215], off
	v_lshl_add_u64 v[214:215], v[220:221], 0, s[10:11]
	s_mov_b32 m0, s39
	s_nop 0
	global_load_lds_dwordx4 v[214:215], off
	s_setprio 1
	s_barrier
	s_waitcnt lgkmcnt(0)
	v_mfma_f32_16x16x32_bf16 v[60:63], v[144:147], v[160:163], v[60:63]
	v_mfma_f32_16x16x32_bf16 v[56:59], v[152:155], v[160:163], v[56:59]
	v_mfma_f32_16x16x32_bf16 v[48:51], v[144:147], v[168:171], v[48:51]
	v_mfma_f32_16x16x32_bf16 v[40:43], v[152:155], v[168:171], v[40:43]
	v_mfma_f32_16x16x32_bf16 v[32:35], v[144:147], v[176:179], v[32:35]
	v_mfma_f32_16x16x32_bf16 v[24:27], v[152:155], v[176:179], v[24:27]
	v_mfma_f32_16x16x32_bf16 v[16:19], v[144:147], v[184:187], v[16:19]
	v_mfma_f32_16x16x32_bf16 v[8:11], v[152:155], v[184:187], v[8:11]
	v_mfma_f32_16x16x32_bf16 v[60:63], v[148:151], v[164:167], v[60:63]
	v_mfma_f32_16x16x32_bf16 v[56:59], v[156:159], v[164:167], v[56:59]
	v_mfma_f32_16x16x32_bf16 v[48:51], v[148:151], v[172:175], v[48:51]
	v_mfma_f32_16x16x32_bf16 v[40:43], v[156:159], v[172:175], v[40:43]
	v_mfma_f32_16x16x32_bf16 v[32:35], v[148:151], v[180:183], v[32:35]
	v_mfma_f32_16x16x32_bf16 v[24:27], v[156:159], v[180:183], v[24:27]
	s_setprio 2
	s_barrier
	v_mfma_f32_16x16x32_bf16 v[16:19], v[148:151], v[188:191], v[16:19]
	v_mfma_f32_16x16x32_bf16 v[8:11], v[156:159], v[188:191], v[8:11]
	s_setprio 0
	s_add_u32 s20, s24, 0xb0080
	s_addc_u32 s21, s25, 0
	s_add_i32 s24, s26, s29
	v_lshl_add_u64 v[144:145], s[20:21], 0, v[130:131]
	s_mov_b32 m0, s24
	s_nop 0
	global_load_lds_dwordx4 v[144:145], off
	v_lshl_add_u64 v[144:145], s[20:21], 0, v[134:135]
	s_add_i32 m0, s24, 0x2000
	s_nop 0
	global_load_lds_dwordx4 v[144:145], off
	s_waitcnt vmcnt(6)
	s_setprio 1
	s_barrier
	v_mfma_f32_16x16x32_bf16 v[52:55], v[192:195], v[160:163], v[52:55]
	v_mfma_f32_16x16x32_bf16 v[44:47], v[206:209], v[160:163], v[44:47]
	v_mfma_f32_16x16x32_bf16 v[36:39], v[192:195], v[168:171], v[36:39]
	v_mfma_f32_16x16x32_bf16 v[28:31], v[206:209], v[168:171], v[28:31]
	v_mfma_f32_16x16x32_bf16 v[20:23], v[192:195], v[176:179], v[20:23]
	v_mfma_f32_16x16x32_bf16 v[12:15], v[206:209], v[176:179], v[12:15]
	v_mfma_f32_16x16x32_bf16 v[4:7], v[192:195], v[184:187], v[4:7]
	v_mfma_f32_16x16x32_bf16 v[0:3], v[206:209], v[184:187], v[0:3]
	v_mfma_f32_16x16x32_bf16 v[52:55], v[202:205], v[164:167], v[52:55]
	v_mfma_f32_16x16x32_bf16 v[44:47], v[210:213], v[164:167], v[44:47]
	v_mfma_f32_16x16x32_bf16 v[36:39], v[202:205], v[172:175], v[36:39]
	v_mfma_f32_16x16x32_bf16 v[28:31], v[210:213], v[172:175], v[28:31]
	v_mfma_f32_16x16x32_bf16 v[20:23], v[202:205], v[180:183], v[20:23]
	v_mfma_f32_16x16x32_bf16 v[12:15], v[210:213], v[180:183], v[12:15]
	s_setprio 2
	s_barrier
	v_mfma_f32_16x16x32_bf16 v[4:7], v[202:205], v[188:191], v[4:7]
	v_mfma_f32_16x16x32_bf16 v[0:3], v[210:213], v[188:191], v[0:3]
	s_setprio 0
	s_add_i32 s58, s58, 2
	s_add_u32 s52, s52, 0x100
	s_addc_u32 s53, s53, 0
	s_cmp_gt_u32 s58, 41
	s_mov_b64 s[20:21], s[22:23]
	s_cbranch_scc0 .LBB0_941
	v_lshl_add_u32 v148, s50, 8, v196
	v_lshl_or_b32 v144, s51, 8, v198
	v_or_b32_e32 v146, 16, v148
	v_ashrrev_i32_e32 v145, 31, v144
	v_ashrrev_i32_e32 v147, 31, v146
	v_lshl_add_u64 v[176:177], v[144:145], 1, s[56:57]
	v_ashrrev_i32_e32 v149, 31, v148
	v_lshlrev_b64 v[146:147], 11, v[146:147]
	v_lshlrev_b64 v[144:145], 11, v[148:149]
	v_lshl_add_u64 v[150:151], v[176:177], 0, v[146:147]
	v_or_b32_e32 v146, 32, v148
	v_or_b32_e32 v148, 48, v148
	v_ashrrev_i32_e32 v147, 31, v146
	v_ashrrev_i32_e32 v149, 31, v148
	v_lshl_add_u64 v[144:145], v[176:177], 0, v[144:145]
	v_lshlrev_b64 v[146:147], 11, v[146:147]
	v_lshlrev_b64 v[148:149], 11, v[148:149]
	global_load_dwordx4 v[152:155], v[144:145], off
	global_load_dwordx4 v[156:159], v[144:145], off offset:256
	v_lshl_add_u64 v[146:147], v[176:177], 0, v[146:147]
	v_lshl_add_u64 v[148:149], v[176:177], 0, v[148:149]
	global_load_dwordx4 v[160:163], v[150:151], off
	global_load_dwordx4 v[164:167], v[150:151], off offset:256
	global_load_dwordx4 v[168:171], v[146:147], off
	global_load_dwordx4 v[172:175], v[146:147], off offset:256
	global_load_dwordx4 v[202:205], v[148:149], off
	global_load_dwordx4 v[206:209], v[148:149], off offset:256
	s_mov_b32 s51, s48
	s_mov_b32 s50, s49
	s_mov_b64 s[22:23], s[4:5]
	s_mov_b64 s[20:21], s[8:9]
	s_waitcnt vmcnt(0)
; DI unsigned pk_bf16(float lo, float hi) { f32x2 v = {lo, hi}; return __builtin_bit_cast(unsigned, __builtin_convertvector(v, bf16v2)); }
; DI f32x4 bf_lo4(u32x4 w) { f32x4 r; r[0] = bf_lo(w.x); r[1] = bf_hi(w.x); r[2] = bf_lo(w.y); r[3] = bf_hi(w.y); return r; }
; DI f32x4 bf_hi4(u32x4 w) { f32x4 r; r[0] = bf_lo(w.z); r[1] = bf_hi(w.z); r[2] = bf_lo(w.w); r[3] = bf_hi(w.w); return r; }
;     DI void operator()(AccRef acc, const Unit& u, int wr, int wc, int fr, int fq) const {
;     ...
;         for (int ai = 0; ai < 2; ++ai) {
;             f32x4 bv[4][2][2];
; #pragma unroll
;             for (int m = 0; m < 4; ++m)
; #pragma unroll
;                 for (int bj = 0; bj < 2; ++bj) {
;                     const size_t o = (size_t)(row0 + ai * 128 + m * 16) * DM + col0 + bj * 128;
;                     if (BASEF32) { bv[m][bj][0] = *(const f32x4*)(basef + o); bv[m][bj][1] = *(const f32x4*)(basef + o + 4); }
;                     else { const u32x4 h = *(const u32x4*)(xnb + o); bv[m][bj][0] = bf_lo4(h); bv[m][bj][1] = bf_hi4(h); }
;                 }
; #pragma unroll
;             for (int m = 0; m < 4; ++m) {
;                 const int row = row0 + ai * 128 + m * 16;
;                 float q = 0.f;
; #pragma unroll
;                 for (int bj = 0; bj < 2; ++bj) {
;                     const size_t o = (size_t)row * DM + col0 + bj * 128;
;                     const f32x4 r0 = bv[m][bj][0] + scale * acc[ai][bj][m][0], r1 = bv[m][bj][1] + scale * acc[ai][bj][m][1];
;                     u32x4 w; w.x = pk_bf16(r0[0], r0[1]); w.y = pk_bf16(r0[2], r0[3]); w.z = pk_bf16(r1[0], r1[1]); w.w = pk_bf16(r1[2], r1[3]);
;                     *(u32x4*)(xnb + o) = w;
	v_lshlrev_b32_e32 v214, 16, v154
	v_and_b32_e32 v215, 0xffff0000, v154
	v_lshlrev_b32_e32 v216, 16, v155
	v_and_b32_e32 v217, 0xffff0000, v155
	v_lshlrev_b32_e32 v210, 16, v152
	v_and_b32_e32 v211, 0xffff0000, v152
	v_lshlrev_b32_e32 v212, 16, v153
	v_and_b32_e32 v213, 0xffff0000, v153
	v_lshlrev_b32_e32 v194, 16, v162
	v_and_b32_e32 v195, 0xffff0000, v162
	v_lshlrev_b32_e32 v230, 16, v163
	v_and_b32_e32 v231, 0xffff0000, v163
	v_lshlrev_b32_e32 v154, 16, v202
	v_and_b32_e32 v155, 0xffff0000, v202
	v_lshlrev_b32_e32 v162, 16, v203
	v_and_b32_e32 v163, 0xffff0000, v203
	v_pk_fma_f32 v[202:203], v[122:123], 0.5, v[216:217] op_sel_hi:[1,0,1]
	v_pk_fma_f32 v[122:123], v[120:121], 0.5, v[214:215] op_sel_hi:[1,0,1]
	v_lshlrev_b32_e32 v218, 16, v156
	v_and_b32_e32 v219, 0xffff0000, v156
	v_lshlrev_b32_e32 v220, 16, v157
	v_and_b32_e32 v221, 0xffff0000, v157
	v_pk_fma_f32 v[126:127], v[126:127], 0.5, v[212:213] op_sel_hi:[1,0,1]
	v_pk_fma_f32 v[124:125], v[124:125], 0.5, v[210:211] op_sel_hi:[1,0,1]
	v_cvt_pk_bf16_f32 v122, v122, v123
	v_cvt_pk_bf16_f32 v123, v202, v203
	v_add_co_u32_e32 v202, vcc, s44, v144
	v_lshlrev_b32_e32 v224, 16, v158
	v_and_b32_e32 v225, 0xffff0000, v158
	v_lshlrev_b32_e32 v226, 16, v159
	v_and_b32_e32 v227, 0xffff0000, v159
	v_cvt_pk_bf16_f32 v120, v124, v125
	v_cvt_pk_bf16_f32 v121, v126, v127
	v_pk_fma_f32 v[118:119], v[118:119], 0.5, v[220:221] op_sel_hi:[1,0,1]
	v_pk_fma_f32 v[116:117], v[116:117], 0.5, v[218:219] op_sel_hi:[1,0,1]
	v_addc_co_u32_e32 v203, vcc, 0, v145, vcc
	v_lshlrev_b32_e32 v192, 16, v160
	v_and_b32_e32 v193, 0xffff0000, v160
	global_store_dwordx4 v[144:145], v[120:123], off
	v_pk_fma_f32 v[108:109], v[108:109], 0.5, v[192:193] op_sel_hi:[1,0,1]
	v_lshl_add_u64 v[192:193], v[144:145], 0, s[12:13]
	v_pk_fma_f32 v[120:121], v[114:115], 0.5, v[226:227] op_sel_hi:[1,0,1]
	v_pk_fma_f32 v[114:115], v[112:113], 0.5, v[224:225] op_sel_hi:[1,0,1]
	v_cvt_pk_bf16_f32 v112, v116, v117
	v_cvt_pk_bf16_f32 v113, v118, v119
	global_load_dwordx4 v[116:119], v[202:203], off
	v_cvt_pk_bf16_f32 v114, v114, v115
	v_cvt_pk_bf16_f32 v115, v120, v121
	v_lshlrev_b32_e32 v228, 16, v161
	v_and_b32_e32 v229, 0xffff0000, v161
	global_store_dwordx4 v[144:145], v[112:115], off offset:256
	v_pk_fma_f32 v[120:121], v[106:107], 0.5, v[230:231] op_sel_hi:[1,0,1]
	v_pk_fma_f32 v[110:111], v[110:111], 0.5, v[228:229] op_sel_hi:[1,0,1]
	v_pk_fma_f32 v[112:113], v[104:105], 0.5, v[194:195] op_sel_hi:[1,0,1]
	global_load_dwordx4 v[104:107], v[192:193], off offset:256
	v_add_co_u32_e32 v194, vcc, s45, v144
	v_lshlrev_b32_e32 v184, 16, v164
	s_nop 0
	v_addc_co_u32_e32 v195, vcc, 0, v145, vcc
	v_and_b32_e32 v185, 0xffff0000, v164
	v_lshlrev_b32_e32 v188, 16, v165
	v_and_b32_e32 v189, 0xffff0000, v165
	v_lshlrev_b32_e32 v186, 16, v166
	v_and_b32_e32 v187, 0xffff0000, v166
	v_lshlrev_b32_e32 v190, 16, v167
	v_and_b32_e32 v191, 0xffff0000, v167
	v_cvt_pk_bf16_f32 v108, v108, v109
	v_cvt_pk_bf16_f32 v109, v110, v111
	v_cvt_pk_bf16_f32 v110, v112, v113
	global_load_dwordx4 v[112:115], v[194:195], off
	v_cvt_pk_bf16_f32 v111, v120, v121
	global_store_dwordx4 v[150:151], v[108:111], off
	v_pk_fma_f32 v[124:125], v[98:99], 0.5, v[190:191] op_sel_hi:[1,0,1]
	v_pk_fma_f32 v[96:97], v[96:97], 0.5, v[186:187] op_sel_hi:[1,0,1]
	v_pk_fma_f32 v[110:111], v[102:103], 0.5, v[188:189] op_sel_hi:[1,0,1]
	v_pk_fma_f32 v[108:109], v[100:101], 0.5, v[184:185] op_sel_hi:[1,0,1]
	v_lshl_add_u64 v[98:99], v[144:145], 0, s[14:15]
	global_load_dwordx4 v[100:103], v[98:99], off offset:256
	v_cvt_pk_bf16_f32 v108, v108, v109
	v_cvt_pk_bf16_f32 v109, v110, v111
	v_cvt_pk_bf16_f32 v110, v96, v97
	v_add_co_u32_e32 v96, vcc, s46, v144
	v_lshlrev_b32_e32 v176, 16, v168
	s_nop 0
	v_addc_co_u32_e32 v97, vcc, 0, v145, vcc
	v_and_b32_e32 v177, 0xffff0000, v168
	v_lshlrev_b32_e32 v180, 16, v169
	v_and_b32_e32 v181, 0xffff0000, v169
	v_lshlrev_b32_e32 v178, 16, v170
	v_and_b32_e32 v179, 0xffff0000, v170
	v_lshlrev_b32_e32 v182, 16, v171
	v_and_b32_e32 v183, 0xffff0000, v171
	global_load_dwordx4 v[120:123], v[96:97], off
	v_cvt_pk_bf16_f32 v111, v124, v125
	global_store_dwordx4 v[150:151], v[108:111], off offset:256
	v_pk_fma_f32 v[150:151], v[90:91], 0.5, v[182:183] op_sel_hi:[1,0,1]
	v_pk_fma_f32 v[88:89], v[88:89], 0.5, v[178:179] op_sel_hi:[1,0,1]
	v_pk_fma_f32 v[110:111], v[94:95], 0.5, v[180:181] op_sel_hi:[1,0,1]
	v_pk_fma_f32 v[108:109], v[92:93], 0.5, v[176:177] op_sel_hi:[1,0,1]
	v_lshl_add_u64 v[90:91], v[144:145], 0, s[16:17]
	global_load_dwordx4 v[92:95], v[90:91], off offset:256
	v_cvt_pk_bf16_f32 v108, v108, v109
	v_cvt_pk_bf16_f32 v109, v110, v111
	v_cvt_pk_bf16_f32 v110, v88, v89
	v_add_co_u32_e32 v88, vcc, s47, v144
	v_lshlrev_b32_e32 v170, 16, v174
	s_nop 0
	v_addc_co_u32_e32 v89, vcc, 0, v145, vcc
	v_and_b32_e32 v171, 0xffff0000, v174
	global_load_dwordx4 v[124:127], v[88:89], off
	v_lshlrev_b32_e32 v168, 16, v172
	v_and_b32_e32 v169, 0xffff0000, v172
	v_lshlrev_b32_e32 v172, 16, v173
	v_and_b32_e32 v173, 0xffff0000, v173
	v_cvt_pk_bf16_f32 v111, v150, v151
	v_pk_fma_f32 v[150:151], v[72:73], 0.5, v[170:171] op_sel_hi:[1,0,1]
	v_lshl_add_u64 v[72:73], v[144:145], 0, s[18:19]
	global_store_dwordx4 v[146:147], v[108:111], off
	v_lshlrev_b32_e32 v174, 16, v175
	v_and_b32_e32 v175, 0xffff0000, v175
	v_pk_fma_f32 v[110:111], v[82:83], 0.5, v[172:173] op_sel_hi:[1,0,1]
	v_pk_fma_f32 v[108:109], v[80:81], 0.5, v[168:169] op_sel_hi:[1,0,1]
	global_load_dwordx4 v[80:83], v[72:73], off offset:256
	v_lshlrev_b32_e32 v160, 16, v204
	v_and_b32_e32 v161, 0xffff0000, v204
	v_lshlrev_b32_e32 v166, 16, v205
	v_and_b32_e32 v167, 0xffff0000, v205
	v_pk_fma_f32 v[74:75], v[74:75], 0.5, v[174:175] op_sel_hi:[1,0,1]
	v_cvt_pk_bf16_f32 v108, v108, v109
	v_cvt_pk_bf16_f32 v109, v110, v111
	v_cvt_pk_bf16_f32 v111, v74, v75
	v_pk_fma_f32 v[86:87], v[86:87], 0.5, v[162:163] op_sel_hi:[1,0,1]
	v_pk_fma_f32 v[74:75], v[84:85], 0.5, v[154:155] op_sel_hi:[1,0,1]
	v_pk_fma_f32 v[78:79], v[78:79], 0.5, v[166:167] op_sel_hi:[1,0,1]
	v_pk_fma_f32 v[76:77], v[76:77], 0.5, v[160:161] op_sel_hi:[1,0,1]
	v_lshlrev_b32_e32 v152, 16, v206
	v_and_b32_e32 v153, 0xffff0000, v206
	v_lshlrev_b32_e32 v158, 16, v207
	v_and_b32_e32 v159, 0xffff0000, v207
	v_lshlrev_b32_e32 v156, 16, v208
	v_and_b32_e32 v157, 0xffff0000, v208
	v_lshlrev_b32_e32 v164, 16, v209
	v_and_b32_e32 v165, 0xffff0000, v209
	v_cvt_pk_bf16_f32 v74, v74, v75
	v_cvt_pk_bf16_f32 v75, v86, v87
	v_cvt_pk_bf16_f32 v76, v76, v77
	v_cvt_pk_bf16_f32 v77, v78, v79
	global_store_dwordx4 v[148:149], v[74:77], off
	v_pk_fma_f32 v[70:71], v[70:71], 0.5, v[158:159] op_sel_hi:[1,0,1]
	v_pk_fma_f32 v[68:69], v[68:69], 0.5, v[152:153] op_sel_hi:[1,0,1]
	v_pk_fma_f32 v[74:75], v[66:67], 0.5, v[164:165] op_sel_hi:[1,0,1]
	v_pk_fma_f32 v[66:67], v[64:65], 0.5, v[156:157] op_sel_hi:[1,0,1]
	v_cvt_pk_bf16_f32 v64, v68, v69
	v_cvt_pk_bf16_f32 v65, v70, v71
	v_cvt_pk_bf16_f32 v66, v66, v67
	v_cvt_pk_bf16_f32 v67, v74, v75
	global_store_dwordx4 v[148:149], v[64:67], off offset:256
	s_waitcnt vmcnt(0)
; DI unsigned pk_bf16(float lo, float hi) { f32x2 v = {lo, hi}; return __builtin_bit_cast(unsigned, __builtin_convertvector(v, bf16v2)); }
; #define PG8_WAIT_V(n) asm volatile("s_waitcnt vmcnt(" #n ")" ::: "memory")
; #define PG8_BAR __builtin_amdgcn_s_barrier()
; #define PG8_WAIT_V(n) asm volatile("s_waitcnt vmcnt(" #n ")" ::: "memory")
; #define PG8_BAR __builtin_amdgcn_s_barrier()
; template <class Epi>
; DI void gemm_phase(LAS unsigned char* lds, const Gemm g, const StaticOrder S, const Epi E) {
;     ...
;         if (!has_next) break;
; #pragma unroll
;         for (int a = 0; a < 2; ++a)
; #pragma unroll
;             for (int b = 0; b < 2; ++b)
; #pragma unroll
;                 for (int m = 0; m < 4; ++m)
; #pragma unroll
;                     for (int n = 0; n < 2; ++n) acc[a][b][m][n] = (f32x4){0.f, 0.f, 0.f, 0.f};
;         cur = nxt; cA = nA; cB = nB; ++ui;
;     }
;     PG8_WAIT_V(0);
;     if (wr == 0) PG8_BAR;
;     PG8_BAR;
;     DI void operator()(AccRef acc, const Unit& u, int wr, int wc, int fr, int fq) const {
;     ...
;             for (int m = 0; m < 4; ++m) {
;                 const int row = row0 + ai * 128 + m * 16;
;                 float q = 0.f;
; #pragma unroll
;                 for (int bj = 0; bj < 2; ++bj) {
;                     const size_t o = (size_t)row * DM + col0 + bj * 128;
;                     const f32x4 r0 = bv[m][bj][0] + scale * acc[ai][bj][m][0], r1 = bv[m][bj][1] + scale * acc[ai][bj][m][1];
;                     u32x4 w; w.x = pk_bf16(r0[0], r0[1]); w.y = pk_bf16(r0[2], r0[3]); w.z = pk_bf16(r1[0], r1[1]); w.w = pk_bf16(r1[2], r1[3]);
;                     *(u32x4*)(xnb + o) = w;
	v_lshlrev_b32_e32 v68, 16, v118
	v_and_b32_e32 v69, 0xffff0000, v118
	v_lshlrev_b32_e32 v64, 16, v116
	v_and_b32_e32 v65, 0xffff0000, v116
	v_lshlrev_b32_e32 v66, 16, v117
	v_and_b32_e32 v67, 0xffff0000, v117
	v_lshlrev_b32_e32 v70, 16, v119
	v_and_b32_e32 v71, 0xffff0000, v119
	v_pk_fma_f32 v[62:63], v[62:63], 0.5, v[66:67] op_sel_hi:[1,0,1]
	v_pk_fma_f32 v[60:61], v[60:61], 0.5, v[64:65] op_sel_hi:[1,0,1]
	v_pk_fma_f32 v[64:65], v[58:59], 0.5, v[70:71] op_sel_hi:[1,0,1]
	v_pk_fma_f32 v[58:59], v[56:57], 0.5, v[68:69] op_sel_hi:[1,0,1]
	v_lshlrev_b32_e32 v74, 16, v104
	v_and_b32_e32 v75, 0xffff0000, v104
	v_lshlrev_b32_e32 v76, 16, v105
	v_and_b32_e32 v77, 0xffff0000, v105
	v_lshlrev_b32_e32 v78, 16, v106
	v_and_b32_e32 v79, 0xffff0000, v106
	v_lshlrev_b32_e32 v84, 16, v107
	v_and_b32_e32 v85, 0xffff0000, v107
	v_cvt_pk_bf16_f32 v56, v60, v61
	v_cvt_pk_bf16_f32 v57, v62, v63
	v_cvt_pk_bf16_f32 v58, v58, v59
	v_cvt_pk_bf16_f32 v59, v64, v65
	v_cvt_pk_bf16_f32 v110, v150, v151
	global_store_dwordx4 v[202:203], v[56:59], off
	v_pk_fma_f32 v[54:55], v[54:55], 0.5, v[76:77] op_sel_hi:[1,0,1]
	v_pk_fma_f32 v[52:53], v[52:53], 0.5, v[74:75] op_sel_hi:[1,0,1]
	v_pk_fma_f32 v[56:57], v[46:47], 0.5, v[84:85] op_sel_hi:[1,0,1]
	v_pk_fma_f32 v[46:47], v[44:45], 0.5, v[78:79] op_sel_hi:[1,0,1]
	global_store_dwordx4 v[146:147], v[108:111], off offset:256
	v_lshlrev_b32_e32 v86, 16, v112
	v_and_b32_e32 v87, 0xffff0000, v112
	v_lshlrev_b32_e32 v104, 16, v113
	v_and_b32_e32 v105, 0xffff0000, v113
	v_lshlrev_b32_e32 v106, 16, v114
	v_and_b32_e32 v107, 0xffff0000, v114
	v_lshlrev_b32_e32 v108, 16, v115
	v_and_b32_e32 v109, 0xffff0000, v115
	v_cvt_pk_bf16_f32 v44, v52, v53
	v_cvt_pk_bf16_f32 v45, v54, v55
	v_cvt_pk_bf16_f32 v46, v46, v47
	v_cvt_pk_bf16_f32 v47, v56, v57
	global_store_dwordx4 v[192:193], v[44:47], off offset:256
	v_lshlrev_b32_e32 v110, 16, v100
	v_and_b32_e32 v111, 0xffff0000, v100
	v_pk_fma_f32 v[44:45], v[50:51], 0.5, v[104:105] op_sel_hi:[1,0,1]
	v_pk_fma_f32 v[46:47], v[48:49], 0.5, v[86:87] op_sel_hi:[1,0,1]
	v_pk_fma_f32 v[48:49], v[42:43], 0.5, v[108:109] op_sel_hi:[1,0,1]
	v_pk_fma_f32 v[42:43], v[40:41], 0.5, v[106:107] op_sel_hi:[1,0,1]
	v_lshlrev_b32_e32 v100, 16, v101
	v_and_b32_e32 v101, 0xffff0000, v101
	v_lshlrev_b32_e32 v112, 16, v102
	v_and_b32_e32 v113, 0xffff0000, v102
	v_lshlrev_b32_e32 v102, 16, v103
	v_and_b32_e32 v103, 0xffff0000, v103
	v_cvt_pk_bf16_f32 v40, v46, v47
	v_cvt_pk_bf16_f32 v41, v44, v45
	v_cvt_pk_bf16_f32 v42, v42, v43
	v_cvt_pk_bf16_f32 v43, v48, v49
	global_store_dwordx4 v[194:195], v[40:43], off
	v_pk_fma_f32 v[38:39], v[38:39], 0.5, v[100:101] op_sel_hi:[1,0,1]
	v_pk_fma_f32 v[36:37], v[36:37], 0.5, v[110:111] op_sel_hi:[1,0,1]
	v_pk_fma_f32 v[40:41], v[30:31], 0.5, v[102:103] op_sel_hi:[1,0,1]
	v_pk_fma_f32 v[30:31], v[28:29], 0.5, v[112:113] op_sel_hi:[1,0,1]
	v_lshlrev_b32_e32 v114, 16, v120
	v_and_b32_e32 v115, 0xffff0000, v120
	v_lshlrev_b32_e32 v116, 16, v121
	v_and_b32_e32 v117, 0xffff0000, v121
	v_lshlrev_b32_e32 v118, 16, v122
	v_and_b32_e32 v119, 0xffff0000, v122
	v_lshlrev_b32_e32 v120, 16, v123
	v_and_b32_e32 v121, 0xffff0000, v123
	v_cvt_pk_bf16_f32 v28, v36, v37
	v_cvt_pk_bf16_f32 v29, v38, v39
	v_cvt_pk_bf16_f32 v30, v30, v31
	v_cvt_pk_bf16_f32 v31, v40, v41
	global_store_dwordx4 v[98:99], v[28:31], off offset:256
	v_lshlrev_b32_e32 v122, 16, v92
	v_and_b32_e32 v123, 0xffff0000, v92
	v_pk_fma_f32 v[28:29], v[34:35], 0.5, v[116:117] op_sel_hi:[1,0,1]
	v_pk_fma_f32 v[30:31], v[32:33], 0.5, v[114:115] op_sel_hi:[1,0,1]
	v_pk_fma_f32 v[32:33], v[26:27], 0.5, v[120:121] op_sel_hi:[1,0,1]
	v_pk_fma_f32 v[26:27], v[24:25], 0.5, v[118:119] op_sel_hi:[1,0,1]
	v_lshlrev_b32_e32 v92, 16, v93
	v_and_b32_e32 v93, 0xffff0000, v93
	v_lshlrev_b32_e32 v144, 16, v94
	v_and_b32_e32 v145, 0xffff0000, v94
	v_lshlrev_b32_e32 v94, 16, v95
	v_and_b32_e32 v95, 0xffff0000, v95
	v_cvt_pk_bf16_f32 v24, v30, v31
	v_cvt_pk_bf16_f32 v25, v28, v29
	v_cvt_pk_bf16_f32 v26, v26, v27
	v_cvt_pk_bf16_f32 v27, v32, v33
	global_store_dwordx4 v[96:97], v[24:27], off
	v_pk_fma_f32 v[22:23], v[22:23], 0.5, v[92:93] op_sel_hi:[1,0,1]
	v_pk_fma_f32 v[20:21], v[20:21], 0.5, v[122:123] op_sel_hi:[1,0,1]
	v_pk_fma_f32 v[24:25], v[14:15], 0.5, v[94:95] op_sel_hi:[1,0,1]
	v_pk_fma_f32 v[14:15], v[12:13], 0.5, v[144:145] op_sel_hi:[1,0,1]
	v_lshlrev_b32_e32 v146, 16, v124
	v_and_b32_e32 v147, 0xffff0000, v124
	v_lshlrev_b32_e32 v124, 16, v125
	v_and_b32_e32 v125, 0xffff0000, v125
	v_lshlrev_b32_e32 v148, 16, v126
	v_and_b32_e32 v149, 0xffff0000, v126
	v_lshlrev_b32_e32 v126, 16, v127
	v_and_b32_e32 v127, 0xffff0000, v127
	v_cvt_pk_bf16_f32 v12, v20, v21
	v_cvt_pk_bf16_f32 v13, v22, v23
	v_cvt_pk_bf16_f32 v14, v14, v15
	v_cvt_pk_bf16_f32 v15, v24, v25
	global_store_dwordx4 v[90:91], v[12:15], off offset:256
	v_lshlrev_b32_e32 v150, 16, v80
	v_and_b32_e32 v151, 0xffff0000, v80
	v_pk_fma_f32 v[12:13], v[18:19], 0.5, v[124:125] op_sel_hi:[1,0,1]
	v_pk_fma_f32 v[14:15], v[16:17], 0.5, v[146:147] op_sel_hi:[1,0,1]
	v_pk_fma_f32 v[16:17], v[10:11], 0.5, v[126:127] op_sel_hi:[1,0,1]
	v_pk_fma_f32 v[10:11], v[8:9], 0.5, v[148:149] op_sel_hi:[1,0,1]
	v_lshlrev_b32_e32 v80, 16, v81
	v_and_b32_e32 v81, 0xffff0000, v81
	v_lshlrev_b32_e32 v152, 16, v82
	v_and_b32_e32 v153, 0xffff0000, v82
	v_lshlrev_b32_e32 v82, 16, v83
	v_and_b32_e32 v83, 0xffff0000, v83
	v_cvt_pk_bf16_f32 v8, v14, v15
	v_cvt_pk_bf16_f32 v9, v12, v13
	v_cvt_pk_bf16_f32 v10, v10, v11
	v_cvt_pk_bf16_f32 v11, v16, v17
	global_store_dwordx4 v[88:89], v[8:11], off
	v_pk_fma_f32 v[6:7], v[6:7], 0.5, v[80:81] op_sel_hi:[1,0,1]
	v_pk_fma_f32 v[4:5], v[4:5], 0.5, v[150:151] op_sel_hi:[1,0,1]
	v_pk_fma_f32 v[8:9], v[2:3], 0.5, v[82:83] op_sel_hi:[1,0,1]
	v_pk_fma_f32 v[2:3], v[0:1], 0.5, v[152:153] op_sel_hi:[1,0,1]
	v_cvt_pk_bf16_f32 v0, v4, v5
	v_cvt_pk_bf16_f32 v1, v6, v7
	v_cvt_pk_bf16_f32 v2, v2, v3
	v_cvt_pk_bf16_f32 v3, v8, v9
	s_and_b64 vcc, exec, s[0:1]
	global_store_dwordx4 v[72:73], v[0:3], off offset:256
	s_cbranch_vccz .LBB0_930
	s_waitcnt vmcnt(0)
	s_cmpk_gt_u32 s6, 0xff
	s_cbranch_scc1 .LBB0_945
	s_barrier
